# GEMM loops: s_setprio flips moved across the phase barriers (MFMA wave reaches/leaves barrier one slot earlier)
# speedup vs baseline: 1.0039x; 1.0039x over previous
; #define PG8_STAGE(bufoff, gbase, voff) do { _Pragma("unroll") for (int _i = 0; _i < 2; ++_i) \
;         __builtin_amdgcn_global_load_lds((const unsigned*)((const char*)(gbase) + (voff)[_i]), (LAS unsigned*)(lds + (bufoff) + ldsw + _i * 8192), 16, 0, 0); } while (0)
; #define PG8_LDA(dst, b, h) do { _Pragma("unroll") for (int m = 0; m < 4; ++m) _Pragma("unroll") for (int k = 0; k < 2; ++k) dst[m][k] = *(const LAS bf16x8*)(lds + PG8_SA(b, h) + aoff + m * 2048 + k * 1024); } while (0)
; #define PG8_LDB(dst, b, h) do { _Pragma("unroll") for (int n = 0; n < 2; ++n) _Pragma("unroll") for (int k = 0; k < 2; ++k) dst[n][k] = *(const LAS bf16x8*)(lds + PG8_SB(b, h) + boff + n * 2048 + k * 1024); } while (0)
; #define PG8_MMA(ai, bj, At, Bt) do { __builtin_amdgcn_s_setprio(3); _Pragma("unroll") for (int m = 0; m < 4; ++m) _Pragma("unroll") for (int n = 0; n < 2; ++n) _Pragma("unroll") for (int k = 0; k < 2; ++k) \
;         acc[ai][bj][m][n] = __builtin_amdgcn_mfma_f32_16x16x32_bf16(Bt[n][k], At[m][k], acc[ai][bj][m][n], 0, 0, 0); __builtin_amdgcn_s_setprio(0); } while (0)
; #define PG8_BAR __builtin_amdgcn_s_barrier()
; template <class Epi, bool ALIGN_EPI>
; __device__ __forceinline__ void gemm_phase(LAS unsigned char* lds, const Gemm g, const StaticOrder& S, const Epi& E) {
;     ...
;         const bool has_next = S.next(ui + 1, nxt);
;         const char* nA = has_next ? (const char*)g.A + (size_t)nxt.pm * tstep : cA; const char* nB = has_next ? (const char*)g.Bt + (size_t)nxt.pn * tstep : cB;
;         for (int t = 0; t < nt; t += 2) {
;             const bool last = (t == nt - 2);
;             const char* a1 = cA + (size_t)(t + 1) * kstep;
;             const char* a2 = last ? nA : cA + (size_t)(t + 2) * kstep; const char* b2 = last ? nB : cB + (size_t)(t + 2) * kstep;
;             const char* a3 = a2 + kstep; const char* b3 = b2 + kstep;
;             PG8_LDB(B0, 0, 0); PG8_LDB(B1, 0, 1); PG8_SCHED; PG8_LDA(At, 0, 0); PG8_STAGE(PG8_SA(1, 1), a1 + hstep, voffA);
;             PG8_WAIT_V(8); PG8_WAIT_L(0); PG8_BAR; PG8_MMA(0, 0, At, B0); PG8_MMA(0, 1, At, B1); PG8_BAR; PG8_SCHED;
;             PG8_LDA(At, 0, 1); PG8_STAGE(PG8_SB(0, 0), b2, voffB); PG8_STAGE(PG8_SB(0, 1), b2 + hstep, voffB); PG8_STAGE(PG8_SA(0, 0), a2, voffA);
;             PG8_WAIT_V(8); PG8_WAIT_L(0); PG8_BAR; PG8_MMA(1, 0, At, B0); PG8_MMA(1, 1, At, B1); PG8_BAR; PG8_SCHED;
.LBB0_292:
	s_ashr_i32 s69, s68, 31
	s_lshl_b64 s[8:9], s[68:69], 19
	s_add_u32 s70, s34, s8
	s_addc_u32 s71, s35, s9
	s_and_b64 s[8:9], s[0:1], exec
	s_cselect_b32 s5, s71, s81
	s_cselect_b32 s69, s70, s80
	s_ashr_i32 s67, s66, 31
	s_lshl_b64 s[8:9], s[66:67], 19
	s_add_u32 s72, s26, s8
	s_addc_u32 s73, s27, s9
	s_and_b64 s[8:9], s[0:1], exec
	s_cselect_b32 s67, s73, s83
	s_cselect_b32 s79, s72, s82
	s_add_u32 s80, s80, 0x40080
	s_addc_u32 s81, s81, 0
	s_add_u32 vcc_lo, s82, 0x100
	s_addc_u32 vcc_hi, s83, 0
	s_mov_b32 s8, -2
	ds_read_b128 v[148:151], v192
	ds_read_b128 v[152:155], v192 offset:1024
	ds_read_b128 v[156:159], v192 offset:2048
	ds_read_b128 v[160:163], v192 offset:3072
	ds_read_b128 v[164:167], v193
	ds_read_b128 v[168:171], v193 offset:1024
	ds_read_b128 v[172:175], v193 offset:2048
	ds_read_b128 v[176:179], v193 offset:3072
	s_add_u32 s9, s80, 0xfffc0080
	s_addc_u32 s50, s81, -1
	s_cmp_eq_u32 s8, 12
	s_cselect_b32 s85, s5, s50
	s_cselect_b32 s84, s69, s9
	s_cselect_b32 s83, s67, vcc_hi
	s_cselect_b32 s82, s79, vcc_lo
	v_lshl_add_u64 v[224:225], s[80:81], 0, v[140:141]
	s_add_i32 m0, s76, 0xc000
	ds_read_b128 v[180:183], v194
	ds_read_b128 v[196:199], v194 offset:1024
	ds_read_b128 v[200:203], v194 offset:2048
	ds_read_b128 v[204:207], v194 offset:3072
	ds_read_b128 v[208:211], v194 offset:4096
	ds_read_b128 v[212:215], v194 offset:5120
	ds_read_b128 v[216:219], v194 offset:6144
	ds_read_b128 v[220:223], v194 offset:7168
	global_load_lds_dwordx4 v[224:225], off
	v_lshl_add_u64 v[224:225], s[80:81], 0, v[142:143]
	s_add_i32 m0, s76, 0xe000
	s_nop 0
	global_load_lds_dwordx4 v[224:225], off
	s_waitcnt vmcnt(8)
	s_waitcnt lgkmcnt(0)
	s_setprio 3
	s_barrier
	s_waitcnt lgkmcnt(0)
	v_mfma_f32_16x16x32_bf16 v[118:121], v[148:151], v[180:183], 0
	v_mfma_f32_16x16x32_bf16 v[114:117], v[156:159], v[180:183], 0
	v_mfma_f32_16x16x32_bf16 v[102:105], v[148:151], v[200:203], 0
	v_mfma_f32_16x16x32_bf16 v[98:101], v[156:159], v[200:203], 0
	v_mfma_f32_16x16x32_bf16 v[86:89], v[148:151], v[208:211], 0
	v_mfma_f32_16x16x32_bf16 v[82:85], v[156:159], v[208:211], 0
	v_mfma_f32_16x16x32_bf16 v[70:73], v[148:151], v[216:219], 0
	v_mfma_f32_16x16x32_bf16 v[66:69], v[156:159], v[216:219], 0
	v_mfma_f32_16x16x32_bf16 v[118:121], v[152:155], v[196:199], v[118:121]
	v_mfma_f32_16x16x32_bf16 v[114:117], v[160:163], v[196:199], v[114:117]
	v_mfma_f32_16x16x32_bf16 v[102:105], v[152:155], v[204:207], v[102:105]
	v_mfma_f32_16x16x32_bf16 v[98:101], v[160:163], v[204:207], v[98:101]
	v_mfma_f32_16x16x32_bf16 v[86:89], v[152:155], v[212:215], v[86:89]
	v_mfma_f32_16x16x32_bf16 v[82:85], v[160:163], v[212:215], v[82:85]
	v_mfma_f32_16x16x32_bf16 v[70:73], v[152:155], v[220:223], v[70:73]
	v_mfma_f32_16x16x32_bf16 v[66:69], v[160:163], v[220:223], v[66:69]
	v_mfma_f32_16x16x32_bf16 v[126:129], v[164:167], v[180:183], 0
	v_mfma_f32_16x16x32_bf16 v[122:125], v[172:175], v[180:183], 0
	v_mfma_f32_16x16x32_bf16 v[110:113], v[164:167], v[200:203], 0
	v_mfma_f32_16x16x32_bf16 v[106:109], v[172:175], v[200:203], 0
	v_mfma_f32_16x16x32_bf16 v[94:97], v[164:167], v[208:211], 0
	v_mfma_f32_16x16x32_bf16 v[90:93], v[172:175], v[208:211], 0
	v_mfma_f32_16x16x32_bf16 v[78:81], v[164:167], v[216:219], 0
	v_mfma_f32_16x16x32_bf16 v[74:77], v[172:175], v[216:219], 0
	v_mfma_f32_16x16x32_bf16 v[126:129], v[168:171], v[196:199], v[126:129]
	v_mfma_f32_16x16x32_bf16 v[122:125], v[176:179], v[196:199], v[122:125]
	v_mfma_f32_16x16x32_bf16 v[110:113], v[168:171], v[204:207], v[110:113]
	v_mfma_f32_16x16x32_bf16 v[106:109], v[176:179], v[204:207], v[106:109]
	v_mfma_f32_16x16x32_bf16 v[94:97], v[168:171], v[212:215], v[94:97]
	v_mfma_f32_16x16x32_bf16 v[90:93], v[176:179], v[212:215], v[90:93]
	v_mfma_f32_16x16x32_bf16 v[78:81], v[168:171], v[220:223], v[78:81]
	v_mfma_f32_16x16x32_bf16 v[74:77], v[176:179], v[220:223], v[74:77]
	s_barrier
	s_setprio 0
	s_add_i32 s9, s95, s33
	v_lshl_add_u64 v[224:225], s[82:83], 0, v[132:133]
	s_mov_b32 m0, s9
	ds_read_b128 v[180:183], v194 offset:16384
	ds_read_b128 v[196:199], v194 offset:17408
	ds_read_b128 v[200:203], v194 offset:18432
	ds_read_b128 v[204:207], v194 offset:19456
	ds_read_b128 v[208:211], v194 offset:20480
	ds_read_b128 v[212:215], v194 offset:21504
	ds_read_b128 v[216:219], v194 offset:22528
	ds_read_b128 v[220:223], v194 offset:23552
	global_load_lds_dwordx4 v[224:225], off
	s_add_i32 m0, s9, 0x2000
	s_add_u32 s50, s82, 0x40000
	v_lshl_add_u64 v[226:227], s[82:83], 0, v[136:137]
	s_addc_u32 s51, s83, 0
	s_add_i32 s9, s96, s33
	global_load_lds_dwordx4 v[226:227], off
	v_lshl_add_u64 v[228:229], s[50:51], 0, v[132:133]
	s_mov_b32 m0, s9
	v_lshl_add_u64 v[230:231], s[84:85], 0, v[134:135]
	global_load_lds_dwordx4 v[228:229], off
	v_lshl_add_u64 v[228:229], s[50:51], 0, v[136:137]
	s_add_i32 m0, s9, 0x2000
	s_nop 0
	global_load_lds_dwordx4 v[228:229], off
	v_lshl_add_u64 v[228:229], s[84:85], 0, v[130:131]
	s_mov_b32 m0, s76
	s_nop 0
	global_load_lds_dwordx4 v[228:229], off
	s_mov_b32 m0, s77
	s_nop 0
	global_load_lds_dwordx4 v[230:231], off
	s_waitcnt vmcnt(8)
	s_waitcnt lgkmcnt(0)
	s_setprio 3
	s_barrier
; #define PG8_STAGE(bufoff, gbase, voff) do { _Pragma("unroll") for (int _i = 0; _i < 2; ++_i) \
;         __builtin_amdgcn_global_load_lds((const unsigned*)((const char*)(gbase) + (voff)[_i]), (LAS unsigned*)(lds + (bufoff) + ldsw + _i * 8192), 16, 0, 0); } while (0)
; #define PG8_LDA(dst, b, h) do { _Pragma("unroll") for (int m = 0; m < 4; ++m) _Pragma("unroll") for (int k = 0; k < 2; ++k) dst[m][k] = *(const LAS bf16x8*)(lds + PG8_SA(b, h) + aoff + m * 2048 + k * 1024); } while (0)
; #define PG8_LDB(dst, b, h) do { _Pragma("unroll") for (int n = 0; n < 2; ++n) _Pragma("unroll") for (int k = 0; k < 2; ++k) dst[n][k] = *(const LAS bf16x8*)(lds + PG8_SB(b, h) + boff + n * 2048 + k * 1024); } while (0)
; #define PG8_MMA(ai, bj, At, Bt) do { __builtin_amdgcn_s_setprio(3); _Pragma("unroll") for (int m = 0; m < 4; ++m) _Pragma("unroll") for (int n = 0; n < 2; ++n) _Pragma("unroll") for (int k = 0; k < 2; ++k) \
;         acc[ai][bj][m][n] = __builtin_amdgcn_mfma_f32_16x16x32_bf16(Bt[n][k], At[m][k], acc[ai][bj][m][n], 0, 0, 0); __builtin_amdgcn_s_setprio(0); } while (0)
; #define PG8_WAIT_V(n) asm volatile("s_waitcnt vmcnt(" #n ")" ::: "memory")
; #define PG8_WAIT_L(n) asm volatile("s_waitcnt lgkmcnt(" #n ")" ::: "memory")
; #define PG8_BAR __builtin_amdgcn_s_barrier()
; #define PG8_SCHED __builtin_amdgcn_sched_barrier(0)
; template <class Epi, bool ALIGN_EPI>
; __device__ __forceinline__ void gemm_phase(LAS unsigned char* lds, const Gemm g, const StaticOrder& S, const Epi& E) {
;     ...
;             PG8_WAIT_V(8); PG8_WAIT_L(0); PG8_BAR; PG8_MMA(0, 0, At, B0); PG8_MMA(0, 1, At, B1); PG8_BAR; PG8_SCHED;
;             PG8_LDA(At, 0, 1); PG8_STAGE(PG8_SB(0, 0), b2, voffB); PG8_STAGE(PG8_SB(0, 1), b2 + hstep, voffB); PG8_STAGE(PG8_SA(0, 0), a2, voffA);
;             PG8_WAIT_V(8); PG8_WAIT_L(0); PG8_BAR; PG8_MMA(1, 0, At, B0); PG8_MMA(1, 1, At, B1); PG8_BAR; PG8_SCHED;
;             PG8_LDB(B0, 1, 0); PG8_LDB(B1, 1, 1); PG8_SCHED; PG8_LDA(At, 1, 0); PG8_STAGE(PG8_SA(0, 1), a2 + hstep, voffA);
;             PG8_WAIT_V(8); PG8_WAIT_L(0); PG8_BAR; PG8_MMA(0, 0, At, B0); PG8_MMA(0, 1, At, B1); PG8_BAR; PG8_SCHED;
	s_waitcnt lgkmcnt(0)
	v_mfma_f32_16x16x32_bf16 v[54:57], v[148:151], v[180:183], 0
	v_mfma_f32_16x16x32_bf16 v[50:53], v[156:159], v[180:183], 0
	v_mfma_f32_16x16x32_bf16 v[38:41], v[148:151], v[200:203], 0
	v_mfma_f32_16x16x32_bf16 v[34:37], v[156:159], v[200:203], 0
	v_mfma_f32_16x16x32_bf16 v[22:25], v[148:151], v[208:211], 0
	v_mfma_f32_16x16x32_bf16 v[18:21], v[156:159], v[208:211], 0
	v_mfma_f32_16x16x32_bf16 v[6:9], v[148:151], v[216:219], 0
	v_mfma_f32_16x16x32_bf16 v[2:5], v[156:159], v[216:219], 0
	v_mfma_f32_16x16x32_bf16 v[54:57], v[152:155], v[196:199], v[54:57]
	v_mfma_f32_16x16x32_bf16 v[50:53], v[160:163], v[196:199], v[50:53]
	v_mfma_f32_16x16x32_bf16 v[38:41], v[152:155], v[204:207], v[38:41]
	v_mfma_f32_16x16x32_bf16 v[34:37], v[160:163], v[204:207], v[34:37]
	v_mfma_f32_16x16x32_bf16 v[22:25], v[152:155], v[212:215], v[22:25]
	v_mfma_f32_16x16x32_bf16 v[18:21], v[160:163], v[212:215], v[18:21]
	v_mfma_f32_16x16x32_bf16 v[6:9], v[152:155], v[220:223], v[6:9]
	v_mfma_f32_16x16x32_bf16 v[2:5], v[160:163], v[220:223], v[2:5]
	v_mfma_f32_16x16x32_bf16 v[62:65], v[164:167], v[180:183], 0
	v_mfma_f32_16x16x32_bf16 v[58:61], v[172:175], v[180:183], 0
	v_mfma_f32_16x16x32_bf16 v[46:49], v[164:167], v[200:203], 0
	v_mfma_f32_16x16x32_bf16 v[42:45], v[172:175], v[200:203], 0
	v_mfma_f32_16x16x32_bf16 v[30:33], v[164:167], v[208:211], 0
	v_mfma_f32_16x16x32_bf16 v[26:29], v[172:175], v[208:211], 0
	v_mfma_f32_16x16x32_bf16 v[14:17], v[164:167], v[216:219], 0
	v_mfma_f32_16x16x32_bf16 v[10:13], v[172:175], v[216:219], 0
	v_mfma_f32_16x16x32_bf16 v[62:65], v[168:171], v[196:199], v[62:65]
	v_mfma_f32_16x16x32_bf16 v[58:61], v[176:179], v[196:199], v[58:61]
	v_mfma_f32_16x16x32_bf16 v[46:49], v[168:171], v[204:207], v[46:49]
	v_mfma_f32_16x16x32_bf16 v[42:45], v[176:179], v[204:207], v[42:45]
	v_mfma_f32_16x16x32_bf16 v[30:33], v[168:171], v[212:215], v[30:33]
	v_mfma_f32_16x16x32_bf16 v[26:29], v[176:179], v[212:215], v[26:29]
	v_mfma_f32_16x16x32_bf16 v[14:17], v[168:171], v[220:223], v[14:17]
	v_mfma_f32_16x16x32_bf16 v[10:13], v[176:179], v[220:223], v[10:13]
	s_barrier
	s_setprio 0
	s_add_i32 s9, 0, 0x18000
	v_add_u32_e32 v138, s9, v189
	s_add_i32 s89, 0, 0x1c000
	ds_read_b128 v[148:151], v138
	ds_read_b128 v[152:155], v138 offset:1024
	ds_read_b128 v[156:159], v138 offset:2048
	ds_read_b128 v[160:163], v138 offset:3072
	v_add_u32_e32 v138, s89, v189
	ds_read_b128 v[164:167], v138
	ds_read_b128 v[168:171], v138 offset:1024
	ds_read_b128 v[172:175], v138 offset:2048
	ds_read_b128 v[176:179], v138 offset:3072
	s_add_u32 s50, s84, 0x40000
	s_addc_u32 s51, s85, 0
	s_mov_b32 m0, s86
	v_lshl_add_u64 v[232:233], s[50:51], 0, v[130:131]
	ds_read_b128 v[180:183], v194 offset:32768
	ds_read_b128 v[196:199], v194 offset:33792
	ds_read_b128 v[200:203], v194 offset:34816
	ds_read_b128 v[204:207], v194 offset:35840
	ds_read_b128 v[208:211], v194 offset:36864
	ds_read_b128 v[212:215], v194 offset:37888
	ds_read_b128 v[216:219], v194 offset:38912
	ds_read_b128 v[220:223], v194 offset:39936
	global_load_lds_dwordx4 v[232:233], off
	v_lshl_add_u64 v[232:233], s[50:51], 0, v[134:135]
	s_mov_b32 m0, s87
	s_nop 0
	global_load_lds_dwordx4 v[232:233], off
	s_waitcnt vmcnt(8)
	s_waitcnt lgkmcnt(0)
	s_setprio 3
	s_barrier
	s_waitcnt lgkmcnt(0)
	v_mfma_f32_16x16x32_bf16 v[118:121], v[148:151], v[180:183], v[118:121]
	v_mfma_f32_16x16x32_bf16 v[114:117], v[156:159], v[180:183], v[114:117]
	v_mfma_f32_16x16x32_bf16 v[102:105], v[148:151], v[200:203], v[102:105]
	v_mfma_f32_16x16x32_bf16 v[98:101], v[156:159], v[200:203], v[98:101]
	v_mfma_f32_16x16x32_bf16 v[86:89], v[148:151], v[208:211], v[86:89]
	v_mfma_f32_16x16x32_bf16 v[82:85], v[156:159], v[208:211], v[82:85]
	v_mfma_f32_16x16x32_bf16 v[70:73], v[148:151], v[216:219], v[70:73]
	v_mfma_f32_16x16x32_bf16 v[66:69], v[156:159], v[216:219], v[66:69]
	v_mfma_f32_16x16x32_bf16 v[118:121], v[152:155], v[196:199], v[118:121]
	v_mfma_f32_16x16x32_bf16 v[114:117], v[160:163], v[196:199], v[114:117]
	v_mfma_f32_16x16x32_bf16 v[102:105], v[152:155], v[204:207], v[102:105]
	v_mfma_f32_16x16x32_bf16 v[98:101], v[160:163], v[204:207], v[98:101]
	v_mfma_f32_16x16x32_bf16 v[86:89], v[152:155], v[212:215], v[86:89]
	v_mfma_f32_16x16x32_bf16 v[82:85], v[160:163], v[212:215], v[82:85]
	v_mfma_f32_16x16x32_bf16 v[70:73], v[152:155], v[220:223], v[70:73]
	v_mfma_f32_16x16x32_bf16 v[66:69], v[160:163], v[220:223], v[66:69]
	v_mfma_f32_16x16x32_bf16 v[126:129], v[164:167], v[180:183], v[126:129]
	v_mfma_f32_16x16x32_bf16 v[122:125], v[172:175], v[180:183], v[122:125]
	v_mfma_f32_16x16x32_bf16 v[110:113], v[164:167], v[200:203], v[110:113]
	v_mfma_f32_16x16x32_bf16 v[106:109], v[172:175], v[200:203], v[106:109]
	v_mfma_f32_16x16x32_bf16 v[94:97], v[164:167], v[208:211], v[94:97]
	v_mfma_f32_16x16x32_bf16 v[90:93], v[172:175], v[208:211], v[90:93]
	v_mfma_f32_16x16x32_bf16 v[78:81], v[164:167], v[216:219], v[78:81]
	v_mfma_f32_16x16x32_bf16 v[74:77], v[172:175], v[216:219], v[74:77]
	v_mfma_f32_16x16x32_bf16 v[126:129], v[168:171], v[196:199], v[126:129]
	v_mfma_f32_16x16x32_bf16 v[122:125], v[176:179], v[196:199], v[122:125]
	v_mfma_f32_16x16x32_bf16 v[110:113], v[168:171], v[204:207], v[110:113]
	v_mfma_f32_16x16x32_bf16 v[106:109], v[176:179], v[204:207], v[106:109]
	v_mfma_f32_16x16x32_bf16 v[94:97], v[168:171], v[212:215], v[94:97]
	v_mfma_f32_16x16x32_bf16 v[90:93], v[176:179], v[212:215], v[90:93]
	v_mfma_f32_16x16x32_bf16 v[78:81], v[168:171], v[220:223], v[78:81]
	v_mfma_f32_16x16x32_bf16 v[74:77], v[176:179], v[220:223], v[74:77]
	s_barrier
; #define PG8_STAGE(bufoff, gbase, voff) do { _Pragma("unroll") for (int _i = 0; _i < 2; ++_i) \
;         __builtin_amdgcn_global_load_lds((const unsigned*)((const char*)(gbase) + (voff)[_i]), (LAS unsigned*)(lds + (bufoff) + ldsw + _i * 8192), 16, 0, 0); } while (0)
; #define PG8_LDA(dst, b, h) do { _Pragma("unroll") for (int m = 0; m < 4; ++m) _Pragma("unroll") for (int k = 0; k < 2; ++k) dst[m][k] = *(const LAS bf16x8*)(lds + PG8_SA(b, h) + aoff + m * 2048 + k * 1024); } while (0)
; #define PG8_LDB(dst, b, h) do { _Pragma("unroll") for (int n = 0; n < 2; ++n) _Pragma("unroll") for (int k = 0; k < 2; ++k) dst[n][k] = *(const LAS bf16x8*)(lds + PG8_SB(b, h) + boff + n * 2048 + k * 1024); } while (0)
; #define PG8_MMA(ai, bj, At, Bt) do { __builtin_amdgcn_s_setprio(3); _Pragma("unroll") for (int m = 0; m < 4; ++m) _Pragma("unroll") for (int n = 0; n < 2; ++n) _Pragma("unroll") for (int k = 0; k < 2; ++k) \
;         acc[ai][bj][m][n] = __builtin_amdgcn_mfma_f32_16x16x32_bf16(Bt[n][k], At[m][k], acc[ai][bj][m][n], 0, 0, 0); __builtin_amdgcn_s_setprio(0); } while (0)
; #define PG8_WAIT_V(n) asm volatile("s_waitcnt vmcnt(" #n ")" ::: "memory")
; #define PG8_WAIT_L(n) asm volatile("s_waitcnt lgkmcnt(" #n ")" ::: "memory")
; #define PG8_BAR __builtin_amdgcn_s_barrier()
; #define PG8_SCHED __builtin_amdgcn_sched_barrier(0)
; template <class Epi, bool ALIGN_EPI>
; __device__ __forceinline__ void gemm_phase(LAS unsigned char* lds, const Gemm g, const StaticOrder& S, const Epi& E) {
;     ...
;             PG8_LDB(B0, 0, 0); PG8_LDB(B1, 0, 1); PG8_SCHED; PG8_LDA(At, 0, 0); PG8_STAGE(PG8_SA(1, 1), a1 + hstep, voffA);
;             PG8_WAIT_V(8); PG8_WAIT_L(0); PG8_BAR; PG8_MMA(0, 0, At, B0); PG8_MMA(0, 1, At, B1); PG8_BAR; PG8_SCHED;
;     ...
;             PG8_LDA(At, 1, 1); PG8_STAGE(PG8_SB(1, 0), b3, voffB); PG8_STAGE(PG8_SB(1, 1), b3 + hstep, voffB); PG8_STAGE(PG8_SA(1, 0), a3, voffA);
;             PG8_WAIT_V(8); PG8_WAIT_L(0); PG8_BAR; PG8_MMA(1, 0, At, B0); PG8_MMA(1, 1, At, B1); PG8_BAR; PG8_SCHED;
	s_setprio 0
	s_add_i32 s9, s9, s33
	v_lshl_add_u64 v[224:225], v[224:225], 0, s[62:63]
	s_mov_b32 m0, s9
	ds_read_b128 v[180:183], v194 offset:49152
	ds_read_b128 v[196:199], v194 offset:50176
	ds_read_b128 v[200:203], v194 offset:51200
	ds_read_b128 v[204:207], v194 offset:52224
	ds_read_b128 v[208:211], v194 offset:53248
	ds_read_b128 v[212:215], v194 offset:54272
	ds_read_b128 v[216:219], v194 offset:55296
	ds_read_b128 v[220:223], v194 offset:56320
	global_load_lds_dwordx4 v[224:225], off
	s_add_i32 m0, s9, 0x2000
	s_add_u32 s50, s82, 0x40080
	v_lshl_add_u64 v[224:225], v[226:227], 0, s[62:63]
	s_addc_u32 s51, s83, 0
	s_add_i32 s9, s89, s33
	global_load_lds_dwordx4 v[224:225], off
	v_lshl_add_u64 v[224:225], s[50:51], 0, v[132:133]
	s_mov_b32 m0, s9
	s_nop 0
	global_load_lds_dwordx4 v[224:225], off
	v_lshl_add_u64 v[224:225], s[50:51], 0, v[136:137]
	s_add_i32 m0, s9, 0x2000
	s_nop 0
	global_load_lds_dwordx4 v[224:225], off
	v_lshl_add_u64 v[224:225], v[228:229], 0, s[62:63]
	s_mov_b32 m0, s93
	s_nop 0
	global_load_lds_dwordx4 v[224:225], off
	v_lshl_add_u64 v[224:225], v[230:231], 0, s[62:63]
	s_mov_b32 m0, s94
	s_nop 0
	global_load_lds_dwordx4 v[224:225], off
	s_waitcnt vmcnt(8)
	s_waitcnt lgkmcnt(0)
	s_setprio 3
	s_barrier
	s_waitcnt lgkmcnt(0)
	v_mfma_f32_16x16x32_bf16 v[54:57], v[148:151], v[180:183], v[54:57]
	v_mfma_f32_16x16x32_bf16 v[50:53], v[156:159], v[180:183], v[50:53]
	v_mfma_f32_16x16x32_bf16 v[38:41], v[148:151], v[200:203], v[38:41]
	v_mfma_f32_16x16x32_bf16 v[34:37], v[156:159], v[200:203], v[34:37]
	v_mfma_f32_16x16x32_bf16 v[22:25], v[148:151], v[208:211], v[22:25]
	v_mfma_f32_16x16x32_bf16 v[18:21], v[156:159], v[208:211], v[18:21]
	v_mfma_f32_16x16x32_bf16 v[6:9], v[148:151], v[216:219], v[6:9]
	v_mfma_f32_16x16x32_bf16 v[2:5], v[156:159], v[216:219], v[2:5]
	v_mfma_f32_16x16x32_bf16 v[54:57], v[152:155], v[196:199], v[54:57]
	v_mfma_f32_16x16x32_bf16 v[50:53], v[160:163], v[196:199], v[50:53]
	v_mfma_f32_16x16x32_bf16 v[38:41], v[152:155], v[204:207], v[38:41]
	v_mfma_f32_16x16x32_bf16 v[34:37], v[160:163], v[204:207], v[34:37]
	v_mfma_f32_16x16x32_bf16 v[22:25], v[152:155], v[212:215], v[22:25]
	v_mfma_f32_16x16x32_bf16 v[18:21], v[160:163], v[212:215], v[18:21]
	v_mfma_f32_16x16x32_bf16 v[6:9], v[152:155], v[220:223], v[6:9]
	v_mfma_f32_16x16x32_bf16 v[2:5], v[160:163], v[220:223], v[2:5]
	v_mfma_f32_16x16x32_bf16 v[62:65], v[164:167], v[180:183], v[62:65]
	v_mfma_f32_16x16x32_bf16 v[58:61], v[172:175], v[180:183], v[58:61]
	v_mfma_f32_16x16x32_bf16 v[46:49], v[164:167], v[200:203], v[46:49]
	v_mfma_f32_16x16x32_bf16 v[42:45], v[172:175], v[200:203], v[42:45]
	v_mfma_f32_16x16x32_bf16 v[30:33], v[164:167], v[208:211], v[30:33]
	v_mfma_f32_16x16x32_bf16 v[26:29], v[172:175], v[208:211], v[26:29]
	v_mfma_f32_16x16x32_bf16 v[14:17], v[164:167], v[216:219], v[14:17]
	v_mfma_f32_16x16x32_bf16 v[10:13], v[172:175], v[216:219], v[10:13]
	v_mfma_f32_16x16x32_bf16 v[62:65], v[168:171], v[196:199], v[62:65]
	v_mfma_f32_16x16x32_bf16 v[58:61], v[176:179], v[196:199], v[58:61]
	v_mfma_f32_16x16x32_bf16 v[46:49], v[168:171], v[204:207], v[46:49]
	v_mfma_f32_16x16x32_bf16 v[42:45], v[176:179], v[204:207], v[42:45]
	v_mfma_f32_16x16x32_bf16 v[30:33], v[168:171], v[212:215], v[30:33]
	v_mfma_f32_16x16x32_bf16 v[26:29], v[176:179], v[212:215], v[26:29]
	v_mfma_f32_16x16x32_bf16 v[14:17], v[168:171], v[220:223], v[14:17]
	v_mfma_f32_16x16x32_bf16 v[10:13], v[176:179], v[220:223], v[10:13]
	s_barrier
	s_setprio 0
	s_add_i32 s8, s8, 2
	s_add_u32 s80, s80, 0x100
	s_addc_u32 s81, s81, 0
	s_add_u32 vcc_lo, vcc_lo, 0x100
	s_addc_u32 vcc_hi, vcc_hi, 0
.LBB0_293:
	ds_read_b128 v[148:151], v192
	ds_read_b128 v[152:155], v192 offset:1024
	ds_read_b128 v[156:159], v192 offset:2048
	ds_read_b128 v[160:163], v192 offset:3072
	ds_read_b128 v[164:167], v193
	ds_read_b128 v[168:171], v193 offset:1024
	ds_read_b128 v[172:175], v193 offset:2048
	ds_read_b128 v[176:179], v193 offset:3072
	s_add_u32 s9, s80, 0xfffc0080
	s_addc_u32 s50, s81, -1
	s_cmp_eq_u32 s8, 12
	s_cselect_b32 s85, s5, s50
	s_cselect_b32 s84, s69, s9
	s_cselect_b32 s83, s67, vcc_hi
	s_cselect_b32 s82, s79, vcc_lo
	v_lshl_add_u64 v[224:225], s[80:81], 0, v[140:141]
	s_add_i32 m0, s76, 0xc000
	ds_read_b128 v[180:183], v194
	ds_read_b128 v[196:199], v194 offset:1024
	ds_read_b128 v[200:203], v194 offset:2048
	ds_read_b128 v[204:207], v194 offset:3072
	ds_read_b128 v[208:211], v194 offset:4096
	ds_read_b128 v[212:215], v194 offset:5120
	ds_read_b128 v[216:219], v194 offset:6144
	ds_read_b128 v[220:223], v194 offset:7168
	global_load_lds_dwordx4 v[224:225], off
	v_lshl_add_u64 v[224:225], s[80:81], 0, v[142:143]
	s_add_i32 m0, s76, 0xe000
	s_nop 0
	global_load_lds_dwordx4 v[224:225], off
	s_waitcnt vmcnt(8)
	s_waitcnt lgkmcnt(0)
	s_setprio 3
	s_barrier
; #define PG8_STAGE(bufoff, gbase, voff) do { _Pragma("unroll") for (int _i = 0; _i < 2; ++_i) \
;         __builtin_amdgcn_global_load_lds((const unsigned*)((const char*)(gbase) + (voff)[_i]), (LAS unsigned*)(lds + (bufoff) + ldsw + _i * 8192), 16, 0, 0); } while (0)
; #define PG8_LDA(dst, b, h) do { _Pragma("unroll") for (int m = 0; m < 4; ++m) _Pragma("unroll") for (int k = 0; k < 2; ++k) dst[m][k] = *(const LAS bf16x8*)(lds + PG8_SA(b, h) + aoff + m * 2048 + k * 1024); } while (0)
; #define PG8_MMA(ai, bj, At, Bt) do { __builtin_amdgcn_s_setprio(3); _Pragma("unroll") for (int m = 0; m < 4; ++m) _Pragma("unroll") for (int n = 0; n < 2; ++n) _Pragma("unroll") for (int k = 0; k < 2; ++k) \
;         acc[ai][bj][m][n] = __builtin_amdgcn_mfma_f32_16x16x32_bf16(Bt[n][k], At[m][k], acc[ai][bj][m][n], 0, 0, 0); __builtin_amdgcn_s_setprio(0); } while (0)
; #define PG8_WAIT_V(n) asm volatile("s_waitcnt vmcnt(" #n ")" ::: "memory")
; #define PG8_WAIT_L(n) asm volatile("s_waitcnt lgkmcnt(" #n ")" ::: "memory")
; #define PG8_BAR __builtin_amdgcn_s_barrier()
; #define PG8_SCHED __builtin_amdgcn_sched_barrier(0)
; template <class Epi, bool ALIGN_EPI>
; __device__ __forceinline__ void gemm_phase(LAS unsigned char* lds, const Gemm g, const StaticOrder& S, const Epi& E) {
;     ...
;             PG8_WAIT_V(8); PG8_WAIT_L(0); PG8_BAR; PG8_MMA(0, 0, At, B0); PG8_MMA(0, 1, At, B1); PG8_BAR; PG8_SCHED;
;             PG8_LDA(At, 0, 1); PG8_STAGE(PG8_SB(0, 0), b2, voffB); PG8_STAGE(PG8_SB(0, 1), b2 + hstep, voffB); PG8_STAGE(PG8_SA(0, 0), a2, voffA);
;             PG8_WAIT_V(8); PG8_WAIT_L(0); PG8_BAR; PG8_MMA(1, 0, At, B0); PG8_MMA(1, 1, At, B1); PG8_BAR; PG8_SCHED;
	s_waitcnt lgkmcnt(0)
	v_mfma_f32_16x16x32_bf16 v[118:121], v[148:151], v[180:183], v[118:121]
	v_mfma_f32_16x16x32_bf16 v[114:117], v[156:159], v[180:183], v[114:117]
	v_mfma_f32_16x16x32_bf16 v[102:105], v[148:151], v[200:203], v[102:105]
	v_mfma_f32_16x16x32_bf16 v[98:101], v[156:159], v[200:203], v[98:101]
	v_mfma_f32_16x16x32_bf16 v[86:89], v[148:151], v[208:211], v[86:89]
	v_mfma_f32_16x16x32_bf16 v[82:85], v[156:159], v[208:211], v[82:85]
	v_mfma_f32_16x16x32_bf16 v[70:73], v[148:151], v[216:219], v[70:73]
	v_mfma_f32_16x16x32_bf16 v[66:69], v[156:159], v[216:219], v[66:69]
	v_mfma_f32_16x16x32_bf16 v[118:121], v[152:155], v[196:199], v[118:121]
	v_mfma_f32_16x16x32_bf16 v[114:117], v[160:163], v[196:199], v[114:117]
	v_mfma_f32_16x16x32_bf16 v[102:105], v[152:155], v[204:207], v[102:105]
	v_mfma_f32_16x16x32_bf16 v[98:101], v[160:163], v[204:207], v[98:101]
	v_mfma_f32_16x16x32_bf16 v[86:89], v[152:155], v[212:215], v[86:89]
	v_mfma_f32_16x16x32_bf16 v[82:85], v[160:163], v[212:215], v[82:85]
	v_mfma_f32_16x16x32_bf16 v[70:73], v[152:155], v[220:223], v[70:73]
	v_mfma_f32_16x16x32_bf16 v[66:69], v[160:163], v[220:223], v[66:69]
	v_mfma_f32_16x16x32_bf16 v[126:129], v[164:167], v[180:183], v[126:129]
	v_mfma_f32_16x16x32_bf16 v[122:125], v[172:175], v[180:183], v[122:125]
	v_mfma_f32_16x16x32_bf16 v[110:113], v[164:167], v[200:203], v[110:113]
	v_mfma_f32_16x16x32_bf16 v[106:109], v[172:175], v[200:203], v[106:109]
	v_mfma_f32_16x16x32_bf16 v[94:97], v[164:167], v[208:211], v[94:97]
	v_mfma_f32_16x16x32_bf16 v[90:93], v[172:175], v[208:211], v[90:93]
	v_mfma_f32_16x16x32_bf16 v[78:81], v[164:167], v[216:219], v[78:81]
	v_mfma_f32_16x16x32_bf16 v[74:77], v[172:175], v[216:219], v[74:77]
	v_mfma_f32_16x16x32_bf16 v[126:129], v[168:171], v[196:199], v[126:129]
	v_mfma_f32_16x16x32_bf16 v[122:125], v[176:179], v[196:199], v[122:125]
	v_mfma_f32_16x16x32_bf16 v[110:113], v[168:171], v[204:207], v[110:113]
	v_mfma_f32_16x16x32_bf16 v[106:109], v[176:179], v[204:207], v[106:109]
	v_mfma_f32_16x16x32_bf16 v[94:97], v[168:171], v[212:215], v[94:97]
	v_mfma_f32_16x16x32_bf16 v[90:93], v[176:179], v[212:215], v[90:93]
	v_mfma_f32_16x16x32_bf16 v[78:81], v[168:171], v[220:223], v[78:81]
	v_mfma_f32_16x16x32_bf16 v[74:77], v[176:179], v[220:223], v[74:77]
	s_barrier
	s_setprio 0
	s_add_i32 s9, s95, s33
	v_lshl_add_u64 v[224:225], s[82:83], 0, v[132:133]
	s_mov_b32 m0, s9
	ds_read_b128 v[180:183], v194 offset:16384
	ds_read_b128 v[196:199], v194 offset:17408
	ds_read_b128 v[200:203], v194 offset:18432
	ds_read_b128 v[204:207], v194 offset:19456
	ds_read_b128 v[208:211], v194 offset:20480
	ds_read_b128 v[212:215], v194 offset:21504
	ds_read_b128 v[216:219], v194 offset:22528
	ds_read_b128 v[220:223], v194 offset:23552
	global_load_lds_dwordx4 v[224:225], off
	s_add_i32 m0, s9, 0x2000
	s_add_u32 s50, s82, 0x40000
	v_lshl_add_u64 v[226:227], s[82:83], 0, v[136:137]
	s_addc_u32 s51, s83, 0
	s_add_i32 s9, s96, s33
	global_load_lds_dwordx4 v[226:227], off
	v_lshl_add_u64 v[228:229], s[50:51], 0, v[132:133]
	s_mov_b32 m0, s9
	v_lshl_add_u64 v[230:231], s[84:85], 0, v[134:135]
	global_load_lds_dwordx4 v[228:229], off
	v_lshl_add_u64 v[228:229], s[50:51], 0, v[136:137]
	s_add_i32 m0, s9, 0x2000
	s_nop 0
	global_load_lds_dwordx4 v[228:229], off
	v_lshl_add_u64 v[228:229], s[84:85], 0, v[130:131]
	s_mov_b32 m0, s76
	s_nop 0
	global_load_lds_dwordx4 v[228:229], off
	s_mov_b32 m0, s77
	s_nop 0
	global_load_lds_dwordx4 v[230:231], off
	s_waitcnt vmcnt(8)
	s_waitcnt lgkmcnt(0)
	s_setprio 3
	s_barrier
	s_waitcnt lgkmcnt(0)
	v_mfma_f32_16x16x32_bf16 v[54:57], v[148:151], v[180:183], v[54:57]
	v_mfma_f32_16x16x32_bf16 v[50:53], v[156:159], v[180:183], v[50:53]
	v_mfma_f32_16x16x32_bf16 v[38:41], v[148:151], v[200:203], v[38:41]
	v_mfma_f32_16x16x32_bf16 v[34:37], v[156:159], v[200:203], v[34:37]
	v_mfma_f32_16x16x32_bf16 v[22:25], v[148:151], v[208:211], v[22:25]
	v_mfma_f32_16x16x32_bf16 v[18:21], v[156:159], v[208:211], v[18:21]
	v_mfma_f32_16x16x32_bf16 v[6:9], v[148:151], v[216:219], v[6:9]
	v_mfma_f32_16x16x32_bf16 v[2:5], v[156:159], v[216:219], v[2:5]
	v_mfma_f32_16x16x32_bf16 v[54:57], v[152:155], v[196:199], v[54:57]
	v_mfma_f32_16x16x32_bf16 v[50:53], v[160:163], v[196:199], v[50:53]
	v_mfma_f32_16x16x32_bf16 v[38:41], v[152:155], v[204:207], v[38:41]
	v_mfma_f32_16x16x32_bf16 v[34:37], v[160:163], v[204:207], v[34:37]
	v_mfma_f32_16x16x32_bf16 v[22:25], v[152:155], v[212:215], v[22:25]
	v_mfma_f32_16x16x32_bf16 v[18:21], v[160:163], v[212:215], v[18:21]
	v_mfma_f32_16x16x32_bf16 v[6:9], v[152:155], v[220:223], v[6:9]
	v_mfma_f32_16x16x32_bf16 v[2:5], v[160:163], v[220:223], v[2:5]
	v_mfma_f32_16x16x32_bf16 v[62:65], v[164:167], v[180:183], v[62:65]
	v_mfma_f32_16x16x32_bf16 v[58:61], v[172:175], v[180:183], v[58:61]
	v_mfma_f32_16x16x32_bf16 v[46:49], v[164:167], v[200:203], v[46:49]
	v_mfma_f32_16x16x32_bf16 v[42:45], v[172:175], v[200:203], v[42:45]
	v_mfma_f32_16x16x32_bf16 v[30:33], v[164:167], v[208:211], v[30:33]
	v_mfma_f32_16x16x32_bf16 v[26:29], v[172:175], v[208:211], v[26:29]
	v_mfma_f32_16x16x32_bf16 v[14:17], v[164:167], v[216:219], v[14:17]
	v_mfma_f32_16x16x32_bf16 v[10:13], v[172:175], v[216:219], v[10:13]
	v_mfma_f32_16x16x32_bf16 v[62:65], v[168:171], v[196:199], v[62:65]
	v_mfma_f32_16x16x32_bf16 v[58:61], v[176:179], v[196:199], v[58:61]
	v_mfma_f32_16x16x32_bf16 v[46:49], v[168:171], v[204:207], v[46:49]
	v_mfma_f32_16x16x32_bf16 v[42:45], v[176:179], v[204:207], v[42:45]
	v_mfma_f32_16x16x32_bf16 v[30:33], v[168:171], v[212:215], v[30:33]
	v_mfma_f32_16x16x32_bf16 v[26:29], v[176:179], v[212:215], v[26:29]
	v_mfma_f32_16x16x32_bf16 v[14:17], v[168:171], v[220:223], v[14:17]
	v_mfma_f32_16x16x32_bf16 v[10:13], v[176:179], v[220:223], v[10:13]
	s_barrier
; #define PG8_STAGE(bufoff, gbase, voff) do { _Pragma("unroll") for (int _i = 0; _i < 2; ++_i) \
;         __builtin_amdgcn_global_load_lds((const unsigned*)((const char*)(gbase) + (voff)[_i]), (LAS unsigned*)(lds + (bufoff) + ldsw + _i * 8192), 16, 0, 0); } while (0)
; #define PG8_LDA(dst, b, h) do { _Pragma("unroll") for (int m = 0; m < 4; ++m) _Pragma("unroll") for (int k = 0; k < 2; ++k) dst[m][k] = *(const LAS bf16x8*)(lds + PG8_SA(b, h) + aoff + m * 2048 + k * 1024); } while (0)
; #define PG8_LDB(dst, b, h) do { _Pragma("unroll") for (int n = 0; n < 2; ++n) _Pragma("unroll") for (int k = 0; k < 2; ++k) dst[n][k] = *(const LAS bf16x8*)(lds + PG8_SB(b, h) + boff + n * 2048 + k * 1024); } while (0)
; #define PG8_MMA(ai, bj, At, Bt) do { __builtin_amdgcn_s_setprio(3); _Pragma("unroll") for (int m = 0; m < 4; ++m) _Pragma("unroll") for (int n = 0; n < 2; ++n) _Pragma("unroll") for (int k = 0; k < 2; ++k) \
;         acc[ai][bj][m][n] = __builtin_amdgcn_mfma_f32_16x16x32_bf16(Bt[n][k], At[m][k], acc[ai][bj][m][n], 0, 0, 0); __builtin_amdgcn_s_setprio(0); } while (0)
; #define PG8_WAIT_V(n) asm volatile("s_waitcnt vmcnt(" #n ")" ::: "memory")
; #define PG8_WAIT_L(n) asm volatile("s_waitcnt lgkmcnt(" #n ")" ::: "memory")
; #define PG8_BAR __builtin_amdgcn_s_barrier()
; #define PG8_SCHED __builtin_amdgcn_sched_barrier(0)
; template <class Epi, bool ALIGN_EPI>
; __device__ __forceinline__ void gemm_phase(LAS unsigned char* lds, const Gemm g, const StaticOrder& S, const Epi& E) {
;     ...
;             PG8_LDB(B0, 1, 0); PG8_LDB(B1, 1, 1); PG8_SCHED; PG8_LDA(At, 1, 0); PG8_STAGE(PG8_SA(0, 1), a2 + hstep, voffA);
;             PG8_WAIT_V(8); PG8_WAIT_L(0); PG8_BAR; PG8_MMA(0, 0, At, B0); PG8_MMA(0, 1, At, B1); PG8_BAR; PG8_SCHED;
	s_setprio 0
	s_add_i32 s9, 0, 0x18000
	v_add_u32_e32 v138, s9, v189
	s_add_i32 s89, 0, 0x1c000
	ds_read_b128 v[148:151], v138
	ds_read_b128 v[152:155], v138 offset:1024
	ds_read_b128 v[156:159], v138 offset:2048
	ds_read_b128 v[160:163], v138 offset:3072
	v_add_u32_e32 v138, s89, v189
	ds_read_b128 v[164:167], v138
	ds_read_b128 v[168:171], v138 offset:1024
	ds_read_b128 v[172:175], v138 offset:2048
	ds_read_b128 v[176:179], v138 offset:3072
	s_add_u32 s50, s84, 0x40000
	s_addc_u32 s51, s85, 0
	s_mov_b32 m0, s86
	v_lshl_add_u64 v[232:233], s[50:51], 0, v[130:131]
	ds_read_b128 v[180:183], v194 offset:32768
	ds_read_b128 v[196:199], v194 offset:33792
	ds_read_b128 v[200:203], v194 offset:34816
	ds_read_b128 v[204:207], v194 offset:35840
	ds_read_b128 v[208:211], v194 offset:36864
	ds_read_b128 v[212:215], v194 offset:37888
	ds_read_b128 v[216:219], v194 offset:38912
	ds_read_b128 v[220:223], v194 offset:39936
	global_load_lds_dwordx4 v[232:233], off
	v_lshl_add_u64 v[232:233], s[50:51], 0, v[134:135]
	s_mov_b32 m0, s87
	s_nop 0
	global_load_lds_dwordx4 v[232:233], off
	s_waitcnt vmcnt(8)
	s_waitcnt lgkmcnt(0)
	s_setprio 3
	s_barrier
	s_waitcnt lgkmcnt(0)
	v_mfma_f32_16x16x32_bf16 v[118:121], v[148:151], v[180:183], v[118:121]
	v_mfma_f32_16x16x32_bf16 v[114:117], v[156:159], v[180:183], v[114:117]
	v_mfma_f32_16x16x32_bf16 v[102:105], v[148:151], v[200:203], v[102:105]
	v_mfma_f32_16x16x32_bf16 v[98:101], v[156:159], v[200:203], v[98:101]
	v_mfma_f32_16x16x32_bf16 v[86:89], v[148:151], v[208:211], v[86:89]
	v_mfma_f32_16x16x32_bf16 v[82:85], v[156:159], v[208:211], v[82:85]
	v_mfma_f32_16x16x32_bf16 v[70:73], v[148:151], v[216:219], v[70:73]
	v_mfma_f32_16x16x32_bf16 v[66:69], v[156:159], v[216:219], v[66:69]
	v_mfma_f32_16x16x32_bf16 v[118:121], v[152:155], v[196:199], v[118:121]
	v_mfma_f32_16x16x32_bf16 v[114:117], v[160:163], v[196:199], v[114:117]
	v_mfma_f32_16x16x32_bf16 v[102:105], v[152:155], v[204:207], v[102:105]
	v_mfma_f32_16x16x32_bf16 v[98:101], v[160:163], v[204:207], v[98:101]
	v_mfma_f32_16x16x32_bf16 v[86:89], v[152:155], v[212:215], v[86:89]
	v_mfma_f32_16x16x32_bf16 v[82:85], v[160:163], v[212:215], v[82:85]
	v_mfma_f32_16x16x32_bf16 v[70:73], v[152:155], v[220:223], v[70:73]
	v_mfma_f32_16x16x32_bf16 v[66:69], v[160:163], v[220:223], v[66:69]
	v_mfma_f32_16x16x32_bf16 v[126:129], v[164:167], v[180:183], v[126:129]
	v_mfma_f32_16x16x32_bf16 v[122:125], v[172:175], v[180:183], v[122:125]
	v_mfma_f32_16x16x32_bf16 v[110:113], v[164:167], v[200:203], v[110:113]
	v_mfma_f32_16x16x32_bf16 v[106:109], v[172:175], v[200:203], v[106:109]
	v_mfma_f32_16x16x32_bf16 v[94:97], v[164:167], v[208:211], v[94:97]
	v_mfma_f32_16x16x32_bf16 v[90:93], v[172:175], v[208:211], v[90:93]
	v_mfma_f32_16x16x32_bf16 v[78:81], v[164:167], v[216:219], v[78:81]
	v_mfma_f32_16x16x32_bf16 v[74:77], v[172:175], v[216:219], v[74:77]
	v_mfma_f32_16x16x32_bf16 v[126:129], v[168:171], v[196:199], v[126:129]
	v_mfma_f32_16x16x32_bf16 v[122:125], v[176:179], v[196:199], v[122:125]
	v_mfma_f32_16x16x32_bf16 v[110:113], v[168:171], v[204:207], v[110:113]
	v_mfma_f32_16x16x32_bf16 v[106:109], v[176:179], v[204:207], v[106:109]
	v_mfma_f32_16x16x32_bf16 v[94:97], v[168:171], v[212:215], v[94:97]
	v_mfma_f32_16x16x32_bf16 v[90:93], v[176:179], v[212:215], v[90:93]
	v_mfma_f32_16x16x32_bf16 v[78:81], v[168:171], v[220:223], v[78:81]
	v_mfma_f32_16x16x32_bf16 v[74:77], v[176:179], v[220:223], v[74:77]
	s_barrier
; #define PG8_STAGE(bufoff, gbase, voff) do { _Pragma("unroll") for (int _i = 0; _i < 2; ++_i) \
;         __builtin_amdgcn_global_load_lds((const unsigned*)((const char*)(gbase) + (voff)[_i]), (LAS unsigned*)(lds + (bufoff) + ldsw + _i * 8192), 16, 0, 0); } while (0)
; #define PG8_LDA(dst, b, h) do { _Pragma("unroll") for (int m = 0; m < 4; ++m) _Pragma("unroll") for (int k = 0; k < 2; ++k) dst[m][k] = *(const LAS bf16x8*)(lds + PG8_SA(b, h) + aoff + m * 2048 + k * 1024); } while (0)
; #define PG8_MMA(ai, bj, At, Bt) do { __builtin_amdgcn_s_setprio(3); _Pragma("unroll") for (int m = 0; m < 4; ++m) _Pragma("unroll") for (int n = 0; n < 2; ++n) _Pragma("unroll") for (int k = 0; k < 2; ++k) \
;         acc[ai][bj][m][n] = __builtin_amdgcn_mfma_f32_16x16x32_bf16(Bt[n][k], At[m][k], acc[ai][bj][m][n], 0, 0, 0); __builtin_amdgcn_s_setprio(0); } while (0)
; #define PG8_WAIT_V(n) asm volatile("s_waitcnt vmcnt(" #n ")" ::: "memory")
; #define PG8_WAIT_L(n) asm volatile("s_waitcnt lgkmcnt(" #n ")" ::: "memory")
; #define PG8_BAR __builtin_amdgcn_s_barrier()
; #define PG8_SCHED __builtin_amdgcn_sched_barrier(0)
; template <class Epi, bool ALIGN_EPI>
; __device__ __forceinline__ void gemm_phase(LAS unsigned char* lds, const Gemm g, const StaticOrder& S, const Epi& E) {
;     ...
;             PG8_LDA(At, 1, 1); PG8_STAGE(PG8_SB(1, 0), b3, voffB); PG8_STAGE(PG8_SB(1, 1), b3 + hstep, voffB); PG8_STAGE(PG8_SA(1, 0), a3, voffA);
;             PG8_WAIT_V(8); PG8_WAIT_L(0); PG8_BAR; PG8_MMA(1, 0, At, B0); PG8_MMA(1, 1, At, B1); PG8_BAR; PG8_SCHED;
;         }
	s_setprio 0
	s_add_i32 s9, s9, s33
	v_lshl_add_u64 v[224:225], v[224:225], 0, s[62:63]
	s_mov_b32 m0, s9
	ds_read_b128 v[180:183], v194 offset:49152
	ds_read_b128 v[196:199], v194 offset:50176
	ds_read_b128 v[200:203], v194 offset:51200
	ds_read_b128 v[204:207], v194 offset:52224
	ds_read_b128 v[208:211], v194 offset:53248
	ds_read_b128 v[212:215], v194 offset:54272
	ds_read_b128 v[216:219], v194 offset:55296
	ds_read_b128 v[220:223], v194 offset:56320
	global_load_lds_dwordx4 v[224:225], off
	s_add_i32 m0, s9, 0x2000
	s_add_u32 s50, s82, 0x40080
	v_lshl_add_u64 v[224:225], v[226:227], 0, s[62:63]
	s_addc_u32 s51, s83, 0
	s_add_i32 s9, s89, s33
	global_load_lds_dwordx4 v[224:225], off
	v_lshl_add_u64 v[224:225], s[50:51], 0, v[132:133]
	s_mov_b32 m0, s9
	s_nop 0
	global_load_lds_dwordx4 v[224:225], off
	v_lshl_add_u64 v[224:225], s[50:51], 0, v[136:137]
	s_add_i32 m0, s9, 0x2000
	s_nop 0
	global_load_lds_dwordx4 v[224:225], off
	v_lshl_add_u64 v[224:225], v[228:229], 0, s[62:63]
	s_mov_b32 m0, s93
	s_nop 0
	global_load_lds_dwordx4 v[224:225], off
	v_lshl_add_u64 v[224:225], v[230:231], 0, s[62:63]
	s_mov_b32 m0, s94
	s_nop 0
	global_load_lds_dwordx4 v[224:225], off
	s_waitcnt vmcnt(8)
	s_waitcnt lgkmcnt(0)
	s_setprio 3
	s_barrier
	s_waitcnt lgkmcnt(0)
	v_mfma_f32_16x16x32_bf16 v[54:57], v[148:151], v[180:183], v[54:57]
	v_mfma_f32_16x16x32_bf16 v[50:53], v[156:159], v[180:183], v[50:53]
	v_mfma_f32_16x16x32_bf16 v[38:41], v[148:151], v[200:203], v[38:41]
	v_mfma_f32_16x16x32_bf16 v[34:37], v[156:159], v[200:203], v[34:37]
	v_mfma_f32_16x16x32_bf16 v[22:25], v[148:151], v[208:211], v[22:25]
	v_mfma_f32_16x16x32_bf16 v[18:21], v[156:159], v[208:211], v[18:21]
	v_mfma_f32_16x16x32_bf16 v[6:9], v[148:151], v[216:219], v[6:9]
	v_mfma_f32_16x16x32_bf16 v[2:5], v[156:159], v[216:219], v[2:5]
	v_mfma_f32_16x16x32_bf16 v[54:57], v[152:155], v[196:199], v[54:57]
	v_mfma_f32_16x16x32_bf16 v[50:53], v[160:163], v[196:199], v[50:53]
	v_mfma_f32_16x16x32_bf16 v[38:41], v[152:155], v[204:207], v[38:41]
	v_mfma_f32_16x16x32_bf16 v[34:37], v[160:163], v[204:207], v[34:37]
	v_mfma_f32_16x16x32_bf16 v[22:25], v[152:155], v[212:215], v[22:25]
	v_mfma_f32_16x16x32_bf16 v[18:21], v[160:163], v[212:215], v[18:21]
	v_mfma_f32_16x16x32_bf16 v[6:9], v[152:155], v[220:223], v[6:9]
	v_mfma_f32_16x16x32_bf16 v[2:5], v[160:163], v[220:223], v[2:5]
	v_mfma_f32_16x16x32_bf16 v[62:65], v[164:167], v[180:183], v[62:65]
	v_mfma_f32_16x16x32_bf16 v[58:61], v[172:175], v[180:183], v[58:61]
	v_mfma_f32_16x16x32_bf16 v[46:49], v[164:167], v[200:203], v[46:49]
	v_mfma_f32_16x16x32_bf16 v[42:45], v[172:175], v[200:203], v[42:45]
	v_mfma_f32_16x16x32_bf16 v[30:33], v[164:167], v[208:211], v[30:33]
	v_mfma_f32_16x16x32_bf16 v[26:29], v[172:175], v[208:211], v[26:29]
	v_mfma_f32_16x16x32_bf16 v[14:17], v[164:167], v[216:219], v[14:17]
	v_mfma_f32_16x16x32_bf16 v[10:13], v[172:175], v[216:219], v[10:13]
	v_mfma_f32_16x16x32_bf16 v[62:65], v[168:171], v[196:199], v[62:65]
	v_mfma_f32_16x16x32_bf16 v[58:61], v[176:179], v[196:199], v[58:61]
	v_mfma_f32_16x16x32_bf16 v[46:49], v[168:171], v[204:207], v[46:49]
	v_mfma_f32_16x16x32_bf16 v[42:45], v[176:179], v[204:207], v[42:45]
	v_mfma_f32_16x16x32_bf16 v[30:33], v[168:171], v[212:215], v[30:33]
	v_mfma_f32_16x16x32_bf16 v[26:29], v[176:179], v[212:215], v[26:29]
	v_mfma_f32_16x16x32_bf16 v[14:17], v[168:171], v[220:223], v[14:17]
	v_mfma_f32_16x16x32_bf16 v[10:13], v[176:179], v[220:223], v[10:13]
	s_barrier
	s_setprio 0
	s_add_i32 s8, s8, 2
	s_add_u32 s80, s80, 0x100
	s_addc_u32 s81, s81, 0
	s_add_u32 vcc_lo, vcc_lo, 0x100
	s_addc_u32 vcc_hi, vcc_hi, 0
	s_cmp_gt_u32 s8, 13
	s_cbranch_scc0 .LBB0_293
	s_and_b64 vcc, exec, s[64:65]
	s_cbranch_vccz .LBB0_296
	s_barrier

; #define PG8_STAGE(bufoff, gbase, voff) do { _Pragma("unroll") for (int _i = 0; _i < 2; ++_i) \
;         __builtin_amdgcn_global_load_lds((const unsigned*)((const char*)(gbase) + (voff)[_i]), (LAS unsigned*)(lds + (bufoff) + ldsw + _i * 8192), 16, 0, 0); } while (0)
; #define PG8_LDA(dst, b, h) do { _Pragma("unroll") for (int m = 0; m < 4; ++m) _Pragma("unroll") for (int k = 0; k < 2; ++k) dst[m][k] = *(const LAS bf16x8*)(lds + PG8_SA(b, h) + aoff + m * 2048 + k * 1024); } while (0)
; #define PG8_LDB(dst, b, h) do { _Pragma("unroll") for (int n = 0; n < 2; ++n) _Pragma("unroll") for (int k = 0; k < 2; ++k) dst[n][k] = *(const LAS bf16x8*)(lds + PG8_SB(b, h) + boff + n * 2048 + k * 1024); } while (0)
; #define PG8_MMA(ai, bj, At, Bt) do { __builtin_amdgcn_s_setprio(3); _Pragma("unroll") for (int m = 0; m < 4; ++m) _Pragma("unroll") for (int n = 0; n < 2; ++n) _Pragma("unroll") for (int k = 0; k < 2; ++k) \
;         acc[ai][bj][m][n] = __builtin_amdgcn_mfma_f32_16x16x32_bf16(Bt[n][k], At[m][k], acc[ai][bj][m][n], 0, 0, 0); __builtin_amdgcn_s_setprio(0); } while (0)
; #define PG8_BAR __builtin_amdgcn_s_barrier()
; template <class Epi, bool ALIGN_EPI>
; __device__ __forceinline__ void gemm_phase(LAS unsigned char* lds, const Gemm g, const StaticOrder& S, const Epi& E) {
;     ...
;         const bool has_next = S.next(ui + 1, nxt);
;         const char* nA = has_next ? (const char*)g.A + (size_t)nxt.pm * tstep : cA; const char* nB = has_next ? (const char*)g.Bt + (size_t)nxt.pn * tstep : cB;
;         for (int t = 0; t < nt; t += 2) {
;             const bool last = (t == nt - 2);
;             const char* a1 = cA + (size_t)(t + 1) * kstep;
;             const char* a2 = last ? nA : cA + (size_t)(t + 2) * kstep; const char* b2 = last ? nB : cB + (size_t)(t + 2) * kstep;
;             const char* a3 = a2 + kstep; const char* b3 = b2 + kstep;
;             PG8_LDB(B0, 0, 0); PG8_LDB(B1, 0, 1); PG8_SCHED; PG8_LDA(At, 0, 0); PG8_STAGE(PG8_SA(1, 1), a1 + hstep, voffA);
;             PG8_WAIT_V(8); PG8_WAIT_L(0); PG8_BAR; PG8_MMA(0, 0, At, B0); PG8_MMA(0, 1, At, B1); PG8_BAR; PG8_SCHED;
;             PG8_LDA(At, 0, 1); PG8_STAGE(PG8_SB(0, 0), b2, voffB); PG8_STAGE(PG8_SB(0, 1), b2 + hstep, voffB); PG8_STAGE(PG8_SA(0, 0), a2, voffA);
;             PG8_WAIT_V(8); PG8_WAIT_L(0); PG8_BAR; PG8_MMA(1, 0, At, B0); PG8_MMA(1, 1, At, B1); PG8_BAR; PG8_SCHED;
.LBB0_519:
	s_ashr_i32 s55, s54, 31
	s_lshl_b64 s[56:57], s[54:55], 19
	s_add_u32 s56, s26, s56
	s_addc_u32 s57, s27, s57
	s_and_b64 s[58:59], s[4:5], exec
	s_cselect_b32 s55, s57, s65
	s_cselect_b32 s61, s56, s64
	s_ashr_i32 s53, s52, 31
	s_lshl_b64 s[58:59], s[52:53], 19
	s_add_u32 s58, s10, s58
	s_addc_u32 s59, s11, s59
	s_and_b64 s[68:69], s[4:5], exec
	s_cselect_b32 s53, s59, s67
	s_cselect_b32 s82, s58, s66
	s_add_u32 s64, s64, 0x40080
	s_addc_u32 s65, s65, 0
	s_add_u32 s83, s66, 0x100
	s_addc_u32 s84, s67, 0
	s_mov_b32 s85, -2
	s_waitcnt lgkmcnt(0)
	ds_read_b128 v[130:133], v214
	ds_read_b128 v[134:137], v214 offset:1024
	ds_read_b128 v[138:141], v214 offset:2048
	ds_read_b128 v[142:145], v214 offset:3072
	ds_read_b128 v[146:149], v215
	ds_read_b128 v[150:153], v215 offset:1024
	ds_read_b128 v[154:157], v215 offset:2048
	ds_read_b128 v[158:161], v215 offset:3072
	s_add_u32 s66, s64, 0xfffc0080
	s_addc_u32 s67, s65, -1
	s_cmp_eq_u32 s85, 12
	s_cselect_b32 s69, s55, s67
	s_cselect_b32 s68, s61, s66
	s_cselect_b32 s67, s53, s84
	s_cselect_b32 s66, s82, s83
	v_lshl_add_u64 v[222:223], s[64:65], 0, v[186:187]
	s_add_i32 m0, s63, 0xc000
	ds_read_b128 v[162:165], v216
	ds_read_b128 v[166:169], v216 offset:1024
	ds_read_b128 v[170:173], v216 offset:2048
	ds_read_b128 v[174:177], v216 offset:3072
	ds_read_b128 v[194:197], v216 offset:4096
	ds_read_b128 v[198:201], v216 offset:5120
	ds_read_b128 v[202:205], v216 offset:6144
	ds_read_b128 v[218:221], v216 offset:7168
	global_load_lds_dwordx4 v[222:223], off
	v_lshl_add_u64 v[222:223], s[64:65], 0, v[188:189]
	s_add_i32 m0, s63, 0xe000
	s_nop 0
	global_load_lds_dwordx4 v[222:223], off
	s_waitcnt vmcnt(8)
	s_waitcnt lgkmcnt(0)
	s_setprio 3
	s_barrier
	s_waitcnt lgkmcnt(0)
	v_mfma_f32_16x16x32_bf16 v[126:129], v[130:133], v[162:165], 0
	v_mfma_f32_16x16x32_bf16 v[122:125], v[138:141], v[162:165], 0
	v_mfma_f32_16x16x32_bf16 v[110:113], v[130:133], v[170:173], 0
	v_mfma_f32_16x16x32_bf16 v[106:109], v[138:141], v[170:173], 0
	v_mfma_f32_16x16x32_bf16 v[94:97], v[130:133], v[194:197], 0
	v_mfma_f32_16x16x32_bf16 v[90:93], v[138:141], v[194:197], 0
	v_mfma_f32_16x16x32_bf16 v[78:81], v[130:133], v[202:205], 0
	v_mfma_f32_16x16x32_bf16 v[74:77], v[138:141], v[202:205], 0
	v_mfma_f32_16x16x32_bf16 v[126:129], v[134:137], v[166:169], v[126:129]
	v_mfma_f32_16x16x32_bf16 v[122:125], v[142:145], v[166:169], v[122:125]
	v_mfma_f32_16x16x32_bf16 v[110:113], v[134:137], v[174:177], v[110:113]
	v_mfma_f32_16x16x32_bf16 v[106:109], v[142:145], v[174:177], v[106:109]
	v_mfma_f32_16x16x32_bf16 v[94:97], v[134:137], v[198:201], v[94:97]
	v_mfma_f32_16x16x32_bf16 v[90:93], v[142:145], v[198:201], v[90:93]
	v_mfma_f32_16x16x32_bf16 v[78:81], v[134:137], v[218:221], v[78:81]
	v_mfma_f32_16x16x32_bf16 v[74:77], v[142:145], v[218:221], v[74:77]
	v_mfma_f32_16x16x32_bf16 v[118:121], v[146:149], v[162:165], 0
	v_mfma_f32_16x16x32_bf16 v[114:117], v[154:157], v[162:165], 0
	v_mfma_f32_16x16x32_bf16 v[102:105], v[146:149], v[170:173], 0
	v_mfma_f32_16x16x32_bf16 v[98:101], v[154:157], v[170:173], 0
	v_mfma_f32_16x16x32_bf16 v[86:89], v[146:149], v[194:197], 0
	v_mfma_f32_16x16x32_bf16 v[82:85], v[154:157], v[194:197], 0
	v_mfma_f32_16x16x32_bf16 v[70:73], v[146:149], v[202:205], 0
	v_mfma_f32_16x16x32_bf16 v[66:69], v[154:157], v[202:205], 0
	v_mfma_f32_16x16x32_bf16 v[118:121], v[150:153], v[166:169], v[118:121]
	v_mfma_f32_16x16x32_bf16 v[114:117], v[158:161], v[166:169], v[114:117]
	v_mfma_f32_16x16x32_bf16 v[102:105], v[150:153], v[174:177], v[102:105]
	v_mfma_f32_16x16x32_bf16 v[98:101], v[158:161], v[174:177], v[98:101]
	v_mfma_f32_16x16x32_bf16 v[86:89], v[150:153], v[198:201], v[86:89]
	v_mfma_f32_16x16x32_bf16 v[82:85], v[158:161], v[198:201], v[82:85]
	v_mfma_f32_16x16x32_bf16 v[70:73], v[150:153], v[218:221], v[70:73]
	v_mfma_f32_16x16x32_bf16 v[66:69], v[158:161], v[218:221], v[66:69]
	s_barrier
	s_setprio 0
	s_add_i32 s86, s80, s33
	v_lshl_add_u64 v[222:223], s[66:67], 0, v[180:181]
	s_mov_b32 m0, s86
	ds_read_b128 v[162:165], v216 offset:16384
	ds_read_b128 v[166:169], v216 offset:17408
	ds_read_b128 v[170:173], v216 offset:18432
	ds_read_b128 v[174:177], v216 offset:19456
	ds_read_b128 v[194:197], v216 offset:20480
	ds_read_b128 v[198:201], v216 offset:21504
	ds_read_b128 v[202:205], v216 offset:22528
	ds_read_b128 v[218:221], v216 offset:23552
	global_load_lds_dwordx4 v[222:223], off
	s_add_i32 m0, s86, 0x2000
	s_add_u32 s86, s66, 0x40000
	v_lshl_add_u64 v[224:225], s[66:67], 0, v[184:185]
	s_addc_u32 s87, s67, 0
	s_add_i32 s88, s81, s33
	global_load_lds_dwordx4 v[224:225], off
	v_lshl_add_u64 v[226:227], s[86:87], 0, v[180:181]
	s_mov_b32 m0, s88
	v_lshl_add_u64 v[228:229], s[68:69], 0, v[182:183]
	global_load_lds_dwordx4 v[226:227], off
	v_lshl_add_u64 v[226:227], s[86:87], 0, v[184:185]
	s_add_i32 m0, s88, 0x2000
	s_nop 0
	global_load_lds_dwordx4 v[226:227], off
	v_lshl_add_u64 v[226:227], s[68:69], 0, v[178:179]
	s_mov_b32 m0, s63
	s_nop 0
	global_load_lds_dwordx4 v[226:227], off
	s_mov_b32 m0, s70
	s_nop 0
	global_load_lds_dwordx4 v[228:229], off
	s_waitcnt vmcnt(8)
	s_waitcnt lgkmcnt(0)
	s_setprio 3
	s_barrier
; #define PG8_STAGE(bufoff, gbase, voff) do { _Pragma("unroll") for (int _i = 0; _i < 2; ++_i) \
;         __builtin_amdgcn_global_load_lds((const unsigned*)((const char*)(gbase) + (voff)[_i]), (LAS unsigned*)(lds + (bufoff) + ldsw + _i * 8192), 16, 0, 0); } while (0)
; #define PG8_LDA(dst, b, h) do { _Pragma("unroll") for (int m = 0; m < 4; ++m) _Pragma("unroll") for (int k = 0; k < 2; ++k) dst[m][k] = *(const LAS bf16x8*)(lds + PG8_SA(b, h) + aoff + m * 2048 + k * 1024); } while (0)
; #define PG8_LDB(dst, b, h) do { _Pragma("unroll") for (int n = 0; n < 2; ++n) _Pragma("unroll") for (int k = 0; k < 2; ++k) dst[n][k] = *(const LAS bf16x8*)(lds + PG8_SB(b, h) + boff + n * 2048 + k * 1024); } while (0)
; #define PG8_MMA(ai, bj, At, Bt) do { __builtin_amdgcn_s_setprio(3); _Pragma("unroll") for (int m = 0; m < 4; ++m) _Pragma("unroll") for (int n = 0; n < 2; ++n) _Pragma("unroll") for (int k = 0; k < 2; ++k) \
;         acc[ai][bj][m][n] = __builtin_amdgcn_mfma_f32_16x16x32_bf16(Bt[n][k], At[m][k], acc[ai][bj][m][n], 0, 0, 0); __builtin_amdgcn_s_setprio(0); } while (0)
; #define PG8_WAIT_V(n) asm volatile("s_waitcnt vmcnt(" #n ")" ::: "memory")
; #define PG8_WAIT_L(n) asm volatile("s_waitcnt lgkmcnt(" #n ")" ::: "memory")
; #define PG8_BAR __builtin_amdgcn_s_barrier()
; #define PG8_SCHED __builtin_amdgcn_sched_barrier(0)
; template <class Epi, bool ALIGN_EPI>
; __device__ __forceinline__ void gemm_phase(LAS unsigned char* lds, const Gemm g, const StaticOrder& S, const Epi& E) {
;     ...
;             PG8_WAIT_V(8); PG8_WAIT_L(0); PG8_BAR; PG8_MMA(0, 0, At, B0); PG8_MMA(0, 1, At, B1); PG8_BAR; PG8_SCHED;
;             PG8_LDA(At, 0, 1); PG8_STAGE(PG8_SB(0, 0), b2, voffB); PG8_STAGE(PG8_SB(0, 1), b2 + hstep, voffB); PG8_STAGE(PG8_SA(0, 0), a2, voffA);
;             PG8_WAIT_V(8); PG8_WAIT_L(0); PG8_BAR; PG8_MMA(1, 0, At, B0); PG8_MMA(1, 1, At, B1); PG8_BAR; PG8_SCHED;
;             PG8_LDB(B0, 1, 0); PG8_LDB(B1, 1, 1); PG8_SCHED; PG8_LDA(At, 1, 0); PG8_STAGE(PG8_SA(0, 1), a2 + hstep, voffA);
;             PG8_WAIT_V(8); PG8_WAIT_L(0); PG8_BAR; PG8_MMA(0, 0, At, B0); PG8_MMA(0, 1, At, B1); PG8_BAR; PG8_SCHED;
	s_waitcnt lgkmcnt(0)
	v_mfma_f32_16x16x32_bf16 v[62:65], v[130:133], v[162:165], 0
	v_mfma_f32_16x16x32_bf16 v[58:61], v[138:141], v[162:165], 0
	v_mfma_f32_16x16x32_bf16 v[46:49], v[130:133], v[170:173], 0
	v_mfma_f32_16x16x32_bf16 v[42:45], v[138:141], v[170:173], 0
	v_mfma_f32_16x16x32_bf16 v[30:33], v[130:133], v[194:197], 0
	v_mfma_f32_16x16x32_bf16 v[26:29], v[138:141], v[194:197], 0
	v_mfma_f32_16x16x32_bf16 v[14:17], v[130:133], v[202:205], 0
	v_mfma_f32_16x16x32_bf16 v[10:13], v[138:141], v[202:205], 0
	v_mfma_f32_16x16x32_bf16 v[62:65], v[134:137], v[166:169], v[62:65]
	v_mfma_f32_16x16x32_bf16 v[58:61], v[142:145], v[166:169], v[58:61]
	v_mfma_f32_16x16x32_bf16 v[46:49], v[134:137], v[174:177], v[46:49]
	v_mfma_f32_16x16x32_bf16 v[42:45], v[142:145], v[174:177], v[42:45]
	v_mfma_f32_16x16x32_bf16 v[30:33], v[134:137], v[198:201], v[30:33]
	v_mfma_f32_16x16x32_bf16 v[26:29], v[142:145], v[198:201], v[26:29]
	v_mfma_f32_16x16x32_bf16 v[14:17], v[134:137], v[218:221], v[14:17]
	v_mfma_f32_16x16x32_bf16 v[10:13], v[142:145], v[218:221], v[10:13]
	v_mfma_f32_16x16x32_bf16 v[54:57], v[146:149], v[162:165], 0
	v_mfma_f32_16x16x32_bf16 v[50:53], v[154:157], v[162:165], 0
	v_mfma_f32_16x16x32_bf16 v[38:41], v[146:149], v[170:173], 0
	v_mfma_f32_16x16x32_bf16 v[34:37], v[154:157], v[170:173], 0
	v_mfma_f32_16x16x32_bf16 v[22:25], v[146:149], v[194:197], 0
	v_mfma_f32_16x16x32_bf16 v[18:21], v[154:157], v[194:197], 0
	v_mfma_f32_16x16x32_bf16 v[6:9], v[146:149], v[202:205], 0
	v_mfma_f32_16x16x32_bf16 v[2:5], v[154:157], v[202:205], 0
	v_mfma_f32_16x16x32_bf16 v[54:57], v[150:153], v[166:169], v[54:57]
	v_mfma_f32_16x16x32_bf16 v[50:53], v[158:161], v[166:169], v[50:53]
	v_mfma_f32_16x16x32_bf16 v[38:41], v[150:153], v[174:177], v[38:41]
	v_mfma_f32_16x16x32_bf16 v[34:37], v[158:161], v[174:177], v[34:37]
	v_mfma_f32_16x16x32_bf16 v[22:25], v[150:153], v[198:201], v[22:25]
	v_mfma_f32_16x16x32_bf16 v[18:21], v[158:161], v[198:201], v[18:21]
	v_mfma_f32_16x16x32_bf16 v[6:9], v[150:153], v[218:221], v[6:9]
	v_mfma_f32_16x16x32_bf16 v[2:5], v[158:161], v[218:221], v[2:5]
	s_barrier
	s_setprio 0
	s_add_i32 s86, 0, 0x18000
	s_add_i32 s87, 0, 0x1c000
	v_add_u32_e32 v142, s86, v212
	v_add_u32_e32 v158, s87, v212
	ds_read_b128 v[130:133], v142
	ds_read_b128 v[134:137], v142 offset:1024
	ds_read_b128 v[138:141], v142 offset:2048
	ds_read_b128 v[142:145], v142 offset:3072
	ds_read_b128 v[146:149], v158
	ds_read_b128 v[150:153], v158 offset:1024
	ds_read_b128 v[154:157], v158 offset:2048
	ds_read_b128 v[158:161], v158 offset:3072
	s_add_u32 s68, s68, 0x40000
	s_addc_u32 s69, s69, 0
	s_mov_b32 m0, s71
	v_lshl_add_u64 v[230:231], s[68:69], 0, v[178:179]
	ds_read_b128 v[162:165], v216 offset:32768
	ds_read_b128 v[166:169], v216 offset:33792
	ds_read_b128 v[170:173], v216 offset:34816
	ds_read_b128 v[174:177], v216 offset:35840
	ds_read_b128 v[194:197], v216 offset:36864
	ds_read_b128 v[198:201], v216 offset:37888
	ds_read_b128 v[202:205], v216 offset:38912
	ds_read_b128 v[218:221], v216 offset:39936
	global_load_lds_dwordx4 v[230:231], off
	v_lshl_add_u64 v[230:231], s[68:69], 0, v[182:183]
	s_mov_b32 m0, s72
	s_nop 0
	global_load_lds_dwordx4 v[230:231], off
	s_waitcnt vmcnt(8)
	s_waitcnt lgkmcnt(0)
	s_setprio 3
	s_barrier
	s_waitcnt lgkmcnt(0)
	v_mfma_f32_16x16x32_bf16 v[126:129], v[130:133], v[162:165], v[126:129]
	v_mfma_f32_16x16x32_bf16 v[122:125], v[138:141], v[162:165], v[122:125]
	v_mfma_f32_16x16x32_bf16 v[110:113], v[130:133], v[170:173], v[110:113]
	v_mfma_f32_16x16x32_bf16 v[106:109], v[138:141], v[170:173], v[106:109]
	v_mfma_f32_16x16x32_bf16 v[94:97], v[130:133], v[194:197], v[94:97]
	v_mfma_f32_16x16x32_bf16 v[90:93], v[138:141], v[194:197], v[90:93]
	v_mfma_f32_16x16x32_bf16 v[78:81], v[130:133], v[202:205], v[78:81]
	v_mfma_f32_16x16x32_bf16 v[74:77], v[138:141], v[202:205], v[74:77]
	v_mfma_f32_16x16x32_bf16 v[126:129], v[134:137], v[166:169], v[126:129]
	v_mfma_f32_16x16x32_bf16 v[122:125], v[142:145], v[166:169], v[122:125]
	v_mfma_f32_16x16x32_bf16 v[110:113], v[134:137], v[174:177], v[110:113]
	v_mfma_f32_16x16x32_bf16 v[106:109], v[142:145], v[174:177], v[106:109]
	v_mfma_f32_16x16x32_bf16 v[94:97], v[134:137], v[198:201], v[94:97]
	v_mfma_f32_16x16x32_bf16 v[90:93], v[142:145], v[198:201], v[90:93]
	v_mfma_f32_16x16x32_bf16 v[78:81], v[134:137], v[218:221], v[78:81]
	v_mfma_f32_16x16x32_bf16 v[74:77], v[142:145], v[218:221], v[74:77]
	v_mfma_f32_16x16x32_bf16 v[118:121], v[146:149], v[162:165], v[118:121]
	v_mfma_f32_16x16x32_bf16 v[114:117], v[154:157], v[162:165], v[114:117]
	v_mfma_f32_16x16x32_bf16 v[102:105], v[146:149], v[170:173], v[102:105]
	v_mfma_f32_16x16x32_bf16 v[98:101], v[154:157], v[170:173], v[98:101]
	v_mfma_f32_16x16x32_bf16 v[86:89], v[146:149], v[194:197], v[86:89]
	v_mfma_f32_16x16x32_bf16 v[82:85], v[154:157], v[194:197], v[82:85]
	v_mfma_f32_16x16x32_bf16 v[70:73], v[146:149], v[202:205], v[70:73]
	v_mfma_f32_16x16x32_bf16 v[66:69], v[154:157], v[202:205], v[66:69]
	v_mfma_f32_16x16x32_bf16 v[118:121], v[150:153], v[166:169], v[118:121]
	v_mfma_f32_16x16x32_bf16 v[114:117], v[158:161], v[166:169], v[114:117]
	v_mfma_f32_16x16x32_bf16 v[102:105], v[150:153], v[174:177], v[102:105]
	v_mfma_f32_16x16x32_bf16 v[98:101], v[158:161], v[174:177], v[98:101]
	v_mfma_f32_16x16x32_bf16 v[86:89], v[150:153], v[198:201], v[86:89]
	v_mfma_f32_16x16x32_bf16 v[82:85], v[158:161], v[198:201], v[82:85]
	v_mfma_f32_16x16x32_bf16 v[70:73], v[150:153], v[218:221], v[70:73]
	v_mfma_f32_16x16x32_bf16 v[66:69], v[158:161], v[218:221], v[66:69]
	s_barrier
; #define PG8_STAGE(bufoff, gbase, voff) do { _Pragma("unroll") for (int _i = 0; _i < 2; ++_i) \
;         __builtin_amdgcn_global_load_lds((const unsigned*)((const char*)(gbase) + (voff)[_i]), (LAS unsigned*)(lds + (bufoff) + ldsw + _i * 8192), 16, 0, 0); } while (0)
; #define PG8_LDA(dst, b, h) do { _Pragma("unroll") for (int m = 0; m < 4; ++m) _Pragma("unroll") for (int k = 0; k < 2; ++k) dst[m][k] = *(const LAS bf16x8*)(lds + PG8_SA(b, h) + aoff + m * 2048 + k * 1024); } while (0)
; #define PG8_LDB(dst, b, h) do { _Pragma("unroll") for (int n = 0; n < 2; ++n) _Pragma("unroll") for (int k = 0; k < 2; ++k) dst[n][k] = *(const LAS bf16x8*)(lds + PG8_SB(b, h) + boff + n * 2048 + k * 1024); } while (0)
; #define PG8_MMA(ai, bj, At, Bt) do { __builtin_amdgcn_s_setprio(3); _Pragma("unroll") for (int m = 0; m < 4; ++m) _Pragma("unroll") for (int n = 0; n < 2; ++n) _Pragma("unroll") for (int k = 0; k < 2; ++k) \
;         acc[ai][bj][m][n] = __builtin_amdgcn_mfma_f32_16x16x32_bf16(Bt[n][k], At[m][k], acc[ai][bj][m][n], 0, 0, 0); __builtin_amdgcn_s_setprio(0); } while (0)
; #define PG8_WAIT_V(n) asm volatile("s_waitcnt vmcnt(" #n ")" ::: "memory")
; #define PG8_WAIT_L(n) asm volatile("s_waitcnt lgkmcnt(" #n ")" ::: "memory")
; #define PG8_BAR __builtin_amdgcn_s_barrier()
; #define PG8_SCHED __builtin_amdgcn_sched_barrier(0)
; template <class Epi, bool ALIGN_EPI>
; __device__ __forceinline__ void gemm_phase(LAS unsigned char* lds, const Gemm g, const StaticOrder& S, const Epi& E) {
;     ...
;             PG8_LDB(B0, 0, 0); PG8_LDB(B1, 0, 1); PG8_SCHED; PG8_LDA(At, 0, 0); PG8_STAGE(PG8_SA(1, 1), a1 + hstep, voffA);
;             PG8_WAIT_V(8); PG8_WAIT_L(0); PG8_BAR; PG8_MMA(0, 0, At, B0); PG8_MMA(0, 1, At, B1); PG8_BAR; PG8_SCHED;
;     ...
;             PG8_LDA(At, 1, 1); PG8_STAGE(PG8_SB(1, 0), b3, voffB); PG8_STAGE(PG8_SB(1, 1), b3 + hstep, voffB); PG8_STAGE(PG8_SA(1, 0), a3, voffA);
;             PG8_WAIT_V(8); PG8_WAIT_L(0); PG8_BAR; PG8_MMA(1, 0, At, B0); PG8_MMA(1, 1, At, B1); PG8_BAR; PG8_SCHED;
	s_setprio 0
	s_add_i32 s68, s86, s33
	v_lshl_add_u64 v[222:223], v[222:223], 0, s[18:19]
	s_mov_b32 m0, s68
	ds_read_b128 v[162:165], v216 offset:49152
	ds_read_b128 v[166:169], v216 offset:50176
	ds_read_b128 v[170:173], v216 offset:51200
	ds_read_b128 v[174:177], v216 offset:52224
	ds_read_b128 v[194:197], v216 offset:53248
	ds_read_b128 v[198:201], v216 offset:54272
	ds_read_b128 v[202:205], v216 offset:55296
	ds_read_b128 v[218:221], v216 offset:56320
	global_load_lds_dwordx4 v[222:223], off
	s_add_i32 m0, s68, 0x2000
	s_add_u32 s66, s66, 0x40080
	v_lshl_add_u64 v[222:223], v[224:225], 0, s[18:19]
	s_addc_u32 s67, s67, 0
	s_add_i32 s68, s87, s33
	global_load_lds_dwordx4 v[222:223], off
	v_lshl_add_u64 v[222:223], s[66:67], 0, v[180:181]
	s_mov_b32 m0, s68
	s_nop 0
	global_load_lds_dwordx4 v[222:223], off
	v_lshl_add_u64 v[222:223], s[66:67], 0, v[184:185]
	s_add_i32 m0, s68, 0x2000
	s_nop 0
	global_load_lds_dwordx4 v[222:223], off
	v_lshl_add_u64 v[222:223], v[226:227], 0, s[18:19]
	s_mov_b32 m0, s78
	s_nop 0
	global_load_lds_dwordx4 v[222:223], off
	v_lshl_add_u64 v[222:223], v[228:229], 0, s[18:19]
	s_mov_b32 m0, s79
	s_nop 0
	global_load_lds_dwordx4 v[222:223], off
	s_waitcnt vmcnt(8)
	s_waitcnt lgkmcnt(0)
	s_setprio 3
	s_barrier
	s_waitcnt lgkmcnt(0)
	v_mfma_f32_16x16x32_bf16 v[62:65], v[130:133], v[162:165], v[62:65]
	v_mfma_f32_16x16x32_bf16 v[58:61], v[138:141], v[162:165], v[58:61]
	v_mfma_f32_16x16x32_bf16 v[46:49], v[130:133], v[170:173], v[46:49]
	v_mfma_f32_16x16x32_bf16 v[42:45], v[138:141], v[170:173], v[42:45]
	v_mfma_f32_16x16x32_bf16 v[30:33], v[130:133], v[194:197], v[30:33]
	v_mfma_f32_16x16x32_bf16 v[26:29], v[138:141], v[194:197], v[26:29]
	v_mfma_f32_16x16x32_bf16 v[14:17], v[130:133], v[202:205], v[14:17]
	v_mfma_f32_16x16x32_bf16 v[10:13], v[138:141], v[202:205], v[10:13]
	v_mfma_f32_16x16x32_bf16 v[62:65], v[134:137], v[166:169], v[62:65]
	v_mfma_f32_16x16x32_bf16 v[58:61], v[142:145], v[166:169], v[58:61]
	v_mfma_f32_16x16x32_bf16 v[46:49], v[134:137], v[174:177], v[46:49]
	v_mfma_f32_16x16x32_bf16 v[42:45], v[142:145], v[174:177], v[42:45]
	v_mfma_f32_16x16x32_bf16 v[30:33], v[134:137], v[198:201], v[30:33]
	v_mfma_f32_16x16x32_bf16 v[26:29], v[142:145], v[198:201], v[26:29]
	v_mfma_f32_16x16x32_bf16 v[14:17], v[134:137], v[218:221], v[14:17]
	v_mfma_f32_16x16x32_bf16 v[10:13], v[142:145], v[218:221], v[10:13]
	v_mfma_f32_16x16x32_bf16 v[54:57], v[146:149], v[162:165], v[54:57]
	v_mfma_f32_16x16x32_bf16 v[50:53], v[154:157], v[162:165], v[50:53]
	v_mfma_f32_16x16x32_bf16 v[38:41], v[146:149], v[170:173], v[38:41]
	v_mfma_f32_16x16x32_bf16 v[34:37], v[154:157], v[170:173], v[34:37]
	v_mfma_f32_16x16x32_bf16 v[22:25], v[146:149], v[194:197], v[22:25]
	v_mfma_f32_16x16x32_bf16 v[18:21], v[154:157], v[194:197], v[18:21]
	v_mfma_f32_16x16x32_bf16 v[6:9], v[146:149], v[202:205], v[6:9]
	v_mfma_f32_16x16x32_bf16 v[2:5], v[154:157], v[202:205], v[2:5]
	v_mfma_f32_16x16x32_bf16 v[54:57], v[150:153], v[166:169], v[54:57]
	v_mfma_f32_16x16x32_bf16 v[50:53], v[158:161], v[166:169], v[50:53]
	v_mfma_f32_16x16x32_bf16 v[38:41], v[150:153], v[174:177], v[38:41]
	v_mfma_f32_16x16x32_bf16 v[34:37], v[158:161], v[174:177], v[34:37]
	v_mfma_f32_16x16x32_bf16 v[22:25], v[150:153], v[198:201], v[22:25]
	v_mfma_f32_16x16x32_bf16 v[18:21], v[158:161], v[198:201], v[18:21]
	v_mfma_f32_16x16x32_bf16 v[6:9], v[150:153], v[218:221], v[6:9]
	v_mfma_f32_16x16x32_bf16 v[2:5], v[158:161], v[218:221], v[2:5]
	s_barrier
	s_setprio 0
	s_add_i32 s85, s85, 2
	s_add_u32 s64, s64, 0x100
	s_addc_u32 s65, s65, 0
	s_add_u32 s83, s83, 0x100
	s_addc_u32 s84, s84, 0
.LBB0_520:
	ds_read_b128 v[130:133], v214
	ds_read_b128 v[134:137], v214 offset:1024
	ds_read_b128 v[138:141], v214 offset:2048
	ds_read_b128 v[142:145], v214 offset:3072
	ds_read_b128 v[146:149], v215
	ds_read_b128 v[150:153], v215 offset:1024
	ds_read_b128 v[154:157], v215 offset:2048
	ds_read_b128 v[158:161], v215 offset:3072
	s_add_u32 s66, s64, 0xfffc0080
	s_addc_u32 s67, s65, -1
	s_cmp_eq_u32 s85, 12
	s_cselect_b32 s69, s55, s67
	s_cselect_b32 s68, s61, s66
	s_cselect_b32 s67, s53, s84
	s_cselect_b32 s66, s82, s83
	v_lshl_add_u64 v[222:223], s[64:65], 0, v[186:187]
	s_add_i32 m0, s63, 0xc000
	ds_read_b128 v[162:165], v216
	ds_read_b128 v[166:169], v216 offset:1024
	ds_read_b128 v[170:173], v216 offset:2048
	ds_read_b128 v[174:177], v216 offset:3072
	ds_read_b128 v[194:197], v216 offset:4096
	ds_read_b128 v[198:201], v216 offset:5120
	ds_read_b128 v[202:205], v216 offset:6144
	ds_read_b128 v[218:221], v216 offset:7168
	global_load_lds_dwordx4 v[222:223], off
	v_lshl_add_u64 v[222:223], s[64:65], 0, v[188:189]
	s_add_i32 m0, s63, 0xe000
	s_nop 0
	global_load_lds_dwordx4 v[222:223], off
	s_waitcnt vmcnt(8)
	s_waitcnt lgkmcnt(0)
	s_setprio 3
	s_barrier
; #define PG8_STAGE(bufoff, gbase, voff) do { _Pragma("unroll") for (int _i = 0; _i < 2; ++_i) \
;         __builtin_amdgcn_global_load_lds((const unsigned*)((const char*)(gbase) + (voff)[_i]), (LAS unsigned*)(lds + (bufoff) + ldsw + _i * 8192), 16, 0, 0); } while (0)
; #define PG8_LDA(dst, b, h) do { _Pragma("unroll") for (int m = 0; m < 4; ++m) _Pragma("unroll") for (int k = 0; k < 2; ++k) dst[m][k] = *(const LAS bf16x8*)(lds + PG8_SA(b, h) + aoff + m * 2048 + k * 1024); } while (0)
; #define PG8_MMA(ai, bj, At, Bt) do { __builtin_amdgcn_s_setprio(3); _Pragma("unroll") for (int m = 0; m < 4; ++m) _Pragma("unroll") for (int n = 0; n < 2; ++n) _Pragma("unroll") for (int k = 0; k < 2; ++k) \
;         acc[ai][bj][m][n] = __builtin_amdgcn_mfma_f32_16x16x32_bf16(Bt[n][k], At[m][k], acc[ai][bj][m][n], 0, 0, 0); __builtin_amdgcn_s_setprio(0); } while (0)
; #define PG8_WAIT_V(n) asm volatile("s_waitcnt vmcnt(" #n ")" ::: "memory")
; #define PG8_WAIT_L(n) asm volatile("s_waitcnt lgkmcnt(" #n ")" ::: "memory")
; #define PG8_BAR __builtin_amdgcn_s_barrier()
; #define PG8_SCHED __builtin_amdgcn_sched_barrier(0)
; template <class Epi, bool ALIGN_EPI>
; __device__ __forceinline__ void gemm_phase(LAS unsigned char* lds, const Gemm g, const StaticOrder& S, const Epi& E) {
;     ...
;             PG8_WAIT_V(8); PG8_WAIT_L(0); PG8_BAR; PG8_MMA(0, 0, At, B0); PG8_MMA(0, 1, At, B1); PG8_BAR; PG8_SCHED;
;             PG8_LDA(At, 0, 1); PG8_STAGE(PG8_SB(0, 0), b2, voffB); PG8_STAGE(PG8_SB(0, 1), b2 + hstep, voffB); PG8_STAGE(PG8_SA(0, 0), a2, voffA);
;             PG8_WAIT_V(8); PG8_WAIT_L(0); PG8_BAR; PG8_MMA(1, 0, At, B0); PG8_MMA(1, 1, At, B1); PG8_BAR; PG8_SCHED;
	s_waitcnt lgkmcnt(0)
	v_mfma_f32_16x16x32_bf16 v[126:129], v[130:133], v[162:165], v[126:129]
	v_mfma_f32_16x16x32_bf16 v[122:125], v[138:141], v[162:165], v[122:125]
	v_mfma_f32_16x16x32_bf16 v[110:113], v[130:133], v[170:173], v[110:113]
	v_mfma_f32_16x16x32_bf16 v[106:109], v[138:141], v[170:173], v[106:109]
	v_mfma_f32_16x16x32_bf16 v[94:97], v[130:133], v[194:197], v[94:97]
	v_mfma_f32_16x16x32_bf16 v[90:93], v[138:141], v[194:197], v[90:93]
	v_mfma_f32_16x16x32_bf16 v[78:81], v[130:133], v[202:205], v[78:81]
	v_mfma_f32_16x16x32_bf16 v[74:77], v[138:141], v[202:205], v[74:77]
	v_mfma_f32_16x16x32_bf16 v[126:129], v[134:137], v[166:169], v[126:129]
	v_mfma_f32_16x16x32_bf16 v[122:125], v[142:145], v[166:169], v[122:125]
	v_mfma_f32_16x16x32_bf16 v[110:113], v[134:137], v[174:177], v[110:113]
	v_mfma_f32_16x16x32_bf16 v[106:109], v[142:145], v[174:177], v[106:109]
	v_mfma_f32_16x16x32_bf16 v[94:97], v[134:137], v[198:201], v[94:97]
	v_mfma_f32_16x16x32_bf16 v[90:93], v[142:145], v[198:201], v[90:93]
	v_mfma_f32_16x16x32_bf16 v[78:81], v[134:137], v[218:221], v[78:81]
	v_mfma_f32_16x16x32_bf16 v[74:77], v[142:145], v[218:221], v[74:77]
	v_mfma_f32_16x16x32_bf16 v[118:121], v[146:149], v[162:165], v[118:121]
	v_mfma_f32_16x16x32_bf16 v[114:117], v[154:157], v[162:165], v[114:117]
	v_mfma_f32_16x16x32_bf16 v[102:105], v[146:149], v[170:173], v[102:105]
	v_mfma_f32_16x16x32_bf16 v[98:101], v[154:157], v[170:173], v[98:101]
	v_mfma_f32_16x16x32_bf16 v[86:89], v[146:149], v[194:197], v[86:89]
	v_mfma_f32_16x16x32_bf16 v[82:85], v[154:157], v[194:197], v[82:85]
	v_mfma_f32_16x16x32_bf16 v[70:73], v[146:149], v[202:205], v[70:73]
	v_mfma_f32_16x16x32_bf16 v[66:69], v[154:157], v[202:205], v[66:69]
	v_mfma_f32_16x16x32_bf16 v[118:121], v[150:153], v[166:169], v[118:121]
	v_mfma_f32_16x16x32_bf16 v[114:117], v[158:161], v[166:169], v[114:117]
	v_mfma_f32_16x16x32_bf16 v[102:105], v[150:153], v[174:177], v[102:105]
	v_mfma_f32_16x16x32_bf16 v[98:101], v[158:161], v[174:177], v[98:101]
	v_mfma_f32_16x16x32_bf16 v[86:89], v[150:153], v[198:201], v[86:89]
	v_mfma_f32_16x16x32_bf16 v[82:85], v[158:161], v[198:201], v[82:85]
	v_mfma_f32_16x16x32_bf16 v[70:73], v[150:153], v[218:221], v[70:73]
	v_mfma_f32_16x16x32_bf16 v[66:69], v[158:161], v[218:221], v[66:69]
	s_barrier
	s_setprio 0
	s_add_i32 s86, s80, s33
	v_lshl_add_u64 v[222:223], s[66:67], 0, v[180:181]
	s_mov_b32 m0, s86
	ds_read_b128 v[162:165], v216 offset:16384
	ds_read_b128 v[166:169], v216 offset:17408
	ds_read_b128 v[170:173], v216 offset:18432
	ds_read_b128 v[174:177], v216 offset:19456
	ds_read_b128 v[194:197], v216 offset:20480
	ds_read_b128 v[198:201], v216 offset:21504
	ds_read_b128 v[202:205], v216 offset:22528
	ds_read_b128 v[218:221], v216 offset:23552
	global_load_lds_dwordx4 v[222:223], off
	s_add_i32 m0, s86, 0x2000
	s_add_u32 s86, s66, 0x40000
	v_lshl_add_u64 v[224:225], s[66:67], 0, v[184:185]
	s_addc_u32 s87, s67, 0
	s_add_i32 s88, s81, s33
	global_load_lds_dwordx4 v[224:225], off
	v_lshl_add_u64 v[226:227], s[86:87], 0, v[180:181]
	s_mov_b32 m0, s88
	v_lshl_add_u64 v[228:229], s[68:69], 0, v[182:183]
	global_load_lds_dwordx4 v[226:227], off
	v_lshl_add_u64 v[226:227], s[86:87], 0, v[184:185]
	s_add_i32 m0, s88, 0x2000
	s_nop 0
	global_load_lds_dwordx4 v[226:227], off
	v_lshl_add_u64 v[226:227], s[68:69], 0, v[178:179]
	s_mov_b32 m0, s63
	s_nop 0
	global_load_lds_dwordx4 v[226:227], off
	s_mov_b32 m0, s70
	s_nop 0
	global_load_lds_dwordx4 v[228:229], off
	s_waitcnt vmcnt(8)
	s_waitcnt lgkmcnt(0)
	s_setprio 3
	s_barrier
	s_waitcnt lgkmcnt(0)
	v_mfma_f32_16x16x32_bf16 v[62:65], v[130:133], v[162:165], v[62:65]
	v_mfma_f32_16x16x32_bf16 v[58:61], v[138:141], v[162:165], v[58:61]
	v_mfma_f32_16x16x32_bf16 v[46:49], v[130:133], v[170:173], v[46:49]
	v_mfma_f32_16x16x32_bf16 v[42:45], v[138:141], v[170:173], v[42:45]
	v_mfma_f32_16x16x32_bf16 v[30:33], v[130:133], v[194:197], v[30:33]
	v_mfma_f32_16x16x32_bf16 v[26:29], v[138:141], v[194:197], v[26:29]
	v_mfma_f32_16x16x32_bf16 v[14:17], v[130:133], v[202:205], v[14:17]
	v_mfma_f32_16x16x32_bf16 v[10:13], v[138:141], v[202:205], v[10:13]
	v_mfma_f32_16x16x32_bf16 v[62:65], v[134:137], v[166:169], v[62:65]
	v_mfma_f32_16x16x32_bf16 v[58:61], v[142:145], v[166:169], v[58:61]
	v_mfma_f32_16x16x32_bf16 v[46:49], v[134:137], v[174:177], v[46:49]
	v_mfma_f32_16x16x32_bf16 v[42:45], v[142:145], v[174:177], v[42:45]
	v_mfma_f32_16x16x32_bf16 v[30:33], v[134:137], v[198:201], v[30:33]
	v_mfma_f32_16x16x32_bf16 v[26:29], v[142:145], v[198:201], v[26:29]
	v_mfma_f32_16x16x32_bf16 v[14:17], v[134:137], v[218:221], v[14:17]
	v_mfma_f32_16x16x32_bf16 v[10:13], v[142:145], v[218:221], v[10:13]
	v_mfma_f32_16x16x32_bf16 v[54:57], v[146:149], v[162:165], v[54:57]
	v_mfma_f32_16x16x32_bf16 v[50:53], v[154:157], v[162:165], v[50:53]
	v_mfma_f32_16x16x32_bf16 v[38:41], v[146:149], v[170:173], v[38:41]
	v_mfma_f32_16x16x32_bf16 v[34:37], v[154:157], v[170:173], v[34:37]
	v_mfma_f32_16x16x32_bf16 v[22:25], v[146:149], v[194:197], v[22:25]
	v_mfma_f32_16x16x32_bf16 v[18:21], v[154:157], v[194:197], v[18:21]
	v_mfma_f32_16x16x32_bf16 v[6:9], v[146:149], v[202:205], v[6:9]
	v_mfma_f32_16x16x32_bf16 v[2:5], v[154:157], v[202:205], v[2:5]
	v_mfma_f32_16x16x32_bf16 v[54:57], v[150:153], v[166:169], v[54:57]
	v_mfma_f32_16x16x32_bf16 v[50:53], v[158:161], v[166:169], v[50:53]
	v_mfma_f32_16x16x32_bf16 v[38:41], v[150:153], v[174:177], v[38:41]
	v_mfma_f32_16x16x32_bf16 v[34:37], v[158:161], v[174:177], v[34:37]
	v_mfma_f32_16x16x32_bf16 v[22:25], v[150:153], v[198:201], v[22:25]
	v_mfma_f32_16x16x32_bf16 v[18:21], v[158:161], v[198:201], v[18:21]
	v_mfma_f32_16x16x32_bf16 v[6:9], v[150:153], v[218:221], v[6:9]
	v_mfma_f32_16x16x32_bf16 v[2:5], v[158:161], v[218:221], v[2:5]
	s_barrier
; #define PG8_STAGE(bufoff, gbase, voff) do { _Pragma("unroll") for (int _i = 0; _i < 2; ++_i) \
;         __builtin_amdgcn_global_load_lds((const unsigned*)((const char*)(gbase) + (voff)[_i]), (LAS unsigned*)(lds + (bufoff) + ldsw + _i * 8192), 16, 0, 0); } while (0)
; #define PG8_LDA(dst, b, h) do { _Pragma("unroll") for (int m = 0; m < 4; ++m) _Pragma("unroll") for (int k = 0; k < 2; ++k) dst[m][k] = *(const LAS bf16x8*)(lds + PG8_SA(b, h) + aoff + m * 2048 + k * 1024); } while (0)
; #define PG8_LDB(dst, b, h) do { _Pragma("unroll") for (int n = 0; n < 2; ++n) _Pragma("unroll") for (int k = 0; k < 2; ++k) dst[n][k] = *(const LAS bf16x8*)(lds + PG8_SB(b, h) + boff + n * 2048 + k * 1024); } while (0)
; #define PG8_MMA(ai, bj, At, Bt) do { __builtin_amdgcn_s_setprio(3); _Pragma("unroll") for (int m = 0; m < 4; ++m) _Pragma("unroll") for (int n = 0; n < 2; ++n) _Pragma("unroll") for (int k = 0; k < 2; ++k) \
;         acc[ai][bj][m][n] = __builtin_amdgcn_mfma_f32_16x16x32_bf16(Bt[n][k], At[m][k], acc[ai][bj][m][n], 0, 0, 0); __builtin_amdgcn_s_setprio(0); } while (0)
; #define PG8_WAIT_V(n) asm volatile("s_waitcnt vmcnt(" #n ")" ::: "memory")
; #define PG8_WAIT_L(n) asm volatile("s_waitcnt lgkmcnt(" #n ")" ::: "memory")
; #define PG8_BAR __builtin_amdgcn_s_barrier()
; #define PG8_SCHED __builtin_amdgcn_sched_barrier(0)
; template <class Epi, bool ALIGN_EPI>
; __device__ __forceinline__ void gemm_phase(LAS unsigned char* lds, const Gemm g, const StaticOrder& S, const Epi& E) {
;     ...
;             PG8_LDB(B0, 1, 0); PG8_LDB(B1, 1, 1); PG8_SCHED; PG8_LDA(At, 1, 0); PG8_STAGE(PG8_SA(0, 1), a2 + hstep, voffA);
;             PG8_WAIT_V(8); PG8_WAIT_L(0); PG8_BAR; PG8_MMA(0, 0, At, B0); PG8_MMA(0, 1, At, B1); PG8_BAR; PG8_SCHED;
	s_setprio 0
	s_add_i32 s86, 0, 0x18000
	s_add_i32 s87, 0, 0x1c000
	v_add_u32_e32 v142, s86, v212
	v_add_u32_e32 v158, s87, v212
	ds_read_b128 v[130:133], v142
	ds_read_b128 v[134:137], v142 offset:1024
	ds_read_b128 v[138:141], v142 offset:2048
	ds_read_b128 v[142:145], v142 offset:3072
	ds_read_b128 v[146:149], v158
	ds_read_b128 v[150:153], v158 offset:1024
	ds_read_b128 v[154:157], v158 offset:2048
	ds_read_b128 v[158:161], v158 offset:3072
	s_add_u32 s68, s68, 0x40000
	s_addc_u32 s69, s69, 0
	s_mov_b32 m0, s71
	v_lshl_add_u64 v[230:231], s[68:69], 0, v[178:179]
	ds_read_b128 v[162:165], v216 offset:32768
	ds_read_b128 v[166:169], v216 offset:33792
	ds_read_b128 v[170:173], v216 offset:34816
	ds_read_b128 v[174:177], v216 offset:35840
	ds_read_b128 v[194:197], v216 offset:36864
	ds_read_b128 v[198:201], v216 offset:37888
	ds_read_b128 v[202:205], v216 offset:38912
	ds_read_b128 v[218:221], v216 offset:39936
	global_load_lds_dwordx4 v[230:231], off
	v_lshl_add_u64 v[230:231], s[68:69], 0, v[182:183]
	s_mov_b32 m0, s72
	s_nop 0
	global_load_lds_dwordx4 v[230:231], off
	s_waitcnt vmcnt(8)
	s_waitcnt lgkmcnt(0)
	s_setprio 3
	s_barrier
	s_waitcnt lgkmcnt(0)
	v_mfma_f32_16x16x32_bf16 v[126:129], v[130:133], v[162:165], v[126:129]
	v_mfma_f32_16x16x32_bf16 v[122:125], v[138:141], v[162:165], v[122:125]
	v_mfma_f32_16x16x32_bf16 v[110:113], v[130:133], v[170:173], v[110:113]
	v_mfma_f32_16x16x32_bf16 v[106:109], v[138:141], v[170:173], v[106:109]
	v_mfma_f32_16x16x32_bf16 v[94:97], v[130:133], v[194:197], v[94:97]
	v_mfma_f32_16x16x32_bf16 v[90:93], v[138:141], v[194:197], v[90:93]
	v_mfma_f32_16x16x32_bf16 v[78:81], v[130:133], v[202:205], v[78:81]
	v_mfma_f32_16x16x32_bf16 v[74:77], v[138:141], v[202:205], v[74:77]
	v_mfma_f32_16x16x32_bf16 v[126:129], v[134:137], v[166:169], v[126:129]
	v_mfma_f32_16x16x32_bf16 v[122:125], v[142:145], v[166:169], v[122:125]
	v_mfma_f32_16x16x32_bf16 v[110:113], v[134:137], v[174:177], v[110:113]
	v_mfma_f32_16x16x32_bf16 v[106:109], v[142:145], v[174:177], v[106:109]
	v_mfma_f32_16x16x32_bf16 v[94:97], v[134:137], v[198:201], v[94:97]
	v_mfma_f32_16x16x32_bf16 v[90:93], v[142:145], v[198:201], v[90:93]
	v_mfma_f32_16x16x32_bf16 v[78:81], v[134:137], v[218:221], v[78:81]
	v_mfma_f32_16x16x32_bf16 v[74:77], v[142:145], v[218:221], v[74:77]
	v_mfma_f32_16x16x32_bf16 v[118:121], v[146:149], v[162:165], v[118:121]
	v_mfma_f32_16x16x32_bf16 v[114:117], v[154:157], v[162:165], v[114:117]
	v_mfma_f32_16x16x32_bf16 v[102:105], v[146:149], v[170:173], v[102:105]
	v_mfma_f32_16x16x32_bf16 v[98:101], v[154:157], v[170:173], v[98:101]
	v_mfma_f32_16x16x32_bf16 v[86:89], v[146:149], v[194:197], v[86:89]
	v_mfma_f32_16x16x32_bf16 v[82:85], v[154:157], v[194:197], v[82:85]
	v_mfma_f32_16x16x32_bf16 v[70:73], v[146:149], v[202:205], v[70:73]
	v_mfma_f32_16x16x32_bf16 v[66:69], v[154:157], v[202:205], v[66:69]
	v_mfma_f32_16x16x32_bf16 v[118:121], v[150:153], v[166:169], v[118:121]
	v_mfma_f32_16x16x32_bf16 v[114:117], v[158:161], v[166:169], v[114:117]
	v_mfma_f32_16x16x32_bf16 v[102:105], v[150:153], v[174:177], v[102:105]
	v_mfma_f32_16x16x32_bf16 v[98:101], v[158:161], v[174:177], v[98:101]
	v_mfma_f32_16x16x32_bf16 v[86:89], v[150:153], v[198:201], v[86:89]
	v_mfma_f32_16x16x32_bf16 v[82:85], v[158:161], v[198:201], v[82:85]
	v_mfma_f32_16x16x32_bf16 v[70:73], v[150:153], v[218:221], v[70:73]
	v_mfma_f32_16x16x32_bf16 v[66:69], v[158:161], v[218:221], v[66:69]
	s_barrier
; #define PG8_STAGE(bufoff, gbase, voff) do { _Pragma("unroll") for (int _i = 0; _i < 2; ++_i) \
;         __builtin_amdgcn_global_load_lds((const unsigned*)((const char*)(gbase) + (voff)[_i]), (LAS unsigned*)(lds + (bufoff) + ldsw + _i * 8192), 16, 0, 0); } while (0)
; #define PG8_LDA(dst, b, h) do { _Pragma("unroll") for (int m = 0; m < 4; ++m) _Pragma("unroll") for (int k = 0; k < 2; ++k) dst[m][k] = *(const LAS bf16x8*)(lds + PG8_SA(b, h) + aoff + m * 2048 + k * 1024); } while (0)
; #define PG8_MMA(ai, bj, At, Bt) do { __builtin_amdgcn_s_setprio(3); _Pragma("unroll") for (int m = 0; m < 4; ++m) _Pragma("unroll") for (int n = 0; n < 2; ++n) _Pragma("unroll") for (int k = 0; k < 2; ++k) \
;         acc[ai][bj][m][n] = __builtin_amdgcn_mfma_f32_16x16x32_bf16(Bt[n][k], At[m][k], acc[ai][bj][m][n], 0, 0, 0); __builtin_amdgcn_s_setprio(0); } while (0)
; #define PG8_WAIT_V(n) asm volatile("s_waitcnt vmcnt(" #n ")" ::: "memory")
; #define PG8_WAIT_L(n) asm volatile("s_waitcnt lgkmcnt(" #n ")" ::: "memory")
; #define PG8_BAR __builtin_amdgcn_s_barrier()
; #define PG8_SCHED __builtin_amdgcn_sched_barrier(0)
; template <class Epi, bool ALIGN_EPI>
; __device__ __forceinline__ void gemm_phase(LAS unsigned char* lds, const Gemm g, const StaticOrder& S, const Epi& E) {
;     ...
;             PG8_LDA(At, 1, 1); PG8_STAGE(PG8_SB(1, 0), b3, voffB); PG8_STAGE(PG8_SB(1, 1), b3 + hstep, voffB); PG8_STAGE(PG8_SA(1, 0), a3, voffA);
;             PG8_WAIT_V(8); PG8_WAIT_L(0); PG8_BAR; PG8_MMA(1, 0, At, B0); PG8_MMA(1, 1, At, B1); PG8_BAR; PG8_SCHED;
;         }
;         if constexpr (ALIGN_EPI) { if (wr == 0) PG8_BAR; }
	s_setprio 0
	s_add_i32 s68, s86, s33
	v_lshl_add_u64 v[222:223], v[222:223], 0, s[18:19]
	s_mov_b32 m0, s68
	ds_read_b128 v[162:165], v216 offset:49152
	ds_read_b128 v[166:169], v216 offset:50176
	ds_read_b128 v[170:173], v216 offset:51200
	ds_read_b128 v[174:177], v216 offset:52224
	ds_read_b128 v[194:197], v216 offset:53248
	ds_read_b128 v[198:201], v216 offset:54272
	ds_read_b128 v[202:205], v216 offset:55296
	ds_read_b128 v[218:221], v216 offset:56320
	global_load_lds_dwordx4 v[222:223], off
	s_add_i32 m0, s68, 0x2000
	s_add_u32 s66, s66, 0x40080
	v_lshl_add_u64 v[222:223], v[224:225], 0, s[18:19]
	s_addc_u32 s67, s67, 0
	s_add_i32 s68, s87, s33
	global_load_lds_dwordx4 v[222:223], off
	v_lshl_add_u64 v[222:223], s[66:67], 0, v[180:181]
	s_mov_b32 m0, s68
	s_nop 0
	global_load_lds_dwordx4 v[222:223], off
	v_lshl_add_u64 v[222:223], s[66:67], 0, v[184:185]
	s_add_i32 m0, s68, 0x2000
	s_nop 0
	global_load_lds_dwordx4 v[222:223], off
	v_lshl_add_u64 v[222:223], v[226:227], 0, s[18:19]
	s_mov_b32 m0, s78
	s_nop 0
	global_load_lds_dwordx4 v[222:223], off
	v_lshl_add_u64 v[222:223], v[228:229], 0, s[18:19]
	s_mov_b32 m0, s79
	s_nop 0
	global_load_lds_dwordx4 v[222:223], off
	s_waitcnt vmcnt(8)
	s_waitcnt lgkmcnt(0)
	s_setprio 3
	s_barrier
	s_waitcnt lgkmcnt(0)
	v_mfma_f32_16x16x32_bf16 v[62:65], v[130:133], v[162:165], v[62:65]
	v_mfma_f32_16x16x32_bf16 v[58:61], v[138:141], v[162:165], v[58:61]
	v_mfma_f32_16x16x32_bf16 v[46:49], v[130:133], v[170:173], v[46:49]
	v_mfma_f32_16x16x32_bf16 v[42:45], v[138:141], v[170:173], v[42:45]
	v_mfma_f32_16x16x32_bf16 v[30:33], v[130:133], v[194:197], v[30:33]
	v_mfma_f32_16x16x32_bf16 v[26:29], v[138:141], v[194:197], v[26:29]
	v_mfma_f32_16x16x32_bf16 v[14:17], v[130:133], v[202:205], v[14:17]
	v_mfma_f32_16x16x32_bf16 v[10:13], v[138:141], v[202:205], v[10:13]
	v_mfma_f32_16x16x32_bf16 v[62:65], v[134:137], v[166:169], v[62:65]
	v_mfma_f32_16x16x32_bf16 v[58:61], v[142:145], v[166:169], v[58:61]
	v_mfma_f32_16x16x32_bf16 v[46:49], v[134:137], v[174:177], v[46:49]
	v_mfma_f32_16x16x32_bf16 v[42:45], v[142:145], v[174:177], v[42:45]
	v_mfma_f32_16x16x32_bf16 v[30:33], v[134:137], v[198:201], v[30:33]
	v_mfma_f32_16x16x32_bf16 v[26:29], v[142:145], v[198:201], v[26:29]
	v_mfma_f32_16x16x32_bf16 v[14:17], v[134:137], v[218:221], v[14:17]
	v_mfma_f32_16x16x32_bf16 v[10:13], v[142:145], v[218:221], v[10:13]
	v_mfma_f32_16x16x32_bf16 v[54:57], v[146:149], v[162:165], v[54:57]
	v_mfma_f32_16x16x32_bf16 v[50:53], v[154:157], v[162:165], v[50:53]
	v_mfma_f32_16x16x32_bf16 v[38:41], v[146:149], v[170:173], v[38:41]
	v_mfma_f32_16x16x32_bf16 v[34:37], v[154:157], v[170:173], v[34:37]
	v_mfma_f32_16x16x32_bf16 v[22:25], v[146:149], v[194:197], v[22:25]
	v_mfma_f32_16x16x32_bf16 v[18:21], v[154:157], v[194:197], v[18:21]
	v_mfma_f32_16x16x32_bf16 v[6:9], v[146:149], v[202:205], v[6:9]
	v_mfma_f32_16x16x32_bf16 v[2:5], v[154:157], v[202:205], v[2:5]
	v_mfma_f32_16x16x32_bf16 v[54:57], v[150:153], v[166:169], v[54:57]
	v_mfma_f32_16x16x32_bf16 v[50:53], v[158:161], v[166:169], v[50:53]
	v_mfma_f32_16x16x32_bf16 v[38:41], v[150:153], v[174:177], v[38:41]
	v_mfma_f32_16x16x32_bf16 v[34:37], v[158:161], v[174:177], v[34:37]
	v_mfma_f32_16x16x32_bf16 v[22:25], v[150:153], v[198:201], v[22:25]
	v_mfma_f32_16x16x32_bf16 v[18:21], v[158:161], v[198:201], v[18:21]
	v_mfma_f32_16x16x32_bf16 v[6:9], v[150:153], v[218:221], v[6:9]
	v_mfma_f32_16x16x32_bf16 v[2:5], v[158:161], v[218:221], v[2:5]
	s_barrier
	s_setprio 0
	s_add_i32 s85, s85, 2
	s_add_u32 s64, s64, 0x100
	s_addc_u32 s65, s65, 0
	s_add_u32 s83, s83, 0x100
	s_addc_u32 s84, s84, 0
	s_cmp_gt_u32 s85, 13
	s_cbranch_scc0 .LBB0_520
	s_and_b64 vcc, exec, s[50:51]
	s_cbranch_vccz .LBB0_523
	s_barrier

; #define PG8_STAGE(bufoff, gbase, voff) do { _Pragma("unroll") for (int _i = 0; _i < 2; ++_i) \
;         __builtin_amdgcn_global_load_lds((const unsigned*)((const char*)(gbase) + (voff)[_i]), (LAS unsigned*)(lds + (bufoff) + ldsw + _i * 8192), 16, 0, 0); } while (0)
; #define PG8_LDA(dst, b, h) do { _Pragma("unroll") for (int m = 0; m < 4; ++m) _Pragma("unroll") for (int k = 0; k < 2; ++k) dst[m][k] = *(const LAS bf16x8*)(lds + PG8_SA(b, h) + aoff + m * 2048 + k * 1024); } while (0)
; #define PG8_LDB(dst, b, h) do { _Pragma("unroll") for (int n = 0; n < 2; ++n) _Pragma("unroll") for (int k = 0; k < 2; ++k) dst[n][k] = *(const LAS bf16x8*)(lds + PG8_SB(b, h) + boff + n * 2048 + k * 1024); } while (0)
; #define PG8_MMA(ai, bj, At, Bt) do { __builtin_amdgcn_s_setprio(3); _Pragma("unroll") for (int m = 0; m < 4; ++m) _Pragma("unroll") for (int n = 0; n < 2; ++n) _Pragma("unroll") for (int k = 0; k < 2; ++k) \
;         acc[ai][bj][m][n] = __builtin_amdgcn_mfma_f32_16x16x32_bf16(Bt[n][k], At[m][k], acc[ai][bj][m][n], 0, 0, 0); __builtin_amdgcn_s_setprio(0); } while (0)
; #define PG8_BAR __builtin_amdgcn_s_barrier()
; template <class Epi, bool ALIGN_EPI>
; __device__ __forceinline__ void gemm_phase(LAS unsigned char* lds, const Gemm g, const StaticOrder& S, const Epi& E) {
;     ...
;         const bool has_next = S.next(ui + 1, nxt);
;         const char* nA = has_next ? (const char*)g.A + (size_t)nxt.pm * tstep : cA; const char* nB = has_next ? (const char*)g.Bt + (size_t)nxt.pn * tstep : cB;
;         for (int t = 0; t < nt; t += 2) {
;             const bool last = (t == nt - 2);
;             const char* a1 = cA + (size_t)(t + 1) * kstep;
;             const char* a2 = last ? nA : cA + (size_t)(t + 2) * kstep; const char* b2 = last ? nB : cB + (size_t)(t + 2) * kstep;
;             const char* a3 = a2 + kstep; const char* b3 = b2 + kstep;
;             PG8_LDB(B0, 0, 0); PG8_LDB(B1, 0, 1); PG8_SCHED; PG8_LDA(At, 0, 0); PG8_STAGE(PG8_SA(1, 1), a1 + hstep, voffA);
;             PG8_WAIT_V(8); PG8_WAIT_L(0); PG8_BAR; PG8_MMA(0, 0, At, B0); PG8_MMA(0, 1, At, B1); PG8_BAR; PG8_SCHED;
;             PG8_LDA(At, 0, 1); PG8_STAGE(PG8_SB(0, 0), b2, voffB); PG8_STAGE(PG8_SB(0, 1), b2 + hstep, voffB); PG8_STAGE(PG8_SA(0, 0), a2, voffA);
;             PG8_WAIT_V(8); PG8_WAIT_L(0); PG8_BAR; PG8_MMA(1, 0, At, B0); PG8_MMA(1, 1, At, B1); PG8_BAR; PG8_SCHED;
.LBB0_608:
	s_ashr_i32 s63, s62, 31
	s_lshl_b64 s[10:11], s[62:63], 19
	s_add_u32 s64, s34, s10
	s_addc_u32 s65, s35, s11
	s_and_b64 s[10:11], s[0:1], exec
	s_cselect_b32 s12, s65, s7
	s_cselect_b32 s13, s64, s6
	s_ashr_i32 s61, s60, 31
	s_lshl_b64 s[10:11], s[60:61], 19
	s_add_u32 s66, s52, s10
	s_addc_u32 s67, s53, s11
	s_and_b64 s[10:11], s[0:1], exec
	s_cselect_b32 s14, s67, s9
	s_cselect_b32 s15, s66, s8
	s_add_u32 s6, s6, 0x40080
	s_addc_u32 s7, s7, 0
	s_add_u32 s16, s8, 0x100
	s_addc_u32 s17, s9, 0
	s_mov_b32 s61, -2
	ds_read_b128 v[146:149], v168
	ds_read_b128 v[150:153], v168 offset:1024
	ds_read_b128 v[154:157], v168 offset:2048
	ds_read_b128 v[158:161], v168 offset:3072
	ds_read_b128 v[172:175], v169
	ds_read_b128 v[176:179], v169 offset:1024
	ds_read_b128 v[180:183], v169 offset:2048
	ds_read_b128 v[184:187], v169 offset:3072
	s_add_u32 s8, s6, 0xfffc0080
	s_addc_u32 s9, s7, -1
	s_cmp_eq_u32 s61, 12
	s_cselect_b32 s11, s12, s9
	s_cselect_b32 s10, s13, s8
	s_cselect_b32 s9, s14, s17
	s_cselect_b32 s8, s15, s16
	v_lshl_add_u64 v[220:221], s[6:7], 0, v[138:139]
	s_add_i32 m0, s70, 0xc000
	ds_read_b128 v[188:191], v170
	ds_read_b128 v[192:195], v170 offset:1024
	ds_read_b128 v[196:199], v170 offset:2048
	ds_read_b128 v[200:203], v170 offset:3072
	ds_read_b128 v[204:207], v170 offset:4096
	ds_read_b128 v[208:211], v170 offset:5120
	ds_read_b128 v[212:215], v170 offset:6144
	ds_read_b128 v[216:219], v170 offset:7168
	global_load_lds_dwordx4 v[220:221], off
	v_lshl_add_u64 v[220:221], s[6:7], 0, v[140:141]
	s_add_i32 m0, s70, 0xe000
	s_nop 0
	global_load_lds_dwordx4 v[220:221], off
	s_waitcnt vmcnt(8)
	s_waitcnt lgkmcnt(0)
	s_setprio 3
	s_barrier
	s_waitcnt lgkmcnt(0)
	v_mfma_f32_16x16x32_bf16 v[126:129], v[146:149], v[188:191], 0
	v_mfma_f32_16x16x32_bf16 v[118:121], v[154:157], v[188:191], 0
	v_mfma_f32_16x16x32_bf16 v[110:113], v[146:149], v[196:199], 0
	v_mfma_f32_16x16x32_bf16 v[102:105], v[154:157], v[196:199], 0
	v_mfma_f32_16x16x32_bf16 v[94:97], v[146:149], v[204:207], 0
	v_mfma_f32_16x16x32_bf16 v[86:89], v[154:157], v[204:207], 0
	v_mfma_f32_16x16x32_bf16 v[78:81], v[146:149], v[212:215], 0
	v_mfma_f32_16x16x32_bf16 v[70:73], v[154:157], v[212:215], 0
	v_mfma_f32_16x16x32_bf16 v[126:129], v[150:153], v[192:195], v[126:129]
	v_mfma_f32_16x16x32_bf16 v[118:121], v[158:161], v[192:195], v[118:121]
	v_mfma_f32_16x16x32_bf16 v[110:113], v[150:153], v[200:203], v[110:113]
	v_mfma_f32_16x16x32_bf16 v[102:105], v[158:161], v[200:203], v[102:105]
	v_mfma_f32_16x16x32_bf16 v[94:97], v[150:153], v[208:211], v[94:97]
	v_mfma_f32_16x16x32_bf16 v[86:89], v[158:161], v[208:211], v[86:89]
	v_mfma_f32_16x16x32_bf16 v[78:81], v[150:153], v[216:219], v[78:81]
	v_mfma_f32_16x16x32_bf16 v[70:73], v[158:161], v[216:219], v[70:73]
	v_mfma_f32_16x16x32_bf16 v[122:125], v[172:175], v[188:191], 0
	v_mfma_f32_16x16x32_bf16 v[114:117], v[180:183], v[188:191], 0
	v_mfma_f32_16x16x32_bf16 v[106:109], v[172:175], v[196:199], 0
	v_mfma_f32_16x16x32_bf16 v[98:101], v[180:183], v[196:199], 0
	v_mfma_f32_16x16x32_bf16 v[90:93], v[172:175], v[204:207], 0
	v_mfma_f32_16x16x32_bf16 v[82:85], v[180:183], v[204:207], 0
	v_mfma_f32_16x16x32_bf16 v[74:77], v[172:175], v[212:215], 0
	v_mfma_f32_16x16x32_bf16 v[66:69], v[180:183], v[212:215], 0
	v_mfma_f32_16x16x32_bf16 v[122:125], v[176:179], v[192:195], v[122:125]
	v_mfma_f32_16x16x32_bf16 v[114:117], v[184:187], v[192:195], v[114:117]
	v_mfma_f32_16x16x32_bf16 v[106:109], v[176:179], v[200:203], v[106:109]
	v_mfma_f32_16x16x32_bf16 v[98:101], v[184:187], v[200:203], v[98:101]
	v_mfma_f32_16x16x32_bf16 v[90:93], v[176:179], v[208:211], v[90:93]
	v_mfma_f32_16x16x32_bf16 v[82:85], v[184:187], v[208:211], v[82:85]
	v_mfma_f32_16x16x32_bf16 v[74:77], v[176:179], v[216:219], v[74:77]
	v_mfma_f32_16x16x32_bf16 v[66:69], v[184:187], v[216:219], v[66:69]
	s_barrier
	s_setprio 0
	s_add_i32 s63, s80, s33
	v_lshl_add_u64 v[220:221], s[8:9], 0, v[132:133]
	s_mov_b32 m0, s63
	ds_read_b128 v[188:191], v170 offset:16384
	ds_read_b128 v[192:195], v170 offset:17408
	ds_read_b128 v[196:199], v170 offset:18432
	ds_read_b128 v[200:203], v170 offset:19456
	ds_read_b128 v[204:207], v170 offset:20480
	ds_read_b128 v[208:211], v170 offset:21504
	ds_read_b128 v[212:215], v170 offset:22528
	ds_read_b128 v[216:219], v170 offset:23552
	global_load_lds_dwordx4 v[220:221], off
	s_add_i32 m0, s63, 0x2000
	s_add_u32 s84, s8, 0x40000
	v_lshl_add_u64 v[222:223], s[8:9], 0, v[136:137]
	s_addc_u32 s85, s9, 0
	s_add_i32 s63, s81, s33
	global_load_lds_dwordx4 v[222:223], off
	v_lshl_add_u64 v[224:225], s[84:85], 0, v[132:133]
	s_mov_b32 m0, s63
	v_lshl_add_u64 v[226:227], s[10:11], 0, v[134:135]
	global_load_lds_dwordx4 v[224:225], off
	v_lshl_add_u64 v[224:225], s[84:85], 0, v[136:137]
	s_add_i32 m0, s63, 0x2000
	s_nop 0
	global_load_lds_dwordx4 v[224:225], off
	v_lshl_add_u64 v[224:225], s[10:11], 0, v[130:131]
	s_mov_b32 m0, s70
	s_nop 0
	global_load_lds_dwordx4 v[224:225], off
	s_mov_b32 m0, s71
	s_nop 0
	global_load_lds_dwordx4 v[226:227], off
	s_waitcnt vmcnt(8)
	s_waitcnt lgkmcnt(0)
	s_setprio 3
	s_barrier
; #define PG8_STAGE(bufoff, gbase, voff) do { _Pragma("unroll") for (int _i = 0; _i < 2; ++_i) \
;         __builtin_amdgcn_global_load_lds((const unsigned*)((const char*)(gbase) + (voff)[_i]), (LAS unsigned*)(lds + (bufoff) + ldsw + _i * 8192), 16, 0, 0); } while (0)
; #define PG8_LDA(dst, b, h) do { _Pragma("unroll") for (int m = 0; m < 4; ++m) _Pragma("unroll") for (int k = 0; k < 2; ++k) dst[m][k] = *(const LAS bf16x8*)(lds + PG8_SA(b, h) + aoff + m * 2048 + k * 1024); } while (0)
; #define PG8_LDB(dst, b, h) do { _Pragma("unroll") for (int n = 0; n < 2; ++n) _Pragma("unroll") for (int k = 0; k < 2; ++k) dst[n][k] = *(const LAS bf16x8*)(lds + PG8_SB(b, h) + boff + n * 2048 + k * 1024); } while (0)
; #define PG8_MMA(ai, bj, At, Bt) do { __builtin_amdgcn_s_setprio(3); _Pragma("unroll") for (int m = 0; m < 4; ++m) _Pragma("unroll") for (int n = 0; n < 2; ++n) _Pragma("unroll") for (int k = 0; k < 2; ++k) \
;         acc[ai][bj][m][n] = __builtin_amdgcn_mfma_f32_16x16x32_bf16(Bt[n][k], At[m][k], acc[ai][bj][m][n], 0, 0, 0); __builtin_amdgcn_s_setprio(0); } while (0)
; #define PG8_WAIT_V(n) asm volatile("s_waitcnt vmcnt(" #n ")" ::: "memory")
; #define PG8_WAIT_L(n) asm volatile("s_waitcnt lgkmcnt(" #n ")" ::: "memory")
; #define PG8_BAR __builtin_amdgcn_s_barrier()
; #define PG8_SCHED __builtin_amdgcn_sched_barrier(0)
; template <class Epi, bool ALIGN_EPI>
; __device__ __forceinline__ void gemm_phase(LAS unsigned char* lds, const Gemm g, const StaticOrder& S, const Epi& E) {
;     ...
;             PG8_WAIT_V(8); PG8_WAIT_L(0); PG8_BAR; PG8_MMA(0, 0, At, B0); PG8_MMA(0, 1, At, B1); PG8_BAR; PG8_SCHED;
;             PG8_LDA(At, 0, 1); PG8_STAGE(PG8_SB(0, 0), b2, voffB); PG8_STAGE(PG8_SB(0, 1), b2 + hstep, voffB); PG8_STAGE(PG8_SA(0, 0), a2, voffA);
;             PG8_WAIT_V(8); PG8_WAIT_L(0); PG8_BAR; PG8_MMA(1, 0, At, B0); PG8_MMA(1, 1, At, B1); PG8_BAR; PG8_SCHED;
;             PG8_LDB(B0, 1, 0); PG8_LDB(B1, 1, 1); PG8_SCHED; PG8_LDA(At, 1, 0); PG8_STAGE(PG8_SA(0, 1), a2 + hstep, voffA);
;             PG8_WAIT_V(8); PG8_WAIT_L(0); PG8_BAR; PG8_MMA(0, 0, At, B0); PG8_MMA(0, 1, At, B1); PG8_BAR; PG8_SCHED;
	s_waitcnt lgkmcnt(0)
	v_mfma_f32_16x16x32_bf16 v[62:65], v[146:149], v[188:191], 0
	v_mfma_f32_16x16x32_bf16 v[54:57], v[154:157], v[188:191], 0
	v_mfma_f32_16x16x32_bf16 v[46:49], v[146:149], v[196:199], 0
	v_mfma_f32_16x16x32_bf16 v[38:41], v[154:157], v[196:199], 0
	v_mfma_f32_16x16x32_bf16 v[30:33], v[146:149], v[204:207], 0
	v_mfma_f32_16x16x32_bf16 v[22:25], v[154:157], v[204:207], 0
	v_mfma_f32_16x16x32_bf16 v[14:17], v[146:149], v[212:215], 0
	v_mfma_f32_16x16x32_bf16 v[6:9], v[154:157], v[212:215], 0
	v_mfma_f32_16x16x32_bf16 v[62:65], v[150:153], v[192:195], v[62:65]
	v_mfma_f32_16x16x32_bf16 v[54:57], v[158:161], v[192:195], v[54:57]
	v_mfma_f32_16x16x32_bf16 v[46:49], v[150:153], v[200:203], v[46:49]
	v_mfma_f32_16x16x32_bf16 v[38:41], v[158:161], v[200:203], v[38:41]
	v_mfma_f32_16x16x32_bf16 v[30:33], v[150:153], v[208:211], v[30:33]
	v_mfma_f32_16x16x32_bf16 v[22:25], v[158:161], v[208:211], v[22:25]
	v_mfma_f32_16x16x32_bf16 v[14:17], v[150:153], v[216:219], v[14:17]
	v_mfma_f32_16x16x32_bf16 v[6:9], v[158:161], v[216:219], v[6:9]
	v_mfma_f32_16x16x32_bf16 v[58:61], v[172:175], v[188:191], 0
	v_mfma_f32_16x16x32_bf16 v[50:53], v[180:183], v[188:191], 0
	v_mfma_f32_16x16x32_bf16 v[42:45], v[172:175], v[196:199], 0
	v_mfma_f32_16x16x32_bf16 v[34:37], v[180:183], v[196:199], 0
	v_mfma_f32_16x16x32_bf16 v[26:29], v[172:175], v[204:207], 0
	v_mfma_f32_16x16x32_bf16 v[18:21], v[180:183], v[204:207], 0
	v_mfma_f32_16x16x32_bf16 v[10:13], v[172:175], v[212:215], 0
	v_mfma_f32_16x16x32_bf16 v[2:5], v[180:183], v[212:215], 0
	v_mfma_f32_16x16x32_bf16 v[58:61], v[176:179], v[192:195], v[58:61]
	v_mfma_f32_16x16x32_bf16 v[50:53], v[184:187], v[192:195], v[50:53]
	v_mfma_f32_16x16x32_bf16 v[42:45], v[176:179], v[200:203], v[42:45]
	v_mfma_f32_16x16x32_bf16 v[34:37], v[184:187], v[200:203], v[34:37]
	v_mfma_f32_16x16x32_bf16 v[26:29], v[176:179], v[208:211], v[26:29]
	v_mfma_f32_16x16x32_bf16 v[18:21], v[184:187], v[208:211], v[18:21]
	v_mfma_f32_16x16x32_bf16 v[10:13], v[176:179], v[216:219], v[10:13]
	v_mfma_f32_16x16x32_bf16 v[2:5], v[184:187], v[216:219], v[2:5]
	s_barrier
	s_setprio 0
	s_add_i32 s63, 0, 0x18000
	s_add_i32 s84, 0, 0x1c000
	v_add_u32_e32 v158, s63, v166
	v_add_u32_e32 v184, s84, v166
	ds_read_b128 v[146:149], v158
	ds_read_b128 v[150:153], v158 offset:1024
	ds_read_b128 v[154:157], v158 offset:2048
	ds_read_b128 v[158:161], v158 offset:3072
	ds_read_b128 v[172:175], v184
	ds_read_b128 v[176:179], v184 offset:1024
	ds_read_b128 v[180:183], v184 offset:2048
	ds_read_b128 v[184:187], v184 offset:3072
	s_add_u32 s10, s10, 0x40000
	s_addc_u32 s11, s11, 0
	s_mov_b32 m0, s72
	v_lshl_add_u64 v[228:229], s[10:11], 0, v[130:131]
	ds_read_b128 v[188:191], v170 offset:32768
	ds_read_b128 v[192:195], v170 offset:33792
	ds_read_b128 v[196:199], v170 offset:34816
	ds_read_b128 v[200:203], v170 offset:35840
	ds_read_b128 v[204:207], v170 offset:36864
	ds_read_b128 v[208:211], v170 offset:37888
	ds_read_b128 v[212:215], v170 offset:38912
	ds_read_b128 v[216:219], v170 offset:39936
	global_load_lds_dwordx4 v[228:229], off
	v_lshl_add_u64 v[228:229], s[10:11], 0, v[134:135]
	s_mov_b32 m0, s73
	s_nop 0
	global_load_lds_dwordx4 v[228:229], off
	s_waitcnt vmcnt(8)
	s_waitcnt lgkmcnt(0)
	s_setprio 3
	s_barrier
	s_waitcnt lgkmcnt(0)
	v_mfma_f32_16x16x32_bf16 v[126:129], v[146:149], v[188:191], v[126:129]
	v_mfma_f32_16x16x32_bf16 v[118:121], v[154:157], v[188:191], v[118:121]
	v_mfma_f32_16x16x32_bf16 v[110:113], v[146:149], v[196:199], v[110:113]
	v_mfma_f32_16x16x32_bf16 v[102:105], v[154:157], v[196:199], v[102:105]
	v_mfma_f32_16x16x32_bf16 v[94:97], v[146:149], v[204:207], v[94:97]
	v_mfma_f32_16x16x32_bf16 v[86:89], v[154:157], v[204:207], v[86:89]
	v_mfma_f32_16x16x32_bf16 v[78:81], v[146:149], v[212:215], v[78:81]
	v_mfma_f32_16x16x32_bf16 v[70:73], v[154:157], v[212:215], v[70:73]
	v_mfma_f32_16x16x32_bf16 v[126:129], v[150:153], v[192:195], v[126:129]
	v_mfma_f32_16x16x32_bf16 v[118:121], v[158:161], v[192:195], v[118:121]
	v_mfma_f32_16x16x32_bf16 v[110:113], v[150:153], v[200:203], v[110:113]
	v_mfma_f32_16x16x32_bf16 v[102:105], v[158:161], v[200:203], v[102:105]
	v_mfma_f32_16x16x32_bf16 v[94:97], v[150:153], v[208:211], v[94:97]
	v_mfma_f32_16x16x32_bf16 v[86:89], v[158:161], v[208:211], v[86:89]
	v_mfma_f32_16x16x32_bf16 v[78:81], v[150:153], v[216:219], v[78:81]
	v_mfma_f32_16x16x32_bf16 v[70:73], v[158:161], v[216:219], v[70:73]
	v_mfma_f32_16x16x32_bf16 v[122:125], v[172:175], v[188:191], v[122:125]
	v_mfma_f32_16x16x32_bf16 v[114:117], v[180:183], v[188:191], v[114:117]
	v_mfma_f32_16x16x32_bf16 v[106:109], v[172:175], v[196:199], v[106:109]
	v_mfma_f32_16x16x32_bf16 v[98:101], v[180:183], v[196:199], v[98:101]
	v_mfma_f32_16x16x32_bf16 v[90:93], v[172:175], v[204:207], v[90:93]
	v_mfma_f32_16x16x32_bf16 v[82:85], v[180:183], v[204:207], v[82:85]
	v_mfma_f32_16x16x32_bf16 v[74:77], v[172:175], v[212:215], v[74:77]
	v_mfma_f32_16x16x32_bf16 v[66:69], v[180:183], v[212:215], v[66:69]
	v_mfma_f32_16x16x32_bf16 v[122:125], v[176:179], v[192:195], v[122:125]
	v_mfma_f32_16x16x32_bf16 v[114:117], v[184:187], v[192:195], v[114:117]
	v_mfma_f32_16x16x32_bf16 v[106:109], v[176:179], v[200:203], v[106:109]
	v_mfma_f32_16x16x32_bf16 v[98:101], v[184:187], v[200:203], v[98:101]
	v_mfma_f32_16x16x32_bf16 v[90:93], v[176:179], v[208:211], v[90:93]
	v_mfma_f32_16x16x32_bf16 v[82:85], v[184:187], v[208:211], v[82:85]
	v_mfma_f32_16x16x32_bf16 v[74:77], v[176:179], v[216:219], v[74:77]
	v_mfma_f32_16x16x32_bf16 v[66:69], v[184:187], v[216:219], v[66:69]
	s_barrier
; #define PG8_STAGE(bufoff, gbase, voff) do { _Pragma("unroll") for (int _i = 0; _i < 2; ++_i) \
;         __builtin_amdgcn_global_load_lds((const unsigned*)((const char*)(gbase) + (voff)[_i]), (LAS unsigned*)(lds + (bufoff) + ldsw + _i * 8192), 16, 0, 0); } while (0)
; #define PG8_LDA(dst, b, h) do { _Pragma("unroll") for (int m = 0; m < 4; ++m) _Pragma("unroll") for (int k = 0; k < 2; ++k) dst[m][k] = *(const LAS bf16x8*)(lds + PG8_SA(b, h) + aoff + m * 2048 + k * 1024); } while (0)
; #define PG8_LDB(dst, b, h) do { _Pragma("unroll") for (int n = 0; n < 2; ++n) _Pragma("unroll") for (int k = 0; k < 2; ++k) dst[n][k] = *(const LAS bf16x8*)(lds + PG8_SB(b, h) + boff + n * 2048 + k * 1024); } while (0)
; #define PG8_MMA(ai, bj, At, Bt) do { __builtin_amdgcn_s_setprio(3); _Pragma("unroll") for (int m = 0; m < 4; ++m) _Pragma("unroll") for (int n = 0; n < 2; ++n) _Pragma("unroll") for (int k = 0; k < 2; ++k) \
;         acc[ai][bj][m][n] = __builtin_amdgcn_mfma_f32_16x16x32_bf16(Bt[n][k], At[m][k], acc[ai][bj][m][n], 0, 0, 0); __builtin_amdgcn_s_setprio(0); } while (0)
; #define PG8_WAIT_V(n) asm volatile("s_waitcnt vmcnt(" #n ")" ::: "memory")
; #define PG8_WAIT_L(n) asm volatile("s_waitcnt lgkmcnt(" #n ")" ::: "memory")
; #define PG8_BAR __builtin_amdgcn_s_barrier()
; #define PG8_SCHED __builtin_amdgcn_sched_barrier(0)
; template <class Epi, bool ALIGN_EPI>
; __device__ __forceinline__ void gemm_phase(LAS unsigned char* lds, const Gemm g, const StaticOrder& S, const Epi& E) {
;     ...
;             PG8_LDB(B0, 0, 0); PG8_LDB(B1, 0, 1); PG8_SCHED; PG8_LDA(At, 0, 0); PG8_STAGE(PG8_SA(1, 1), a1 + hstep, voffA);
;             PG8_WAIT_V(8); PG8_WAIT_L(0); PG8_BAR; PG8_MMA(0, 0, At, B0); PG8_MMA(0, 1, At, B1); PG8_BAR; PG8_SCHED;
;     ...
;             PG8_LDA(At, 1, 1); PG8_STAGE(PG8_SB(1, 0), b3, voffB); PG8_STAGE(PG8_SB(1, 1), b3 + hstep, voffB); PG8_STAGE(PG8_SA(1, 0), a3, voffA);
;             PG8_WAIT_V(8); PG8_WAIT_L(0); PG8_BAR; PG8_MMA(1, 0, At, B0); PG8_MMA(1, 1, At, B1); PG8_BAR; PG8_SCHED;
	s_setprio 0
	s_add_i32 s10, s63, s33
	v_lshl_add_u64 v[220:221], v[220:221], 0, s[56:57]
	s_mov_b32 m0, s10
	ds_read_b128 v[188:191], v170 offset:49152
	ds_read_b128 v[192:195], v170 offset:50176
	ds_read_b128 v[196:199], v170 offset:51200
	ds_read_b128 v[200:203], v170 offset:52224
	ds_read_b128 v[204:207], v170 offset:53248
	ds_read_b128 v[208:211], v170 offset:54272
	ds_read_b128 v[212:215], v170 offset:55296
	ds_read_b128 v[216:219], v170 offset:56320
	global_load_lds_dwordx4 v[220:221], off
	s_add_i32 m0, s10, 0x2000
	s_add_u32 s8, s8, 0x40080
	v_lshl_add_u64 v[220:221], v[222:223], 0, s[56:57]
	s_addc_u32 s9, s9, 0
	s_add_i32 s10, s84, s33
	global_load_lds_dwordx4 v[220:221], off
	v_lshl_add_u64 v[220:221], s[8:9], 0, v[132:133]
	s_mov_b32 m0, s10
	s_nop 0
	global_load_lds_dwordx4 v[220:221], off
	v_lshl_add_u64 v[220:221], s[8:9], 0, v[136:137]
	s_add_i32 m0, s10, 0x2000
	s_nop 0
	global_load_lds_dwordx4 v[220:221], off
	v_lshl_add_u64 v[220:221], v[224:225], 0, s[56:57]
	s_mov_b32 m0, s78
	s_nop 0
	global_load_lds_dwordx4 v[220:221], off
	v_lshl_add_u64 v[220:221], v[226:227], 0, s[56:57]
	s_mov_b32 m0, s79
	s_nop 0
	global_load_lds_dwordx4 v[220:221], off
	s_waitcnt vmcnt(8)
	s_waitcnt lgkmcnt(0)
	s_setprio 3
	s_barrier
	s_waitcnt lgkmcnt(0)
	v_mfma_f32_16x16x32_bf16 v[62:65], v[146:149], v[188:191], v[62:65]
	v_mfma_f32_16x16x32_bf16 v[54:57], v[154:157], v[188:191], v[54:57]
	v_mfma_f32_16x16x32_bf16 v[46:49], v[146:149], v[196:199], v[46:49]
	v_mfma_f32_16x16x32_bf16 v[38:41], v[154:157], v[196:199], v[38:41]
	v_mfma_f32_16x16x32_bf16 v[30:33], v[146:149], v[204:207], v[30:33]
	v_mfma_f32_16x16x32_bf16 v[22:25], v[154:157], v[204:207], v[22:25]
	v_mfma_f32_16x16x32_bf16 v[14:17], v[146:149], v[212:215], v[14:17]
	v_mfma_f32_16x16x32_bf16 v[6:9], v[154:157], v[212:215], v[6:9]
	v_mfma_f32_16x16x32_bf16 v[62:65], v[150:153], v[192:195], v[62:65]
	v_mfma_f32_16x16x32_bf16 v[54:57], v[158:161], v[192:195], v[54:57]
	v_mfma_f32_16x16x32_bf16 v[46:49], v[150:153], v[200:203], v[46:49]
	v_mfma_f32_16x16x32_bf16 v[38:41], v[158:161], v[200:203], v[38:41]
	v_mfma_f32_16x16x32_bf16 v[30:33], v[150:153], v[208:211], v[30:33]
	v_mfma_f32_16x16x32_bf16 v[22:25], v[158:161], v[208:211], v[22:25]
	v_mfma_f32_16x16x32_bf16 v[14:17], v[150:153], v[216:219], v[14:17]
	v_mfma_f32_16x16x32_bf16 v[6:9], v[158:161], v[216:219], v[6:9]
	v_mfma_f32_16x16x32_bf16 v[58:61], v[172:175], v[188:191], v[58:61]
	v_mfma_f32_16x16x32_bf16 v[50:53], v[180:183], v[188:191], v[50:53]
	v_mfma_f32_16x16x32_bf16 v[42:45], v[172:175], v[196:199], v[42:45]
	v_mfma_f32_16x16x32_bf16 v[34:37], v[180:183], v[196:199], v[34:37]
	v_mfma_f32_16x16x32_bf16 v[26:29], v[172:175], v[204:207], v[26:29]
	v_mfma_f32_16x16x32_bf16 v[18:21], v[180:183], v[204:207], v[18:21]
	v_mfma_f32_16x16x32_bf16 v[10:13], v[172:175], v[212:215], v[10:13]
	v_mfma_f32_16x16x32_bf16 v[2:5], v[180:183], v[212:215], v[2:5]
	v_mfma_f32_16x16x32_bf16 v[58:61], v[176:179], v[192:195], v[58:61]
	v_mfma_f32_16x16x32_bf16 v[50:53], v[184:187], v[192:195], v[50:53]
	v_mfma_f32_16x16x32_bf16 v[42:45], v[176:179], v[200:203], v[42:45]
	v_mfma_f32_16x16x32_bf16 v[34:37], v[184:187], v[200:203], v[34:37]
	v_mfma_f32_16x16x32_bf16 v[26:29], v[176:179], v[208:211], v[26:29]
	v_mfma_f32_16x16x32_bf16 v[18:21], v[184:187], v[208:211], v[18:21]
	v_mfma_f32_16x16x32_bf16 v[10:13], v[176:179], v[216:219], v[10:13]
	v_mfma_f32_16x16x32_bf16 v[2:5], v[184:187], v[216:219], v[2:5]
	s_barrier
	s_setprio 0
	s_add_i32 s61, s61, 2
	s_add_u32 s6, s6, 0x100
	s_addc_u32 s7, s7, 0
	s_add_u32 s16, s16, 0x100
	s_addc_u32 s17, s17, 0
.LBB0_609:
	ds_read_b128 v[146:149], v168
	ds_read_b128 v[150:153], v168 offset:1024
	ds_read_b128 v[154:157], v168 offset:2048
	ds_read_b128 v[158:161], v168 offset:3072
	ds_read_b128 v[172:175], v169
	ds_read_b128 v[176:179], v169 offset:1024
	ds_read_b128 v[180:183], v169 offset:2048
	ds_read_b128 v[184:187], v169 offset:3072
	s_add_u32 s8, s6, 0xfffc0080
	s_addc_u32 s9, s7, -1
	s_cmp_eq_u32 s61, 12
	s_cselect_b32 s11, s12, s9
	s_cselect_b32 s10, s13, s8
	s_cselect_b32 s9, s14, s17
	s_cselect_b32 s8, s15, s16
	v_lshl_add_u64 v[220:221], s[6:7], 0, v[138:139]
	s_add_i32 m0, s70, 0xc000
	ds_read_b128 v[188:191], v170
	ds_read_b128 v[192:195], v170 offset:1024
	ds_read_b128 v[196:199], v170 offset:2048
	ds_read_b128 v[200:203], v170 offset:3072
	ds_read_b128 v[204:207], v170 offset:4096
	ds_read_b128 v[208:211], v170 offset:5120
	ds_read_b128 v[212:215], v170 offset:6144
	ds_read_b128 v[216:219], v170 offset:7168
	global_load_lds_dwordx4 v[220:221], off
	v_lshl_add_u64 v[220:221], s[6:7], 0, v[140:141]
	s_add_i32 m0, s70, 0xe000
	s_nop 0
	global_load_lds_dwordx4 v[220:221], off
	s_waitcnt vmcnt(8)
	s_waitcnt lgkmcnt(0)
	s_setprio 3
	s_barrier
; #define PG8_STAGE(bufoff, gbase, voff) do { _Pragma("unroll") for (int _i = 0; _i < 2; ++_i) \
;         __builtin_amdgcn_global_load_lds((const unsigned*)((const char*)(gbase) + (voff)[_i]), (LAS unsigned*)(lds + (bufoff) + ldsw + _i * 8192), 16, 0, 0); } while (0)
; #define PG8_LDA(dst, b, h) do { _Pragma("unroll") for (int m = 0; m < 4; ++m) _Pragma("unroll") for (int k = 0; k < 2; ++k) dst[m][k] = *(const LAS bf16x8*)(lds + PG8_SA(b, h) + aoff + m * 2048 + k * 1024); } while (0)
; #define PG8_MMA(ai, bj, At, Bt) do { __builtin_amdgcn_s_setprio(3); _Pragma("unroll") for (int m = 0; m < 4; ++m) _Pragma("unroll") for (int n = 0; n < 2; ++n) _Pragma("unroll") for (int k = 0; k < 2; ++k) \
;         acc[ai][bj][m][n] = __builtin_amdgcn_mfma_f32_16x16x32_bf16(Bt[n][k], At[m][k], acc[ai][bj][m][n], 0, 0, 0); __builtin_amdgcn_s_setprio(0); } while (0)
; #define PG8_WAIT_V(n) asm volatile("s_waitcnt vmcnt(" #n ")" ::: "memory")
; #define PG8_WAIT_L(n) asm volatile("s_waitcnt lgkmcnt(" #n ")" ::: "memory")
; #define PG8_BAR __builtin_amdgcn_s_barrier()
; #define PG8_SCHED __builtin_amdgcn_sched_barrier(0)
; template <class Epi, bool ALIGN_EPI>
; __device__ __forceinline__ void gemm_phase(LAS unsigned char* lds, const Gemm g, const StaticOrder& S, const Epi& E) {
;     ...
;             PG8_WAIT_V(8); PG8_WAIT_L(0); PG8_BAR; PG8_MMA(0, 0, At, B0); PG8_MMA(0, 1, At, B1); PG8_BAR; PG8_SCHED;
;             PG8_LDA(At, 0, 1); PG8_STAGE(PG8_SB(0, 0), b2, voffB); PG8_STAGE(PG8_SB(0, 1), b2 + hstep, voffB); PG8_STAGE(PG8_SA(0, 0), a2, voffA);
;             PG8_WAIT_V(8); PG8_WAIT_L(0); PG8_BAR; PG8_MMA(1, 0, At, B0); PG8_MMA(1, 1, At, B1); PG8_BAR; PG8_SCHED;
	s_waitcnt lgkmcnt(0)
	v_mfma_f32_16x16x32_bf16 v[126:129], v[146:149], v[188:191], v[126:129]
	v_mfma_f32_16x16x32_bf16 v[118:121], v[154:157], v[188:191], v[118:121]
	v_mfma_f32_16x16x32_bf16 v[110:113], v[146:149], v[196:199], v[110:113]
	v_mfma_f32_16x16x32_bf16 v[102:105], v[154:157], v[196:199], v[102:105]
	v_mfma_f32_16x16x32_bf16 v[94:97], v[146:149], v[204:207], v[94:97]
	v_mfma_f32_16x16x32_bf16 v[86:89], v[154:157], v[204:207], v[86:89]
	v_mfma_f32_16x16x32_bf16 v[78:81], v[146:149], v[212:215], v[78:81]
	v_mfma_f32_16x16x32_bf16 v[70:73], v[154:157], v[212:215], v[70:73]
	v_mfma_f32_16x16x32_bf16 v[126:129], v[150:153], v[192:195], v[126:129]
	v_mfma_f32_16x16x32_bf16 v[118:121], v[158:161], v[192:195], v[118:121]
	v_mfma_f32_16x16x32_bf16 v[110:113], v[150:153], v[200:203], v[110:113]
	v_mfma_f32_16x16x32_bf16 v[102:105], v[158:161], v[200:203], v[102:105]
	v_mfma_f32_16x16x32_bf16 v[94:97], v[150:153], v[208:211], v[94:97]
	v_mfma_f32_16x16x32_bf16 v[86:89], v[158:161], v[208:211], v[86:89]
	v_mfma_f32_16x16x32_bf16 v[78:81], v[150:153], v[216:219], v[78:81]
	v_mfma_f32_16x16x32_bf16 v[70:73], v[158:161], v[216:219], v[70:73]
	v_mfma_f32_16x16x32_bf16 v[122:125], v[172:175], v[188:191], v[122:125]
	v_mfma_f32_16x16x32_bf16 v[114:117], v[180:183], v[188:191], v[114:117]
	v_mfma_f32_16x16x32_bf16 v[106:109], v[172:175], v[196:199], v[106:109]
	v_mfma_f32_16x16x32_bf16 v[98:101], v[180:183], v[196:199], v[98:101]
	v_mfma_f32_16x16x32_bf16 v[90:93], v[172:175], v[204:207], v[90:93]
	v_mfma_f32_16x16x32_bf16 v[82:85], v[180:183], v[204:207], v[82:85]
	v_mfma_f32_16x16x32_bf16 v[74:77], v[172:175], v[212:215], v[74:77]
	v_mfma_f32_16x16x32_bf16 v[66:69], v[180:183], v[212:215], v[66:69]
	v_mfma_f32_16x16x32_bf16 v[122:125], v[176:179], v[192:195], v[122:125]
	v_mfma_f32_16x16x32_bf16 v[114:117], v[184:187], v[192:195], v[114:117]
	v_mfma_f32_16x16x32_bf16 v[106:109], v[176:179], v[200:203], v[106:109]
	v_mfma_f32_16x16x32_bf16 v[98:101], v[184:187], v[200:203], v[98:101]
	v_mfma_f32_16x16x32_bf16 v[90:93], v[176:179], v[208:211], v[90:93]
	v_mfma_f32_16x16x32_bf16 v[82:85], v[184:187], v[208:211], v[82:85]
	v_mfma_f32_16x16x32_bf16 v[74:77], v[176:179], v[216:219], v[74:77]
	v_mfma_f32_16x16x32_bf16 v[66:69], v[184:187], v[216:219], v[66:69]
	s_barrier
	s_setprio 0
	s_add_i32 s63, s80, s33
	v_lshl_add_u64 v[220:221], s[8:9], 0, v[132:133]
	s_mov_b32 m0, s63
	ds_read_b128 v[188:191], v170 offset:16384
	ds_read_b128 v[192:195], v170 offset:17408
	ds_read_b128 v[196:199], v170 offset:18432
	ds_read_b128 v[200:203], v170 offset:19456
	ds_read_b128 v[204:207], v170 offset:20480
	ds_read_b128 v[208:211], v170 offset:21504
	ds_read_b128 v[212:215], v170 offset:22528
	ds_read_b128 v[216:219], v170 offset:23552
	global_load_lds_dwordx4 v[220:221], off
	s_add_i32 m0, s63, 0x2000
	s_add_u32 s84, s8, 0x40000
	v_lshl_add_u64 v[222:223], s[8:9], 0, v[136:137]
	s_addc_u32 s85, s9, 0
	s_add_i32 s63, s81, s33
	global_load_lds_dwordx4 v[222:223], off
	v_lshl_add_u64 v[224:225], s[84:85], 0, v[132:133]
	s_mov_b32 m0, s63
	v_lshl_add_u64 v[226:227], s[10:11], 0, v[134:135]
	global_load_lds_dwordx4 v[224:225], off
	v_lshl_add_u64 v[224:225], s[84:85], 0, v[136:137]
	s_add_i32 m0, s63, 0x2000
	s_nop 0
	global_load_lds_dwordx4 v[224:225], off
	v_lshl_add_u64 v[224:225], s[10:11], 0, v[130:131]
	s_mov_b32 m0, s70
	s_nop 0
	global_load_lds_dwordx4 v[224:225], off
	s_mov_b32 m0, s71
	s_nop 0
	global_load_lds_dwordx4 v[226:227], off
	s_waitcnt vmcnt(8)
	s_waitcnt lgkmcnt(0)
	s_setprio 3
	s_barrier
	s_waitcnt lgkmcnt(0)
	v_mfma_f32_16x16x32_bf16 v[62:65], v[146:149], v[188:191], v[62:65]
	v_mfma_f32_16x16x32_bf16 v[54:57], v[154:157], v[188:191], v[54:57]
	v_mfma_f32_16x16x32_bf16 v[46:49], v[146:149], v[196:199], v[46:49]
	v_mfma_f32_16x16x32_bf16 v[38:41], v[154:157], v[196:199], v[38:41]
	v_mfma_f32_16x16x32_bf16 v[30:33], v[146:149], v[204:207], v[30:33]
	v_mfma_f32_16x16x32_bf16 v[22:25], v[154:157], v[204:207], v[22:25]
	v_mfma_f32_16x16x32_bf16 v[14:17], v[146:149], v[212:215], v[14:17]
	v_mfma_f32_16x16x32_bf16 v[6:9], v[154:157], v[212:215], v[6:9]
	v_mfma_f32_16x16x32_bf16 v[62:65], v[150:153], v[192:195], v[62:65]
	v_mfma_f32_16x16x32_bf16 v[54:57], v[158:161], v[192:195], v[54:57]
	v_mfma_f32_16x16x32_bf16 v[46:49], v[150:153], v[200:203], v[46:49]
	v_mfma_f32_16x16x32_bf16 v[38:41], v[158:161], v[200:203], v[38:41]
	v_mfma_f32_16x16x32_bf16 v[30:33], v[150:153], v[208:211], v[30:33]
	v_mfma_f32_16x16x32_bf16 v[22:25], v[158:161], v[208:211], v[22:25]
	v_mfma_f32_16x16x32_bf16 v[14:17], v[150:153], v[216:219], v[14:17]
	v_mfma_f32_16x16x32_bf16 v[6:9], v[158:161], v[216:219], v[6:9]
	v_mfma_f32_16x16x32_bf16 v[58:61], v[172:175], v[188:191], v[58:61]
	v_mfma_f32_16x16x32_bf16 v[50:53], v[180:183], v[188:191], v[50:53]
	v_mfma_f32_16x16x32_bf16 v[42:45], v[172:175], v[196:199], v[42:45]
	v_mfma_f32_16x16x32_bf16 v[34:37], v[180:183], v[196:199], v[34:37]
	v_mfma_f32_16x16x32_bf16 v[26:29], v[172:175], v[204:207], v[26:29]
	v_mfma_f32_16x16x32_bf16 v[18:21], v[180:183], v[204:207], v[18:21]
	v_mfma_f32_16x16x32_bf16 v[10:13], v[172:175], v[212:215], v[10:13]
	v_mfma_f32_16x16x32_bf16 v[2:5], v[180:183], v[212:215], v[2:5]
	v_mfma_f32_16x16x32_bf16 v[58:61], v[176:179], v[192:195], v[58:61]
	v_mfma_f32_16x16x32_bf16 v[50:53], v[184:187], v[192:195], v[50:53]
	v_mfma_f32_16x16x32_bf16 v[42:45], v[176:179], v[200:203], v[42:45]
	v_mfma_f32_16x16x32_bf16 v[34:37], v[184:187], v[200:203], v[34:37]
	v_mfma_f32_16x16x32_bf16 v[26:29], v[176:179], v[208:211], v[26:29]
	v_mfma_f32_16x16x32_bf16 v[18:21], v[184:187], v[208:211], v[18:21]
	v_mfma_f32_16x16x32_bf16 v[10:13], v[176:179], v[216:219], v[10:13]
	v_mfma_f32_16x16x32_bf16 v[2:5], v[184:187], v[216:219], v[2:5]
	s_barrier
; #define PG8_STAGE(bufoff, gbase, voff) do { _Pragma("unroll") for (int _i = 0; _i < 2; ++_i) \
;         __builtin_amdgcn_global_load_lds((const unsigned*)((const char*)(gbase) + (voff)[_i]), (LAS unsigned*)(lds + (bufoff) + ldsw + _i * 8192), 16, 0, 0); } while (0)
; #define PG8_LDA(dst, b, h) do { _Pragma("unroll") for (int m = 0; m < 4; ++m) _Pragma("unroll") for (int k = 0; k < 2; ++k) dst[m][k] = *(const LAS bf16x8*)(lds + PG8_SA(b, h) + aoff + m * 2048 + k * 1024); } while (0)
; #define PG8_LDB(dst, b, h) do { _Pragma("unroll") for (int n = 0; n < 2; ++n) _Pragma("unroll") for (int k = 0; k < 2; ++k) dst[n][k] = *(const LAS bf16x8*)(lds + PG8_SB(b, h) + boff + n * 2048 + k * 1024); } while (0)
; #define PG8_MMA(ai, bj, At, Bt) do { __builtin_amdgcn_s_setprio(3); _Pragma("unroll") for (int m = 0; m < 4; ++m) _Pragma("unroll") for (int n = 0; n < 2; ++n) _Pragma("unroll") for (int k = 0; k < 2; ++k) \
;         acc[ai][bj][m][n] = __builtin_amdgcn_mfma_f32_16x16x32_bf16(Bt[n][k], At[m][k], acc[ai][bj][m][n], 0, 0, 0); __builtin_amdgcn_s_setprio(0); } while (0)
; #define PG8_WAIT_V(n) asm volatile("s_waitcnt vmcnt(" #n ")" ::: "memory")
; #define PG8_WAIT_L(n) asm volatile("s_waitcnt lgkmcnt(" #n ")" ::: "memory")
; #define PG8_BAR __builtin_amdgcn_s_barrier()
; #define PG8_SCHED __builtin_amdgcn_sched_barrier(0)
; template <class Epi, bool ALIGN_EPI>
; __device__ __forceinline__ void gemm_phase(LAS unsigned char* lds, const Gemm g, const StaticOrder& S, const Epi& E) {
;     ...
;             PG8_LDB(B0, 1, 0); PG8_LDB(B1, 1, 1); PG8_SCHED; PG8_LDA(At, 1, 0); PG8_STAGE(PG8_SA(0, 1), a2 + hstep, voffA);
;             PG8_WAIT_V(8); PG8_WAIT_L(0); PG8_BAR; PG8_MMA(0, 0, At, B0); PG8_MMA(0, 1, At, B1); PG8_BAR; PG8_SCHED;
	s_setprio 0
	s_add_i32 s63, 0, 0x18000
	s_add_i32 s84, 0, 0x1c000
	v_add_u32_e32 v158, s63, v166
	v_add_u32_e32 v184, s84, v166
	ds_read_b128 v[146:149], v158
	ds_read_b128 v[150:153], v158 offset:1024
	ds_read_b128 v[154:157], v158 offset:2048
	ds_read_b128 v[158:161], v158 offset:3072
	ds_read_b128 v[172:175], v184
	ds_read_b128 v[176:179], v184 offset:1024
	ds_read_b128 v[180:183], v184 offset:2048
	ds_read_b128 v[184:187], v184 offset:3072
	s_add_u32 s10, s10, 0x40000
	s_addc_u32 s11, s11, 0
	s_mov_b32 m0, s72
	v_lshl_add_u64 v[228:229], s[10:11], 0, v[130:131]
	ds_read_b128 v[188:191], v170 offset:32768
	ds_read_b128 v[192:195], v170 offset:33792
	ds_read_b128 v[196:199], v170 offset:34816
	ds_read_b128 v[200:203], v170 offset:35840
	ds_read_b128 v[204:207], v170 offset:36864
	ds_read_b128 v[208:211], v170 offset:37888
	ds_read_b128 v[212:215], v170 offset:38912
	ds_read_b128 v[216:219], v170 offset:39936
	global_load_lds_dwordx4 v[228:229], off
	v_lshl_add_u64 v[228:229], s[10:11], 0, v[134:135]
	s_mov_b32 m0, s73
	s_nop 0
	global_load_lds_dwordx4 v[228:229], off
	s_waitcnt vmcnt(8)
	s_waitcnt lgkmcnt(0)
	s_setprio 3
	s_barrier
	s_waitcnt lgkmcnt(0)
	v_mfma_f32_16x16x32_bf16 v[126:129], v[146:149], v[188:191], v[126:129]
	v_mfma_f32_16x16x32_bf16 v[118:121], v[154:157], v[188:191], v[118:121]
	v_mfma_f32_16x16x32_bf16 v[110:113], v[146:149], v[196:199], v[110:113]
	v_mfma_f32_16x16x32_bf16 v[102:105], v[154:157], v[196:199], v[102:105]
	v_mfma_f32_16x16x32_bf16 v[94:97], v[146:149], v[204:207], v[94:97]
	v_mfma_f32_16x16x32_bf16 v[86:89], v[154:157], v[204:207], v[86:89]
	v_mfma_f32_16x16x32_bf16 v[78:81], v[146:149], v[212:215], v[78:81]
	v_mfma_f32_16x16x32_bf16 v[70:73], v[154:157], v[212:215], v[70:73]
	v_mfma_f32_16x16x32_bf16 v[126:129], v[150:153], v[192:195], v[126:129]
	v_mfma_f32_16x16x32_bf16 v[118:121], v[158:161], v[192:195], v[118:121]
	v_mfma_f32_16x16x32_bf16 v[110:113], v[150:153], v[200:203], v[110:113]
	v_mfma_f32_16x16x32_bf16 v[102:105], v[158:161], v[200:203], v[102:105]
	v_mfma_f32_16x16x32_bf16 v[94:97], v[150:153], v[208:211], v[94:97]
	v_mfma_f32_16x16x32_bf16 v[86:89], v[158:161], v[208:211], v[86:89]
	v_mfma_f32_16x16x32_bf16 v[78:81], v[150:153], v[216:219], v[78:81]
	v_mfma_f32_16x16x32_bf16 v[70:73], v[158:161], v[216:219], v[70:73]
	v_mfma_f32_16x16x32_bf16 v[122:125], v[172:175], v[188:191], v[122:125]
	v_mfma_f32_16x16x32_bf16 v[114:117], v[180:183], v[188:191], v[114:117]
	v_mfma_f32_16x16x32_bf16 v[106:109], v[172:175], v[196:199], v[106:109]
	v_mfma_f32_16x16x32_bf16 v[98:101], v[180:183], v[196:199], v[98:101]
	v_mfma_f32_16x16x32_bf16 v[90:93], v[172:175], v[204:207], v[90:93]
	v_mfma_f32_16x16x32_bf16 v[82:85], v[180:183], v[204:207], v[82:85]
	v_mfma_f32_16x16x32_bf16 v[74:77], v[172:175], v[212:215], v[74:77]
	v_mfma_f32_16x16x32_bf16 v[66:69], v[180:183], v[212:215], v[66:69]
	v_mfma_f32_16x16x32_bf16 v[122:125], v[176:179], v[192:195], v[122:125]
	v_mfma_f32_16x16x32_bf16 v[114:117], v[184:187], v[192:195], v[114:117]
	v_mfma_f32_16x16x32_bf16 v[106:109], v[176:179], v[200:203], v[106:109]
	v_mfma_f32_16x16x32_bf16 v[98:101], v[184:187], v[200:203], v[98:101]
	v_mfma_f32_16x16x32_bf16 v[90:93], v[176:179], v[208:211], v[90:93]
	v_mfma_f32_16x16x32_bf16 v[82:85], v[184:187], v[208:211], v[82:85]
	v_mfma_f32_16x16x32_bf16 v[74:77], v[176:179], v[216:219], v[74:77]
	v_mfma_f32_16x16x32_bf16 v[66:69], v[184:187], v[216:219], v[66:69]
	s_barrier
; #define PG8_STAGE(bufoff, gbase, voff) do { _Pragma("unroll") for (int _i = 0; _i < 2; ++_i) \
;         __builtin_amdgcn_global_load_lds((const unsigned*)((const char*)(gbase) + (voff)[_i]), (LAS unsigned*)(lds + (bufoff) + ldsw + _i * 8192), 16, 0, 0); } while (0)
; #define PG8_LDA(dst, b, h) do { _Pragma("unroll") for (int m = 0; m < 4; ++m) _Pragma("unroll") for (int k = 0; k < 2; ++k) dst[m][k] = *(const LAS bf16x8*)(lds + PG8_SA(b, h) + aoff + m * 2048 + k * 1024); } while (0)
; #define PG8_MMA(ai, bj, At, Bt) do { __builtin_amdgcn_s_setprio(3); _Pragma("unroll") for (int m = 0; m < 4; ++m) _Pragma("unroll") for (int n = 0; n < 2; ++n) _Pragma("unroll") for (int k = 0; k < 2; ++k) \
;         acc[ai][bj][m][n] = __builtin_amdgcn_mfma_f32_16x16x32_bf16(Bt[n][k], At[m][k], acc[ai][bj][m][n], 0, 0, 0); __builtin_amdgcn_s_setprio(0); } while (0)
; #define PG8_WAIT_V(n) asm volatile("s_waitcnt vmcnt(" #n ")" ::: "memory")
; #define PG8_WAIT_L(n) asm volatile("s_waitcnt lgkmcnt(" #n ")" ::: "memory")
; #define PG8_BAR __builtin_amdgcn_s_barrier()
; #define PG8_SCHED __builtin_amdgcn_sched_barrier(0)
; template <class Epi, bool ALIGN_EPI>
; __device__ __forceinline__ void gemm_phase(LAS unsigned char* lds, const Gemm g, const StaticOrder& S, const Epi& E) {
;     ...
;             PG8_LDA(At, 1, 1); PG8_STAGE(PG8_SB(1, 0), b3, voffB); PG8_STAGE(PG8_SB(1, 1), b3 + hstep, voffB); PG8_STAGE(PG8_SA(1, 0), a3, voffA);
;             PG8_WAIT_V(8); PG8_WAIT_L(0); PG8_BAR; PG8_MMA(1, 0, At, B0); PG8_MMA(1, 1, At, B1); PG8_BAR; PG8_SCHED;
;         }
;         if constexpr (ALIGN_EPI) { if (wr == 0) PG8_BAR; }
	s_setprio 0
	s_add_i32 s10, s63, s33
	v_lshl_add_u64 v[220:221], v[220:221], 0, s[56:57]
	s_mov_b32 m0, s10
	ds_read_b128 v[188:191], v170 offset:49152
	ds_read_b128 v[192:195], v170 offset:50176
	ds_read_b128 v[196:199], v170 offset:51200
	ds_read_b128 v[200:203], v170 offset:52224
	ds_read_b128 v[204:207], v170 offset:53248
	ds_read_b128 v[208:211], v170 offset:54272
	ds_read_b128 v[212:215], v170 offset:55296
	ds_read_b128 v[216:219], v170 offset:56320
	global_load_lds_dwordx4 v[220:221], off
	s_add_i32 m0, s10, 0x2000
	s_add_u32 s8, s8, 0x40080
	v_lshl_add_u64 v[220:221], v[222:223], 0, s[56:57]
	s_addc_u32 s9, s9, 0
	s_add_i32 s10, s84, s33
	global_load_lds_dwordx4 v[220:221], off
	v_lshl_add_u64 v[220:221], s[8:9], 0, v[132:133]
	s_mov_b32 m0, s10
	s_nop 0
	global_load_lds_dwordx4 v[220:221], off
	v_lshl_add_u64 v[220:221], s[8:9], 0, v[136:137]
	s_add_i32 m0, s10, 0x2000
	s_nop 0
	global_load_lds_dwordx4 v[220:221], off
	v_lshl_add_u64 v[220:221], v[224:225], 0, s[56:57]
	s_mov_b32 m0, s78
	s_nop 0
	global_load_lds_dwordx4 v[220:221], off
	v_lshl_add_u64 v[220:221], v[226:227], 0, s[56:57]
	s_mov_b32 m0, s79
	s_nop 0
	global_load_lds_dwordx4 v[220:221], off
	s_waitcnt vmcnt(8)
	s_waitcnt lgkmcnt(0)
	s_setprio 3
	s_barrier
	s_waitcnt lgkmcnt(0)
	v_mfma_f32_16x16x32_bf16 v[62:65], v[146:149], v[188:191], v[62:65]
	v_mfma_f32_16x16x32_bf16 v[54:57], v[154:157], v[188:191], v[54:57]
	v_mfma_f32_16x16x32_bf16 v[46:49], v[146:149], v[196:199], v[46:49]
	v_mfma_f32_16x16x32_bf16 v[38:41], v[154:157], v[196:199], v[38:41]
	v_mfma_f32_16x16x32_bf16 v[30:33], v[146:149], v[204:207], v[30:33]
	v_mfma_f32_16x16x32_bf16 v[22:25], v[154:157], v[204:207], v[22:25]
	v_mfma_f32_16x16x32_bf16 v[14:17], v[146:149], v[212:215], v[14:17]
	v_mfma_f32_16x16x32_bf16 v[6:9], v[154:157], v[212:215], v[6:9]
	v_mfma_f32_16x16x32_bf16 v[62:65], v[150:153], v[192:195], v[62:65]
	v_mfma_f32_16x16x32_bf16 v[54:57], v[158:161], v[192:195], v[54:57]
	v_mfma_f32_16x16x32_bf16 v[46:49], v[150:153], v[200:203], v[46:49]
	v_mfma_f32_16x16x32_bf16 v[38:41], v[158:161], v[200:203], v[38:41]
	v_mfma_f32_16x16x32_bf16 v[30:33], v[150:153], v[208:211], v[30:33]
	v_mfma_f32_16x16x32_bf16 v[22:25], v[158:161], v[208:211], v[22:25]
	v_mfma_f32_16x16x32_bf16 v[14:17], v[150:153], v[216:219], v[14:17]
	v_mfma_f32_16x16x32_bf16 v[6:9], v[158:161], v[216:219], v[6:9]
	v_mfma_f32_16x16x32_bf16 v[58:61], v[172:175], v[188:191], v[58:61]
	v_mfma_f32_16x16x32_bf16 v[50:53], v[180:183], v[188:191], v[50:53]
	v_mfma_f32_16x16x32_bf16 v[42:45], v[172:175], v[196:199], v[42:45]
	v_mfma_f32_16x16x32_bf16 v[34:37], v[180:183], v[196:199], v[34:37]
	v_mfma_f32_16x16x32_bf16 v[26:29], v[172:175], v[204:207], v[26:29]
	v_mfma_f32_16x16x32_bf16 v[18:21], v[180:183], v[204:207], v[18:21]
	v_mfma_f32_16x16x32_bf16 v[10:13], v[172:175], v[212:215], v[10:13]
	v_mfma_f32_16x16x32_bf16 v[2:5], v[180:183], v[212:215], v[2:5]
	v_mfma_f32_16x16x32_bf16 v[58:61], v[176:179], v[192:195], v[58:61]
	v_mfma_f32_16x16x32_bf16 v[50:53], v[184:187], v[192:195], v[50:53]
	v_mfma_f32_16x16x32_bf16 v[42:45], v[176:179], v[200:203], v[42:45]
	v_mfma_f32_16x16x32_bf16 v[34:37], v[184:187], v[200:203], v[34:37]
	v_mfma_f32_16x16x32_bf16 v[26:29], v[176:179], v[208:211], v[26:29]
	v_mfma_f32_16x16x32_bf16 v[18:21], v[184:187], v[208:211], v[18:21]
	v_mfma_f32_16x16x32_bf16 v[10:13], v[176:179], v[216:219], v[10:13]
	v_mfma_f32_16x16x32_bf16 v[2:5], v[184:187], v[216:219], v[2:5]
	s_barrier
	s_setprio 0
	s_add_i32 s61, s61, 2
	s_add_u32 s6, s6, 0x100
	s_addc_u32 s7, s7, 0
	s_add_u32 s16, s16, 0x100
	s_addc_u32 s17, s17, 0
	s_cmp_gt_u32 s61, 13
	s_cbranch_scc0 .LBB0_609
	s_and_b64 vcc, exec, s[58:59]
	s_cbranch_vccz .LBB0_612
	s_barrier

; #define PG8_STAGE(bufoff, gbase, voff) do { _Pragma("unroll") for (int _i = 0; _i < 2; ++_i) \
;         __builtin_amdgcn_global_load_lds((const unsigned*)((const char*)(gbase) + (voff)[_i]), (LAS unsigned*)(lds + (bufoff) + ldsw + _i * 8192), 16, 0, 0); } while (0)
; #define PG8_LDA(dst, b, h) do { _Pragma("unroll") for (int m = 0; m < 4; ++m) _Pragma("unroll") for (int k = 0; k < 2; ++k) dst[m][k] = *(const LAS bf16x8*)(lds + PG8_SA(b, h) + aoff + m * 2048 + k * 1024); } while (0)
; #define PG8_LDB(dst, b, h) do { _Pragma("unroll") for (int n = 0; n < 2; ++n) _Pragma("unroll") for (int k = 0; k < 2; ++k) dst[n][k] = *(const LAS bf16x8*)(lds + PG8_SB(b, h) + boff + n * 2048 + k * 1024); } while (0)
; #define PG8_MMA(ai, bj, At, Bt) do { __builtin_amdgcn_s_setprio(3); _Pragma("unroll") for (int m = 0; m < 4; ++m) _Pragma("unroll") for (int n = 0; n < 2; ++n) _Pragma("unroll") for (int k = 0; k < 2; ++k) \
;         acc[ai][bj][m][n] = __builtin_amdgcn_mfma_f32_16x16x32_bf16(Bt[n][k], At[m][k], acc[ai][bj][m][n], 0, 0, 0); __builtin_amdgcn_s_setprio(0); } while (0)
; #define PG8_WAIT_V(n) asm volatile("s_waitcnt vmcnt(" #n ")" ::: "memory")
; #define PG8_WAIT_L(n) asm volatile("s_waitcnt lgkmcnt(" #n ")" ::: "memory")
; #define PG8_BAR __builtin_amdgcn_s_barrier()
; #define PG8_SCHED __builtin_amdgcn_sched_barrier(0)
; template <class Epi, bool ALIGN_EPI>
; __device__ __forceinline__ void gemm_phase(LAS unsigned char* lds, const Gemm g, const StaticOrder& S, const Epi& E) {
;     ...
;         for (int t = 0; t < nt; t += 2) {
;             const bool last = (t == nt - 2);
;             const char* a1 = cA + (size_t)(t + 1) * kstep;
;             const char* a2 = last ? nA : cA + (size_t)(t + 2) * kstep; const char* b2 = last ? nB : cB + (size_t)(t + 2) * kstep;
;             const char* a3 = a2 + kstep; const char* b3 = b2 + kstep;
;             PG8_LDB(B0, 0, 0); PG8_LDB(B1, 0, 1); PG8_SCHED; PG8_LDA(At, 0, 0); PG8_STAGE(PG8_SA(1, 1), a1 + hstep, voffA);
;             PG8_WAIT_V(8); PG8_WAIT_L(0); PG8_BAR; PG8_MMA(0, 0, At, B0); PG8_MMA(0, 1, At, B1); PG8_BAR; PG8_SCHED;
;             PG8_LDA(At, 0, 1); PG8_STAGE(PG8_SB(0, 0), b2, voffB); PG8_STAGE(PG8_SB(0, 1), b2 + hstep, voffB); PG8_STAGE(PG8_SA(0, 0), a2, voffA);
.LBB0_695:
	s_add_u32 s50, s50, 0xb0080
	s_addc_u32 s51, s51, 0
	s_add_u32 s73, s52, 0x100
	s_addc_u32 s76, s53, 0
	s_mov_b32 s77, -2
	s_waitcnt lgkmcnt(0)
	ds_read_b128 v[130:133], v196
	ds_read_b128 v[134:137], v196 offset:1024
	ds_read_b128 v[138:141], v196 offset:2048
	ds_read_b128 v[142:145], v196 offset:3072
	ds_read_b128 v[146:149], v197
	ds_read_b128 v[150:153], v197 offset:1024
	ds_read_b128 v[170:173], v197 offset:2048
	ds_read_b128 v[174:177], v197 offset:3072
	s_add_u32 s52, s50, 0xfff50080
	s_addc_u32 s53, s51, -1
	s_cmp_eq_u32 s77, 40
	s_cselect_b32 s55, s5, s53
	s_cselect_b32 s54, s4, s52
	s_cselect_b32 s53, s19, s76
	s_cselect_b32 s52, s18, s73
	v_lshl_add_u64 v[186:187], s[50:51], 0, v[162:163]
	s_add_i32 m0, s58, 0xc000
	ds_read_b128 v[178:181], v198
	ds_read_b128 v[182:185], v198 offset:1024
	ds_read_b128 v[200:203], v198 offset:2048
	ds_read_b128 v[204:207], v198 offset:3072
	ds_read_b128 v[208:211], v198 offset:4096
	ds_read_b128 v[212:215], v198 offset:5120
	ds_read_b128 v[216:219], v198 offset:6144
	ds_read_b128 v[220:223], v198 offset:7168
	global_load_lds_dwordx4 v[186:187], off
	v_lshl_add_u64 v[186:187], s[50:51], 0, v[164:165]
	s_add_i32 m0, s58, 0xe000
	s_nop 0
	global_load_lds_dwordx4 v[186:187], off
	s_waitcnt vmcnt(8)
	s_waitcnt lgkmcnt(0)
	s_setprio 3
	s_barrier
	s_waitcnt lgkmcnt(0)
	v_mfma_f32_16x16x32_bf16 v[126:129], v[130:133], v[178:181], 0
	v_mfma_f32_16x16x32_bf16 v[122:125], v[138:141], v[178:181], 0
	v_mfma_f32_16x16x32_bf16 v[110:113], v[130:133], v[200:203], 0
	v_mfma_f32_16x16x32_bf16 v[106:109], v[138:141], v[200:203], 0
	v_mfma_f32_16x16x32_bf16 v[94:97], v[130:133], v[208:211], 0
	v_mfma_f32_16x16x32_bf16 v[90:93], v[138:141], v[208:211], 0
	v_mfma_f32_16x16x32_bf16 v[78:81], v[130:133], v[216:219], 0
	v_mfma_f32_16x16x32_bf16 v[74:77], v[138:141], v[216:219], 0
	v_mfma_f32_16x16x32_bf16 v[126:129], v[134:137], v[182:185], v[126:129]
	v_mfma_f32_16x16x32_bf16 v[122:125], v[142:145], v[182:185], v[122:125]
	v_mfma_f32_16x16x32_bf16 v[110:113], v[134:137], v[204:207], v[110:113]
	v_mfma_f32_16x16x32_bf16 v[106:109], v[142:145], v[204:207], v[106:109]
	v_mfma_f32_16x16x32_bf16 v[94:97], v[134:137], v[212:215], v[94:97]
	v_mfma_f32_16x16x32_bf16 v[90:93], v[142:145], v[212:215], v[90:93]
	v_mfma_f32_16x16x32_bf16 v[78:81], v[134:137], v[220:223], v[78:81]
	v_mfma_f32_16x16x32_bf16 v[74:77], v[142:145], v[220:223], v[74:77]
	v_mfma_f32_16x16x32_bf16 v[118:121], v[146:149], v[178:181], 0
	v_mfma_f32_16x16x32_bf16 v[114:117], v[170:173], v[178:181], 0
	v_mfma_f32_16x16x32_bf16 v[102:105], v[146:149], v[200:203], 0
	v_mfma_f32_16x16x32_bf16 v[98:101], v[170:173], v[200:203], 0
	v_mfma_f32_16x16x32_bf16 v[86:89], v[146:149], v[208:211], 0
	v_mfma_f32_16x16x32_bf16 v[82:85], v[170:173], v[208:211], 0
	v_mfma_f32_16x16x32_bf16 v[70:73], v[146:149], v[216:219], 0
	v_mfma_f32_16x16x32_bf16 v[66:69], v[170:173], v[216:219], 0
	v_mfma_f32_16x16x32_bf16 v[118:121], v[150:153], v[182:185], v[118:121]
	v_mfma_f32_16x16x32_bf16 v[114:117], v[174:177], v[182:185], v[114:117]
	v_mfma_f32_16x16x32_bf16 v[102:105], v[150:153], v[204:207], v[102:105]
	v_mfma_f32_16x16x32_bf16 v[98:101], v[174:177], v[204:207], v[98:101]
	v_mfma_f32_16x16x32_bf16 v[86:89], v[150:153], v[212:215], v[86:89]
	v_mfma_f32_16x16x32_bf16 v[82:85], v[174:177], v[212:215], v[82:85]
	v_mfma_f32_16x16x32_bf16 v[70:73], v[150:153], v[220:223], v[70:73]
	v_mfma_f32_16x16x32_bf16 v[66:69], v[174:177], v[220:223], v[66:69]
	s_barrier
	s_setprio 0
	s_add_i32 s78, s67, s57
	v_lshl_add_u64 v[186:187], s[52:53], 0, v[156:157]
	s_mov_b32 m0, s78
	ds_read_b128 v[178:181], v198 offset:16384
	ds_read_b128 v[182:185], v198 offset:17408
	ds_read_b128 v[200:203], v198 offset:18432
	ds_read_b128 v[204:207], v198 offset:19456
	ds_read_b128 v[208:211], v198 offset:20480
	ds_read_b128 v[212:215], v198 offset:21504
	ds_read_b128 v[216:219], v198 offset:22528
	ds_read_b128 v[220:223], v198 offset:23552
	global_load_lds_dwordx4 v[186:187], off
	s_add_i32 m0, s78, 0x2000
	s_add_u32 s78, s52, 0xb0000
	v_lshl_add_u64 v[224:225], s[52:53], 0, v[160:161]
	s_addc_u32 s79, s53, 0
	s_add_i32 s80, s68, s57
	global_load_lds_dwordx4 v[224:225], off
	v_lshl_add_u64 v[226:227], s[78:79], 0, v[156:157]
	s_mov_b32 m0, s80
	v_lshl_add_u64 v[228:229], s[54:55], 0, v[158:159]
	global_load_lds_dwordx4 v[226:227], off
	v_lshl_add_u64 v[226:227], s[78:79], 0, v[160:161]
	s_add_i32 m0, s80, 0x2000
	s_nop 0
	global_load_lds_dwordx4 v[226:227], off
	v_lshl_add_u64 v[226:227], s[54:55], 0, v[154:155]
	s_mov_b32 m0, s58
	s_nop 0
	global_load_lds_dwordx4 v[226:227], off
	s_mov_b32 m0, s59
	s_nop 0
	global_load_lds_dwordx4 v[228:229], off
	s_waitcnt vmcnt(8)
	s_waitcnt lgkmcnt(0)
	s_setprio 3
	s_barrier
; #define PG8_STAGE(bufoff, gbase, voff) do { _Pragma("unroll") for (int _i = 0; _i < 2; ++_i) \
;         __builtin_amdgcn_global_load_lds((const unsigned*)((const char*)(gbase) + (voff)[_i]), (LAS unsigned*)(lds + (bufoff) + ldsw + _i * 8192), 16, 0, 0); } while (0)
; #define PG8_LDA(dst, b, h) do { _Pragma("unroll") for (int m = 0; m < 4; ++m) _Pragma("unroll") for (int k = 0; k < 2; ++k) dst[m][k] = *(const LAS bf16x8*)(lds + PG8_SA(b, h) + aoff + m * 2048 + k * 1024); } while (0)
; #define PG8_LDB(dst, b, h) do { _Pragma("unroll") for (int n = 0; n < 2; ++n) _Pragma("unroll") for (int k = 0; k < 2; ++k) dst[n][k] = *(const LAS bf16x8*)(lds + PG8_SB(b, h) + boff + n * 2048 + k * 1024); } while (0)
; #define PG8_MMA(ai, bj, At, Bt) do { __builtin_amdgcn_s_setprio(3); _Pragma("unroll") for (int m = 0; m < 4; ++m) _Pragma("unroll") for (int n = 0; n < 2; ++n) _Pragma("unroll") for (int k = 0; k < 2; ++k) \
;         acc[ai][bj][m][n] = __builtin_amdgcn_mfma_f32_16x16x32_bf16(Bt[n][k], At[m][k], acc[ai][bj][m][n], 0, 0, 0); __builtin_amdgcn_s_setprio(0); } while (0)
; #define PG8_WAIT_V(n) asm volatile("s_waitcnt vmcnt(" #n ")" ::: "memory")
; #define PG8_WAIT_L(n) asm volatile("s_waitcnt lgkmcnt(" #n ")" ::: "memory")
; #define PG8_BAR __builtin_amdgcn_s_barrier()
; #define PG8_SCHED __builtin_amdgcn_sched_barrier(0)
; template <class Epi, bool ALIGN_EPI>
; __device__ __forceinline__ void gemm_phase(LAS unsigned char* lds, const Gemm g, const StaticOrder& S, const Epi& E) {
;     ...
;             PG8_WAIT_V(8); PG8_WAIT_L(0); PG8_BAR; PG8_MMA(1, 0, At, B0); PG8_MMA(1, 1, At, B1); PG8_BAR; PG8_SCHED;
;             PG8_LDB(B0, 1, 0); PG8_LDB(B1, 1, 1); PG8_SCHED; PG8_LDA(At, 1, 0); PG8_STAGE(PG8_SA(0, 1), a2 + hstep, voffA);
;             PG8_WAIT_V(8); PG8_WAIT_L(0); PG8_BAR; PG8_MMA(0, 0, At, B0); PG8_MMA(0, 1, At, B1); PG8_BAR; PG8_SCHED;
	s_waitcnt lgkmcnt(0)
	v_mfma_f32_16x16x32_bf16 v[62:65], v[130:133], v[178:181], 0
	v_mfma_f32_16x16x32_bf16 v[58:61], v[138:141], v[178:181], 0
	v_mfma_f32_16x16x32_bf16 v[46:49], v[130:133], v[200:203], 0
	v_mfma_f32_16x16x32_bf16 v[42:45], v[138:141], v[200:203], 0
	v_mfma_f32_16x16x32_bf16 v[30:33], v[130:133], v[208:211], 0
	v_mfma_f32_16x16x32_bf16 v[26:29], v[138:141], v[208:211], 0
	v_mfma_f32_16x16x32_bf16 v[14:17], v[130:133], v[216:219], 0
	v_mfma_f32_16x16x32_bf16 v[10:13], v[138:141], v[216:219], 0
	v_mfma_f32_16x16x32_bf16 v[62:65], v[134:137], v[182:185], v[62:65]
	v_mfma_f32_16x16x32_bf16 v[58:61], v[142:145], v[182:185], v[58:61]
	v_mfma_f32_16x16x32_bf16 v[46:49], v[134:137], v[204:207], v[46:49]
	v_mfma_f32_16x16x32_bf16 v[42:45], v[142:145], v[204:207], v[42:45]
	v_mfma_f32_16x16x32_bf16 v[30:33], v[134:137], v[212:215], v[30:33]
	v_mfma_f32_16x16x32_bf16 v[26:29], v[142:145], v[212:215], v[26:29]
	v_mfma_f32_16x16x32_bf16 v[14:17], v[134:137], v[220:223], v[14:17]
	v_mfma_f32_16x16x32_bf16 v[10:13], v[142:145], v[220:223], v[10:13]
	v_mfma_f32_16x16x32_bf16 v[54:57], v[146:149], v[178:181], 0
	v_mfma_f32_16x16x32_bf16 v[50:53], v[170:173], v[178:181], 0
	v_mfma_f32_16x16x32_bf16 v[38:41], v[146:149], v[200:203], 0
	v_mfma_f32_16x16x32_bf16 v[34:37], v[170:173], v[200:203], 0
	v_mfma_f32_16x16x32_bf16 v[22:25], v[146:149], v[208:211], 0
	v_mfma_f32_16x16x32_bf16 v[18:21], v[170:173], v[208:211], 0
	v_mfma_f32_16x16x32_bf16 v[6:9], v[146:149], v[216:219], 0
	v_mfma_f32_16x16x32_bf16 v[2:5], v[170:173], v[216:219], 0
	v_mfma_f32_16x16x32_bf16 v[54:57], v[150:153], v[182:185], v[54:57]
	v_mfma_f32_16x16x32_bf16 v[50:53], v[174:177], v[182:185], v[50:53]
	v_mfma_f32_16x16x32_bf16 v[38:41], v[150:153], v[204:207], v[38:41]
	v_mfma_f32_16x16x32_bf16 v[34:37], v[174:177], v[204:207], v[34:37]
	v_mfma_f32_16x16x32_bf16 v[22:25], v[150:153], v[212:215], v[22:25]
	v_mfma_f32_16x16x32_bf16 v[18:21], v[174:177], v[212:215], v[18:21]
	v_mfma_f32_16x16x32_bf16 v[6:9], v[150:153], v[220:223], v[6:9]
	v_mfma_f32_16x16x32_bf16 v[2:5], v[174:177], v[220:223], v[2:5]
	s_barrier
	s_setprio 0
	s_add_i32 s78, 0, 0x18000
	s_add_i32 s79, 0, 0x1c000
	v_add_u32_e32 v142, s78, v194
	v_add_u32_e32 v174, s79, v194
	ds_read_b128 v[130:133], v142
	ds_read_b128 v[134:137], v142 offset:1024
	ds_read_b128 v[138:141], v142 offset:2048
	ds_read_b128 v[142:145], v142 offset:3072
	ds_read_b128 v[146:149], v174
	ds_read_b128 v[150:153], v174 offset:1024
	ds_read_b128 v[170:173], v174 offset:2048
	ds_read_b128 v[174:177], v174 offset:3072
	s_add_u32 s54, s54, 0xb0000
	s_addc_u32 s55, s55, 0
	s_mov_b32 m0, s60
	v_lshl_add_u64 v[230:231], s[54:55], 0, v[154:155]
	ds_read_b128 v[178:181], v198 offset:32768
	ds_read_b128 v[182:185], v198 offset:33792
	ds_read_b128 v[200:203], v198 offset:34816
	ds_read_b128 v[204:207], v198 offset:35840
	ds_read_b128 v[208:211], v198 offset:36864
	ds_read_b128 v[212:215], v198 offset:37888
	ds_read_b128 v[216:219], v198 offset:38912
	ds_read_b128 v[220:223], v198 offset:39936
	global_load_lds_dwordx4 v[230:231], off
	v_lshl_add_u64 v[230:231], s[54:55], 0, v[158:159]
	s_mov_b32 m0, s61
	s_nop 0
	global_load_lds_dwordx4 v[230:231], off
	s_waitcnt vmcnt(8)
	s_waitcnt lgkmcnt(0)
	s_setprio 3
	s_barrier
	s_waitcnt lgkmcnt(0)
	v_mfma_f32_16x16x32_bf16 v[126:129], v[130:133], v[178:181], v[126:129]
	v_mfma_f32_16x16x32_bf16 v[122:125], v[138:141], v[178:181], v[122:125]
	v_mfma_f32_16x16x32_bf16 v[110:113], v[130:133], v[200:203], v[110:113]
	v_mfma_f32_16x16x32_bf16 v[106:109], v[138:141], v[200:203], v[106:109]
	v_mfma_f32_16x16x32_bf16 v[94:97], v[130:133], v[208:211], v[94:97]
	v_mfma_f32_16x16x32_bf16 v[90:93], v[138:141], v[208:211], v[90:93]
	v_mfma_f32_16x16x32_bf16 v[78:81], v[130:133], v[216:219], v[78:81]
	v_mfma_f32_16x16x32_bf16 v[74:77], v[138:141], v[216:219], v[74:77]
	v_mfma_f32_16x16x32_bf16 v[126:129], v[134:137], v[182:185], v[126:129]
	v_mfma_f32_16x16x32_bf16 v[122:125], v[142:145], v[182:185], v[122:125]
	v_mfma_f32_16x16x32_bf16 v[110:113], v[134:137], v[204:207], v[110:113]
	v_mfma_f32_16x16x32_bf16 v[106:109], v[142:145], v[204:207], v[106:109]
	v_mfma_f32_16x16x32_bf16 v[94:97], v[134:137], v[212:215], v[94:97]
	v_mfma_f32_16x16x32_bf16 v[90:93], v[142:145], v[212:215], v[90:93]
	v_mfma_f32_16x16x32_bf16 v[78:81], v[134:137], v[220:223], v[78:81]
	v_mfma_f32_16x16x32_bf16 v[74:77], v[142:145], v[220:223], v[74:77]
	v_mfma_f32_16x16x32_bf16 v[118:121], v[146:149], v[178:181], v[118:121]
	v_mfma_f32_16x16x32_bf16 v[114:117], v[170:173], v[178:181], v[114:117]
	v_mfma_f32_16x16x32_bf16 v[102:105], v[146:149], v[200:203], v[102:105]
	v_mfma_f32_16x16x32_bf16 v[98:101], v[170:173], v[200:203], v[98:101]
	v_mfma_f32_16x16x32_bf16 v[86:89], v[146:149], v[208:211], v[86:89]
	v_mfma_f32_16x16x32_bf16 v[82:85], v[170:173], v[208:211], v[82:85]
	v_mfma_f32_16x16x32_bf16 v[70:73], v[146:149], v[216:219], v[70:73]
	v_mfma_f32_16x16x32_bf16 v[66:69], v[170:173], v[216:219], v[66:69]
	v_mfma_f32_16x16x32_bf16 v[118:121], v[150:153], v[182:185], v[118:121]
	v_mfma_f32_16x16x32_bf16 v[114:117], v[174:177], v[182:185], v[114:117]
	v_mfma_f32_16x16x32_bf16 v[102:105], v[150:153], v[204:207], v[102:105]
	v_mfma_f32_16x16x32_bf16 v[98:101], v[174:177], v[204:207], v[98:101]
	v_mfma_f32_16x16x32_bf16 v[86:89], v[150:153], v[212:215], v[86:89]
	v_mfma_f32_16x16x32_bf16 v[82:85], v[174:177], v[212:215], v[82:85]
	v_mfma_f32_16x16x32_bf16 v[70:73], v[150:153], v[220:223], v[70:73]
	v_mfma_f32_16x16x32_bf16 v[66:69], v[174:177], v[220:223], v[66:69]
	s_barrier
; #define PG8_STAGE(bufoff, gbase, voff) do { _Pragma("unroll") for (int _i = 0; _i < 2; ++_i) \
;         __builtin_amdgcn_global_load_lds((const unsigned*)((const char*)(gbase) + (voff)[_i]), (LAS unsigned*)(lds + (bufoff) + ldsw + _i * 8192), 16, 0, 0); } while (0)
; #define PG8_LDA(dst, b, h) do { _Pragma("unroll") for (int m = 0; m < 4; ++m) _Pragma("unroll") for (int k = 0; k < 2; ++k) dst[m][k] = *(const LAS bf16x8*)(lds + PG8_SA(b, h) + aoff + m * 2048 + k * 1024); } while (0)
; #define PG8_LDB(dst, b, h) do { _Pragma("unroll") for (int n = 0; n < 2; ++n) _Pragma("unroll") for (int k = 0; k < 2; ++k) dst[n][k] = *(const LAS bf16x8*)(lds + PG8_SB(b, h) + boff + n * 2048 + k * 1024); } while (0)
; #define PG8_MMA(ai, bj, At, Bt) do { __builtin_amdgcn_s_setprio(3); _Pragma("unroll") for (int m = 0; m < 4; ++m) _Pragma("unroll") for (int n = 0; n < 2; ++n) _Pragma("unroll") for (int k = 0; k < 2; ++k) \
;         acc[ai][bj][m][n] = __builtin_amdgcn_mfma_f32_16x16x32_bf16(Bt[n][k], At[m][k], acc[ai][bj][m][n], 0, 0, 0); __builtin_amdgcn_s_setprio(0); } while (0)
; #define PG8_WAIT_V(n) asm volatile("s_waitcnt vmcnt(" #n ")" ::: "memory")
; #define PG8_BAR __builtin_amdgcn_s_barrier()
; template <class Epi, bool ALIGN_EPI>
; __device__ __forceinline__ void gemm_phase(LAS unsigned char* lds, const Gemm g, const StaticOrder& S, const Epi& E) {
;     ...
;             PG8_LDB(B0, 0, 0); PG8_LDB(B1, 0, 1); PG8_SCHED; PG8_LDA(At, 0, 0); PG8_STAGE(PG8_SA(1, 1), a1 + hstep, voffA);
;             PG8_WAIT_V(8); PG8_WAIT_L(0); PG8_BAR; PG8_MMA(0, 0, At, B0); PG8_MMA(0, 1, At, B1); PG8_BAR; PG8_SCHED;
;             PG8_LDA(At, 0, 1); PG8_STAGE(PG8_SB(0, 0), b2, voffB); PG8_STAGE(PG8_SB(0, 1), b2 + hstep, voffB); PG8_STAGE(PG8_SA(0, 0), a2, voffA);
;             PG8_WAIT_V(8); PG8_WAIT_L(0); PG8_BAR; PG8_MMA(1, 0, At, B0); PG8_MMA(1, 1, At, B1); PG8_BAR; PG8_SCHED;
;             PG8_LDB(B0, 1, 0); PG8_LDB(B1, 1, 1); PG8_SCHED; PG8_LDA(At, 1, 0); PG8_STAGE(PG8_SA(0, 1), a2 + hstep, voffA);
;             PG8_WAIT_V(8); PG8_WAIT_L(0); PG8_BAR; PG8_MMA(0, 0, At, B0); PG8_MMA(0, 1, At, B1); PG8_BAR; PG8_SCHED;
;             PG8_LDA(At, 1, 1); PG8_STAGE(PG8_SB(1, 0), b3, voffB); PG8_STAGE(PG8_SB(1, 1), b3 + hstep, voffB); PG8_STAGE(PG8_SA(1, 0), a3, voffA);
;             PG8_WAIT_V(8); PG8_WAIT_L(0); PG8_BAR; PG8_MMA(1, 0, At, B0); PG8_MMA(1, 1, At, B1); PG8_BAR; PG8_SCHED;
	s_setprio 0
	s_add_i32 s54, s78, s57
	v_lshl_add_u64 v[186:187], v[186:187], 0, s[14:15]
	s_mov_b32 m0, s54
	ds_read_b128 v[178:181], v198 offset:49152
	ds_read_b128 v[182:185], v198 offset:50176
	ds_read_b128 v[200:203], v198 offset:51200
	ds_read_b128 v[204:207], v198 offset:52224
	ds_read_b128 v[208:211], v198 offset:53248
	ds_read_b128 v[212:215], v198 offset:54272
	ds_read_b128 v[216:219], v198 offset:55296
	ds_read_b128 v[220:223], v198 offset:56320
	global_load_lds_dwordx4 v[186:187], off
	s_add_i32 m0, s54, 0x2000
	s_add_u32 s52, s52, 0xb0080
	v_lshl_add_u64 v[186:187], v[224:225], 0, s[14:15]
	s_addc_u32 s53, s53, 0
	s_add_i32 s54, s79, s57
	global_load_lds_dwordx4 v[186:187], off
	v_lshl_add_u64 v[186:187], s[52:53], 0, v[156:157]
	s_mov_b32 m0, s54
	s_nop 0
	global_load_lds_dwordx4 v[186:187], off
	v_lshl_add_u64 v[186:187], s[52:53], 0, v[160:161]
	s_add_i32 m0, s54, 0x2000
	s_nop 0
	global_load_lds_dwordx4 v[186:187], off
	v_lshl_add_u64 v[186:187], v[226:227], 0, s[14:15]
	s_mov_b32 m0, s63
	s_nop 0
	global_load_lds_dwordx4 v[186:187], off
	v_lshl_add_u64 v[186:187], v[228:229], 0, s[14:15]
	s_mov_b32 m0, s64
	s_nop 0
	global_load_lds_dwordx4 v[186:187], off
	s_waitcnt vmcnt(8)
	s_waitcnt lgkmcnt(0)
	s_setprio 3
	s_barrier
	s_waitcnt lgkmcnt(0)
	v_mfma_f32_16x16x32_bf16 v[62:65], v[130:133], v[178:181], v[62:65]
	v_mfma_f32_16x16x32_bf16 v[58:61], v[138:141], v[178:181], v[58:61]
	v_mfma_f32_16x16x32_bf16 v[46:49], v[130:133], v[200:203], v[46:49]
	v_mfma_f32_16x16x32_bf16 v[42:45], v[138:141], v[200:203], v[42:45]
	v_mfma_f32_16x16x32_bf16 v[30:33], v[130:133], v[208:211], v[30:33]
	v_mfma_f32_16x16x32_bf16 v[26:29], v[138:141], v[208:211], v[26:29]
	v_mfma_f32_16x16x32_bf16 v[14:17], v[130:133], v[216:219], v[14:17]
	v_mfma_f32_16x16x32_bf16 v[10:13], v[138:141], v[216:219], v[10:13]
	v_mfma_f32_16x16x32_bf16 v[62:65], v[134:137], v[182:185], v[62:65]
	v_mfma_f32_16x16x32_bf16 v[58:61], v[142:145], v[182:185], v[58:61]
	v_mfma_f32_16x16x32_bf16 v[46:49], v[134:137], v[204:207], v[46:49]
	v_mfma_f32_16x16x32_bf16 v[42:45], v[142:145], v[204:207], v[42:45]
	v_mfma_f32_16x16x32_bf16 v[30:33], v[134:137], v[212:215], v[30:33]
	v_mfma_f32_16x16x32_bf16 v[26:29], v[142:145], v[212:215], v[26:29]
	v_mfma_f32_16x16x32_bf16 v[14:17], v[134:137], v[220:223], v[14:17]
	v_mfma_f32_16x16x32_bf16 v[10:13], v[142:145], v[220:223], v[10:13]
	v_mfma_f32_16x16x32_bf16 v[54:57], v[146:149], v[178:181], v[54:57]
	v_mfma_f32_16x16x32_bf16 v[50:53], v[170:173], v[178:181], v[50:53]
	v_mfma_f32_16x16x32_bf16 v[38:41], v[146:149], v[200:203], v[38:41]
	v_mfma_f32_16x16x32_bf16 v[34:37], v[170:173], v[200:203], v[34:37]
	v_mfma_f32_16x16x32_bf16 v[22:25], v[146:149], v[208:211], v[22:25]
	v_mfma_f32_16x16x32_bf16 v[18:21], v[170:173], v[208:211], v[18:21]
	v_mfma_f32_16x16x32_bf16 v[6:9], v[146:149], v[216:219], v[6:9]
	v_mfma_f32_16x16x32_bf16 v[2:5], v[170:173], v[216:219], v[2:5]
	v_mfma_f32_16x16x32_bf16 v[54:57], v[150:153], v[182:185], v[54:57]
	v_mfma_f32_16x16x32_bf16 v[50:53], v[174:177], v[182:185], v[50:53]
	v_mfma_f32_16x16x32_bf16 v[38:41], v[150:153], v[204:207], v[38:41]
	v_mfma_f32_16x16x32_bf16 v[34:37], v[174:177], v[204:207], v[34:37]
	v_mfma_f32_16x16x32_bf16 v[22:25], v[150:153], v[212:215], v[22:25]
	v_mfma_f32_16x16x32_bf16 v[18:21], v[174:177], v[212:215], v[18:21]
	v_mfma_f32_16x16x32_bf16 v[6:9], v[150:153], v[220:223], v[6:9]
	v_mfma_f32_16x16x32_bf16 v[2:5], v[174:177], v[220:223], v[2:5]
	s_barrier
	s_setprio 0
	s_add_i32 s77, s77, 2
	s_add_u32 s50, s50, 0x100
	s_addc_u32 s51, s51, 0
	s_add_u32 s73, s73, 0x100
	s_addc_u32 s76, s76, 0
.LBB0_696:
	ds_read_b128 v[130:133], v196
	ds_read_b128 v[134:137], v196 offset:1024
	ds_read_b128 v[138:141], v196 offset:2048
	ds_read_b128 v[142:145], v196 offset:3072
	ds_read_b128 v[146:149], v197
	ds_read_b128 v[150:153], v197 offset:1024
	ds_read_b128 v[170:173], v197 offset:2048
	ds_read_b128 v[174:177], v197 offset:3072
	s_add_u32 s52, s50, 0xfff50080
	s_addc_u32 s53, s51, -1
	s_cmp_eq_u32 s77, 40
	s_cselect_b32 s55, s5, s53
	s_cselect_b32 s54, s4, s52
	s_cselect_b32 s53, s19, s76
	s_cselect_b32 s52, s18, s73
	v_lshl_add_u64 v[186:187], s[50:51], 0, v[162:163]
	s_add_i32 m0, s58, 0xc000
	ds_read_b128 v[178:181], v198
	ds_read_b128 v[182:185], v198 offset:1024
	ds_read_b128 v[200:203], v198 offset:2048
	ds_read_b128 v[204:207], v198 offset:3072
	ds_read_b128 v[208:211], v198 offset:4096
	ds_read_b128 v[212:215], v198 offset:5120
	ds_read_b128 v[216:219], v198 offset:6144
	ds_read_b128 v[220:223], v198 offset:7168
	global_load_lds_dwordx4 v[186:187], off
	v_lshl_add_u64 v[186:187], s[50:51], 0, v[164:165]
	s_add_i32 m0, s58, 0xe000
	s_nop 0
	global_load_lds_dwordx4 v[186:187], off
	s_waitcnt vmcnt(8)
	s_waitcnt lgkmcnt(0)
	s_setprio 3
	s_barrier
; #define PG8_STAGE(bufoff, gbase, voff) do { _Pragma("unroll") for (int _i = 0; _i < 2; ++_i) \
;         __builtin_amdgcn_global_load_lds((const unsigned*)((const char*)(gbase) + (voff)[_i]), (LAS unsigned*)(lds + (bufoff) + ldsw + _i * 8192), 16, 0, 0); } while (0)
; #define PG8_LDA(dst, b, h) do { _Pragma("unroll") for (int m = 0; m < 4; ++m) _Pragma("unroll") for (int k = 0; k < 2; ++k) dst[m][k] = *(const LAS bf16x8*)(lds + PG8_SA(b, h) + aoff + m * 2048 + k * 1024); } while (0)
; #define PG8_MMA(ai, bj, At, Bt) do { __builtin_amdgcn_s_setprio(3); _Pragma("unroll") for (int m = 0; m < 4; ++m) _Pragma("unroll") for (int n = 0; n < 2; ++n) _Pragma("unroll") for (int k = 0; k < 2; ++k) \
;         acc[ai][bj][m][n] = __builtin_amdgcn_mfma_f32_16x16x32_bf16(Bt[n][k], At[m][k], acc[ai][bj][m][n], 0, 0, 0); __builtin_amdgcn_s_setprio(0); } while (0)
; #define PG8_WAIT_V(n) asm volatile("s_waitcnt vmcnt(" #n ")" ::: "memory")
; #define PG8_WAIT_L(n) asm volatile("s_waitcnt lgkmcnt(" #n ")" ::: "memory")
; #define PG8_BAR __builtin_amdgcn_s_barrier()
; #define PG8_SCHED __builtin_amdgcn_sched_barrier(0)
; template <class Epi, bool ALIGN_EPI>
; __device__ __forceinline__ void gemm_phase(LAS unsigned char* lds, const Gemm g, const StaticOrder& S, const Epi& E) {
;     ...
;             PG8_WAIT_V(8); PG8_WAIT_L(0); PG8_BAR; PG8_MMA(0, 0, At, B0); PG8_MMA(0, 1, At, B1); PG8_BAR; PG8_SCHED;
;             PG8_LDA(At, 0, 1); PG8_STAGE(PG8_SB(0, 0), b2, voffB); PG8_STAGE(PG8_SB(0, 1), b2 + hstep, voffB); PG8_STAGE(PG8_SA(0, 0), a2, voffA);
;             PG8_WAIT_V(8); PG8_WAIT_L(0); PG8_BAR; PG8_MMA(1, 0, At, B0); PG8_MMA(1, 1, At, B1); PG8_BAR; PG8_SCHED;
	s_waitcnt lgkmcnt(0)
	v_mfma_f32_16x16x32_bf16 v[126:129], v[130:133], v[178:181], v[126:129]
	v_mfma_f32_16x16x32_bf16 v[122:125], v[138:141], v[178:181], v[122:125]
	v_mfma_f32_16x16x32_bf16 v[110:113], v[130:133], v[200:203], v[110:113]
	v_mfma_f32_16x16x32_bf16 v[106:109], v[138:141], v[200:203], v[106:109]
	v_mfma_f32_16x16x32_bf16 v[94:97], v[130:133], v[208:211], v[94:97]
	v_mfma_f32_16x16x32_bf16 v[90:93], v[138:141], v[208:211], v[90:93]
	v_mfma_f32_16x16x32_bf16 v[78:81], v[130:133], v[216:219], v[78:81]
	v_mfma_f32_16x16x32_bf16 v[74:77], v[138:141], v[216:219], v[74:77]
	v_mfma_f32_16x16x32_bf16 v[126:129], v[134:137], v[182:185], v[126:129]
	v_mfma_f32_16x16x32_bf16 v[122:125], v[142:145], v[182:185], v[122:125]
	v_mfma_f32_16x16x32_bf16 v[110:113], v[134:137], v[204:207], v[110:113]
	v_mfma_f32_16x16x32_bf16 v[106:109], v[142:145], v[204:207], v[106:109]
	v_mfma_f32_16x16x32_bf16 v[94:97], v[134:137], v[212:215], v[94:97]
	v_mfma_f32_16x16x32_bf16 v[90:93], v[142:145], v[212:215], v[90:93]
	v_mfma_f32_16x16x32_bf16 v[78:81], v[134:137], v[220:223], v[78:81]
	v_mfma_f32_16x16x32_bf16 v[74:77], v[142:145], v[220:223], v[74:77]
	v_mfma_f32_16x16x32_bf16 v[118:121], v[146:149], v[178:181], v[118:121]
	v_mfma_f32_16x16x32_bf16 v[114:117], v[170:173], v[178:181], v[114:117]
	v_mfma_f32_16x16x32_bf16 v[102:105], v[146:149], v[200:203], v[102:105]
	v_mfma_f32_16x16x32_bf16 v[98:101], v[170:173], v[200:203], v[98:101]
	v_mfma_f32_16x16x32_bf16 v[86:89], v[146:149], v[208:211], v[86:89]
	v_mfma_f32_16x16x32_bf16 v[82:85], v[170:173], v[208:211], v[82:85]
	v_mfma_f32_16x16x32_bf16 v[70:73], v[146:149], v[216:219], v[70:73]
	v_mfma_f32_16x16x32_bf16 v[66:69], v[170:173], v[216:219], v[66:69]
	v_mfma_f32_16x16x32_bf16 v[118:121], v[150:153], v[182:185], v[118:121]
	v_mfma_f32_16x16x32_bf16 v[114:117], v[174:177], v[182:185], v[114:117]
	v_mfma_f32_16x16x32_bf16 v[102:105], v[150:153], v[204:207], v[102:105]
	v_mfma_f32_16x16x32_bf16 v[98:101], v[174:177], v[204:207], v[98:101]
	v_mfma_f32_16x16x32_bf16 v[86:89], v[150:153], v[212:215], v[86:89]
	v_mfma_f32_16x16x32_bf16 v[82:85], v[174:177], v[212:215], v[82:85]
	v_mfma_f32_16x16x32_bf16 v[70:73], v[150:153], v[220:223], v[70:73]
	v_mfma_f32_16x16x32_bf16 v[66:69], v[174:177], v[220:223], v[66:69]
	s_barrier
	s_setprio 0
	s_add_i32 s78, s67, s57
	v_lshl_add_u64 v[186:187], s[52:53], 0, v[156:157]
	s_mov_b32 m0, s78
	ds_read_b128 v[178:181], v198 offset:16384
	ds_read_b128 v[182:185], v198 offset:17408
	ds_read_b128 v[200:203], v198 offset:18432
	ds_read_b128 v[204:207], v198 offset:19456
	ds_read_b128 v[208:211], v198 offset:20480
	ds_read_b128 v[212:215], v198 offset:21504
	ds_read_b128 v[216:219], v198 offset:22528
	ds_read_b128 v[220:223], v198 offset:23552
	global_load_lds_dwordx4 v[186:187], off
	s_add_i32 m0, s78, 0x2000
	s_add_u32 s78, s52, 0xb0000
	v_lshl_add_u64 v[224:225], s[52:53], 0, v[160:161]
	s_addc_u32 s79, s53, 0
	s_add_i32 s80, s68, s57
	global_load_lds_dwordx4 v[224:225], off
	v_lshl_add_u64 v[226:227], s[78:79], 0, v[156:157]
	s_mov_b32 m0, s80
	v_lshl_add_u64 v[228:229], s[54:55], 0, v[158:159]
	global_load_lds_dwordx4 v[226:227], off
	v_lshl_add_u64 v[226:227], s[78:79], 0, v[160:161]
	s_add_i32 m0, s80, 0x2000
	s_nop 0
	global_load_lds_dwordx4 v[226:227], off
	v_lshl_add_u64 v[226:227], s[54:55], 0, v[154:155]
	s_mov_b32 m0, s58
	s_nop 0
	global_load_lds_dwordx4 v[226:227], off
	s_mov_b32 m0, s59
	s_nop 0
	global_load_lds_dwordx4 v[228:229], off
	s_waitcnt vmcnt(8)
	s_waitcnt lgkmcnt(0)
	s_setprio 3
	s_barrier
	s_waitcnt lgkmcnt(0)
	v_mfma_f32_16x16x32_bf16 v[62:65], v[130:133], v[178:181], v[62:65]
	v_mfma_f32_16x16x32_bf16 v[58:61], v[138:141], v[178:181], v[58:61]
	v_mfma_f32_16x16x32_bf16 v[46:49], v[130:133], v[200:203], v[46:49]
	v_mfma_f32_16x16x32_bf16 v[42:45], v[138:141], v[200:203], v[42:45]
	v_mfma_f32_16x16x32_bf16 v[30:33], v[130:133], v[208:211], v[30:33]
	v_mfma_f32_16x16x32_bf16 v[26:29], v[138:141], v[208:211], v[26:29]
	v_mfma_f32_16x16x32_bf16 v[14:17], v[130:133], v[216:219], v[14:17]
	v_mfma_f32_16x16x32_bf16 v[10:13], v[138:141], v[216:219], v[10:13]
	v_mfma_f32_16x16x32_bf16 v[62:65], v[134:137], v[182:185], v[62:65]
	v_mfma_f32_16x16x32_bf16 v[58:61], v[142:145], v[182:185], v[58:61]
	v_mfma_f32_16x16x32_bf16 v[46:49], v[134:137], v[204:207], v[46:49]
	v_mfma_f32_16x16x32_bf16 v[42:45], v[142:145], v[204:207], v[42:45]
	v_mfma_f32_16x16x32_bf16 v[30:33], v[134:137], v[212:215], v[30:33]
	v_mfma_f32_16x16x32_bf16 v[26:29], v[142:145], v[212:215], v[26:29]
	v_mfma_f32_16x16x32_bf16 v[14:17], v[134:137], v[220:223], v[14:17]
	v_mfma_f32_16x16x32_bf16 v[10:13], v[142:145], v[220:223], v[10:13]
	v_mfma_f32_16x16x32_bf16 v[54:57], v[146:149], v[178:181], v[54:57]
	v_mfma_f32_16x16x32_bf16 v[50:53], v[170:173], v[178:181], v[50:53]
	v_mfma_f32_16x16x32_bf16 v[38:41], v[146:149], v[200:203], v[38:41]
	v_mfma_f32_16x16x32_bf16 v[34:37], v[170:173], v[200:203], v[34:37]
	v_mfma_f32_16x16x32_bf16 v[22:25], v[146:149], v[208:211], v[22:25]
	v_mfma_f32_16x16x32_bf16 v[18:21], v[170:173], v[208:211], v[18:21]
	v_mfma_f32_16x16x32_bf16 v[6:9], v[146:149], v[216:219], v[6:9]
	v_mfma_f32_16x16x32_bf16 v[2:5], v[170:173], v[216:219], v[2:5]
	v_mfma_f32_16x16x32_bf16 v[54:57], v[150:153], v[182:185], v[54:57]
	v_mfma_f32_16x16x32_bf16 v[50:53], v[174:177], v[182:185], v[50:53]
	v_mfma_f32_16x16x32_bf16 v[38:41], v[150:153], v[204:207], v[38:41]
	v_mfma_f32_16x16x32_bf16 v[34:37], v[174:177], v[204:207], v[34:37]
	v_mfma_f32_16x16x32_bf16 v[22:25], v[150:153], v[212:215], v[22:25]
	v_mfma_f32_16x16x32_bf16 v[18:21], v[174:177], v[212:215], v[18:21]
	v_mfma_f32_16x16x32_bf16 v[6:9], v[150:153], v[220:223], v[6:9]
	v_mfma_f32_16x16x32_bf16 v[2:5], v[174:177], v[220:223], v[2:5]
	s_barrier
; #define PG8_STAGE(bufoff, gbase, voff) do { _Pragma("unroll") for (int _i = 0; _i < 2; ++_i) \
;         __builtin_amdgcn_global_load_lds((const unsigned*)((const char*)(gbase) + (voff)[_i]), (LAS unsigned*)(lds + (bufoff) + ldsw + _i * 8192), 16, 0, 0); } while (0)
; #define PG8_LDA(dst, b, h) do { _Pragma("unroll") for (int m = 0; m < 4; ++m) _Pragma("unroll") for (int k = 0; k < 2; ++k) dst[m][k] = *(const LAS bf16x8*)(lds + PG8_SA(b, h) + aoff + m * 2048 + k * 1024); } while (0)
; #define PG8_LDB(dst, b, h) do { _Pragma("unroll") for (int n = 0; n < 2; ++n) _Pragma("unroll") for (int k = 0; k < 2; ++k) dst[n][k] = *(const LAS bf16x8*)(lds + PG8_SB(b, h) + boff + n * 2048 + k * 1024); } while (0)
; #define PG8_MMA(ai, bj, At, Bt) do { __builtin_amdgcn_s_setprio(3); _Pragma("unroll") for (int m = 0; m < 4; ++m) _Pragma("unroll") for (int n = 0; n < 2; ++n) _Pragma("unroll") for (int k = 0; k < 2; ++k) \
;         acc[ai][bj][m][n] = __builtin_amdgcn_mfma_f32_16x16x32_bf16(Bt[n][k], At[m][k], acc[ai][bj][m][n], 0, 0, 0); __builtin_amdgcn_s_setprio(0); } while (0)
; #define PG8_WAIT_V(n) asm volatile("s_waitcnt vmcnt(" #n ")" ::: "memory")
; #define PG8_WAIT_L(n) asm volatile("s_waitcnt lgkmcnt(" #n ")" ::: "memory")
; #define PG8_BAR __builtin_amdgcn_s_barrier()
; #define PG8_SCHED __builtin_amdgcn_sched_barrier(0)
; template <class Epi, bool ALIGN_EPI>
; __device__ __forceinline__ void gemm_phase(LAS unsigned char* lds, const Gemm g, const StaticOrder& S, const Epi& E) {
;     ...
;             PG8_LDB(B0, 1, 0); PG8_LDB(B1, 1, 1); PG8_SCHED; PG8_LDA(At, 1, 0); PG8_STAGE(PG8_SA(0, 1), a2 + hstep, voffA);
;             PG8_WAIT_V(8); PG8_WAIT_L(0); PG8_BAR; PG8_MMA(0, 0, At, B0); PG8_MMA(0, 1, At, B1); PG8_BAR; PG8_SCHED;
	s_setprio 0
	s_add_i32 s78, 0, 0x18000
	s_add_i32 s79, 0, 0x1c000
	v_add_u32_e32 v142, s78, v194
	v_add_u32_e32 v174, s79, v194
	ds_read_b128 v[130:133], v142
	ds_read_b128 v[134:137], v142 offset:1024
	ds_read_b128 v[138:141], v142 offset:2048
	ds_read_b128 v[142:145], v142 offset:3072
	ds_read_b128 v[146:149], v174
	ds_read_b128 v[150:153], v174 offset:1024
	ds_read_b128 v[170:173], v174 offset:2048
	ds_read_b128 v[174:177], v174 offset:3072
	s_add_u32 s54, s54, 0xb0000
	s_addc_u32 s55, s55, 0
	s_mov_b32 m0, s60
	v_lshl_add_u64 v[230:231], s[54:55], 0, v[154:155]
	ds_read_b128 v[178:181], v198 offset:32768
	ds_read_b128 v[182:185], v198 offset:33792
	ds_read_b128 v[200:203], v198 offset:34816
	ds_read_b128 v[204:207], v198 offset:35840
	ds_read_b128 v[208:211], v198 offset:36864
	ds_read_b128 v[212:215], v198 offset:37888
	ds_read_b128 v[216:219], v198 offset:38912
	ds_read_b128 v[220:223], v198 offset:39936
	global_load_lds_dwordx4 v[230:231], off
	v_lshl_add_u64 v[230:231], s[54:55], 0, v[158:159]
	s_mov_b32 m0, s61
	s_nop 0
	global_load_lds_dwordx4 v[230:231], off
	s_waitcnt vmcnt(8)
	s_waitcnt lgkmcnt(0)
	s_setprio 3
	s_barrier
	s_waitcnt lgkmcnt(0)
	v_mfma_f32_16x16x32_bf16 v[126:129], v[130:133], v[178:181], v[126:129]
	v_mfma_f32_16x16x32_bf16 v[122:125], v[138:141], v[178:181], v[122:125]
	v_mfma_f32_16x16x32_bf16 v[110:113], v[130:133], v[200:203], v[110:113]
	v_mfma_f32_16x16x32_bf16 v[106:109], v[138:141], v[200:203], v[106:109]
	v_mfma_f32_16x16x32_bf16 v[94:97], v[130:133], v[208:211], v[94:97]
	v_mfma_f32_16x16x32_bf16 v[90:93], v[138:141], v[208:211], v[90:93]
	v_mfma_f32_16x16x32_bf16 v[78:81], v[130:133], v[216:219], v[78:81]
	v_mfma_f32_16x16x32_bf16 v[74:77], v[138:141], v[216:219], v[74:77]
	v_mfma_f32_16x16x32_bf16 v[126:129], v[134:137], v[182:185], v[126:129]
	v_mfma_f32_16x16x32_bf16 v[122:125], v[142:145], v[182:185], v[122:125]
	v_mfma_f32_16x16x32_bf16 v[110:113], v[134:137], v[204:207], v[110:113]
	v_mfma_f32_16x16x32_bf16 v[106:109], v[142:145], v[204:207], v[106:109]
	v_mfma_f32_16x16x32_bf16 v[94:97], v[134:137], v[212:215], v[94:97]
	v_mfma_f32_16x16x32_bf16 v[90:93], v[142:145], v[212:215], v[90:93]
	v_mfma_f32_16x16x32_bf16 v[78:81], v[134:137], v[220:223], v[78:81]
	v_mfma_f32_16x16x32_bf16 v[74:77], v[142:145], v[220:223], v[74:77]
	v_mfma_f32_16x16x32_bf16 v[118:121], v[146:149], v[178:181], v[118:121]
	v_mfma_f32_16x16x32_bf16 v[114:117], v[170:173], v[178:181], v[114:117]
	v_mfma_f32_16x16x32_bf16 v[102:105], v[146:149], v[200:203], v[102:105]
	v_mfma_f32_16x16x32_bf16 v[98:101], v[170:173], v[200:203], v[98:101]
	v_mfma_f32_16x16x32_bf16 v[86:89], v[146:149], v[208:211], v[86:89]
	v_mfma_f32_16x16x32_bf16 v[82:85], v[170:173], v[208:211], v[82:85]
	v_mfma_f32_16x16x32_bf16 v[70:73], v[146:149], v[216:219], v[70:73]
	v_mfma_f32_16x16x32_bf16 v[66:69], v[170:173], v[216:219], v[66:69]
	v_mfma_f32_16x16x32_bf16 v[118:121], v[150:153], v[182:185], v[118:121]
	v_mfma_f32_16x16x32_bf16 v[114:117], v[174:177], v[182:185], v[114:117]
	v_mfma_f32_16x16x32_bf16 v[102:105], v[150:153], v[204:207], v[102:105]
	v_mfma_f32_16x16x32_bf16 v[98:101], v[174:177], v[204:207], v[98:101]
	v_mfma_f32_16x16x32_bf16 v[86:89], v[150:153], v[212:215], v[86:89]
	v_mfma_f32_16x16x32_bf16 v[82:85], v[174:177], v[212:215], v[82:85]
	v_mfma_f32_16x16x32_bf16 v[70:73], v[150:153], v[220:223], v[70:73]
	v_mfma_f32_16x16x32_bf16 v[66:69], v[174:177], v[220:223], v[66:69]
	s_barrier
; #define PG8_STAGE(bufoff, gbase, voff) do { _Pragma("unroll") for (int _i = 0; _i < 2; ++_i) \
;         __builtin_amdgcn_global_load_lds((const unsigned*)((const char*)(gbase) + (voff)[_i]), (LAS unsigned*)(lds + (bufoff) + ldsw + _i * 8192), 16, 0, 0); } while (0)
; #define PG8_LDA(dst, b, h) do { _Pragma("unroll") for (int m = 0; m < 4; ++m) _Pragma("unroll") for (int k = 0; k < 2; ++k) dst[m][k] = *(const LAS bf16x8*)(lds + PG8_SA(b, h) + aoff + m * 2048 + k * 1024); } while (0)
; #define PG8_MMA(ai, bj, At, Bt) do { __builtin_amdgcn_s_setprio(3); _Pragma("unroll") for (int m = 0; m < 4; ++m) _Pragma("unroll") for (int n = 0; n < 2; ++n) _Pragma("unroll") for (int k = 0; k < 2; ++k) \
;         acc[ai][bj][m][n] = __builtin_amdgcn_mfma_f32_16x16x32_bf16(Bt[n][k], At[m][k], acc[ai][bj][m][n], 0, 0, 0); __builtin_amdgcn_s_setprio(0); } while (0)
; #define PG8_WAIT_V(n) asm volatile("s_waitcnt vmcnt(" #n ")" ::: "memory")
; #define PG8_WAIT_L(n) asm volatile("s_waitcnt lgkmcnt(" #n ")" ::: "memory")
; #define PG8_BAR __builtin_amdgcn_s_barrier()
; #define PG8_SCHED __builtin_amdgcn_sched_barrier(0)
; template <class Epi, bool ALIGN_EPI>
; __device__ __forceinline__ void gemm_phase(LAS unsigned char* lds, const Gemm g, const StaticOrder& S, const Epi& E) {
;     ...
;             PG8_LDA(At, 1, 1); PG8_STAGE(PG8_SB(1, 0), b3, voffB); PG8_STAGE(PG8_SB(1, 1), b3 + hstep, voffB); PG8_STAGE(PG8_SA(1, 0), a3, voffA);
;             PG8_WAIT_V(8); PG8_WAIT_L(0); PG8_BAR; PG8_MMA(1, 0, At, B0); PG8_MMA(1, 1, At, B1); PG8_BAR; PG8_SCHED;
;         }
;         if constexpr (ALIGN_EPI) { if (wr == 0) PG8_BAR; }
	s_setprio 0
	s_add_i32 s54, s78, s57
	v_lshl_add_u64 v[186:187], v[186:187], 0, s[14:15]
	s_mov_b32 m0, s54
	ds_read_b128 v[178:181], v198 offset:49152
	ds_read_b128 v[182:185], v198 offset:50176
	ds_read_b128 v[200:203], v198 offset:51200
	ds_read_b128 v[204:207], v198 offset:52224
	ds_read_b128 v[208:211], v198 offset:53248
	ds_read_b128 v[212:215], v198 offset:54272
	ds_read_b128 v[216:219], v198 offset:55296
	ds_read_b128 v[220:223], v198 offset:56320
	global_load_lds_dwordx4 v[186:187], off
	s_add_i32 m0, s54, 0x2000
	s_add_u32 s52, s52, 0xb0080
	v_lshl_add_u64 v[186:187], v[224:225], 0, s[14:15]
	s_addc_u32 s53, s53, 0
	s_add_i32 s54, s79, s57
	global_load_lds_dwordx4 v[186:187], off
	v_lshl_add_u64 v[186:187], s[52:53], 0, v[156:157]
	s_mov_b32 m0, s54
	s_nop 0
	global_load_lds_dwordx4 v[186:187], off
	v_lshl_add_u64 v[186:187], s[52:53], 0, v[160:161]
	s_add_i32 m0, s54, 0x2000
	s_nop 0
	global_load_lds_dwordx4 v[186:187], off
	v_lshl_add_u64 v[186:187], v[226:227], 0, s[14:15]
	s_mov_b32 m0, s63
	s_nop 0
	global_load_lds_dwordx4 v[186:187], off
	v_lshl_add_u64 v[186:187], v[228:229], 0, s[14:15]
	s_mov_b32 m0, s64
	s_nop 0
	global_load_lds_dwordx4 v[186:187], off
	s_waitcnt vmcnt(8)
	s_waitcnt lgkmcnt(0)
	s_setprio 3
	s_barrier
	s_waitcnt lgkmcnt(0)
	v_mfma_f32_16x16x32_bf16 v[62:65], v[130:133], v[178:181], v[62:65]
	v_mfma_f32_16x16x32_bf16 v[58:61], v[138:141], v[178:181], v[58:61]
	v_mfma_f32_16x16x32_bf16 v[46:49], v[130:133], v[200:203], v[46:49]
	v_mfma_f32_16x16x32_bf16 v[42:45], v[138:141], v[200:203], v[42:45]
	v_mfma_f32_16x16x32_bf16 v[30:33], v[130:133], v[208:211], v[30:33]
	v_mfma_f32_16x16x32_bf16 v[26:29], v[138:141], v[208:211], v[26:29]
	v_mfma_f32_16x16x32_bf16 v[14:17], v[130:133], v[216:219], v[14:17]
	v_mfma_f32_16x16x32_bf16 v[10:13], v[138:141], v[216:219], v[10:13]
	v_mfma_f32_16x16x32_bf16 v[62:65], v[134:137], v[182:185], v[62:65]
	v_mfma_f32_16x16x32_bf16 v[58:61], v[142:145], v[182:185], v[58:61]
	v_mfma_f32_16x16x32_bf16 v[46:49], v[134:137], v[204:207], v[46:49]
	v_mfma_f32_16x16x32_bf16 v[42:45], v[142:145], v[204:207], v[42:45]
	v_mfma_f32_16x16x32_bf16 v[30:33], v[134:137], v[212:215], v[30:33]
	v_mfma_f32_16x16x32_bf16 v[26:29], v[142:145], v[212:215], v[26:29]
	v_mfma_f32_16x16x32_bf16 v[14:17], v[134:137], v[220:223], v[14:17]
	v_mfma_f32_16x16x32_bf16 v[10:13], v[142:145], v[220:223], v[10:13]
	v_mfma_f32_16x16x32_bf16 v[54:57], v[146:149], v[178:181], v[54:57]
	v_mfma_f32_16x16x32_bf16 v[50:53], v[170:173], v[178:181], v[50:53]
	v_mfma_f32_16x16x32_bf16 v[38:41], v[146:149], v[200:203], v[38:41]
	v_mfma_f32_16x16x32_bf16 v[34:37], v[170:173], v[200:203], v[34:37]
	v_mfma_f32_16x16x32_bf16 v[22:25], v[146:149], v[208:211], v[22:25]
	v_mfma_f32_16x16x32_bf16 v[18:21], v[170:173], v[208:211], v[18:21]
	v_mfma_f32_16x16x32_bf16 v[6:9], v[146:149], v[216:219], v[6:9]
	v_mfma_f32_16x16x32_bf16 v[2:5], v[170:173], v[216:219], v[2:5]
	v_mfma_f32_16x16x32_bf16 v[54:57], v[150:153], v[182:185], v[54:57]
	v_mfma_f32_16x16x32_bf16 v[50:53], v[174:177], v[182:185], v[50:53]
	v_mfma_f32_16x16x32_bf16 v[38:41], v[150:153], v[204:207], v[38:41]
	v_mfma_f32_16x16x32_bf16 v[34:37], v[174:177], v[204:207], v[34:37]
	v_mfma_f32_16x16x32_bf16 v[22:25], v[150:153], v[212:215], v[22:25]
	v_mfma_f32_16x16x32_bf16 v[18:21], v[174:177], v[212:215], v[18:21]
	v_mfma_f32_16x16x32_bf16 v[6:9], v[150:153], v[220:223], v[6:9]
	v_mfma_f32_16x16x32_bf16 v[2:5], v[174:177], v[220:223], v[2:5]
	s_barrier
	s_setprio 0
	s_add_i32 s77, s77, 2
	s_add_u32 s50, s50, 0x100
	s_addc_u32 s51, s51, 0
	s_add_u32 s73, s73, 0x100
	s_addc_u32 s76, s76, 0
	s_cmp_gt_u32 s77, 41
	s_cbranch_scc0 .LBB0_696
	s_and_b64 vcc, exec, s[16:17]
	s_cbranch_vccz .LBB0_699
	s_barrier

; #define PG8_STAGE(bufoff, gbase, voff) do { _Pragma("unroll") for (int _i = 0; _i < 2; ++_i) \
;         __builtin_amdgcn_global_load_lds((const unsigned*)((const char*)(gbase) + (voff)[_i]), (LAS unsigned*)(lds + (bufoff) + ldsw + _i * 8192), 16, 0, 0); } while (0)
; #define PG8_LDA(dst, b, h) do { _Pragma("unroll") for (int m = 0; m < 4; ++m) _Pragma("unroll") for (int k = 0; k < 2; ++k) dst[m][k] = *(const LAS bf16x8*)(lds + PG8_SA(b, h) + aoff + m * 2048 + k * 1024); } while (0)
; #define PG8_LDB(dst, b, h) do { _Pragma("unroll") for (int n = 0; n < 2; ++n) _Pragma("unroll") for (int k = 0; k < 2; ++k) dst[n][k] = *(const LAS bf16x8*)(lds + PG8_SB(b, h) + boff + n * 2048 + k * 1024); } while (0)
; #define PG8_MMA(ai, bj, At, Bt) do { __builtin_amdgcn_s_setprio(3); _Pragma("unroll") for (int m = 0; m < 4; ++m) _Pragma("unroll") for (int n = 0; n < 2; ++n) _Pragma("unroll") for (int k = 0; k < 2; ++k) \
;         acc[ai][bj][m][n] = __builtin_amdgcn_mfma_f32_16x16x32_bf16(Bt[n][k], At[m][k], acc[ai][bj][m][n], 0, 0, 0); __builtin_amdgcn_s_setprio(0); } while (0)
; #define PG8_WAIT_V(n) asm volatile("s_waitcnt vmcnt(" #n ")" ::: "memory")
; #define PG8_WAIT_L(n) asm volatile("s_waitcnt lgkmcnt(" #n ")" ::: "memory")
; template <class Epi, bool ALIGN_EPI>
; __device__ __forceinline__ void gemm_phase(LAS unsigned char* lds, const Gemm g, const StaticOrder& S, const Epi& E) {
;     ...
;         const bool has_next = S.next(ui + 1, nxt);
;         const char* nA = has_next ? (const char*)g.A + (size_t)nxt.pm * tstep : cA; const char* nB = has_next ? (const char*)g.Bt + (size_t)nxt.pn * tstep : cB;
;         for (int t = 0; t < nt; t += 2) {
;             const bool last = (t == nt - 2);
;             const char* a1 = cA + (size_t)(t + 1) * kstep;
;             const char* a2 = last ? nA : cA + (size_t)(t + 2) * kstep; const char* b2 = last ? nB : cB + (size_t)(t + 2) * kstep;
;             const char* a3 = a2 + kstep; const char* b3 = b2 + kstep;
;             PG8_LDB(B0, 0, 0); PG8_LDB(B1, 0, 1); PG8_SCHED; PG8_LDA(At, 0, 0); PG8_STAGE(PG8_SA(1, 1), a1 + hstep, voffA);
;             PG8_WAIT_V(8); PG8_WAIT_L(0); PG8_BAR; PG8_MMA(0, 0, At, B0); PG8_MMA(0, 1, At, B1); PG8_BAR; PG8_SCHED;
;             PG8_LDA(At, 0, 1); PG8_STAGE(PG8_SB(0, 0), b2, voffB); PG8_STAGE(PG8_SB(0, 1), b2 + hstep, voffB); PG8_STAGE(PG8_SA(0, 0), a2, voffA);
.LBB0_786:
	s_ashr_i32 s79, s78, 31
	s_lshl_b64 s[8:9], s[78:79], 19
	s_add_u32 s80, s34, s8
	s_addc_u32 s81, s35, s9
	s_and_b64 s[8:9], s[10:11], exec
	s_cselect_b32 s50, s81, s5
	s_cselect_b32 s55, s80, s4
	s_ashr_i32 s73, s72, 31
	s_lshl_b64 s[8:9], s[72:73], 19
	s_add_u32 s82, s18, s8
	s_addc_u32 s83, s19, s9
	s_and_b64 s[8:9], s[10:11], exec
	s_cselect_b32 s73, s83, s7
	s_cselect_b32 s79, s82, s6
	s_add_u32 s4, s4, 0x40080
	s_addc_u32 s5, s5, 0
	s_add_u32 s85, s6, 0x100
	s_addc_u32 s88, s7, 0
	s_mov_b32 s89, -2
	s_waitcnt lgkmcnt(0)
	ds_read_b128 v[130:133], v220
	ds_read_b128 v[134:137], v220 offset:1024
	ds_read_b128 v[138:141], v220 offset:2048
	ds_read_b128 v[142:145], v220 offset:3072
	ds_read_b128 v[166:169], v221
	ds_read_b128 v[170:173], v221 offset:1024
	ds_read_b128 v[174:177], v221 offset:2048
	ds_read_b128 v[178:181], v221 offset:3072
	s_add_u32 s6, s4, 0xfffc0080
	s_addc_u32 s7, s5, -1
	s_cmp_eq_u32 s89, 12
	s_cselect_b32 s9, s50, s7
	s_cselect_b32 s8, s55, s6
	s_cselect_b32 s7, s73, s88
	s_cselect_b32 s6, s79, s85
	v_lshl_add_u64 v[230:231], s[4:5], 0, v[158:159]
	s_add_i32 m0, s77, 0xc000
	ds_read_b128 v[182:185], v222
	ds_read_b128 v[186:189], v222 offset:1024
	ds_read_b128 v[190:193], v222 offset:2048
	ds_read_b128 v[194:197], v222 offset:3072
	ds_read_b128 v[198:201], v222 offset:4096
	ds_read_b128 v[202:205], v222 offset:5120
	ds_read_b128 v[206:209], v222 offset:6144
	ds_read_b128 v[226:229], v222 offset:7168
	global_load_lds_dwordx4 v[230:231], off
	v_lshl_add_u64 v[230:231], s[4:5], 0, v[160:161]
	s_add_i32 m0, s77, 0xe000
	s_nop 0
	global_load_lds_dwordx4 v[230:231], off
	s_waitcnt vmcnt(8)
	s_waitcnt lgkmcnt(0)
	s_setprio 3
	s_barrier
	s_waitcnt lgkmcnt(0)
	v_mfma_f32_16x16x32_bf16 v[126:129], v[130:133], v[182:185], 0
	v_mfma_f32_16x16x32_bf16 v[122:125], v[138:141], v[182:185], 0
	v_mfma_f32_16x16x32_bf16 v[110:113], v[130:133], v[190:193], 0
	v_mfma_f32_16x16x32_bf16 v[106:109], v[138:141], v[190:193], 0
	v_mfma_f32_16x16x32_bf16 v[94:97], v[130:133], v[198:201], 0
	v_mfma_f32_16x16x32_bf16 v[90:93], v[138:141], v[198:201], 0
	v_mfma_f32_16x16x32_bf16 v[78:81], v[130:133], v[206:209], 0
	v_mfma_f32_16x16x32_bf16 v[74:77], v[138:141], v[206:209], 0
	v_mfma_f32_16x16x32_bf16 v[126:129], v[134:137], v[186:189], v[126:129]
	v_mfma_f32_16x16x32_bf16 v[122:125], v[142:145], v[186:189], v[122:125]
	v_mfma_f32_16x16x32_bf16 v[110:113], v[134:137], v[194:197], v[110:113]
	v_mfma_f32_16x16x32_bf16 v[106:109], v[142:145], v[194:197], v[106:109]
	v_mfma_f32_16x16x32_bf16 v[94:97], v[134:137], v[202:205], v[94:97]
	v_mfma_f32_16x16x32_bf16 v[90:93], v[142:145], v[202:205], v[90:93]
	v_mfma_f32_16x16x32_bf16 v[78:81], v[134:137], v[226:229], v[78:81]
	v_mfma_f32_16x16x32_bf16 v[74:77], v[142:145], v[226:229], v[74:77]
	v_mfma_f32_16x16x32_bf16 v[118:121], v[166:169], v[182:185], 0
	v_mfma_f32_16x16x32_bf16 v[114:117], v[174:177], v[182:185], 0
	v_mfma_f32_16x16x32_bf16 v[102:105], v[166:169], v[190:193], 0
	v_mfma_f32_16x16x32_bf16 v[98:101], v[174:177], v[190:193], 0
	v_mfma_f32_16x16x32_bf16 v[86:89], v[166:169], v[198:201], 0
	v_mfma_f32_16x16x32_bf16 v[82:85], v[174:177], v[198:201], 0
	v_mfma_f32_16x16x32_bf16 v[70:73], v[166:169], v[206:209], 0
	v_mfma_f32_16x16x32_bf16 v[66:69], v[174:177], v[206:209], 0
	v_mfma_f32_16x16x32_bf16 v[118:121], v[170:173], v[186:189], v[118:121]
	v_mfma_f32_16x16x32_bf16 v[114:117], v[178:181], v[186:189], v[114:117]
	v_mfma_f32_16x16x32_bf16 v[102:105], v[170:173], v[194:197], v[102:105]
	v_mfma_f32_16x16x32_bf16 v[98:101], v[178:181], v[194:197], v[98:101]
	v_mfma_f32_16x16x32_bf16 v[86:89], v[170:173], v[202:205], v[86:89]
	v_mfma_f32_16x16x32_bf16 v[82:85], v[178:181], v[202:205], v[82:85]
	v_mfma_f32_16x16x32_bf16 v[70:73], v[170:173], v[226:229], v[70:73]
	v_mfma_f32_16x16x32_bf16 v[66:69], v[178:181], v[226:229], v[66:69]
	s_barrier
	s_setprio 0
	s_add_i32 s90, s69, s76
	v_lshl_add_u64 v[230:231], s[6:7], 0, v[148:149]
	s_mov_b32 m0, s90
	ds_read_b128 v[182:185], v222 offset:16384
	ds_read_b128 v[186:189], v222 offset:17408
	ds_read_b128 v[190:193], v222 offset:18432
	ds_read_b128 v[194:197], v222 offset:19456
	ds_read_b128 v[198:201], v222 offset:20480
	ds_read_b128 v[202:205], v222 offset:21504
	ds_read_b128 v[206:209], v222 offset:22528
	ds_read_b128 v[226:229], v222 offset:23552
	global_load_lds_dwordx4 v[230:231], off
	s_add_i32 m0, s90, 0x2000
	s_add_u32 s90, s6, 0x40000
	v_lshl_add_u64 v[232:233], s[6:7], 0, v[152:153]
	s_addc_u32 s91, s7, 0
	s_add_i32 s92, s70, s76
	global_load_lds_dwordx4 v[232:233], off
	v_lshl_add_u64 v[234:235], s[90:91], 0, v[148:149]
	s_mov_b32 m0, s92
	v_lshl_add_u64 v[236:237], s[8:9], 0, v[150:151]
	global_load_lds_dwordx4 v[234:235], off
	v_lshl_add_u64 v[234:235], s[90:91], 0, v[152:153]
	s_add_i32 m0, s92, 0x2000
	s_nop 0
	global_load_lds_dwordx4 v[234:235], off
	v_lshl_add_u64 v[234:235], s[8:9], 0, v[146:147]
	s_mov_b32 m0, s77
	s_nop 0
	global_load_lds_dwordx4 v[234:235], off
	s_mov_b32 m0, s87
	s_nop 0
	global_load_lds_dwordx4 v[236:237], off
	s_waitcnt vmcnt(8)
	s_waitcnt lgkmcnt(0)
	s_setprio 3
	s_barrier
; #define PG8_STAGE(bufoff, gbase, voff) do { _Pragma("unroll") for (int _i = 0; _i < 2; ++_i) \
;         __builtin_amdgcn_global_load_lds((const unsigned*)((const char*)(gbase) + (voff)[_i]), (LAS unsigned*)(lds + (bufoff) + ldsw + _i * 8192), 16, 0, 0); } while (0)
; #define PG8_LDA(dst, b, h) do { _Pragma("unroll") for (int m = 0; m < 4; ++m) _Pragma("unroll") for (int k = 0; k < 2; ++k) dst[m][k] = *(const LAS bf16x8*)(lds + PG8_SA(b, h) + aoff + m * 2048 + k * 1024); } while (0)
; #define PG8_LDB(dst, b, h) do { _Pragma("unroll") for (int n = 0; n < 2; ++n) _Pragma("unroll") for (int k = 0; k < 2; ++k) dst[n][k] = *(const LAS bf16x8*)(lds + PG8_SB(b, h) + boff + n * 2048 + k * 1024); } while (0)
; #define PG8_MMA(ai, bj, At, Bt) do { __builtin_amdgcn_s_setprio(3); _Pragma("unroll") for (int m = 0; m < 4; ++m) _Pragma("unroll") for (int n = 0; n < 2; ++n) _Pragma("unroll") for (int k = 0; k < 2; ++k) \
;         acc[ai][bj][m][n] = __builtin_amdgcn_mfma_f32_16x16x32_bf16(Bt[n][k], At[m][k], acc[ai][bj][m][n], 0, 0, 0); __builtin_amdgcn_s_setprio(0); } while (0)
; #define PG8_WAIT_V(n) asm volatile("s_waitcnt vmcnt(" #n ")" ::: "memory")
; #define PG8_WAIT_L(n) asm volatile("s_waitcnt lgkmcnt(" #n ")" ::: "memory")
; #define PG8_BAR __builtin_amdgcn_s_barrier()
; #define PG8_SCHED __builtin_amdgcn_sched_barrier(0)
; template <class Epi, bool ALIGN_EPI>
; __device__ __forceinline__ void gemm_phase(LAS unsigned char* lds, const Gemm g, const StaticOrder& S, const Epi& E) {
;     ...
;             PG8_WAIT_V(8); PG8_WAIT_L(0); PG8_BAR; PG8_MMA(1, 0, At, B0); PG8_MMA(1, 1, At, B1); PG8_BAR; PG8_SCHED;
;             PG8_LDB(B0, 1, 0); PG8_LDB(B1, 1, 1); PG8_SCHED; PG8_LDA(At, 1, 0); PG8_STAGE(PG8_SA(0, 1), a2 + hstep, voffA);
;             PG8_WAIT_V(8); PG8_WAIT_L(0); PG8_BAR; PG8_MMA(0, 0, At, B0); PG8_MMA(0, 1, At, B1); PG8_BAR; PG8_SCHED;
	s_waitcnt lgkmcnt(0)
	v_mfma_f32_16x16x32_bf16 v[62:65], v[130:133], v[182:185], 0
	v_mfma_f32_16x16x32_bf16 v[58:61], v[138:141], v[182:185], 0
	v_mfma_f32_16x16x32_bf16 v[46:49], v[130:133], v[190:193], 0
	v_mfma_f32_16x16x32_bf16 v[42:45], v[138:141], v[190:193], 0
	v_mfma_f32_16x16x32_bf16 v[30:33], v[130:133], v[198:201], 0
	v_mfma_f32_16x16x32_bf16 v[26:29], v[138:141], v[198:201], 0
	v_mfma_f32_16x16x32_bf16 v[14:17], v[130:133], v[206:209], 0
	v_mfma_f32_16x16x32_bf16 v[10:13], v[138:141], v[206:209], 0
	v_mfma_f32_16x16x32_bf16 v[62:65], v[134:137], v[186:189], v[62:65]
	v_mfma_f32_16x16x32_bf16 v[58:61], v[142:145], v[186:189], v[58:61]
	v_mfma_f32_16x16x32_bf16 v[46:49], v[134:137], v[194:197], v[46:49]
	v_mfma_f32_16x16x32_bf16 v[42:45], v[142:145], v[194:197], v[42:45]
	v_mfma_f32_16x16x32_bf16 v[30:33], v[134:137], v[202:205], v[30:33]
	v_mfma_f32_16x16x32_bf16 v[26:29], v[142:145], v[202:205], v[26:29]
	v_mfma_f32_16x16x32_bf16 v[14:17], v[134:137], v[226:229], v[14:17]
	v_mfma_f32_16x16x32_bf16 v[10:13], v[142:145], v[226:229], v[10:13]
	v_mfma_f32_16x16x32_bf16 v[54:57], v[166:169], v[182:185], 0
	v_mfma_f32_16x16x32_bf16 v[50:53], v[174:177], v[182:185], 0
	v_mfma_f32_16x16x32_bf16 v[38:41], v[166:169], v[190:193], 0
	v_mfma_f32_16x16x32_bf16 v[34:37], v[174:177], v[190:193], 0
	v_mfma_f32_16x16x32_bf16 v[22:25], v[166:169], v[198:201], 0
	v_mfma_f32_16x16x32_bf16 v[18:21], v[174:177], v[198:201], 0
	v_mfma_f32_16x16x32_bf16 v[6:9], v[166:169], v[206:209], 0
	v_mfma_f32_16x16x32_bf16 v[2:5], v[174:177], v[206:209], 0
	v_mfma_f32_16x16x32_bf16 v[54:57], v[170:173], v[186:189], v[54:57]
	v_mfma_f32_16x16x32_bf16 v[50:53], v[178:181], v[186:189], v[50:53]
	v_mfma_f32_16x16x32_bf16 v[38:41], v[170:173], v[194:197], v[38:41]
	v_mfma_f32_16x16x32_bf16 v[34:37], v[178:181], v[194:197], v[34:37]
	v_mfma_f32_16x16x32_bf16 v[22:25], v[170:173], v[202:205], v[22:25]
	v_mfma_f32_16x16x32_bf16 v[18:21], v[178:181], v[202:205], v[18:21]
	v_mfma_f32_16x16x32_bf16 v[6:9], v[170:173], v[226:229], v[6:9]
	v_mfma_f32_16x16x32_bf16 v[2:5], v[178:181], v[226:229], v[2:5]
	s_barrier
	s_setprio 0
	s_add_i32 s90, 0, 0x18000
	s_add_i32 s91, 0, 0x1c000
	v_add_u32_e32 v142, s90, v217
	v_add_u32_e32 v154, s91, v217
	ds_read_b128 v[130:133], v142
	ds_read_b128 v[134:137], v142 offset:1024
	ds_read_b128 v[138:141], v142 offset:2048
	ds_read_b128 v[142:145], v142 offset:3072
	ds_read_b128 v[166:169], v154
	ds_read_b128 v[170:173], v154 offset:1024
	ds_read_b128 v[174:177], v154 offset:2048
	ds_read_b128 v[178:181], v154 offset:3072
	s_add_u32 s8, s8, 0x40000
	s_addc_u32 s9, s9, 0
	s_mov_b32 m0, s33
	v_lshl_add_u64 v[238:239], s[8:9], 0, v[146:147]
	ds_read_b128 v[182:185], v222 offset:32768
	ds_read_b128 v[186:189], v222 offset:33792
	ds_read_b128 v[190:193], v222 offset:34816
	ds_read_b128 v[194:197], v222 offset:35840
	ds_read_b128 v[198:201], v222 offset:36864
	ds_read_b128 v[202:205], v222 offset:37888
	ds_read_b128 v[206:209], v222 offset:38912
	ds_read_b128 v[226:229], v222 offset:39936
	global_load_lds_dwordx4 v[238:239], off
	v_lshl_add_u64 v[238:239], s[8:9], 0, v[150:151]
	s_mov_b32 m0, s14
	s_nop 0
	global_load_lds_dwordx4 v[238:239], off
	s_waitcnt vmcnt(8)
	s_waitcnt lgkmcnt(0)
	s_setprio 3
	s_barrier
	s_waitcnt lgkmcnt(0)
	v_mfma_f32_16x16x32_bf16 v[126:129], v[130:133], v[182:185], v[126:129]
	v_mfma_f32_16x16x32_bf16 v[122:125], v[138:141], v[182:185], v[122:125]
	v_mfma_f32_16x16x32_bf16 v[110:113], v[130:133], v[190:193], v[110:113]
	v_mfma_f32_16x16x32_bf16 v[106:109], v[138:141], v[190:193], v[106:109]
	v_mfma_f32_16x16x32_bf16 v[94:97], v[130:133], v[198:201], v[94:97]
	v_mfma_f32_16x16x32_bf16 v[90:93], v[138:141], v[198:201], v[90:93]
	v_mfma_f32_16x16x32_bf16 v[78:81], v[130:133], v[206:209], v[78:81]
	v_mfma_f32_16x16x32_bf16 v[74:77], v[138:141], v[206:209], v[74:77]
	v_mfma_f32_16x16x32_bf16 v[126:129], v[134:137], v[186:189], v[126:129]
	v_mfma_f32_16x16x32_bf16 v[122:125], v[142:145], v[186:189], v[122:125]
	v_mfma_f32_16x16x32_bf16 v[110:113], v[134:137], v[194:197], v[110:113]
	v_mfma_f32_16x16x32_bf16 v[106:109], v[142:145], v[194:197], v[106:109]
	v_mfma_f32_16x16x32_bf16 v[94:97], v[134:137], v[202:205], v[94:97]
	v_mfma_f32_16x16x32_bf16 v[90:93], v[142:145], v[202:205], v[90:93]
	v_mfma_f32_16x16x32_bf16 v[78:81], v[134:137], v[226:229], v[78:81]
	v_mfma_f32_16x16x32_bf16 v[74:77], v[142:145], v[226:229], v[74:77]
	v_mfma_f32_16x16x32_bf16 v[118:121], v[166:169], v[182:185], v[118:121]
	v_mfma_f32_16x16x32_bf16 v[114:117], v[174:177], v[182:185], v[114:117]
	v_mfma_f32_16x16x32_bf16 v[102:105], v[166:169], v[190:193], v[102:105]
	v_mfma_f32_16x16x32_bf16 v[98:101], v[174:177], v[190:193], v[98:101]
	v_mfma_f32_16x16x32_bf16 v[86:89], v[166:169], v[198:201], v[86:89]
	v_mfma_f32_16x16x32_bf16 v[82:85], v[174:177], v[198:201], v[82:85]
	v_mfma_f32_16x16x32_bf16 v[70:73], v[166:169], v[206:209], v[70:73]
	v_mfma_f32_16x16x32_bf16 v[66:69], v[174:177], v[206:209], v[66:69]
	v_mfma_f32_16x16x32_bf16 v[118:121], v[170:173], v[186:189], v[118:121]
	v_mfma_f32_16x16x32_bf16 v[114:117], v[178:181], v[186:189], v[114:117]
	v_mfma_f32_16x16x32_bf16 v[102:105], v[170:173], v[194:197], v[102:105]
	v_mfma_f32_16x16x32_bf16 v[98:101], v[178:181], v[194:197], v[98:101]
	v_mfma_f32_16x16x32_bf16 v[86:89], v[170:173], v[202:205], v[86:89]
	v_mfma_f32_16x16x32_bf16 v[82:85], v[178:181], v[202:205], v[82:85]
	v_mfma_f32_16x16x32_bf16 v[70:73], v[170:173], v[226:229], v[70:73]
	v_mfma_f32_16x16x32_bf16 v[66:69], v[178:181], v[226:229], v[66:69]
	s_barrier
; #define PG8_STAGE(bufoff, gbase, voff) do { _Pragma("unroll") for (int _i = 0; _i < 2; ++_i) \
;         __builtin_amdgcn_global_load_lds((const unsigned*)((const char*)(gbase) + (voff)[_i]), (LAS unsigned*)(lds + (bufoff) + ldsw + _i * 8192), 16, 0, 0); } while (0)
; #define PG8_LDA(dst, b, h) do { _Pragma("unroll") for (int m = 0; m < 4; ++m) _Pragma("unroll") for (int k = 0; k < 2; ++k) dst[m][k] = *(const LAS bf16x8*)(lds + PG8_SA(b, h) + aoff + m * 2048 + k * 1024); } while (0)
; #define PG8_LDB(dst, b, h) do { _Pragma("unroll") for (int n = 0; n < 2; ++n) _Pragma("unroll") for (int k = 0; k < 2; ++k) dst[n][k] = *(const LAS bf16x8*)(lds + PG8_SB(b, h) + boff + n * 2048 + k * 1024); } while (0)
; #define PG8_MMA(ai, bj, At, Bt) do { __builtin_amdgcn_s_setprio(3); _Pragma("unroll") for (int m = 0; m < 4; ++m) _Pragma("unroll") for (int n = 0; n < 2; ++n) _Pragma("unroll") for (int k = 0; k < 2; ++k) \
;         acc[ai][bj][m][n] = __builtin_amdgcn_mfma_f32_16x16x32_bf16(Bt[n][k], At[m][k], acc[ai][bj][m][n], 0, 0, 0); __builtin_amdgcn_s_setprio(0); } while (0)
; #define PG8_WAIT_V(n) asm volatile("s_waitcnt vmcnt(" #n ")" ::: "memory")
; #define PG8_BAR __builtin_amdgcn_s_barrier()
; template <class Epi, bool ALIGN_EPI>
; __device__ __forceinline__ void gemm_phase(LAS unsigned char* lds, const Gemm g, const StaticOrder& S, const Epi& E) {
;     ...
;             PG8_LDB(B0, 0, 0); PG8_LDB(B1, 0, 1); PG8_SCHED; PG8_LDA(At, 0, 0); PG8_STAGE(PG8_SA(1, 1), a1 + hstep, voffA);
;             PG8_WAIT_V(8); PG8_WAIT_L(0); PG8_BAR; PG8_MMA(0, 0, At, B0); PG8_MMA(0, 1, At, B1); PG8_BAR; PG8_SCHED;
;             PG8_LDA(At, 0, 1); PG8_STAGE(PG8_SB(0, 0), b2, voffB); PG8_STAGE(PG8_SB(0, 1), b2 + hstep, voffB); PG8_STAGE(PG8_SA(0, 0), a2, voffA);
;             PG8_WAIT_V(8); PG8_WAIT_L(0); PG8_BAR; PG8_MMA(1, 0, At, B0); PG8_MMA(1, 1, At, B1); PG8_BAR; PG8_SCHED;
;             PG8_LDB(B0, 1, 0); PG8_LDB(B1, 1, 1); PG8_SCHED; PG8_LDA(At, 1, 0); PG8_STAGE(PG8_SA(0, 1), a2 + hstep, voffA);
;             PG8_WAIT_V(8); PG8_WAIT_L(0); PG8_BAR; PG8_MMA(0, 0, At, B0); PG8_MMA(0, 1, At, B1); PG8_BAR; PG8_SCHED;
;             PG8_LDA(At, 1, 1); PG8_STAGE(PG8_SB(1, 0), b3, voffB); PG8_STAGE(PG8_SB(1, 1), b3 + hstep, voffB); PG8_STAGE(PG8_SA(1, 0), a3, voffA);
;             PG8_WAIT_V(8); PG8_WAIT_L(0); PG8_BAR; PG8_MMA(1, 0, At, B0); PG8_MMA(1, 1, At, B1); PG8_BAR; PG8_SCHED;
	s_setprio 0
	s_add_i32 s8, s90, s76
	v_lshl_add_u64 v[230:231], v[230:231], 0, s[60:61]
	s_mov_b32 m0, s8
	ds_read_b128 v[182:185], v222 offset:49152
	ds_read_b128 v[186:189], v222 offset:50176
	ds_read_b128 v[190:193], v222 offset:51200
	ds_read_b128 v[194:197], v222 offset:52224
	ds_read_b128 v[198:201], v222 offset:53248
	ds_read_b128 v[202:205], v222 offset:54272
	ds_read_b128 v[206:209], v222 offset:55296
	ds_read_b128 v[226:229], v222 offset:56320
	global_load_lds_dwordx4 v[230:231], off
	s_add_i32 m0, s8, 0x2000
	s_add_u32 s6, s6, 0x40080
	v_lshl_add_u64 v[230:231], v[232:233], 0, s[60:61]
	s_addc_u32 s7, s7, 0
	s_add_i32 s8, s91, s76
	global_load_lds_dwordx4 v[230:231], off
	v_lshl_add_u64 v[230:231], s[6:7], 0, v[148:149]
	s_mov_b32 m0, s8
	s_nop 0
	global_load_lds_dwordx4 v[230:231], off
	v_lshl_add_u64 v[230:231], s[6:7], 0, v[152:153]
	s_add_i32 m0, s8, 0x2000
	s_nop 0
	global_load_lds_dwordx4 v[230:231], off
	v_lshl_add_u64 v[230:231], v[234:235], 0, s[60:61]
	s_mov_b32 m0, s65
	s_nop 0
	global_load_lds_dwordx4 v[230:231], off
	v_lshl_add_u64 v[230:231], v[236:237], 0, s[60:61]
	s_mov_b32 m0, s66
	s_nop 0
	global_load_lds_dwordx4 v[230:231], off
	s_waitcnt vmcnt(8)
	s_waitcnt lgkmcnt(0)
	s_setprio 3
	s_barrier
	s_waitcnt lgkmcnt(0)
	v_mfma_f32_16x16x32_bf16 v[62:65], v[130:133], v[182:185], v[62:65]
	v_mfma_f32_16x16x32_bf16 v[58:61], v[138:141], v[182:185], v[58:61]
	v_mfma_f32_16x16x32_bf16 v[46:49], v[130:133], v[190:193], v[46:49]
	v_mfma_f32_16x16x32_bf16 v[42:45], v[138:141], v[190:193], v[42:45]
	v_mfma_f32_16x16x32_bf16 v[30:33], v[130:133], v[198:201], v[30:33]
	v_mfma_f32_16x16x32_bf16 v[26:29], v[138:141], v[198:201], v[26:29]
	v_mfma_f32_16x16x32_bf16 v[14:17], v[130:133], v[206:209], v[14:17]
	v_mfma_f32_16x16x32_bf16 v[10:13], v[138:141], v[206:209], v[10:13]
	v_mfma_f32_16x16x32_bf16 v[62:65], v[134:137], v[186:189], v[62:65]
	v_mfma_f32_16x16x32_bf16 v[58:61], v[142:145], v[186:189], v[58:61]
	v_mfma_f32_16x16x32_bf16 v[46:49], v[134:137], v[194:197], v[46:49]
	v_mfma_f32_16x16x32_bf16 v[42:45], v[142:145], v[194:197], v[42:45]
	v_mfma_f32_16x16x32_bf16 v[30:33], v[134:137], v[202:205], v[30:33]
	v_mfma_f32_16x16x32_bf16 v[26:29], v[142:145], v[202:205], v[26:29]
	v_mfma_f32_16x16x32_bf16 v[14:17], v[134:137], v[226:229], v[14:17]
	v_mfma_f32_16x16x32_bf16 v[10:13], v[142:145], v[226:229], v[10:13]
	v_mfma_f32_16x16x32_bf16 v[54:57], v[166:169], v[182:185], v[54:57]
	v_mfma_f32_16x16x32_bf16 v[50:53], v[174:177], v[182:185], v[50:53]
	v_mfma_f32_16x16x32_bf16 v[38:41], v[166:169], v[190:193], v[38:41]
	v_mfma_f32_16x16x32_bf16 v[34:37], v[174:177], v[190:193], v[34:37]
	v_mfma_f32_16x16x32_bf16 v[22:25], v[166:169], v[198:201], v[22:25]
	v_mfma_f32_16x16x32_bf16 v[18:21], v[174:177], v[198:201], v[18:21]
	v_mfma_f32_16x16x32_bf16 v[6:9], v[166:169], v[206:209], v[6:9]
	v_mfma_f32_16x16x32_bf16 v[2:5], v[174:177], v[206:209], v[2:5]
	v_mfma_f32_16x16x32_bf16 v[54:57], v[170:173], v[186:189], v[54:57]
	v_mfma_f32_16x16x32_bf16 v[50:53], v[178:181], v[186:189], v[50:53]
	v_mfma_f32_16x16x32_bf16 v[38:41], v[170:173], v[194:197], v[38:41]
	v_mfma_f32_16x16x32_bf16 v[34:37], v[178:181], v[194:197], v[34:37]
	v_mfma_f32_16x16x32_bf16 v[22:25], v[170:173], v[202:205], v[22:25]
	v_mfma_f32_16x16x32_bf16 v[18:21], v[178:181], v[202:205], v[18:21]
	v_mfma_f32_16x16x32_bf16 v[6:9], v[170:173], v[226:229], v[6:9]
	v_mfma_f32_16x16x32_bf16 v[2:5], v[178:181], v[226:229], v[2:5]
	s_barrier
	s_setprio 0
	s_add_i32 s89, s89, 2
	s_add_u32 s4, s4, 0x100
	s_addc_u32 s5, s5, 0
	s_add_u32 s85, s85, 0x100
	s_addc_u32 s88, s88, 0
.LBB0_787:
	s_waitcnt lgkmcnt(0)
	ds_read_b128 v[130:133], v220
	ds_read_b128 v[134:137], v220 offset:1024
	ds_read_b128 v[138:141], v220 offset:2048
	ds_read_b128 v[142:145], v220 offset:3072
	ds_read_b128 v[166:169], v221
	ds_read_b128 v[170:173], v221 offset:1024
	ds_read_b128 v[174:177], v221 offset:2048
	ds_read_b128 v[178:181], v221 offset:3072
	s_add_u32 s6, s4, 0xfffc0080
	s_addc_u32 s7, s5, -1
	s_cmp_eq_u32 s89, 12
	s_cselect_b32 s9, s50, s7
	s_cselect_b32 s8, s55, s6
	s_cselect_b32 s7, s73, s88
	s_cselect_b32 s6, s79, s85
	v_lshl_add_u64 v[230:231], s[4:5], 0, v[158:159]
	s_add_i32 m0, s77, 0xc000
	ds_read_b128 v[182:185], v222
	ds_read_b128 v[186:189], v222 offset:1024
	ds_read_b128 v[190:193], v222 offset:2048
	ds_read_b128 v[194:197], v222 offset:3072
	ds_read_b128 v[198:201], v222 offset:4096
	ds_read_b128 v[202:205], v222 offset:5120
	ds_read_b128 v[206:209], v222 offset:6144
	ds_read_b128 v[226:229], v222 offset:7168
	global_load_lds_dwordx4 v[230:231], off
	v_lshl_add_u64 v[230:231], s[4:5], 0, v[160:161]
	s_add_i32 m0, s77, 0xe000
	s_nop 0
	global_load_lds_dwordx4 v[230:231], off
	s_waitcnt vmcnt(8)
	s_waitcnt lgkmcnt(0)
	s_setprio 3
	s_barrier
; #define PG8_STAGE(bufoff, gbase, voff) do { _Pragma("unroll") for (int _i = 0; _i < 2; ++_i) \
;         __builtin_amdgcn_global_load_lds((const unsigned*)((const char*)(gbase) + (voff)[_i]), (LAS unsigned*)(lds + (bufoff) + ldsw + _i * 8192), 16, 0, 0); } while (0)
; #define PG8_LDA(dst, b, h) do { _Pragma("unroll") for (int m = 0; m < 4; ++m) _Pragma("unroll") for (int k = 0; k < 2; ++k) dst[m][k] = *(const LAS bf16x8*)(lds + PG8_SA(b, h) + aoff + m * 2048 + k * 1024); } while (0)
; #define PG8_MMA(ai, bj, At, Bt) do { __builtin_amdgcn_s_setprio(3); _Pragma("unroll") for (int m = 0; m < 4; ++m) _Pragma("unroll") for (int n = 0; n < 2; ++n) _Pragma("unroll") for (int k = 0; k < 2; ++k) \
;         acc[ai][bj][m][n] = __builtin_amdgcn_mfma_f32_16x16x32_bf16(Bt[n][k], At[m][k], acc[ai][bj][m][n], 0, 0, 0); __builtin_amdgcn_s_setprio(0); } while (0)
; #define PG8_WAIT_V(n) asm volatile("s_waitcnt vmcnt(" #n ")" ::: "memory")
; #define PG8_WAIT_L(n) asm volatile("s_waitcnt lgkmcnt(" #n ")" ::: "memory")
; #define PG8_BAR __builtin_amdgcn_s_barrier()
; #define PG8_SCHED __builtin_amdgcn_sched_barrier(0)
; template <class Epi, bool ALIGN_EPI>
; __device__ __forceinline__ void gemm_phase(LAS unsigned char* lds, const Gemm g, const StaticOrder& S, const Epi& E) {
;     ...
;             PG8_WAIT_V(8); PG8_WAIT_L(0); PG8_BAR; PG8_MMA(0, 0, At, B0); PG8_MMA(0, 1, At, B1); PG8_BAR; PG8_SCHED;
;             PG8_LDA(At, 0, 1); PG8_STAGE(PG8_SB(0, 0), b2, voffB); PG8_STAGE(PG8_SB(0, 1), b2 + hstep, voffB); PG8_STAGE(PG8_SA(0, 0), a2, voffA);
;             PG8_WAIT_V(8); PG8_WAIT_L(0); PG8_BAR; PG8_MMA(1, 0, At, B0); PG8_MMA(1, 1, At, B1); PG8_BAR; PG8_SCHED;
	s_waitcnt lgkmcnt(0)
	v_mfma_f32_16x16x32_bf16 v[126:129], v[130:133], v[182:185], v[126:129]
	v_mfma_f32_16x16x32_bf16 v[122:125], v[138:141], v[182:185], v[122:125]
	v_mfma_f32_16x16x32_bf16 v[110:113], v[130:133], v[190:193], v[110:113]
	v_mfma_f32_16x16x32_bf16 v[106:109], v[138:141], v[190:193], v[106:109]
	v_mfma_f32_16x16x32_bf16 v[94:97], v[130:133], v[198:201], v[94:97]
	v_mfma_f32_16x16x32_bf16 v[90:93], v[138:141], v[198:201], v[90:93]
	v_mfma_f32_16x16x32_bf16 v[78:81], v[130:133], v[206:209], v[78:81]
	v_mfma_f32_16x16x32_bf16 v[74:77], v[138:141], v[206:209], v[74:77]
	v_mfma_f32_16x16x32_bf16 v[126:129], v[134:137], v[186:189], v[126:129]
	v_mfma_f32_16x16x32_bf16 v[122:125], v[142:145], v[186:189], v[122:125]
	v_mfma_f32_16x16x32_bf16 v[110:113], v[134:137], v[194:197], v[110:113]
	v_mfma_f32_16x16x32_bf16 v[106:109], v[142:145], v[194:197], v[106:109]
	v_mfma_f32_16x16x32_bf16 v[94:97], v[134:137], v[202:205], v[94:97]
	v_mfma_f32_16x16x32_bf16 v[90:93], v[142:145], v[202:205], v[90:93]
	v_mfma_f32_16x16x32_bf16 v[78:81], v[134:137], v[226:229], v[78:81]
	v_mfma_f32_16x16x32_bf16 v[74:77], v[142:145], v[226:229], v[74:77]
	v_mfma_f32_16x16x32_bf16 v[118:121], v[166:169], v[182:185], v[118:121]
	v_mfma_f32_16x16x32_bf16 v[114:117], v[174:177], v[182:185], v[114:117]
	v_mfma_f32_16x16x32_bf16 v[102:105], v[166:169], v[190:193], v[102:105]
	v_mfma_f32_16x16x32_bf16 v[98:101], v[174:177], v[190:193], v[98:101]
	v_mfma_f32_16x16x32_bf16 v[86:89], v[166:169], v[198:201], v[86:89]
	v_mfma_f32_16x16x32_bf16 v[82:85], v[174:177], v[198:201], v[82:85]
	v_mfma_f32_16x16x32_bf16 v[70:73], v[166:169], v[206:209], v[70:73]
	v_mfma_f32_16x16x32_bf16 v[66:69], v[174:177], v[206:209], v[66:69]
	v_mfma_f32_16x16x32_bf16 v[118:121], v[170:173], v[186:189], v[118:121]
	v_mfma_f32_16x16x32_bf16 v[114:117], v[178:181], v[186:189], v[114:117]
	v_mfma_f32_16x16x32_bf16 v[102:105], v[170:173], v[194:197], v[102:105]
	v_mfma_f32_16x16x32_bf16 v[98:101], v[178:181], v[194:197], v[98:101]
	v_mfma_f32_16x16x32_bf16 v[86:89], v[170:173], v[202:205], v[86:89]
	v_mfma_f32_16x16x32_bf16 v[82:85], v[178:181], v[202:205], v[82:85]
	v_mfma_f32_16x16x32_bf16 v[70:73], v[170:173], v[226:229], v[70:73]
	v_mfma_f32_16x16x32_bf16 v[66:69], v[178:181], v[226:229], v[66:69]
	s_barrier
	s_setprio 0
	s_add_i32 s90, s69, s76
	v_lshl_add_u64 v[230:231], s[6:7], 0, v[148:149]
	s_mov_b32 m0, s90
	ds_read_b128 v[182:185], v222 offset:16384
	ds_read_b128 v[186:189], v222 offset:17408
	ds_read_b128 v[190:193], v222 offset:18432
	ds_read_b128 v[194:197], v222 offset:19456
	ds_read_b128 v[198:201], v222 offset:20480
	ds_read_b128 v[202:205], v222 offset:21504
	ds_read_b128 v[206:209], v222 offset:22528
	ds_read_b128 v[226:229], v222 offset:23552
	global_load_lds_dwordx4 v[230:231], off
	s_add_i32 m0, s90, 0x2000
	s_add_u32 s90, s6, 0x40000
	v_lshl_add_u64 v[232:233], s[6:7], 0, v[152:153]
	s_addc_u32 s91, s7, 0
	s_add_i32 s92, s70, s76
	global_load_lds_dwordx4 v[232:233], off
	v_lshl_add_u64 v[234:235], s[90:91], 0, v[148:149]
	s_mov_b32 m0, s92
	v_lshl_add_u64 v[236:237], s[8:9], 0, v[150:151]
	global_load_lds_dwordx4 v[234:235], off
	v_lshl_add_u64 v[234:235], s[90:91], 0, v[152:153]
	s_add_i32 m0, s92, 0x2000
	s_nop 0
	global_load_lds_dwordx4 v[234:235], off
	v_lshl_add_u64 v[234:235], s[8:9], 0, v[146:147]
	s_mov_b32 m0, s77
	s_nop 0
	global_load_lds_dwordx4 v[234:235], off
	s_mov_b32 m0, s87
	s_nop 0
	global_load_lds_dwordx4 v[236:237], off
	s_waitcnt vmcnt(8)
	s_waitcnt lgkmcnt(0)
	s_setprio 3
	s_barrier
	s_waitcnt lgkmcnt(0)
	v_mfma_f32_16x16x32_bf16 v[62:65], v[130:133], v[182:185], v[62:65]
	v_mfma_f32_16x16x32_bf16 v[58:61], v[138:141], v[182:185], v[58:61]
	v_mfma_f32_16x16x32_bf16 v[46:49], v[130:133], v[190:193], v[46:49]
	v_mfma_f32_16x16x32_bf16 v[42:45], v[138:141], v[190:193], v[42:45]
	v_mfma_f32_16x16x32_bf16 v[30:33], v[130:133], v[198:201], v[30:33]
	v_mfma_f32_16x16x32_bf16 v[26:29], v[138:141], v[198:201], v[26:29]
	v_mfma_f32_16x16x32_bf16 v[14:17], v[130:133], v[206:209], v[14:17]
	v_mfma_f32_16x16x32_bf16 v[10:13], v[138:141], v[206:209], v[10:13]
	v_mfma_f32_16x16x32_bf16 v[62:65], v[134:137], v[186:189], v[62:65]
	v_mfma_f32_16x16x32_bf16 v[58:61], v[142:145], v[186:189], v[58:61]
	v_mfma_f32_16x16x32_bf16 v[46:49], v[134:137], v[194:197], v[46:49]
	v_mfma_f32_16x16x32_bf16 v[42:45], v[142:145], v[194:197], v[42:45]
	v_mfma_f32_16x16x32_bf16 v[30:33], v[134:137], v[202:205], v[30:33]
	v_mfma_f32_16x16x32_bf16 v[26:29], v[142:145], v[202:205], v[26:29]
	v_mfma_f32_16x16x32_bf16 v[14:17], v[134:137], v[226:229], v[14:17]
	v_mfma_f32_16x16x32_bf16 v[10:13], v[142:145], v[226:229], v[10:13]
	v_mfma_f32_16x16x32_bf16 v[54:57], v[166:169], v[182:185], v[54:57]
	v_mfma_f32_16x16x32_bf16 v[50:53], v[174:177], v[182:185], v[50:53]
	v_mfma_f32_16x16x32_bf16 v[38:41], v[166:169], v[190:193], v[38:41]
	v_mfma_f32_16x16x32_bf16 v[34:37], v[174:177], v[190:193], v[34:37]
	v_mfma_f32_16x16x32_bf16 v[22:25], v[166:169], v[198:201], v[22:25]
	v_mfma_f32_16x16x32_bf16 v[18:21], v[174:177], v[198:201], v[18:21]
	v_mfma_f32_16x16x32_bf16 v[6:9], v[166:169], v[206:209], v[6:9]
	v_mfma_f32_16x16x32_bf16 v[2:5], v[174:177], v[206:209], v[2:5]
	v_mfma_f32_16x16x32_bf16 v[54:57], v[170:173], v[186:189], v[54:57]
	v_mfma_f32_16x16x32_bf16 v[50:53], v[178:181], v[186:189], v[50:53]
	v_mfma_f32_16x16x32_bf16 v[38:41], v[170:173], v[194:197], v[38:41]
	v_mfma_f32_16x16x32_bf16 v[34:37], v[178:181], v[194:197], v[34:37]
	v_mfma_f32_16x16x32_bf16 v[22:25], v[170:173], v[202:205], v[22:25]
	v_mfma_f32_16x16x32_bf16 v[18:21], v[178:181], v[202:205], v[18:21]
	v_mfma_f32_16x16x32_bf16 v[6:9], v[170:173], v[226:229], v[6:9]
	v_mfma_f32_16x16x32_bf16 v[2:5], v[178:181], v[226:229], v[2:5]
	s_barrier
; #define PG8_STAGE(bufoff, gbase, voff) do { _Pragma("unroll") for (int _i = 0; _i < 2; ++_i) \
;         __builtin_amdgcn_global_load_lds((const unsigned*)((const char*)(gbase) + (voff)[_i]), (LAS unsigned*)(lds + (bufoff) + ldsw + _i * 8192), 16, 0, 0); } while (0)
; #define PG8_LDA(dst, b, h) do { _Pragma("unroll") for (int m = 0; m < 4; ++m) _Pragma("unroll") for (int k = 0; k < 2; ++k) dst[m][k] = *(const LAS bf16x8*)(lds + PG8_SA(b, h) + aoff + m * 2048 + k * 1024); } while (0)
; #define PG8_LDB(dst, b, h) do { _Pragma("unroll") for (int n = 0; n < 2; ++n) _Pragma("unroll") for (int k = 0; k < 2; ++k) dst[n][k] = *(const LAS bf16x8*)(lds + PG8_SB(b, h) + boff + n * 2048 + k * 1024); } while (0)
; #define PG8_MMA(ai, bj, At, Bt) do { __builtin_amdgcn_s_setprio(3); _Pragma("unroll") for (int m = 0; m < 4; ++m) _Pragma("unroll") for (int n = 0; n < 2; ++n) _Pragma("unroll") for (int k = 0; k < 2; ++k) \
;         acc[ai][bj][m][n] = __builtin_amdgcn_mfma_f32_16x16x32_bf16(Bt[n][k], At[m][k], acc[ai][bj][m][n], 0, 0, 0); __builtin_amdgcn_s_setprio(0); } while (0)
; #define PG8_WAIT_V(n) asm volatile("s_waitcnt vmcnt(" #n ")" ::: "memory")
; #define PG8_WAIT_L(n) asm volatile("s_waitcnt lgkmcnt(" #n ")" ::: "memory")
; #define PG8_BAR __builtin_amdgcn_s_barrier()
; #define PG8_SCHED __builtin_amdgcn_sched_barrier(0)
; template <class Epi, bool ALIGN_EPI>
; __device__ __forceinline__ void gemm_phase(LAS unsigned char* lds, const Gemm g, const StaticOrder& S, const Epi& E) {
;     ...
;             PG8_LDB(B0, 1, 0); PG8_LDB(B1, 1, 1); PG8_SCHED; PG8_LDA(At, 1, 0); PG8_STAGE(PG8_SA(0, 1), a2 + hstep, voffA);
;             PG8_WAIT_V(8); PG8_WAIT_L(0); PG8_BAR; PG8_MMA(0, 0, At, B0); PG8_MMA(0, 1, At, B1); PG8_BAR; PG8_SCHED;
	s_setprio 0
	s_add_i32 s90, 0, 0x18000
	s_add_i32 s91, 0, 0x1c000
	v_add_u32_e32 v142, s90, v217
	v_add_u32_e32 v154, s91, v217
	ds_read_b128 v[130:133], v142
	ds_read_b128 v[134:137], v142 offset:1024
	ds_read_b128 v[138:141], v142 offset:2048
	ds_read_b128 v[142:145], v142 offset:3072
	ds_read_b128 v[166:169], v154
	ds_read_b128 v[170:173], v154 offset:1024
	ds_read_b128 v[174:177], v154 offset:2048
	ds_read_b128 v[178:181], v154 offset:3072
	s_add_u32 s8, s8, 0x40000
	s_addc_u32 s9, s9, 0
	s_mov_b32 m0, s33
	v_lshl_add_u64 v[238:239], s[8:9], 0, v[146:147]
	ds_read_b128 v[182:185], v222 offset:32768
	ds_read_b128 v[186:189], v222 offset:33792
	ds_read_b128 v[190:193], v222 offset:34816
	ds_read_b128 v[194:197], v222 offset:35840
	ds_read_b128 v[198:201], v222 offset:36864
	ds_read_b128 v[202:205], v222 offset:37888
	ds_read_b128 v[206:209], v222 offset:38912
	ds_read_b128 v[226:229], v222 offset:39936
	global_load_lds_dwordx4 v[238:239], off
	v_lshl_add_u64 v[238:239], s[8:9], 0, v[150:151]
	s_mov_b32 m0, s14
	s_nop 0
	global_load_lds_dwordx4 v[238:239], off
	s_waitcnt vmcnt(8)
	s_waitcnt lgkmcnt(0)
	s_setprio 3
	s_barrier
	s_waitcnt lgkmcnt(0)
	v_mfma_f32_16x16x32_bf16 v[126:129], v[130:133], v[182:185], v[126:129]
	v_mfma_f32_16x16x32_bf16 v[122:125], v[138:141], v[182:185], v[122:125]
	v_mfma_f32_16x16x32_bf16 v[110:113], v[130:133], v[190:193], v[110:113]
	v_mfma_f32_16x16x32_bf16 v[106:109], v[138:141], v[190:193], v[106:109]
	v_mfma_f32_16x16x32_bf16 v[94:97], v[130:133], v[198:201], v[94:97]
	v_mfma_f32_16x16x32_bf16 v[90:93], v[138:141], v[198:201], v[90:93]
	v_mfma_f32_16x16x32_bf16 v[78:81], v[130:133], v[206:209], v[78:81]
	v_mfma_f32_16x16x32_bf16 v[74:77], v[138:141], v[206:209], v[74:77]
	v_mfma_f32_16x16x32_bf16 v[126:129], v[134:137], v[186:189], v[126:129]
	v_mfma_f32_16x16x32_bf16 v[122:125], v[142:145], v[186:189], v[122:125]
	v_mfma_f32_16x16x32_bf16 v[110:113], v[134:137], v[194:197], v[110:113]
	v_mfma_f32_16x16x32_bf16 v[106:109], v[142:145], v[194:197], v[106:109]
	v_mfma_f32_16x16x32_bf16 v[94:97], v[134:137], v[202:205], v[94:97]
	v_mfma_f32_16x16x32_bf16 v[90:93], v[142:145], v[202:205], v[90:93]
	v_mfma_f32_16x16x32_bf16 v[78:81], v[134:137], v[226:229], v[78:81]
	v_mfma_f32_16x16x32_bf16 v[74:77], v[142:145], v[226:229], v[74:77]
	v_mfma_f32_16x16x32_bf16 v[118:121], v[166:169], v[182:185], v[118:121]
	v_mfma_f32_16x16x32_bf16 v[114:117], v[174:177], v[182:185], v[114:117]
	v_mfma_f32_16x16x32_bf16 v[102:105], v[166:169], v[190:193], v[102:105]
	v_mfma_f32_16x16x32_bf16 v[98:101], v[174:177], v[190:193], v[98:101]
	v_mfma_f32_16x16x32_bf16 v[86:89], v[166:169], v[198:201], v[86:89]
	v_mfma_f32_16x16x32_bf16 v[82:85], v[174:177], v[198:201], v[82:85]
	v_mfma_f32_16x16x32_bf16 v[70:73], v[166:169], v[206:209], v[70:73]
	v_mfma_f32_16x16x32_bf16 v[66:69], v[174:177], v[206:209], v[66:69]
	v_mfma_f32_16x16x32_bf16 v[118:121], v[170:173], v[186:189], v[118:121]
	v_mfma_f32_16x16x32_bf16 v[114:117], v[178:181], v[186:189], v[114:117]
	v_mfma_f32_16x16x32_bf16 v[102:105], v[170:173], v[194:197], v[102:105]
	v_mfma_f32_16x16x32_bf16 v[98:101], v[178:181], v[194:197], v[98:101]
	v_mfma_f32_16x16x32_bf16 v[86:89], v[170:173], v[202:205], v[86:89]
	v_mfma_f32_16x16x32_bf16 v[82:85], v[178:181], v[202:205], v[82:85]
	v_mfma_f32_16x16x32_bf16 v[70:73], v[170:173], v[226:229], v[70:73]
	v_mfma_f32_16x16x32_bf16 v[66:69], v[178:181], v[226:229], v[66:69]
	s_barrier
; #define PG8_STAGE(bufoff, gbase, voff) do { _Pragma("unroll") for (int _i = 0; _i < 2; ++_i) \
;         __builtin_amdgcn_global_load_lds((const unsigned*)((const char*)(gbase) + (voff)[_i]), (LAS unsigned*)(lds + (bufoff) + ldsw + _i * 8192), 16, 0, 0); } while (0)
; #define PG8_LDA(dst, b, h) do { _Pragma("unroll") for (int m = 0; m < 4; ++m) _Pragma("unroll") for (int k = 0; k < 2; ++k) dst[m][k] = *(const LAS bf16x8*)(lds + PG8_SA(b, h) + aoff + m * 2048 + k * 1024); } while (0)
; #define PG8_MMA(ai, bj, At, Bt) do { __builtin_amdgcn_s_setprio(3); _Pragma("unroll") for (int m = 0; m < 4; ++m) _Pragma("unroll") for (int n = 0; n < 2; ++n) _Pragma("unroll") for (int k = 0; k < 2; ++k) \
;         acc[ai][bj][m][n] = __builtin_amdgcn_mfma_f32_16x16x32_bf16(Bt[n][k], At[m][k], acc[ai][bj][m][n], 0, 0, 0); __builtin_amdgcn_s_setprio(0); } while (0)
; #define PG8_WAIT_V(n) asm volatile("s_waitcnt vmcnt(" #n ")" ::: "memory")
; #define PG8_WAIT_L(n) asm volatile("s_waitcnt lgkmcnt(" #n ")" ::: "memory")
; #define PG8_BAR __builtin_amdgcn_s_barrier()
; #define PG8_SCHED __builtin_amdgcn_sched_barrier(0)
; template <class Epi, bool ALIGN_EPI>
; __device__ __forceinline__ void gemm_phase(LAS unsigned char* lds, const Gemm g, const StaticOrder& S, const Epi& E) {
;     ...
;             PG8_LDA(At, 1, 1); PG8_STAGE(PG8_SB(1, 0), b3, voffB); PG8_STAGE(PG8_SB(1, 1), b3 + hstep, voffB); PG8_STAGE(PG8_SA(1, 0), a3, voffA);
;             PG8_WAIT_V(8); PG8_WAIT_L(0); PG8_BAR; PG8_MMA(1, 0, At, B0); PG8_MMA(1, 1, At, B1); PG8_BAR; PG8_SCHED;
;         }
;         if constexpr (ALIGN_EPI) { if (wr == 0) PG8_BAR; }
	s_setprio 0
	s_add_i32 s8, s90, s76
	v_lshl_add_u64 v[230:231], v[230:231], 0, s[60:61]
	s_mov_b32 m0, s8
	ds_read_b128 v[182:185], v222 offset:49152
	ds_read_b128 v[186:189], v222 offset:50176
	ds_read_b128 v[190:193], v222 offset:51200
	ds_read_b128 v[194:197], v222 offset:52224
	ds_read_b128 v[198:201], v222 offset:53248
	ds_read_b128 v[202:205], v222 offset:54272
	ds_read_b128 v[206:209], v222 offset:55296
	ds_read_b128 v[226:229], v222 offset:56320
	global_load_lds_dwordx4 v[230:231], off
	s_add_i32 m0, s8, 0x2000
	s_add_u32 s6, s6, 0x40080
	v_lshl_add_u64 v[230:231], v[232:233], 0, s[60:61]
	s_addc_u32 s7, s7, 0
	s_add_i32 s8, s91, s76
	global_load_lds_dwordx4 v[230:231], off
	v_lshl_add_u64 v[230:231], s[6:7], 0, v[148:149]
	s_mov_b32 m0, s8
	s_nop 0
	global_load_lds_dwordx4 v[230:231], off
	v_lshl_add_u64 v[230:231], s[6:7], 0, v[152:153]
	s_add_i32 m0, s8, 0x2000
	s_nop 0
	global_load_lds_dwordx4 v[230:231], off
	v_lshl_add_u64 v[230:231], v[234:235], 0, s[60:61]
	s_mov_b32 m0, s65
	s_nop 0
	global_load_lds_dwordx4 v[230:231], off
	v_lshl_add_u64 v[230:231], v[236:237], 0, s[60:61]
	s_mov_b32 m0, s66
	s_nop 0
	global_load_lds_dwordx4 v[230:231], off
	s_waitcnt vmcnt(8)
	s_waitcnt lgkmcnt(0)
	s_setprio 3
	s_barrier
	s_waitcnt lgkmcnt(0)
	v_mfma_f32_16x16x32_bf16 v[62:65], v[130:133], v[182:185], v[62:65]
	v_mfma_f32_16x16x32_bf16 v[58:61], v[138:141], v[182:185], v[58:61]
	v_mfma_f32_16x16x32_bf16 v[46:49], v[130:133], v[190:193], v[46:49]
	v_mfma_f32_16x16x32_bf16 v[42:45], v[138:141], v[190:193], v[42:45]
	v_mfma_f32_16x16x32_bf16 v[30:33], v[130:133], v[198:201], v[30:33]
	v_mfma_f32_16x16x32_bf16 v[26:29], v[138:141], v[198:201], v[26:29]
	v_mfma_f32_16x16x32_bf16 v[14:17], v[130:133], v[206:209], v[14:17]
	v_mfma_f32_16x16x32_bf16 v[10:13], v[138:141], v[206:209], v[10:13]
	v_mfma_f32_16x16x32_bf16 v[62:65], v[134:137], v[186:189], v[62:65]
	v_mfma_f32_16x16x32_bf16 v[58:61], v[142:145], v[186:189], v[58:61]
	v_mfma_f32_16x16x32_bf16 v[46:49], v[134:137], v[194:197], v[46:49]
	v_mfma_f32_16x16x32_bf16 v[42:45], v[142:145], v[194:197], v[42:45]
	v_mfma_f32_16x16x32_bf16 v[30:33], v[134:137], v[202:205], v[30:33]
	v_mfma_f32_16x16x32_bf16 v[26:29], v[142:145], v[202:205], v[26:29]
	v_mfma_f32_16x16x32_bf16 v[14:17], v[134:137], v[226:229], v[14:17]
	v_mfma_f32_16x16x32_bf16 v[10:13], v[142:145], v[226:229], v[10:13]
	v_mfma_f32_16x16x32_bf16 v[54:57], v[166:169], v[182:185], v[54:57]
	v_mfma_f32_16x16x32_bf16 v[50:53], v[174:177], v[182:185], v[50:53]
	v_mfma_f32_16x16x32_bf16 v[38:41], v[166:169], v[190:193], v[38:41]
	v_mfma_f32_16x16x32_bf16 v[34:37], v[174:177], v[190:193], v[34:37]
	v_mfma_f32_16x16x32_bf16 v[22:25], v[166:169], v[198:201], v[22:25]
	v_mfma_f32_16x16x32_bf16 v[18:21], v[174:177], v[198:201], v[18:21]
	v_mfma_f32_16x16x32_bf16 v[6:9], v[166:169], v[206:209], v[6:9]
	v_mfma_f32_16x16x32_bf16 v[2:5], v[174:177], v[206:209], v[2:5]
	v_mfma_f32_16x16x32_bf16 v[54:57], v[170:173], v[186:189], v[54:57]
	v_mfma_f32_16x16x32_bf16 v[50:53], v[178:181], v[186:189], v[50:53]
	v_mfma_f32_16x16x32_bf16 v[38:41], v[170:173], v[194:197], v[38:41]
	v_mfma_f32_16x16x32_bf16 v[34:37], v[178:181], v[194:197], v[34:37]
	v_mfma_f32_16x16x32_bf16 v[22:25], v[170:173], v[202:205], v[22:25]
	v_mfma_f32_16x16x32_bf16 v[18:21], v[178:181], v[202:205], v[18:21]
	v_mfma_f32_16x16x32_bf16 v[6:9], v[170:173], v[226:229], v[6:9]
	v_mfma_f32_16x16x32_bf16 v[2:5], v[178:181], v[226:229], v[2:5]
	s_barrier
	s_setprio 0
	s_add_i32 s89, s89, 2
	s_add_u32 s4, s4, 0x100
	s_addc_u32 s5, s5, 0
	s_add_u32 s85, s85, 0x100
	s_addc_u32 s88, s88, 0
	s_cmp_gt_u32 s89, 13
	s_cbranch_scc0 .LBB0_787
	s_and_b64 vcc, exec, s[62:63]
	s_cbranch_vccz .LBB0_790
	s_barrier

; #define PG8_STAGE(bufoff, gbase, voff) do { _Pragma("unroll") for (int _i = 0; _i < 2; ++_i) \
;         __builtin_amdgcn_global_load_lds((const unsigned*)((const char*)(gbase) + (voff)[_i]), (LAS unsigned*)(lds + (bufoff) + ldsw + _i * 8192), 16, 0, 0); } while (0)
; #define PG8_LDA(dst, b, h) do { _Pragma("unroll") for (int m = 0; m < 4; ++m) _Pragma("unroll") for (int k = 0; k < 2; ++k) dst[m][k] = *(const LAS bf16x8*)(lds + PG8_SA(b, h) + aoff + m * 2048 + k * 1024); } while (0)
; #define PG8_LDB(dst, b, h) do { _Pragma("unroll") for (int n = 0; n < 2; ++n) _Pragma("unroll") for (int k = 0; k < 2; ++k) dst[n][k] = *(const LAS bf16x8*)(lds + PG8_SB(b, h) + boff + n * 2048 + k * 1024); } while (0)
; #define PG8_MMA(ai, bj, At, Bt) do { __builtin_amdgcn_s_setprio(3); _Pragma("unroll") for (int m = 0; m < 4; ++m) _Pragma("unroll") for (int n = 0; n < 2; ++n) _Pragma("unroll") for (int k = 0; k < 2; ++k) \
;         acc[ai][bj][m][n] = __builtin_amdgcn_mfma_f32_16x16x32_bf16(Bt[n][k], At[m][k], acc[ai][bj][m][n], 0, 0, 0); __builtin_amdgcn_s_setprio(0); } while (0)
; #define PG8_WAIT_V(n) asm volatile("s_waitcnt vmcnt(" #n ")" ::: "memory")
; #define PG8_WAIT_L(n) asm volatile("s_waitcnt lgkmcnt(" #n ")" ::: "memory")
; template <class Epi, bool ALIGN_EPI>
; __device__ __forceinline__ void gemm_phase(LAS unsigned char* lds, const Gemm g, const StaticOrder& S, const Epi& E) {
;     ...
;         const bool has_next = S.next(ui + 1, nxt);
;         const char* nA = has_next ? (const char*)g.A + (size_t)nxt.pm * tstep : cA; const char* nB = has_next ? (const char*)g.Bt + (size_t)nxt.pn * tstep : cB;
;         for (int t = 0; t < nt; t += 2) {
;             const bool last = (t == nt - 2);
;             const char* a1 = cA + (size_t)(t + 1) * kstep;
;             const char* a2 = last ? nA : cA + (size_t)(t + 2) * kstep; const char* b2 = last ? nB : cB + (size_t)(t + 2) * kstep;
;             const char* a3 = a2 + kstep; const char* b3 = b2 + kstep;
;             PG8_LDB(B0, 0, 0); PG8_LDB(B1, 0, 1); PG8_SCHED; PG8_LDA(At, 0, 0); PG8_STAGE(PG8_SA(1, 1), a1 + hstep, voffA);
;             PG8_WAIT_V(8); PG8_WAIT_L(0); PG8_BAR; PG8_MMA(0, 0, At, B0); PG8_MMA(0, 1, At, B1); PG8_BAR; PG8_SCHED;
;             PG8_LDA(At, 0, 1); PG8_STAGE(PG8_SB(0, 0), b2, voffB); PG8_STAGE(PG8_SB(0, 1), b2 + hstep, voffB); PG8_STAGE(PG8_SA(0, 0), a2, voffA);
.LBB0_1338:
	s_ashr_i32 s19, s18, 31
	s_lshl_b64 s[20:21], s[18:19], 19
	s_add_u32 s20, s26, s20
	s_addc_u32 s21, s27, s21
	s_and_b64 s[22:23], s[4:5], exec
	s_cselect_b32 s19, s21, s41
	s_cselect_b32 s37, s20, s40
	s_ashr_i32 s17, s16, 31
	s_lshl_b64 s[22:23], s[16:17], 19
	s_add_u32 s22, s33, s22
	s_addc_u32 s23, s46, s23
	s_and_b64 s[44:45], s[4:5], exec
	s_cselect_b32 s17, s23, s43
	s_cselect_b32 s58, s22, s42
	s_add_u32 s40, s40, 0x40080
	s_addc_u32 s41, s41, 0
	s_add_u32 s59, s42, 0x100
	s_addc_u32 s60, s43, 0
	s_mov_b32 s61, -2
	s_waitcnt lgkmcnt(0)
	ds_read_b128 v[130:133], v196
	ds_read_b128 v[134:137], v196 offset:1024
	ds_read_b128 v[138:141], v196 offset:2048
	ds_read_b128 v[142:145], v196 offset:3072
	ds_read_b128 v[146:149], v197
	ds_read_b128 v[150:153], v197 offset:1024
	ds_read_b128 v[170:173], v197 offset:2048
	ds_read_b128 v[174:177], v197 offset:3072
	s_add_u32 s42, s40, 0xfffc0080
	s_addc_u32 s43, s41, -1
	s_cmp_eq_u32 s61, 12
	s_cselect_b32 s45, s19, s43
	s_cselect_b32 s44, s37, s42
	s_cselect_b32 s43, s17, s60
	s_cselect_b32 s42, s58, s59
	v_lshl_add_u64 v[186:187], s[40:41], 0, v[162:163]
	s_add_i32 m0, s39, 0xc000
	ds_read_b128 v[178:181], v198
	ds_read_b128 v[182:185], v198 offset:1024
	ds_read_b128 v[200:203], v198 offset:2048
	ds_read_b128 v[204:207], v198 offset:3072
	ds_read_b128 v[208:211], v198 offset:4096
	ds_read_b128 v[212:215], v198 offset:5120
	ds_read_b128 v[216:219], v198 offset:6144
	ds_read_b128 v[220:223], v198 offset:7168
	global_load_lds_dwordx4 v[186:187], off
	v_lshl_add_u64 v[186:187], s[40:41], 0, v[164:165]
	s_add_i32 m0, s39, 0xe000
	s_nop 0
	global_load_lds_dwordx4 v[186:187], off
	s_waitcnt vmcnt(8)
	s_waitcnt lgkmcnt(0)
	s_setprio 3
	s_barrier
	s_waitcnt lgkmcnt(0)
	v_mfma_f32_16x16x32_bf16 v[126:129], v[130:133], v[178:181], 0
	v_mfma_f32_16x16x32_bf16 v[122:125], v[138:141], v[178:181], 0
	v_mfma_f32_16x16x32_bf16 v[110:113], v[130:133], v[200:203], 0
	v_mfma_f32_16x16x32_bf16 v[106:109], v[138:141], v[200:203], 0
	v_mfma_f32_16x16x32_bf16 v[94:97], v[130:133], v[208:211], 0
	v_mfma_f32_16x16x32_bf16 v[90:93], v[138:141], v[208:211], 0
	v_mfma_f32_16x16x32_bf16 v[78:81], v[130:133], v[216:219], 0
	v_mfma_f32_16x16x32_bf16 v[74:77], v[138:141], v[216:219], 0
	v_mfma_f32_16x16x32_bf16 v[126:129], v[134:137], v[182:185], v[126:129]
	v_mfma_f32_16x16x32_bf16 v[122:125], v[142:145], v[182:185], v[122:125]
	v_mfma_f32_16x16x32_bf16 v[110:113], v[134:137], v[204:207], v[110:113]
	v_mfma_f32_16x16x32_bf16 v[106:109], v[142:145], v[204:207], v[106:109]
	v_mfma_f32_16x16x32_bf16 v[94:97], v[134:137], v[212:215], v[94:97]
	v_mfma_f32_16x16x32_bf16 v[90:93], v[142:145], v[212:215], v[90:93]
	v_mfma_f32_16x16x32_bf16 v[78:81], v[134:137], v[220:223], v[78:81]
	v_mfma_f32_16x16x32_bf16 v[74:77], v[142:145], v[220:223], v[74:77]
	v_mfma_f32_16x16x32_bf16 v[118:121], v[146:149], v[178:181], 0
	v_mfma_f32_16x16x32_bf16 v[114:117], v[170:173], v[178:181], 0
	v_mfma_f32_16x16x32_bf16 v[102:105], v[146:149], v[200:203], 0
	v_mfma_f32_16x16x32_bf16 v[98:101], v[170:173], v[200:203], 0
	v_mfma_f32_16x16x32_bf16 v[86:89], v[146:149], v[208:211], 0
	v_mfma_f32_16x16x32_bf16 v[82:85], v[170:173], v[208:211], 0
	v_mfma_f32_16x16x32_bf16 v[70:73], v[146:149], v[216:219], 0
	v_mfma_f32_16x16x32_bf16 v[66:69], v[170:173], v[216:219], 0
	v_mfma_f32_16x16x32_bf16 v[118:121], v[150:153], v[182:185], v[118:121]
	v_mfma_f32_16x16x32_bf16 v[114:117], v[174:177], v[182:185], v[114:117]
	v_mfma_f32_16x16x32_bf16 v[102:105], v[150:153], v[204:207], v[102:105]
	v_mfma_f32_16x16x32_bf16 v[98:101], v[174:177], v[204:207], v[98:101]
	v_mfma_f32_16x16x32_bf16 v[86:89], v[150:153], v[212:215], v[86:89]
	v_mfma_f32_16x16x32_bf16 v[82:85], v[174:177], v[212:215], v[82:85]
	v_mfma_f32_16x16x32_bf16 v[70:73], v[150:153], v[220:223], v[70:73]
	v_mfma_f32_16x16x32_bf16 v[66:69], v[174:177], v[220:223], v[66:69]
	s_barrier
	s_setprio 0
	s_add_i32 s62, s56, s47
	v_lshl_add_u64 v[186:187], s[42:43], 0, v[156:157]
	s_mov_b32 m0, s62
	ds_read_b128 v[178:181], v198 offset:16384
	ds_read_b128 v[182:185], v198 offset:17408
	ds_read_b128 v[200:203], v198 offset:18432
	ds_read_b128 v[204:207], v198 offset:19456
	ds_read_b128 v[208:211], v198 offset:20480
	ds_read_b128 v[212:215], v198 offset:21504
	ds_read_b128 v[216:219], v198 offset:22528
	ds_read_b128 v[220:223], v198 offset:23552
	global_load_lds_dwordx4 v[186:187], off
	s_add_i32 m0, s62, 0x2000
	s_add_u32 s62, s42, 0x40000
	v_lshl_add_u64 v[224:225], s[42:43], 0, v[160:161]
	s_addc_u32 s63, s43, 0
	s_add_i32 s64, s57, s47
	global_load_lds_dwordx4 v[224:225], off
	v_lshl_add_u64 v[226:227], s[62:63], 0, v[156:157]
	s_mov_b32 m0, s64
	v_lshl_add_u64 v[228:229], s[44:45], 0, v[158:159]
	global_load_lds_dwordx4 v[226:227], off
	v_lshl_add_u64 v[226:227], s[62:63], 0, v[160:161]
	s_add_i32 m0, s64, 0x2000
	s_nop 0
	global_load_lds_dwordx4 v[226:227], off
	v_lshl_add_u64 v[226:227], s[44:45], 0, v[154:155]
	s_mov_b32 m0, s39
	s_nop 0
	global_load_lds_dwordx4 v[226:227], off
	s_mov_b32 m0, s48
	s_nop 0
	global_load_lds_dwordx4 v[228:229], off
	s_waitcnt vmcnt(8)
	s_waitcnt lgkmcnt(0)
	s_setprio 3
	s_barrier
; #define PG8_STAGE(bufoff, gbase, voff) do { _Pragma("unroll") for (int _i = 0; _i < 2; ++_i) \
;         __builtin_amdgcn_global_load_lds((const unsigned*)((const char*)(gbase) + (voff)[_i]), (LAS unsigned*)(lds + (bufoff) + ldsw + _i * 8192), 16, 0, 0); } while (0)
; #define PG8_LDA(dst, b, h) do { _Pragma("unroll") for (int m = 0; m < 4; ++m) _Pragma("unroll") for (int k = 0; k < 2; ++k) dst[m][k] = *(const LAS bf16x8*)(lds + PG8_SA(b, h) + aoff + m * 2048 + k * 1024); } while (0)
; #define PG8_LDB(dst, b, h) do { _Pragma("unroll") for (int n = 0; n < 2; ++n) _Pragma("unroll") for (int k = 0; k < 2; ++k) dst[n][k] = *(const LAS bf16x8*)(lds + PG8_SB(b, h) + boff + n * 2048 + k * 1024); } while (0)
; #define PG8_MMA(ai, bj, At, Bt) do { __builtin_amdgcn_s_setprio(3); _Pragma("unroll") for (int m = 0; m < 4; ++m) _Pragma("unroll") for (int n = 0; n < 2; ++n) _Pragma("unroll") for (int k = 0; k < 2; ++k) \
;         acc[ai][bj][m][n] = __builtin_amdgcn_mfma_f32_16x16x32_bf16(Bt[n][k], At[m][k], acc[ai][bj][m][n], 0, 0, 0); __builtin_amdgcn_s_setprio(0); } while (0)
; #define PG8_WAIT_V(n) asm volatile("s_waitcnt vmcnt(" #n ")" ::: "memory")
; #define PG8_WAIT_L(n) asm volatile("s_waitcnt lgkmcnt(" #n ")" ::: "memory")
; #define PG8_BAR __builtin_amdgcn_s_barrier()
; #define PG8_SCHED __builtin_amdgcn_sched_barrier(0)
; template <class Epi, bool ALIGN_EPI>
; __device__ __forceinline__ void gemm_phase(LAS unsigned char* lds, const Gemm g, const StaticOrder& S, const Epi& E) {
;     ...
;             PG8_WAIT_V(8); PG8_WAIT_L(0); PG8_BAR; PG8_MMA(1, 0, At, B0); PG8_MMA(1, 1, At, B1); PG8_BAR; PG8_SCHED;
;             PG8_LDB(B0, 1, 0); PG8_LDB(B1, 1, 1); PG8_SCHED; PG8_LDA(At, 1, 0); PG8_STAGE(PG8_SA(0, 1), a2 + hstep, voffA);
;             PG8_WAIT_V(8); PG8_WAIT_L(0); PG8_BAR; PG8_MMA(0, 0, At, B0); PG8_MMA(0, 1, At, B1); PG8_BAR; PG8_SCHED;
	s_waitcnt lgkmcnt(0)
	v_mfma_f32_16x16x32_bf16 v[62:65], v[130:133], v[178:181], 0
	v_mfma_f32_16x16x32_bf16 v[58:61], v[138:141], v[178:181], 0
	v_mfma_f32_16x16x32_bf16 v[46:49], v[130:133], v[200:203], 0
	v_mfma_f32_16x16x32_bf16 v[42:45], v[138:141], v[200:203], 0
	v_mfma_f32_16x16x32_bf16 v[30:33], v[130:133], v[208:211], 0
	v_mfma_f32_16x16x32_bf16 v[26:29], v[138:141], v[208:211], 0
	v_mfma_f32_16x16x32_bf16 v[14:17], v[130:133], v[216:219], 0
	v_mfma_f32_16x16x32_bf16 v[10:13], v[138:141], v[216:219], 0
	v_mfma_f32_16x16x32_bf16 v[62:65], v[134:137], v[182:185], v[62:65]
	v_mfma_f32_16x16x32_bf16 v[58:61], v[142:145], v[182:185], v[58:61]
	v_mfma_f32_16x16x32_bf16 v[46:49], v[134:137], v[204:207], v[46:49]
	v_mfma_f32_16x16x32_bf16 v[42:45], v[142:145], v[204:207], v[42:45]
	v_mfma_f32_16x16x32_bf16 v[30:33], v[134:137], v[212:215], v[30:33]
	v_mfma_f32_16x16x32_bf16 v[26:29], v[142:145], v[212:215], v[26:29]
	v_mfma_f32_16x16x32_bf16 v[14:17], v[134:137], v[220:223], v[14:17]
	v_mfma_f32_16x16x32_bf16 v[10:13], v[142:145], v[220:223], v[10:13]
	v_mfma_f32_16x16x32_bf16 v[54:57], v[146:149], v[178:181], 0
	v_mfma_f32_16x16x32_bf16 v[50:53], v[170:173], v[178:181], 0
	v_mfma_f32_16x16x32_bf16 v[38:41], v[146:149], v[200:203], 0
	v_mfma_f32_16x16x32_bf16 v[34:37], v[170:173], v[200:203], 0
	v_mfma_f32_16x16x32_bf16 v[22:25], v[146:149], v[208:211], 0
	v_mfma_f32_16x16x32_bf16 v[18:21], v[170:173], v[208:211], 0
	v_mfma_f32_16x16x32_bf16 v[6:9], v[146:149], v[216:219], 0
	v_mfma_f32_16x16x32_bf16 v[2:5], v[170:173], v[216:219], 0
	v_mfma_f32_16x16x32_bf16 v[54:57], v[150:153], v[182:185], v[54:57]
	v_mfma_f32_16x16x32_bf16 v[50:53], v[174:177], v[182:185], v[50:53]
	v_mfma_f32_16x16x32_bf16 v[38:41], v[150:153], v[204:207], v[38:41]
	v_mfma_f32_16x16x32_bf16 v[34:37], v[174:177], v[204:207], v[34:37]
	v_mfma_f32_16x16x32_bf16 v[22:25], v[150:153], v[212:215], v[22:25]
	v_mfma_f32_16x16x32_bf16 v[18:21], v[174:177], v[212:215], v[18:21]
	v_mfma_f32_16x16x32_bf16 v[6:9], v[150:153], v[220:223], v[6:9]
	v_mfma_f32_16x16x32_bf16 v[2:5], v[174:177], v[220:223], v[2:5]
	s_barrier
	s_setprio 0
	s_add_i32 s62, 0, 0x18000
	s_add_i32 s63, 0, 0x1c000
	v_add_u32_e32 v142, s62, v194
	v_add_u32_e32 v174, s63, v194
	ds_read_b128 v[130:133], v142
	ds_read_b128 v[134:137], v142 offset:1024
	ds_read_b128 v[138:141], v142 offset:2048
	ds_read_b128 v[142:145], v142 offset:3072
	ds_read_b128 v[146:149], v174
	ds_read_b128 v[150:153], v174 offset:1024
	ds_read_b128 v[170:173], v174 offset:2048
	ds_read_b128 v[174:177], v174 offset:3072
	s_add_u32 s44, s44, 0x40000
	s_addc_u32 s45, s45, 0
	s_mov_b32 m0, s49
	v_lshl_add_u64 v[230:231], s[44:45], 0, v[154:155]
	ds_read_b128 v[178:181], v198 offset:32768
	ds_read_b128 v[182:185], v198 offset:33792
	ds_read_b128 v[200:203], v198 offset:34816
	ds_read_b128 v[204:207], v198 offset:35840
	ds_read_b128 v[208:211], v198 offset:36864
	ds_read_b128 v[212:215], v198 offset:37888
	ds_read_b128 v[216:219], v198 offset:38912
	ds_read_b128 v[220:223], v198 offset:39936
	global_load_lds_dwordx4 v[230:231], off
	v_lshl_add_u64 v[230:231], s[44:45], 0, v[158:159]
	s_mov_b32 m0, s50
	s_nop 0
	global_load_lds_dwordx4 v[230:231], off
	s_waitcnt vmcnt(8)
	s_waitcnt lgkmcnt(0)
	s_setprio 3
	s_barrier
	s_waitcnt lgkmcnt(0)
	v_mfma_f32_16x16x32_bf16 v[126:129], v[130:133], v[178:181], v[126:129]
	v_mfma_f32_16x16x32_bf16 v[122:125], v[138:141], v[178:181], v[122:125]
	v_mfma_f32_16x16x32_bf16 v[110:113], v[130:133], v[200:203], v[110:113]
	v_mfma_f32_16x16x32_bf16 v[106:109], v[138:141], v[200:203], v[106:109]
	v_mfma_f32_16x16x32_bf16 v[94:97], v[130:133], v[208:211], v[94:97]
	v_mfma_f32_16x16x32_bf16 v[90:93], v[138:141], v[208:211], v[90:93]
	v_mfma_f32_16x16x32_bf16 v[78:81], v[130:133], v[216:219], v[78:81]
	v_mfma_f32_16x16x32_bf16 v[74:77], v[138:141], v[216:219], v[74:77]
	v_mfma_f32_16x16x32_bf16 v[126:129], v[134:137], v[182:185], v[126:129]
	v_mfma_f32_16x16x32_bf16 v[122:125], v[142:145], v[182:185], v[122:125]
	v_mfma_f32_16x16x32_bf16 v[110:113], v[134:137], v[204:207], v[110:113]
	v_mfma_f32_16x16x32_bf16 v[106:109], v[142:145], v[204:207], v[106:109]
	v_mfma_f32_16x16x32_bf16 v[94:97], v[134:137], v[212:215], v[94:97]
	v_mfma_f32_16x16x32_bf16 v[90:93], v[142:145], v[212:215], v[90:93]
	v_mfma_f32_16x16x32_bf16 v[78:81], v[134:137], v[220:223], v[78:81]
	v_mfma_f32_16x16x32_bf16 v[74:77], v[142:145], v[220:223], v[74:77]
	v_mfma_f32_16x16x32_bf16 v[118:121], v[146:149], v[178:181], v[118:121]
	v_mfma_f32_16x16x32_bf16 v[114:117], v[170:173], v[178:181], v[114:117]
	v_mfma_f32_16x16x32_bf16 v[102:105], v[146:149], v[200:203], v[102:105]
	v_mfma_f32_16x16x32_bf16 v[98:101], v[170:173], v[200:203], v[98:101]
	v_mfma_f32_16x16x32_bf16 v[86:89], v[146:149], v[208:211], v[86:89]
	v_mfma_f32_16x16x32_bf16 v[82:85], v[170:173], v[208:211], v[82:85]
	v_mfma_f32_16x16x32_bf16 v[70:73], v[146:149], v[216:219], v[70:73]
	v_mfma_f32_16x16x32_bf16 v[66:69], v[170:173], v[216:219], v[66:69]
	v_mfma_f32_16x16x32_bf16 v[118:121], v[150:153], v[182:185], v[118:121]
	v_mfma_f32_16x16x32_bf16 v[114:117], v[174:177], v[182:185], v[114:117]
	v_mfma_f32_16x16x32_bf16 v[102:105], v[150:153], v[204:207], v[102:105]
	v_mfma_f32_16x16x32_bf16 v[98:101], v[174:177], v[204:207], v[98:101]
	v_mfma_f32_16x16x32_bf16 v[86:89], v[150:153], v[212:215], v[86:89]
	v_mfma_f32_16x16x32_bf16 v[82:85], v[174:177], v[212:215], v[82:85]
	v_mfma_f32_16x16x32_bf16 v[70:73], v[150:153], v[220:223], v[70:73]
	v_mfma_f32_16x16x32_bf16 v[66:69], v[174:177], v[220:223], v[66:69]
	s_barrier
; #define PG8_STAGE(bufoff, gbase, voff) do { _Pragma("unroll") for (int _i = 0; _i < 2; ++_i) \
;         __builtin_amdgcn_global_load_lds((const unsigned*)((const char*)(gbase) + (voff)[_i]), (LAS unsigned*)(lds + (bufoff) + ldsw + _i * 8192), 16, 0, 0); } while (0)
; #define PG8_LDA(dst, b, h) do { _Pragma("unroll") for (int m = 0; m < 4; ++m) _Pragma("unroll") for (int k = 0; k < 2; ++k) dst[m][k] = *(const LAS bf16x8*)(lds + PG8_SA(b, h) + aoff + m * 2048 + k * 1024); } while (0)
; #define PG8_LDB(dst, b, h) do { _Pragma("unroll") for (int n = 0; n < 2; ++n) _Pragma("unroll") for (int k = 0; k < 2; ++k) dst[n][k] = *(const LAS bf16x8*)(lds + PG8_SB(b, h) + boff + n * 2048 + k * 1024); } while (0)
; #define PG8_MMA(ai, bj, At, Bt) do { __builtin_amdgcn_s_setprio(3); _Pragma("unroll") for (int m = 0; m < 4; ++m) _Pragma("unroll") for (int n = 0; n < 2; ++n) _Pragma("unroll") for (int k = 0; k < 2; ++k) \
;         acc[ai][bj][m][n] = __builtin_amdgcn_mfma_f32_16x16x32_bf16(Bt[n][k], At[m][k], acc[ai][bj][m][n], 0, 0, 0); __builtin_amdgcn_s_setprio(0); } while (0)
; #define PG8_WAIT_V(n) asm volatile("s_waitcnt vmcnt(" #n ")" ::: "memory")
; #define PG8_BAR __builtin_amdgcn_s_barrier()
; template <class Epi, bool ALIGN_EPI>
; __device__ __forceinline__ void gemm_phase(LAS unsigned char* lds, const Gemm g, const StaticOrder& S, const Epi& E) {
;     ...
;             PG8_LDB(B0, 0, 0); PG8_LDB(B1, 0, 1); PG8_SCHED; PG8_LDA(At, 0, 0); PG8_STAGE(PG8_SA(1, 1), a1 + hstep, voffA);
;             PG8_WAIT_V(8); PG8_WAIT_L(0); PG8_BAR; PG8_MMA(0, 0, At, B0); PG8_MMA(0, 1, At, B1); PG8_BAR; PG8_SCHED;
;             PG8_LDA(At, 0, 1); PG8_STAGE(PG8_SB(0, 0), b2, voffB); PG8_STAGE(PG8_SB(0, 1), b2 + hstep, voffB); PG8_STAGE(PG8_SA(0, 0), a2, voffA);
;             PG8_WAIT_V(8); PG8_WAIT_L(0); PG8_BAR; PG8_MMA(1, 0, At, B0); PG8_MMA(1, 1, At, B1); PG8_BAR; PG8_SCHED;
;             PG8_LDB(B0, 1, 0); PG8_LDB(B1, 1, 1); PG8_SCHED; PG8_LDA(At, 1, 0); PG8_STAGE(PG8_SA(0, 1), a2 + hstep, voffA);
;             PG8_WAIT_V(8); PG8_WAIT_L(0); PG8_BAR; PG8_MMA(0, 0, At, B0); PG8_MMA(0, 1, At, B1); PG8_BAR; PG8_SCHED;
;             PG8_LDA(At, 1, 1); PG8_STAGE(PG8_SB(1, 0), b3, voffB); PG8_STAGE(PG8_SB(1, 1), b3 + hstep, voffB); PG8_STAGE(PG8_SA(1, 0), a3, voffA);
;             PG8_WAIT_V(8); PG8_WAIT_L(0); PG8_BAR; PG8_MMA(1, 0, At, B0); PG8_MMA(1, 1, At, B1); PG8_BAR; PG8_SCHED;
	s_setprio 0
	s_add_i32 s44, s62, s47
	v_lshl_add_u64 v[186:187], v[186:187], 0, s[12:13]
	s_mov_b32 m0, s44
	ds_read_b128 v[178:181], v198 offset:49152
	ds_read_b128 v[182:185], v198 offset:50176
	ds_read_b128 v[200:203], v198 offset:51200
	ds_read_b128 v[204:207], v198 offset:52224
	ds_read_b128 v[208:211], v198 offset:53248
	ds_read_b128 v[212:215], v198 offset:54272
	ds_read_b128 v[216:219], v198 offset:55296
	ds_read_b128 v[220:223], v198 offset:56320
	global_load_lds_dwordx4 v[186:187], off
	s_add_i32 m0, s44, 0x2000
	s_add_u32 s42, s42, 0x40080
	v_lshl_add_u64 v[186:187], v[224:225], 0, s[12:13]
	s_addc_u32 s43, s43, 0
	s_add_i32 s44, s63, s47
	global_load_lds_dwordx4 v[186:187], off
	v_lshl_add_u64 v[186:187], s[42:43], 0, v[156:157]
	s_mov_b32 m0, s44
	s_nop 0
	global_load_lds_dwordx4 v[186:187], off
	v_lshl_add_u64 v[186:187], s[42:43], 0, v[160:161]
	s_add_i32 m0, s44, 0x2000
	s_nop 0
	global_load_lds_dwordx4 v[186:187], off
	v_lshl_add_u64 v[186:187], v[226:227], 0, s[12:13]
	s_mov_b32 m0, s52
	s_nop 0
	global_load_lds_dwordx4 v[186:187], off
	v_lshl_add_u64 v[186:187], v[228:229], 0, s[12:13]
	s_mov_b32 m0, s53
	s_nop 0
	global_load_lds_dwordx4 v[186:187], off
	s_waitcnt vmcnt(8)
	s_waitcnt lgkmcnt(0)
	s_setprio 3
	s_barrier
	s_waitcnt lgkmcnt(0)
	v_mfma_f32_16x16x32_bf16 v[62:65], v[130:133], v[178:181], v[62:65]
	v_mfma_f32_16x16x32_bf16 v[58:61], v[138:141], v[178:181], v[58:61]
	v_mfma_f32_16x16x32_bf16 v[46:49], v[130:133], v[200:203], v[46:49]
	v_mfma_f32_16x16x32_bf16 v[42:45], v[138:141], v[200:203], v[42:45]
	v_mfma_f32_16x16x32_bf16 v[30:33], v[130:133], v[208:211], v[30:33]
	v_mfma_f32_16x16x32_bf16 v[26:29], v[138:141], v[208:211], v[26:29]
	v_mfma_f32_16x16x32_bf16 v[14:17], v[130:133], v[216:219], v[14:17]
	v_mfma_f32_16x16x32_bf16 v[10:13], v[138:141], v[216:219], v[10:13]
	v_mfma_f32_16x16x32_bf16 v[62:65], v[134:137], v[182:185], v[62:65]
	v_mfma_f32_16x16x32_bf16 v[58:61], v[142:145], v[182:185], v[58:61]
	v_mfma_f32_16x16x32_bf16 v[46:49], v[134:137], v[204:207], v[46:49]
	v_mfma_f32_16x16x32_bf16 v[42:45], v[142:145], v[204:207], v[42:45]
	v_mfma_f32_16x16x32_bf16 v[30:33], v[134:137], v[212:215], v[30:33]
	v_mfma_f32_16x16x32_bf16 v[26:29], v[142:145], v[212:215], v[26:29]
	v_mfma_f32_16x16x32_bf16 v[14:17], v[134:137], v[220:223], v[14:17]
	v_mfma_f32_16x16x32_bf16 v[10:13], v[142:145], v[220:223], v[10:13]
	v_mfma_f32_16x16x32_bf16 v[54:57], v[146:149], v[178:181], v[54:57]
	v_mfma_f32_16x16x32_bf16 v[50:53], v[170:173], v[178:181], v[50:53]
	v_mfma_f32_16x16x32_bf16 v[38:41], v[146:149], v[200:203], v[38:41]
	v_mfma_f32_16x16x32_bf16 v[34:37], v[170:173], v[200:203], v[34:37]
	v_mfma_f32_16x16x32_bf16 v[22:25], v[146:149], v[208:211], v[22:25]
	v_mfma_f32_16x16x32_bf16 v[18:21], v[170:173], v[208:211], v[18:21]
	v_mfma_f32_16x16x32_bf16 v[6:9], v[146:149], v[216:219], v[6:9]
	v_mfma_f32_16x16x32_bf16 v[2:5], v[170:173], v[216:219], v[2:5]
	v_mfma_f32_16x16x32_bf16 v[54:57], v[150:153], v[182:185], v[54:57]
	v_mfma_f32_16x16x32_bf16 v[50:53], v[174:177], v[182:185], v[50:53]
	v_mfma_f32_16x16x32_bf16 v[38:41], v[150:153], v[204:207], v[38:41]
	v_mfma_f32_16x16x32_bf16 v[34:37], v[174:177], v[204:207], v[34:37]
	v_mfma_f32_16x16x32_bf16 v[22:25], v[150:153], v[212:215], v[22:25]
	v_mfma_f32_16x16x32_bf16 v[18:21], v[174:177], v[212:215], v[18:21]
	v_mfma_f32_16x16x32_bf16 v[6:9], v[150:153], v[220:223], v[6:9]
	v_mfma_f32_16x16x32_bf16 v[2:5], v[174:177], v[220:223], v[2:5]
	s_barrier
	s_setprio 0
	s_add_i32 s61, s61, 2
	s_add_u32 s40, s40, 0x100
	s_addc_u32 s41, s41, 0
	s_add_u32 s59, s59, 0x100
	s_addc_u32 s60, s60, 0
.LBB0_1339:
	ds_read_b128 v[130:133], v196
	ds_read_b128 v[134:137], v196 offset:1024
	ds_read_b128 v[138:141], v196 offset:2048
	ds_read_b128 v[142:145], v196 offset:3072
	ds_read_b128 v[146:149], v197
	ds_read_b128 v[150:153], v197 offset:1024
	ds_read_b128 v[170:173], v197 offset:2048
	ds_read_b128 v[174:177], v197 offset:3072
	s_add_u32 s42, s40, 0xfffc0080
	s_addc_u32 s43, s41, -1
	s_cmp_eq_u32 s61, 12
	s_cselect_b32 s45, s19, s43
	s_cselect_b32 s44, s37, s42
	s_cselect_b32 s43, s17, s60
	s_cselect_b32 s42, s58, s59
	v_lshl_add_u64 v[186:187], s[40:41], 0, v[162:163]
	s_add_i32 m0, s39, 0xc000
	ds_read_b128 v[178:181], v198
	ds_read_b128 v[182:185], v198 offset:1024
	ds_read_b128 v[200:203], v198 offset:2048
	ds_read_b128 v[204:207], v198 offset:3072
	ds_read_b128 v[208:211], v198 offset:4096
	ds_read_b128 v[212:215], v198 offset:5120
	ds_read_b128 v[216:219], v198 offset:6144
	ds_read_b128 v[220:223], v198 offset:7168
	global_load_lds_dwordx4 v[186:187], off
	v_lshl_add_u64 v[186:187], s[40:41], 0, v[164:165]
	s_add_i32 m0, s39, 0xe000
	s_nop 0
	global_load_lds_dwordx4 v[186:187], off
	s_waitcnt vmcnt(8)
	s_waitcnt lgkmcnt(0)
	s_setprio 3
	s_barrier
; #define PG8_STAGE(bufoff, gbase, voff) do { _Pragma("unroll") for (int _i = 0; _i < 2; ++_i) \
;         __builtin_amdgcn_global_load_lds((const unsigned*)((const char*)(gbase) + (voff)[_i]), (LAS unsigned*)(lds + (bufoff) + ldsw + _i * 8192), 16, 0, 0); } while (0)
; #define PG8_LDA(dst, b, h) do { _Pragma("unroll") for (int m = 0; m < 4; ++m) _Pragma("unroll") for (int k = 0; k < 2; ++k) dst[m][k] = *(const LAS bf16x8*)(lds + PG8_SA(b, h) + aoff + m * 2048 + k * 1024); } while (0)
; #define PG8_MMA(ai, bj, At, Bt) do { __builtin_amdgcn_s_setprio(3); _Pragma("unroll") for (int m = 0; m < 4; ++m) _Pragma("unroll") for (int n = 0; n < 2; ++n) _Pragma("unroll") for (int k = 0; k < 2; ++k) \
;         acc[ai][bj][m][n] = __builtin_amdgcn_mfma_f32_16x16x32_bf16(Bt[n][k], At[m][k], acc[ai][bj][m][n], 0, 0, 0); __builtin_amdgcn_s_setprio(0); } while (0)
; #define PG8_WAIT_V(n) asm volatile("s_waitcnt vmcnt(" #n ")" ::: "memory")
; #define PG8_WAIT_L(n) asm volatile("s_waitcnt lgkmcnt(" #n ")" ::: "memory")
; #define PG8_BAR __builtin_amdgcn_s_barrier()
; #define PG8_SCHED __builtin_amdgcn_sched_barrier(0)
; template <class Epi, bool ALIGN_EPI>
; __device__ __forceinline__ void gemm_phase(LAS unsigned char* lds, const Gemm g, const StaticOrder& S, const Epi& E) {
;     ...
;             PG8_WAIT_V(8); PG8_WAIT_L(0); PG8_BAR; PG8_MMA(0, 0, At, B0); PG8_MMA(0, 1, At, B1); PG8_BAR; PG8_SCHED;
;             PG8_LDA(At, 0, 1); PG8_STAGE(PG8_SB(0, 0), b2, voffB); PG8_STAGE(PG8_SB(0, 1), b2 + hstep, voffB); PG8_STAGE(PG8_SA(0, 0), a2, voffA);
;             PG8_WAIT_V(8); PG8_WAIT_L(0); PG8_BAR; PG8_MMA(1, 0, At, B0); PG8_MMA(1, 1, At, B1); PG8_BAR; PG8_SCHED;
	s_waitcnt lgkmcnt(0)
	v_mfma_f32_16x16x32_bf16 v[126:129], v[130:133], v[178:181], v[126:129]
	v_mfma_f32_16x16x32_bf16 v[122:125], v[138:141], v[178:181], v[122:125]
	v_mfma_f32_16x16x32_bf16 v[110:113], v[130:133], v[200:203], v[110:113]
	v_mfma_f32_16x16x32_bf16 v[106:109], v[138:141], v[200:203], v[106:109]
	v_mfma_f32_16x16x32_bf16 v[94:97], v[130:133], v[208:211], v[94:97]
	v_mfma_f32_16x16x32_bf16 v[90:93], v[138:141], v[208:211], v[90:93]
	v_mfma_f32_16x16x32_bf16 v[78:81], v[130:133], v[216:219], v[78:81]
	v_mfma_f32_16x16x32_bf16 v[74:77], v[138:141], v[216:219], v[74:77]
	v_mfma_f32_16x16x32_bf16 v[126:129], v[134:137], v[182:185], v[126:129]
	v_mfma_f32_16x16x32_bf16 v[122:125], v[142:145], v[182:185], v[122:125]
	v_mfma_f32_16x16x32_bf16 v[110:113], v[134:137], v[204:207], v[110:113]
	v_mfma_f32_16x16x32_bf16 v[106:109], v[142:145], v[204:207], v[106:109]
	v_mfma_f32_16x16x32_bf16 v[94:97], v[134:137], v[212:215], v[94:97]
	v_mfma_f32_16x16x32_bf16 v[90:93], v[142:145], v[212:215], v[90:93]
	v_mfma_f32_16x16x32_bf16 v[78:81], v[134:137], v[220:223], v[78:81]
	v_mfma_f32_16x16x32_bf16 v[74:77], v[142:145], v[220:223], v[74:77]
	v_mfma_f32_16x16x32_bf16 v[118:121], v[146:149], v[178:181], v[118:121]
	v_mfma_f32_16x16x32_bf16 v[114:117], v[170:173], v[178:181], v[114:117]
	v_mfma_f32_16x16x32_bf16 v[102:105], v[146:149], v[200:203], v[102:105]
	v_mfma_f32_16x16x32_bf16 v[98:101], v[170:173], v[200:203], v[98:101]
	v_mfma_f32_16x16x32_bf16 v[86:89], v[146:149], v[208:211], v[86:89]
	v_mfma_f32_16x16x32_bf16 v[82:85], v[170:173], v[208:211], v[82:85]
	v_mfma_f32_16x16x32_bf16 v[70:73], v[146:149], v[216:219], v[70:73]
	v_mfma_f32_16x16x32_bf16 v[66:69], v[170:173], v[216:219], v[66:69]
	v_mfma_f32_16x16x32_bf16 v[118:121], v[150:153], v[182:185], v[118:121]
	v_mfma_f32_16x16x32_bf16 v[114:117], v[174:177], v[182:185], v[114:117]
	v_mfma_f32_16x16x32_bf16 v[102:105], v[150:153], v[204:207], v[102:105]
	v_mfma_f32_16x16x32_bf16 v[98:101], v[174:177], v[204:207], v[98:101]
	v_mfma_f32_16x16x32_bf16 v[86:89], v[150:153], v[212:215], v[86:89]
	v_mfma_f32_16x16x32_bf16 v[82:85], v[174:177], v[212:215], v[82:85]
	v_mfma_f32_16x16x32_bf16 v[70:73], v[150:153], v[220:223], v[70:73]
	v_mfma_f32_16x16x32_bf16 v[66:69], v[174:177], v[220:223], v[66:69]
	s_barrier
	s_setprio 0
	s_add_i32 s62, s56, s47
	v_lshl_add_u64 v[186:187], s[42:43], 0, v[156:157]
	s_mov_b32 m0, s62
	ds_read_b128 v[178:181], v198 offset:16384
	ds_read_b128 v[182:185], v198 offset:17408
	ds_read_b128 v[200:203], v198 offset:18432
	ds_read_b128 v[204:207], v198 offset:19456
	ds_read_b128 v[208:211], v198 offset:20480
	ds_read_b128 v[212:215], v198 offset:21504
	ds_read_b128 v[216:219], v198 offset:22528
	ds_read_b128 v[220:223], v198 offset:23552
	global_load_lds_dwordx4 v[186:187], off
	s_add_i32 m0, s62, 0x2000
	s_add_u32 s62, s42, 0x40000
	v_lshl_add_u64 v[224:225], s[42:43], 0, v[160:161]
	s_addc_u32 s63, s43, 0
	s_add_i32 s64, s57, s47
	global_load_lds_dwordx4 v[224:225], off
	v_lshl_add_u64 v[226:227], s[62:63], 0, v[156:157]
	s_mov_b32 m0, s64
	v_lshl_add_u64 v[228:229], s[44:45], 0, v[158:159]
	global_load_lds_dwordx4 v[226:227], off
	v_lshl_add_u64 v[226:227], s[62:63], 0, v[160:161]
	s_add_i32 m0, s64, 0x2000
	s_nop 0
	global_load_lds_dwordx4 v[226:227], off
	v_lshl_add_u64 v[226:227], s[44:45], 0, v[154:155]
	s_mov_b32 m0, s39
	s_nop 0
	global_load_lds_dwordx4 v[226:227], off
	s_mov_b32 m0, s48
	s_nop 0
	global_load_lds_dwordx4 v[228:229], off
	s_waitcnt vmcnt(8)
	s_waitcnt lgkmcnt(0)
	s_setprio 3
	s_barrier
	s_waitcnt lgkmcnt(0)
	v_mfma_f32_16x16x32_bf16 v[62:65], v[130:133], v[178:181], v[62:65]
	v_mfma_f32_16x16x32_bf16 v[58:61], v[138:141], v[178:181], v[58:61]
	v_mfma_f32_16x16x32_bf16 v[46:49], v[130:133], v[200:203], v[46:49]
	v_mfma_f32_16x16x32_bf16 v[42:45], v[138:141], v[200:203], v[42:45]
	v_mfma_f32_16x16x32_bf16 v[30:33], v[130:133], v[208:211], v[30:33]
	v_mfma_f32_16x16x32_bf16 v[26:29], v[138:141], v[208:211], v[26:29]
	v_mfma_f32_16x16x32_bf16 v[14:17], v[130:133], v[216:219], v[14:17]
	v_mfma_f32_16x16x32_bf16 v[10:13], v[138:141], v[216:219], v[10:13]
	v_mfma_f32_16x16x32_bf16 v[62:65], v[134:137], v[182:185], v[62:65]
	v_mfma_f32_16x16x32_bf16 v[58:61], v[142:145], v[182:185], v[58:61]
	v_mfma_f32_16x16x32_bf16 v[46:49], v[134:137], v[204:207], v[46:49]
	v_mfma_f32_16x16x32_bf16 v[42:45], v[142:145], v[204:207], v[42:45]
	v_mfma_f32_16x16x32_bf16 v[30:33], v[134:137], v[212:215], v[30:33]
	v_mfma_f32_16x16x32_bf16 v[26:29], v[142:145], v[212:215], v[26:29]
	v_mfma_f32_16x16x32_bf16 v[14:17], v[134:137], v[220:223], v[14:17]
	v_mfma_f32_16x16x32_bf16 v[10:13], v[142:145], v[220:223], v[10:13]
	v_mfma_f32_16x16x32_bf16 v[54:57], v[146:149], v[178:181], v[54:57]
	v_mfma_f32_16x16x32_bf16 v[50:53], v[170:173], v[178:181], v[50:53]
	v_mfma_f32_16x16x32_bf16 v[38:41], v[146:149], v[200:203], v[38:41]
	v_mfma_f32_16x16x32_bf16 v[34:37], v[170:173], v[200:203], v[34:37]
	v_mfma_f32_16x16x32_bf16 v[22:25], v[146:149], v[208:211], v[22:25]
	v_mfma_f32_16x16x32_bf16 v[18:21], v[170:173], v[208:211], v[18:21]
	v_mfma_f32_16x16x32_bf16 v[6:9], v[146:149], v[216:219], v[6:9]
	v_mfma_f32_16x16x32_bf16 v[2:5], v[170:173], v[216:219], v[2:5]
	v_mfma_f32_16x16x32_bf16 v[54:57], v[150:153], v[182:185], v[54:57]
	v_mfma_f32_16x16x32_bf16 v[50:53], v[174:177], v[182:185], v[50:53]
	v_mfma_f32_16x16x32_bf16 v[38:41], v[150:153], v[204:207], v[38:41]
	v_mfma_f32_16x16x32_bf16 v[34:37], v[174:177], v[204:207], v[34:37]
	v_mfma_f32_16x16x32_bf16 v[22:25], v[150:153], v[212:215], v[22:25]
	v_mfma_f32_16x16x32_bf16 v[18:21], v[174:177], v[212:215], v[18:21]
	v_mfma_f32_16x16x32_bf16 v[6:9], v[150:153], v[220:223], v[6:9]
	v_mfma_f32_16x16x32_bf16 v[2:5], v[174:177], v[220:223], v[2:5]
	s_barrier
; #define PG8_STAGE(bufoff, gbase, voff) do { _Pragma("unroll") for (int _i = 0; _i < 2; ++_i) \
;         __builtin_amdgcn_global_load_lds((const unsigned*)((const char*)(gbase) + (voff)[_i]), (LAS unsigned*)(lds + (bufoff) + ldsw + _i * 8192), 16, 0, 0); } while (0)
; #define PG8_LDA(dst, b, h) do { _Pragma("unroll") for (int m = 0; m < 4; ++m) _Pragma("unroll") for (int k = 0; k < 2; ++k) dst[m][k] = *(const LAS bf16x8*)(lds + PG8_SA(b, h) + aoff + m * 2048 + k * 1024); } while (0)
; #define PG8_LDB(dst, b, h) do { _Pragma("unroll") for (int n = 0; n < 2; ++n) _Pragma("unroll") for (int k = 0; k < 2; ++k) dst[n][k] = *(const LAS bf16x8*)(lds + PG8_SB(b, h) + boff + n * 2048 + k * 1024); } while (0)
; #define PG8_MMA(ai, bj, At, Bt) do { __builtin_amdgcn_s_setprio(3); _Pragma("unroll") for (int m = 0; m < 4; ++m) _Pragma("unroll") for (int n = 0; n < 2; ++n) _Pragma("unroll") for (int k = 0; k < 2; ++k) \
;         acc[ai][bj][m][n] = __builtin_amdgcn_mfma_f32_16x16x32_bf16(Bt[n][k], At[m][k], acc[ai][bj][m][n], 0, 0, 0); __builtin_amdgcn_s_setprio(0); } while (0)
; #define PG8_WAIT_V(n) asm volatile("s_waitcnt vmcnt(" #n ")" ::: "memory")
; #define PG8_WAIT_L(n) asm volatile("s_waitcnt lgkmcnt(" #n ")" ::: "memory")
; #define PG8_BAR __builtin_amdgcn_s_barrier()
; #define PG8_SCHED __builtin_amdgcn_sched_barrier(0)
; template <class Epi, bool ALIGN_EPI>
; __device__ __forceinline__ void gemm_phase(LAS unsigned char* lds, const Gemm g, const StaticOrder& S, const Epi& E) {
;     ...
;             PG8_LDB(B0, 1, 0); PG8_LDB(B1, 1, 1); PG8_SCHED; PG8_LDA(At, 1, 0); PG8_STAGE(PG8_SA(0, 1), a2 + hstep, voffA);
;             PG8_WAIT_V(8); PG8_WAIT_L(0); PG8_BAR; PG8_MMA(0, 0, At, B0); PG8_MMA(0, 1, At, B1); PG8_BAR; PG8_SCHED;
	s_setprio 0
	s_add_i32 s62, 0, 0x18000
	s_add_i32 s63, 0, 0x1c000
	v_add_u32_e32 v142, s62, v194
	v_add_u32_e32 v174, s63, v194
	ds_read_b128 v[130:133], v142
	ds_read_b128 v[134:137], v142 offset:1024
	ds_read_b128 v[138:141], v142 offset:2048
	ds_read_b128 v[142:145], v142 offset:3072
	ds_read_b128 v[146:149], v174
	ds_read_b128 v[150:153], v174 offset:1024
	ds_read_b128 v[170:173], v174 offset:2048
	ds_read_b128 v[174:177], v174 offset:3072
	s_add_u32 s44, s44, 0x40000
	s_addc_u32 s45, s45, 0
	s_mov_b32 m0, s49
	v_lshl_add_u64 v[230:231], s[44:45], 0, v[154:155]
	ds_read_b128 v[178:181], v198 offset:32768
	ds_read_b128 v[182:185], v198 offset:33792
	ds_read_b128 v[200:203], v198 offset:34816
	ds_read_b128 v[204:207], v198 offset:35840
	ds_read_b128 v[208:211], v198 offset:36864
	ds_read_b128 v[212:215], v198 offset:37888
	ds_read_b128 v[216:219], v198 offset:38912
	ds_read_b128 v[220:223], v198 offset:39936
	global_load_lds_dwordx4 v[230:231], off
	v_lshl_add_u64 v[230:231], s[44:45], 0, v[158:159]
	s_mov_b32 m0, s50
	s_nop 0
	global_load_lds_dwordx4 v[230:231], off
	s_waitcnt vmcnt(8)
	s_waitcnt lgkmcnt(0)
	s_setprio 3
	s_barrier
	s_waitcnt lgkmcnt(0)
	v_mfma_f32_16x16x32_bf16 v[126:129], v[130:133], v[178:181], v[126:129]
	v_mfma_f32_16x16x32_bf16 v[122:125], v[138:141], v[178:181], v[122:125]
	v_mfma_f32_16x16x32_bf16 v[110:113], v[130:133], v[200:203], v[110:113]
	v_mfma_f32_16x16x32_bf16 v[106:109], v[138:141], v[200:203], v[106:109]
	v_mfma_f32_16x16x32_bf16 v[94:97], v[130:133], v[208:211], v[94:97]
	v_mfma_f32_16x16x32_bf16 v[90:93], v[138:141], v[208:211], v[90:93]
	v_mfma_f32_16x16x32_bf16 v[78:81], v[130:133], v[216:219], v[78:81]
	v_mfma_f32_16x16x32_bf16 v[74:77], v[138:141], v[216:219], v[74:77]
	v_mfma_f32_16x16x32_bf16 v[126:129], v[134:137], v[182:185], v[126:129]
	v_mfma_f32_16x16x32_bf16 v[122:125], v[142:145], v[182:185], v[122:125]
	v_mfma_f32_16x16x32_bf16 v[110:113], v[134:137], v[204:207], v[110:113]
	v_mfma_f32_16x16x32_bf16 v[106:109], v[142:145], v[204:207], v[106:109]
	v_mfma_f32_16x16x32_bf16 v[94:97], v[134:137], v[212:215], v[94:97]
	v_mfma_f32_16x16x32_bf16 v[90:93], v[142:145], v[212:215], v[90:93]
	v_mfma_f32_16x16x32_bf16 v[78:81], v[134:137], v[220:223], v[78:81]
	v_mfma_f32_16x16x32_bf16 v[74:77], v[142:145], v[220:223], v[74:77]
	v_mfma_f32_16x16x32_bf16 v[118:121], v[146:149], v[178:181], v[118:121]
	v_mfma_f32_16x16x32_bf16 v[114:117], v[170:173], v[178:181], v[114:117]
	v_mfma_f32_16x16x32_bf16 v[102:105], v[146:149], v[200:203], v[102:105]
	v_mfma_f32_16x16x32_bf16 v[98:101], v[170:173], v[200:203], v[98:101]
	v_mfma_f32_16x16x32_bf16 v[86:89], v[146:149], v[208:211], v[86:89]
	v_mfma_f32_16x16x32_bf16 v[82:85], v[170:173], v[208:211], v[82:85]
	v_mfma_f32_16x16x32_bf16 v[70:73], v[146:149], v[216:219], v[70:73]
	v_mfma_f32_16x16x32_bf16 v[66:69], v[170:173], v[216:219], v[66:69]
	v_mfma_f32_16x16x32_bf16 v[118:121], v[150:153], v[182:185], v[118:121]
	v_mfma_f32_16x16x32_bf16 v[114:117], v[174:177], v[182:185], v[114:117]
	v_mfma_f32_16x16x32_bf16 v[102:105], v[150:153], v[204:207], v[102:105]
	v_mfma_f32_16x16x32_bf16 v[98:101], v[174:177], v[204:207], v[98:101]
	v_mfma_f32_16x16x32_bf16 v[86:89], v[150:153], v[212:215], v[86:89]
	v_mfma_f32_16x16x32_bf16 v[82:85], v[174:177], v[212:215], v[82:85]
	v_mfma_f32_16x16x32_bf16 v[70:73], v[150:153], v[220:223], v[70:73]
	v_mfma_f32_16x16x32_bf16 v[66:69], v[174:177], v[220:223], v[66:69]
	s_barrier
; #define PG8_STAGE(bufoff, gbase, voff) do { _Pragma("unroll") for (int _i = 0; _i < 2; ++_i) \
;         __builtin_amdgcn_global_load_lds((const unsigned*)((const char*)(gbase) + (voff)[_i]), (LAS unsigned*)(lds + (bufoff) + ldsw + _i * 8192), 16, 0, 0); } while (0)
; #define PG8_LDA(dst, b, h) do { _Pragma("unroll") for (int m = 0; m < 4; ++m) _Pragma("unroll") for (int k = 0; k < 2; ++k) dst[m][k] = *(const LAS bf16x8*)(lds + PG8_SA(b, h) + aoff + m * 2048 + k * 1024); } while (0)
; #define PG8_MMA(ai, bj, At, Bt) do { __builtin_amdgcn_s_setprio(3); _Pragma("unroll") for (int m = 0; m < 4; ++m) _Pragma("unroll") for (int n = 0; n < 2; ++n) _Pragma("unroll") for (int k = 0; k < 2; ++k) \
;         acc[ai][bj][m][n] = __builtin_amdgcn_mfma_f32_16x16x32_bf16(Bt[n][k], At[m][k], acc[ai][bj][m][n], 0, 0, 0); __builtin_amdgcn_s_setprio(0); } while (0)
; #define PG8_WAIT_V(n) asm volatile("s_waitcnt vmcnt(" #n ")" ::: "memory")
; #define PG8_WAIT_L(n) asm volatile("s_waitcnt lgkmcnt(" #n ")" ::: "memory")
; #define PG8_BAR __builtin_amdgcn_s_barrier()
; #define PG8_SCHED __builtin_amdgcn_sched_barrier(0)
; template <class Epi, bool ALIGN_EPI>
; __device__ __forceinline__ void gemm_phase(LAS unsigned char* lds, const Gemm g, const StaticOrder& S, const Epi& E) {
;     ...
;             PG8_LDA(At, 1, 1); PG8_STAGE(PG8_SB(1, 0), b3, voffB); PG8_STAGE(PG8_SB(1, 1), b3 + hstep, voffB); PG8_STAGE(PG8_SA(1, 0), a3, voffA);
;             PG8_WAIT_V(8); PG8_WAIT_L(0); PG8_BAR; PG8_MMA(1, 0, At, B0); PG8_MMA(1, 1, At, B1); PG8_BAR; PG8_SCHED;
;         }
;         if constexpr (ALIGN_EPI) { if (wr == 0) PG8_BAR; }
	s_setprio 0
	s_add_i32 s44, s62, s47
	v_lshl_add_u64 v[186:187], v[186:187], 0, s[12:13]
	s_mov_b32 m0, s44
	ds_read_b128 v[178:181], v198 offset:49152
	ds_read_b128 v[182:185], v198 offset:50176
	ds_read_b128 v[200:203], v198 offset:51200
	ds_read_b128 v[204:207], v198 offset:52224
	ds_read_b128 v[208:211], v198 offset:53248
	ds_read_b128 v[212:215], v198 offset:54272
	ds_read_b128 v[216:219], v198 offset:55296
	ds_read_b128 v[220:223], v198 offset:56320
	global_load_lds_dwordx4 v[186:187], off
	s_add_i32 m0, s44, 0x2000
	s_add_u32 s42, s42, 0x40080
	v_lshl_add_u64 v[186:187], v[224:225], 0, s[12:13]
	s_addc_u32 s43, s43, 0
	s_add_i32 s44, s63, s47
	global_load_lds_dwordx4 v[186:187], off
	v_lshl_add_u64 v[186:187], s[42:43], 0, v[156:157]
	s_mov_b32 m0, s44
	s_nop 0
	global_load_lds_dwordx4 v[186:187], off
	v_lshl_add_u64 v[186:187], s[42:43], 0, v[160:161]
	s_add_i32 m0, s44, 0x2000
	s_nop 0
	global_load_lds_dwordx4 v[186:187], off
	v_lshl_add_u64 v[186:187], v[226:227], 0, s[12:13]
	s_mov_b32 m0, s52
	s_nop 0
	global_load_lds_dwordx4 v[186:187], off
	v_lshl_add_u64 v[186:187], v[228:229], 0, s[12:13]
	s_mov_b32 m0, s53
	s_nop 0
	global_load_lds_dwordx4 v[186:187], off
	s_waitcnt vmcnt(8)
	s_waitcnt lgkmcnt(0)
	s_setprio 3
	s_barrier
	s_waitcnt lgkmcnt(0)
	v_mfma_f32_16x16x32_bf16 v[62:65], v[130:133], v[178:181], v[62:65]
	v_mfma_f32_16x16x32_bf16 v[58:61], v[138:141], v[178:181], v[58:61]
	v_mfma_f32_16x16x32_bf16 v[46:49], v[130:133], v[200:203], v[46:49]
	v_mfma_f32_16x16x32_bf16 v[42:45], v[138:141], v[200:203], v[42:45]
	v_mfma_f32_16x16x32_bf16 v[30:33], v[130:133], v[208:211], v[30:33]
	v_mfma_f32_16x16x32_bf16 v[26:29], v[138:141], v[208:211], v[26:29]
	v_mfma_f32_16x16x32_bf16 v[14:17], v[130:133], v[216:219], v[14:17]
	v_mfma_f32_16x16x32_bf16 v[10:13], v[138:141], v[216:219], v[10:13]
	v_mfma_f32_16x16x32_bf16 v[62:65], v[134:137], v[182:185], v[62:65]
	v_mfma_f32_16x16x32_bf16 v[58:61], v[142:145], v[182:185], v[58:61]
	v_mfma_f32_16x16x32_bf16 v[46:49], v[134:137], v[204:207], v[46:49]
	v_mfma_f32_16x16x32_bf16 v[42:45], v[142:145], v[204:207], v[42:45]
	v_mfma_f32_16x16x32_bf16 v[30:33], v[134:137], v[212:215], v[30:33]
	v_mfma_f32_16x16x32_bf16 v[26:29], v[142:145], v[212:215], v[26:29]
	v_mfma_f32_16x16x32_bf16 v[14:17], v[134:137], v[220:223], v[14:17]
	v_mfma_f32_16x16x32_bf16 v[10:13], v[142:145], v[220:223], v[10:13]
	v_mfma_f32_16x16x32_bf16 v[54:57], v[146:149], v[178:181], v[54:57]
	v_mfma_f32_16x16x32_bf16 v[50:53], v[170:173], v[178:181], v[50:53]
	v_mfma_f32_16x16x32_bf16 v[38:41], v[146:149], v[200:203], v[38:41]
	v_mfma_f32_16x16x32_bf16 v[34:37], v[170:173], v[200:203], v[34:37]
	v_mfma_f32_16x16x32_bf16 v[22:25], v[146:149], v[208:211], v[22:25]
	v_mfma_f32_16x16x32_bf16 v[18:21], v[170:173], v[208:211], v[18:21]
	v_mfma_f32_16x16x32_bf16 v[6:9], v[146:149], v[216:219], v[6:9]
	v_mfma_f32_16x16x32_bf16 v[2:5], v[170:173], v[216:219], v[2:5]
	v_mfma_f32_16x16x32_bf16 v[54:57], v[150:153], v[182:185], v[54:57]
	v_mfma_f32_16x16x32_bf16 v[50:53], v[174:177], v[182:185], v[50:53]
	v_mfma_f32_16x16x32_bf16 v[38:41], v[150:153], v[204:207], v[38:41]
	v_mfma_f32_16x16x32_bf16 v[34:37], v[174:177], v[204:207], v[34:37]
	v_mfma_f32_16x16x32_bf16 v[22:25], v[150:153], v[212:215], v[22:25]
	v_mfma_f32_16x16x32_bf16 v[18:21], v[174:177], v[212:215], v[18:21]
	v_mfma_f32_16x16x32_bf16 v[6:9], v[150:153], v[220:223], v[6:9]
	v_mfma_f32_16x16x32_bf16 v[2:5], v[174:177], v[220:223], v[2:5]
	s_barrier
	s_setprio 0
	s_add_i32 s61, s61, 2
	s_add_u32 s40, s40, 0x100
	s_addc_u32 s41, s41, 0
	s_add_u32 s59, s59, 0x100
	s_addc_u32 s60, s60, 0
	s_cmp_gt_u32 s61, 13
	s_cbranch_scc0 .LBB0_1339
	s_and_b64 vcc, exec, s[14:15]
	s_cbranch_vccz .LBB0_1342
	s_barrier

; #define PG8_STAGE(bufoff, gbase, voff) do { _Pragma("unroll") for (int _i = 0; _i < 2; ++_i) \
;         __builtin_amdgcn_global_load_lds((const unsigned*)((const char*)(gbase) + (voff)[_i]), (LAS unsigned*)(lds + (bufoff) + ldsw + _i * 8192), 16, 0, 0); } while (0)
; #define PG8_LDA(dst, b, h) do { _Pragma("unroll") for (int m = 0; m < 4; ++m) _Pragma("unroll") for (int k = 0; k < 2; ++k) dst[m][k] = *(const LAS bf16x8*)(lds + PG8_SA(b, h) + aoff + m * 2048 + k * 1024); } while (0)
; #define PG8_LDB(dst, b, h) do { _Pragma("unroll") for (int n = 0; n < 2; ++n) _Pragma("unroll") for (int k = 0; k < 2; ++k) dst[n][k] = *(const LAS bf16x8*)(lds + PG8_SB(b, h) + boff + n * 2048 + k * 1024); } while (0)
; #define PG8_MMA(ai, bj, At, Bt) do { __builtin_amdgcn_s_setprio(3); _Pragma("unroll") for (int m = 0; m < 4; ++m) _Pragma("unroll") for (int n = 0; n < 2; ++n) _Pragma("unroll") for (int k = 0; k < 2; ++k) \
;         acc[ai][bj][m][n] = __builtin_amdgcn_mfma_f32_16x16x32_bf16(Bt[n][k], At[m][k], acc[ai][bj][m][n], 0, 0, 0); __builtin_amdgcn_s_setprio(0); } while (0)
; #define PG8_WAIT_V(n) asm volatile("s_waitcnt vmcnt(" #n ")" ::: "memory")
; #define PG8_WAIT_L(n) asm volatile("s_waitcnt lgkmcnt(" #n ")" ::: "memory")
; template <class Epi, bool ALIGN_EPI>
; __device__ __forceinline__ void gemm_phase(LAS unsigned char* lds, const Gemm g, const StaticOrder& S, const Epi& E) {
;     ...
;         const bool has_next = S.next(ui + 1, nxt);
;         const char* nA = has_next ? (const char*)g.A + (size_t)nxt.pm * tstep : cA; const char* nB = has_next ? (const char*)g.Bt + (size_t)nxt.pn * tstep : cB;
;         for (int t = 0; t < nt; t += 2) {
;             const bool last = (t == nt - 2);
;             const char* a1 = cA + (size_t)(t + 1) * kstep;
;             const char* a2 = last ? nA : cA + (size_t)(t + 2) * kstep; const char* b2 = last ? nB : cB + (size_t)(t + 2) * kstep;
;             const char* a3 = a2 + kstep; const char* b3 = b2 + kstep;
;             PG8_LDB(B0, 0, 0); PG8_LDB(B1, 0, 1); PG8_SCHED; PG8_LDA(At, 0, 0); PG8_STAGE(PG8_SA(1, 1), a1 + hstep, voffA);
;             PG8_WAIT_V(8); PG8_WAIT_L(0); PG8_BAR; PG8_MMA(0, 0, At, B0); PG8_MMA(0, 1, At, B1); PG8_BAR; PG8_SCHED;
;             PG8_LDA(At, 0, 1); PG8_STAGE(PG8_SB(0, 0), b2, voffB); PG8_STAGE(PG8_SB(0, 1), b2 + hstep, voffB); PG8_STAGE(PG8_SA(0, 0), a2, voffA);
.LBB0_1427:
	s_ashr_i32 s43, s42, 31
	s_lshl_b64 s[10:11], s[42:43], 19
	s_add_u32 s44, s34, s10
	s_addc_u32 s45, s35, s11
	s_and_b64 s[10:11], s[0:1], exec
	s_cselect_b32 s12, s45, s7
	s_cselect_b32 s13, s44, s6
	s_ashr_i32 s41, s40, 31
	s_lshl_b64 s[10:11], s[40:41], 19
	s_add_u32 s46, s22, s10
	s_addc_u32 s47, s23, s11
	s_and_b64 s[10:11], s[0:1], exec
	s_cselect_b32 s14, s47, s9
	s_cselect_b32 s15, s46, s8
	s_add_u32 s6, s6, 0x40080
	s_addc_u32 s7, s7, 0
	s_add_u32 s16, s8, 0x100
	s_addc_u32 s17, s9, 0
	s_mov_b32 s41, -2
	ds_read_b128 v[146:149], v168
	ds_read_b128 v[150:153], v168 offset:1024
	ds_read_b128 v[154:157], v168 offset:2048
	ds_read_b128 v[158:161], v168 offset:3072
	ds_read_b128 v[172:175], v169
	ds_read_b128 v[176:179], v169 offset:1024
	ds_read_b128 v[180:183], v169 offset:2048
	ds_read_b128 v[184:187], v169 offset:3072
	s_add_u32 s8, s6, 0xfffc0080
	s_addc_u32 s9, s7, -1
	s_cmp_eq_u32 s41, 12
	s_cselect_b32 s11, s12, s9
	s_cselect_b32 s10, s13, s8
	s_cselect_b32 s9, s14, s17
	s_cselect_b32 s8, s15, s16
	v_lshl_add_u64 v[220:221], s[6:7], 0, v[138:139]
	s_add_i32 m0, s50, 0xc000
	ds_read_b128 v[188:191], v170
	ds_read_b128 v[192:195], v170 offset:1024
	ds_read_b128 v[196:199], v170 offset:2048
	ds_read_b128 v[200:203], v170 offset:3072
	ds_read_b128 v[204:207], v170 offset:4096
	ds_read_b128 v[208:211], v170 offset:5120
	ds_read_b128 v[212:215], v170 offset:6144
	ds_read_b128 v[216:219], v170 offset:7168
	global_load_lds_dwordx4 v[220:221], off
	v_lshl_add_u64 v[220:221], s[6:7], 0, v[140:141]
	s_add_i32 m0, s50, 0xe000
	s_nop 0
	global_load_lds_dwordx4 v[220:221], off
	s_waitcnt vmcnt(8)
	s_waitcnt lgkmcnt(0)
	s_setprio 3
	s_barrier
	s_waitcnt lgkmcnt(0)
	v_mfma_f32_16x16x32_bf16 v[126:129], v[146:149], v[188:191], 0
	v_mfma_f32_16x16x32_bf16 v[118:121], v[154:157], v[188:191], 0
	v_mfma_f32_16x16x32_bf16 v[110:113], v[146:149], v[196:199], 0
	v_mfma_f32_16x16x32_bf16 v[102:105], v[154:157], v[196:199], 0
	v_mfma_f32_16x16x32_bf16 v[94:97], v[146:149], v[204:207], 0
	v_mfma_f32_16x16x32_bf16 v[86:89], v[154:157], v[204:207], 0
	v_mfma_f32_16x16x32_bf16 v[78:81], v[146:149], v[212:215], 0
	v_mfma_f32_16x16x32_bf16 v[70:73], v[154:157], v[212:215], 0
	v_mfma_f32_16x16x32_bf16 v[126:129], v[150:153], v[192:195], v[126:129]
	v_mfma_f32_16x16x32_bf16 v[118:121], v[158:161], v[192:195], v[118:121]
	v_mfma_f32_16x16x32_bf16 v[110:113], v[150:153], v[200:203], v[110:113]
	v_mfma_f32_16x16x32_bf16 v[102:105], v[158:161], v[200:203], v[102:105]
	v_mfma_f32_16x16x32_bf16 v[94:97], v[150:153], v[208:211], v[94:97]
	v_mfma_f32_16x16x32_bf16 v[86:89], v[158:161], v[208:211], v[86:89]
	v_mfma_f32_16x16x32_bf16 v[78:81], v[150:153], v[216:219], v[78:81]
	v_mfma_f32_16x16x32_bf16 v[70:73], v[158:161], v[216:219], v[70:73]
	v_mfma_f32_16x16x32_bf16 v[122:125], v[172:175], v[188:191], 0
	v_mfma_f32_16x16x32_bf16 v[114:117], v[180:183], v[188:191], 0
	v_mfma_f32_16x16x32_bf16 v[106:109], v[172:175], v[196:199], 0
	v_mfma_f32_16x16x32_bf16 v[98:101], v[180:183], v[196:199], 0
	v_mfma_f32_16x16x32_bf16 v[90:93], v[172:175], v[204:207], 0
	v_mfma_f32_16x16x32_bf16 v[82:85], v[180:183], v[204:207], 0
	v_mfma_f32_16x16x32_bf16 v[74:77], v[172:175], v[212:215], 0
	v_mfma_f32_16x16x32_bf16 v[66:69], v[180:183], v[212:215], 0
	v_mfma_f32_16x16x32_bf16 v[122:125], v[176:179], v[192:195], v[122:125]
	v_mfma_f32_16x16x32_bf16 v[114:117], v[184:187], v[192:195], v[114:117]
	v_mfma_f32_16x16x32_bf16 v[106:109], v[176:179], v[200:203], v[106:109]
	v_mfma_f32_16x16x32_bf16 v[98:101], v[184:187], v[200:203], v[98:101]
	v_mfma_f32_16x16x32_bf16 v[90:93], v[176:179], v[208:211], v[90:93]
	v_mfma_f32_16x16x32_bf16 v[82:85], v[184:187], v[208:211], v[82:85]
	v_mfma_f32_16x16x32_bf16 v[74:77], v[176:179], v[216:219], v[74:77]
	v_mfma_f32_16x16x32_bf16 v[66:69], v[184:187], v[216:219], v[66:69]
	s_barrier
	s_setprio 0
	s_add_i32 s43, s58, s33
	v_lshl_add_u64 v[220:221], s[8:9], 0, v[132:133]
	s_mov_b32 m0, s43
	ds_read_b128 v[188:191], v170 offset:16384
	ds_read_b128 v[192:195], v170 offset:17408
	ds_read_b128 v[196:199], v170 offset:18432
	ds_read_b128 v[200:203], v170 offset:19456
	ds_read_b128 v[204:207], v170 offset:20480
	ds_read_b128 v[208:211], v170 offset:21504
	ds_read_b128 v[212:215], v170 offset:22528
	ds_read_b128 v[216:219], v170 offset:23552
	global_load_lds_dwordx4 v[220:221], off
	s_add_i32 m0, s43, 0x2000
	s_add_u32 s62, s8, 0x40000
	v_lshl_add_u64 v[222:223], s[8:9], 0, v[136:137]
	s_addc_u32 s63, s9, 0
	s_add_i32 s43, s59, s33
	global_load_lds_dwordx4 v[222:223], off
	v_lshl_add_u64 v[224:225], s[62:63], 0, v[132:133]
	s_mov_b32 m0, s43
	v_lshl_add_u64 v[226:227], s[10:11], 0, v[134:135]
	global_load_lds_dwordx4 v[224:225], off
	v_lshl_add_u64 v[224:225], s[62:63], 0, v[136:137]
	s_add_i32 m0, s43, 0x2000
	s_nop 0
	global_load_lds_dwordx4 v[224:225], off
	v_lshl_add_u64 v[224:225], s[10:11], 0, v[130:131]
	s_mov_b32 m0, s50
	s_nop 0
	global_load_lds_dwordx4 v[224:225], off
	s_mov_b32 m0, s51
	s_nop 0
	global_load_lds_dwordx4 v[226:227], off
	s_waitcnt vmcnt(8)
	s_waitcnt lgkmcnt(0)
	s_setprio 3
	s_barrier
; #define PG8_STAGE(bufoff, gbase, voff) do { _Pragma("unroll") for (int _i = 0; _i < 2; ++_i) \
;         __builtin_amdgcn_global_load_lds((const unsigned*)((const char*)(gbase) + (voff)[_i]), (LAS unsigned*)(lds + (bufoff) + ldsw + _i * 8192), 16, 0, 0); } while (0)
; #define PG8_LDA(dst, b, h) do { _Pragma("unroll") for (int m = 0; m < 4; ++m) _Pragma("unroll") for (int k = 0; k < 2; ++k) dst[m][k] = *(const LAS bf16x8*)(lds + PG8_SA(b, h) + aoff + m * 2048 + k * 1024); } while (0)
; #define PG8_LDB(dst, b, h) do { _Pragma("unroll") for (int n = 0; n < 2; ++n) _Pragma("unroll") for (int k = 0; k < 2; ++k) dst[n][k] = *(const LAS bf16x8*)(lds + PG8_SB(b, h) + boff + n * 2048 + k * 1024); } while (0)
; #define PG8_MMA(ai, bj, At, Bt) do { __builtin_amdgcn_s_setprio(3); _Pragma("unroll") for (int m = 0; m < 4; ++m) _Pragma("unroll") for (int n = 0; n < 2; ++n) _Pragma("unroll") for (int k = 0; k < 2; ++k) \
;         acc[ai][bj][m][n] = __builtin_amdgcn_mfma_f32_16x16x32_bf16(Bt[n][k], At[m][k], acc[ai][bj][m][n], 0, 0, 0); __builtin_amdgcn_s_setprio(0); } while (0)
; #define PG8_WAIT_V(n) asm volatile("s_waitcnt vmcnt(" #n ")" ::: "memory")
; #define PG8_WAIT_L(n) asm volatile("s_waitcnt lgkmcnt(" #n ")" ::: "memory")
; #define PG8_BAR __builtin_amdgcn_s_barrier()
; #define PG8_SCHED __builtin_amdgcn_sched_barrier(0)
; template <class Epi, bool ALIGN_EPI>
; __device__ __forceinline__ void gemm_phase(LAS unsigned char* lds, const Gemm g, const StaticOrder& S, const Epi& E) {
;     ...
;             PG8_WAIT_V(8); PG8_WAIT_L(0); PG8_BAR; PG8_MMA(1, 0, At, B0); PG8_MMA(1, 1, At, B1); PG8_BAR; PG8_SCHED;
;             PG8_LDB(B0, 1, 0); PG8_LDB(B1, 1, 1); PG8_SCHED; PG8_LDA(At, 1, 0); PG8_STAGE(PG8_SA(0, 1), a2 + hstep, voffA);
;             PG8_WAIT_V(8); PG8_WAIT_L(0); PG8_BAR; PG8_MMA(0, 0, At, B0); PG8_MMA(0, 1, At, B1); PG8_BAR; PG8_SCHED;
	s_waitcnt lgkmcnt(0)
	v_mfma_f32_16x16x32_bf16 v[62:65], v[146:149], v[188:191], 0
	v_mfma_f32_16x16x32_bf16 v[54:57], v[154:157], v[188:191], 0
	v_mfma_f32_16x16x32_bf16 v[46:49], v[146:149], v[196:199], 0
	v_mfma_f32_16x16x32_bf16 v[38:41], v[154:157], v[196:199], 0
	v_mfma_f32_16x16x32_bf16 v[30:33], v[146:149], v[204:207], 0
	v_mfma_f32_16x16x32_bf16 v[22:25], v[154:157], v[204:207], 0
	v_mfma_f32_16x16x32_bf16 v[14:17], v[146:149], v[212:215], 0
	v_mfma_f32_16x16x32_bf16 v[6:9], v[154:157], v[212:215], 0
	v_mfma_f32_16x16x32_bf16 v[62:65], v[150:153], v[192:195], v[62:65]
	v_mfma_f32_16x16x32_bf16 v[54:57], v[158:161], v[192:195], v[54:57]
	v_mfma_f32_16x16x32_bf16 v[46:49], v[150:153], v[200:203], v[46:49]
	v_mfma_f32_16x16x32_bf16 v[38:41], v[158:161], v[200:203], v[38:41]
	v_mfma_f32_16x16x32_bf16 v[30:33], v[150:153], v[208:211], v[30:33]
	v_mfma_f32_16x16x32_bf16 v[22:25], v[158:161], v[208:211], v[22:25]
	v_mfma_f32_16x16x32_bf16 v[14:17], v[150:153], v[216:219], v[14:17]
	v_mfma_f32_16x16x32_bf16 v[6:9], v[158:161], v[216:219], v[6:9]
	v_mfma_f32_16x16x32_bf16 v[58:61], v[172:175], v[188:191], 0
	v_mfma_f32_16x16x32_bf16 v[50:53], v[180:183], v[188:191], 0
	v_mfma_f32_16x16x32_bf16 v[42:45], v[172:175], v[196:199], 0
	v_mfma_f32_16x16x32_bf16 v[34:37], v[180:183], v[196:199], 0
	v_mfma_f32_16x16x32_bf16 v[26:29], v[172:175], v[204:207], 0
	v_mfma_f32_16x16x32_bf16 v[18:21], v[180:183], v[204:207], 0
	v_mfma_f32_16x16x32_bf16 v[10:13], v[172:175], v[212:215], 0
	v_mfma_f32_16x16x32_bf16 v[2:5], v[180:183], v[212:215], 0
	v_mfma_f32_16x16x32_bf16 v[58:61], v[176:179], v[192:195], v[58:61]
	v_mfma_f32_16x16x32_bf16 v[50:53], v[184:187], v[192:195], v[50:53]
	v_mfma_f32_16x16x32_bf16 v[42:45], v[176:179], v[200:203], v[42:45]
	v_mfma_f32_16x16x32_bf16 v[34:37], v[184:187], v[200:203], v[34:37]
	v_mfma_f32_16x16x32_bf16 v[26:29], v[176:179], v[208:211], v[26:29]
	v_mfma_f32_16x16x32_bf16 v[18:21], v[184:187], v[208:211], v[18:21]
	v_mfma_f32_16x16x32_bf16 v[10:13], v[176:179], v[216:219], v[10:13]
	v_mfma_f32_16x16x32_bf16 v[2:5], v[184:187], v[216:219], v[2:5]
	s_barrier
	s_setprio 0
	s_add_i32 s43, 0, 0x18000
	s_add_i32 s62, 0, 0x1c000
	v_add_u32_e32 v158, s43, v166
	v_add_u32_e32 v184, s62, v166
	ds_read_b128 v[146:149], v158
	ds_read_b128 v[150:153], v158 offset:1024
	ds_read_b128 v[154:157], v158 offset:2048
	ds_read_b128 v[158:161], v158 offset:3072
	ds_read_b128 v[172:175], v184
	ds_read_b128 v[176:179], v184 offset:1024
	ds_read_b128 v[180:183], v184 offset:2048
	ds_read_b128 v[184:187], v184 offset:3072
	s_add_u32 s10, s10, 0x40000
	s_addc_u32 s11, s11, 0
	s_mov_b32 m0, s52
	v_lshl_add_u64 v[228:229], s[10:11], 0, v[130:131]
	ds_read_b128 v[188:191], v170 offset:32768
	ds_read_b128 v[192:195], v170 offset:33792
	ds_read_b128 v[196:199], v170 offset:34816
	ds_read_b128 v[200:203], v170 offset:35840
	ds_read_b128 v[204:207], v170 offset:36864
	ds_read_b128 v[208:211], v170 offset:37888
	ds_read_b128 v[212:215], v170 offset:38912
	ds_read_b128 v[216:219], v170 offset:39936
	global_load_lds_dwordx4 v[228:229], off
	v_lshl_add_u64 v[228:229], s[10:11], 0, v[134:135]
	s_mov_b32 m0, s53
	s_nop 0
	global_load_lds_dwordx4 v[228:229], off
	s_waitcnt vmcnt(8)
	s_waitcnt lgkmcnt(0)
	s_setprio 3
	s_barrier
	s_waitcnt lgkmcnt(0)
	v_mfma_f32_16x16x32_bf16 v[126:129], v[146:149], v[188:191], v[126:129]
	v_mfma_f32_16x16x32_bf16 v[118:121], v[154:157], v[188:191], v[118:121]
	v_mfma_f32_16x16x32_bf16 v[110:113], v[146:149], v[196:199], v[110:113]
	v_mfma_f32_16x16x32_bf16 v[102:105], v[154:157], v[196:199], v[102:105]
	v_mfma_f32_16x16x32_bf16 v[94:97], v[146:149], v[204:207], v[94:97]
	v_mfma_f32_16x16x32_bf16 v[86:89], v[154:157], v[204:207], v[86:89]
	v_mfma_f32_16x16x32_bf16 v[78:81], v[146:149], v[212:215], v[78:81]
	v_mfma_f32_16x16x32_bf16 v[70:73], v[154:157], v[212:215], v[70:73]
	v_mfma_f32_16x16x32_bf16 v[126:129], v[150:153], v[192:195], v[126:129]
	v_mfma_f32_16x16x32_bf16 v[118:121], v[158:161], v[192:195], v[118:121]
	v_mfma_f32_16x16x32_bf16 v[110:113], v[150:153], v[200:203], v[110:113]
	v_mfma_f32_16x16x32_bf16 v[102:105], v[158:161], v[200:203], v[102:105]
	v_mfma_f32_16x16x32_bf16 v[94:97], v[150:153], v[208:211], v[94:97]
	v_mfma_f32_16x16x32_bf16 v[86:89], v[158:161], v[208:211], v[86:89]
	v_mfma_f32_16x16x32_bf16 v[78:81], v[150:153], v[216:219], v[78:81]
	v_mfma_f32_16x16x32_bf16 v[70:73], v[158:161], v[216:219], v[70:73]
	v_mfma_f32_16x16x32_bf16 v[122:125], v[172:175], v[188:191], v[122:125]
	v_mfma_f32_16x16x32_bf16 v[114:117], v[180:183], v[188:191], v[114:117]
	v_mfma_f32_16x16x32_bf16 v[106:109], v[172:175], v[196:199], v[106:109]
	v_mfma_f32_16x16x32_bf16 v[98:101], v[180:183], v[196:199], v[98:101]
	v_mfma_f32_16x16x32_bf16 v[90:93], v[172:175], v[204:207], v[90:93]
	v_mfma_f32_16x16x32_bf16 v[82:85], v[180:183], v[204:207], v[82:85]
	v_mfma_f32_16x16x32_bf16 v[74:77], v[172:175], v[212:215], v[74:77]
	v_mfma_f32_16x16x32_bf16 v[66:69], v[180:183], v[212:215], v[66:69]
	v_mfma_f32_16x16x32_bf16 v[122:125], v[176:179], v[192:195], v[122:125]
	v_mfma_f32_16x16x32_bf16 v[114:117], v[184:187], v[192:195], v[114:117]
	v_mfma_f32_16x16x32_bf16 v[106:109], v[176:179], v[200:203], v[106:109]
	v_mfma_f32_16x16x32_bf16 v[98:101], v[184:187], v[200:203], v[98:101]
	v_mfma_f32_16x16x32_bf16 v[90:93], v[176:179], v[208:211], v[90:93]
	v_mfma_f32_16x16x32_bf16 v[82:85], v[184:187], v[208:211], v[82:85]
	v_mfma_f32_16x16x32_bf16 v[74:77], v[176:179], v[216:219], v[74:77]
	v_mfma_f32_16x16x32_bf16 v[66:69], v[184:187], v[216:219], v[66:69]
	s_barrier
; #define PG8_STAGE(bufoff, gbase, voff) do { _Pragma("unroll") for (int _i = 0; _i < 2; ++_i) \
;         __builtin_amdgcn_global_load_lds((const unsigned*)((const char*)(gbase) + (voff)[_i]), (LAS unsigned*)(lds + (bufoff) + ldsw + _i * 8192), 16, 0, 0); } while (0)
; #define PG8_LDA(dst, b, h) do { _Pragma("unroll") for (int m = 0; m < 4; ++m) _Pragma("unroll") for (int k = 0; k < 2; ++k) dst[m][k] = *(const LAS bf16x8*)(lds + PG8_SA(b, h) + aoff + m * 2048 + k * 1024); } while (0)
; #define PG8_LDB(dst, b, h) do { _Pragma("unroll") for (int n = 0; n < 2; ++n) _Pragma("unroll") for (int k = 0; k < 2; ++k) dst[n][k] = *(const LAS bf16x8*)(lds + PG8_SB(b, h) + boff + n * 2048 + k * 1024); } while (0)
; #define PG8_MMA(ai, bj, At, Bt) do { __builtin_amdgcn_s_setprio(3); _Pragma("unroll") for (int m = 0; m < 4; ++m) _Pragma("unroll") for (int n = 0; n < 2; ++n) _Pragma("unroll") for (int k = 0; k < 2; ++k) \
;         acc[ai][bj][m][n] = __builtin_amdgcn_mfma_f32_16x16x32_bf16(Bt[n][k], At[m][k], acc[ai][bj][m][n], 0, 0, 0); __builtin_amdgcn_s_setprio(0); } while (0)
; #define PG8_WAIT_V(n) asm volatile("s_waitcnt vmcnt(" #n ")" ::: "memory")
; #define PG8_BAR __builtin_amdgcn_s_barrier()
; template <class Epi, bool ALIGN_EPI>
; __device__ __forceinline__ void gemm_phase(LAS unsigned char* lds, const Gemm g, const StaticOrder& S, const Epi& E) {
;     ...
;             PG8_LDB(B0, 0, 0); PG8_LDB(B1, 0, 1); PG8_SCHED; PG8_LDA(At, 0, 0); PG8_STAGE(PG8_SA(1, 1), a1 + hstep, voffA);
;             PG8_WAIT_V(8); PG8_WAIT_L(0); PG8_BAR; PG8_MMA(0, 0, At, B0); PG8_MMA(0, 1, At, B1); PG8_BAR; PG8_SCHED;
;             PG8_LDA(At, 0, 1); PG8_STAGE(PG8_SB(0, 0), b2, voffB); PG8_STAGE(PG8_SB(0, 1), b2 + hstep, voffB); PG8_STAGE(PG8_SA(0, 0), a2, voffA);
;             PG8_WAIT_V(8); PG8_WAIT_L(0); PG8_BAR; PG8_MMA(1, 0, At, B0); PG8_MMA(1, 1, At, B1); PG8_BAR; PG8_SCHED;
;             PG8_LDB(B0, 1, 0); PG8_LDB(B1, 1, 1); PG8_SCHED; PG8_LDA(At, 1, 0); PG8_STAGE(PG8_SA(0, 1), a2 + hstep, voffA);
;             PG8_WAIT_V(8); PG8_WAIT_L(0); PG8_BAR; PG8_MMA(0, 0, At, B0); PG8_MMA(0, 1, At, B1); PG8_BAR; PG8_SCHED;
;             PG8_LDA(At, 1, 1); PG8_STAGE(PG8_SB(1, 0), b3, voffB); PG8_STAGE(PG8_SB(1, 1), b3 + hstep, voffB); PG8_STAGE(PG8_SA(1, 0), a3, voffA);
;             PG8_WAIT_V(8); PG8_WAIT_L(0); PG8_BAR; PG8_MMA(1, 0, At, B0); PG8_MMA(1, 1, At, B1); PG8_BAR; PG8_SCHED;
	s_setprio 0
	s_add_i32 s10, s43, s33
	v_lshl_add_u64 v[220:221], v[220:221], 0, s[36:37]
	s_mov_b32 m0, s10
	ds_read_b128 v[188:191], v170 offset:49152
	ds_read_b128 v[192:195], v170 offset:50176
	ds_read_b128 v[196:199], v170 offset:51200
	ds_read_b128 v[200:203], v170 offset:52224
	ds_read_b128 v[204:207], v170 offset:53248
	ds_read_b128 v[208:211], v170 offset:54272
	ds_read_b128 v[212:215], v170 offset:55296
	ds_read_b128 v[216:219], v170 offset:56320
	global_load_lds_dwordx4 v[220:221], off
	s_add_i32 m0, s10, 0x2000
	s_add_u32 s8, s8, 0x40080
	v_lshl_add_u64 v[220:221], v[222:223], 0, s[36:37]
	s_addc_u32 s9, s9, 0
	s_add_i32 s10, s62, s33
	global_load_lds_dwordx4 v[220:221], off
	v_lshl_add_u64 v[220:221], s[8:9], 0, v[132:133]
	s_mov_b32 m0, s10
	s_nop 0
	global_load_lds_dwordx4 v[220:221], off
	v_lshl_add_u64 v[220:221], s[8:9], 0, v[136:137]
	s_add_i32 m0, s10, 0x2000
	s_nop 0
	global_load_lds_dwordx4 v[220:221], off
	v_lshl_add_u64 v[220:221], v[224:225], 0, s[36:37]
	s_mov_b32 m0, s56
	s_nop 0
	global_load_lds_dwordx4 v[220:221], off
	v_lshl_add_u64 v[220:221], v[226:227], 0, s[36:37]
	s_mov_b32 m0, s57
	s_nop 0
	global_load_lds_dwordx4 v[220:221], off
	s_waitcnt vmcnt(8)
	s_waitcnt lgkmcnt(0)
	s_setprio 3
	s_barrier
	s_waitcnt lgkmcnt(0)
	v_mfma_f32_16x16x32_bf16 v[62:65], v[146:149], v[188:191], v[62:65]
	v_mfma_f32_16x16x32_bf16 v[54:57], v[154:157], v[188:191], v[54:57]
	v_mfma_f32_16x16x32_bf16 v[46:49], v[146:149], v[196:199], v[46:49]
	v_mfma_f32_16x16x32_bf16 v[38:41], v[154:157], v[196:199], v[38:41]
	v_mfma_f32_16x16x32_bf16 v[30:33], v[146:149], v[204:207], v[30:33]
	v_mfma_f32_16x16x32_bf16 v[22:25], v[154:157], v[204:207], v[22:25]
	v_mfma_f32_16x16x32_bf16 v[14:17], v[146:149], v[212:215], v[14:17]
	v_mfma_f32_16x16x32_bf16 v[6:9], v[154:157], v[212:215], v[6:9]
	v_mfma_f32_16x16x32_bf16 v[62:65], v[150:153], v[192:195], v[62:65]
	v_mfma_f32_16x16x32_bf16 v[54:57], v[158:161], v[192:195], v[54:57]
	v_mfma_f32_16x16x32_bf16 v[46:49], v[150:153], v[200:203], v[46:49]
	v_mfma_f32_16x16x32_bf16 v[38:41], v[158:161], v[200:203], v[38:41]
	v_mfma_f32_16x16x32_bf16 v[30:33], v[150:153], v[208:211], v[30:33]
	v_mfma_f32_16x16x32_bf16 v[22:25], v[158:161], v[208:211], v[22:25]
	v_mfma_f32_16x16x32_bf16 v[14:17], v[150:153], v[216:219], v[14:17]
	v_mfma_f32_16x16x32_bf16 v[6:9], v[158:161], v[216:219], v[6:9]
	v_mfma_f32_16x16x32_bf16 v[58:61], v[172:175], v[188:191], v[58:61]
	v_mfma_f32_16x16x32_bf16 v[50:53], v[180:183], v[188:191], v[50:53]
	v_mfma_f32_16x16x32_bf16 v[42:45], v[172:175], v[196:199], v[42:45]
	v_mfma_f32_16x16x32_bf16 v[34:37], v[180:183], v[196:199], v[34:37]
	v_mfma_f32_16x16x32_bf16 v[26:29], v[172:175], v[204:207], v[26:29]
	v_mfma_f32_16x16x32_bf16 v[18:21], v[180:183], v[204:207], v[18:21]
	v_mfma_f32_16x16x32_bf16 v[10:13], v[172:175], v[212:215], v[10:13]
	v_mfma_f32_16x16x32_bf16 v[2:5], v[180:183], v[212:215], v[2:5]
	v_mfma_f32_16x16x32_bf16 v[58:61], v[176:179], v[192:195], v[58:61]
	v_mfma_f32_16x16x32_bf16 v[50:53], v[184:187], v[192:195], v[50:53]
	v_mfma_f32_16x16x32_bf16 v[42:45], v[176:179], v[200:203], v[42:45]
	v_mfma_f32_16x16x32_bf16 v[34:37], v[184:187], v[200:203], v[34:37]
	v_mfma_f32_16x16x32_bf16 v[26:29], v[176:179], v[208:211], v[26:29]
	v_mfma_f32_16x16x32_bf16 v[18:21], v[184:187], v[208:211], v[18:21]
	v_mfma_f32_16x16x32_bf16 v[10:13], v[176:179], v[216:219], v[10:13]
	v_mfma_f32_16x16x32_bf16 v[2:5], v[184:187], v[216:219], v[2:5]
	s_barrier
	s_setprio 0
	s_add_i32 s41, s41, 2
	s_add_u32 s6, s6, 0x100
	s_addc_u32 s7, s7, 0
	s_add_u32 s16, s16, 0x100
	s_addc_u32 s17, s17, 0
.LBB0_1428:
	ds_read_b128 v[146:149], v168
	ds_read_b128 v[150:153], v168 offset:1024
	ds_read_b128 v[154:157], v168 offset:2048
	ds_read_b128 v[158:161], v168 offset:3072
	ds_read_b128 v[172:175], v169
	ds_read_b128 v[176:179], v169 offset:1024
	ds_read_b128 v[180:183], v169 offset:2048
	ds_read_b128 v[184:187], v169 offset:3072
	s_add_u32 s8, s6, 0xfffc0080
	s_addc_u32 s9, s7, -1
	s_cmp_eq_u32 s41, 12
	s_cselect_b32 s11, s12, s9
	s_cselect_b32 s10, s13, s8
	s_cselect_b32 s9, s14, s17
	s_cselect_b32 s8, s15, s16
	v_lshl_add_u64 v[220:221], s[6:7], 0, v[138:139]
	s_add_i32 m0, s50, 0xc000
	ds_read_b128 v[188:191], v170
	ds_read_b128 v[192:195], v170 offset:1024
	ds_read_b128 v[196:199], v170 offset:2048
	ds_read_b128 v[200:203], v170 offset:3072
	ds_read_b128 v[204:207], v170 offset:4096
	ds_read_b128 v[208:211], v170 offset:5120
	ds_read_b128 v[212:215], v170 offset:6144
	ds_read_b128 v[216:219], v170 offset:7168
	global_load_lds_dwordx4 v[220:221], off
	v_lshl_add_u64 v[220:221], s[6:7], 0, v[140:141]
	s_add_i32 m0, s50, 0xe000
	s_nop 0
	global_load_lds_dwordx4 v[220:221], off
	s_waitcnt vmcnt(8)
	s_waitcnt lgkmcnt(0)
	s_setprio 3
	s_barrier
; #define PG8_STAGE(bufoff, gbase, voff) do { _Pragma("unroll") for (int _i = 0; _i < 2; ++_i) \
;         __builtin_amdgcn_global_load_lds((const unsigned*)((const char*)(gbase) + (voff)[_i]), (LAS unsigned*)(lds + (bufoff) + ldsw + _i * 8192), 16, 0, 0); } while (0)
; #define PG8_LDA(dst, b, h) do { _Pragma("unroll") for (int m = 0; m < 4; ++m) _Pragma("unroll") for (int k = 0; k < 2; ++k) dst[m][k] = *(const LAS bf16x8*)(lds + PG8_SA(b, h) + aoff + m * 2048 + k * 1024); } while (0)
; #define PG8_MMA(ai, bj, At, Bt) do { __builtin_amdgcn_s_setprio(3); _Pragma("unroll") for (int m = 0; m < 4; ++m) _Pragma("unroll") for (int n = 0; n < 2; ++n) _Pragma("unroll") for (int k = 0; k < 2; ++k) \
;         acc[ai][bj][m][n] = __builtin_amdgcn_mfma_f32_16x16x32_bf16(Bt[n][k], At[m][k], acc[ai][bj][m][n], 0, 0, 0); __builtin_amdgcn_s_setprio(0); } while (0)
; #define PG8_WAIT_V(n) asm volatile("s_waitcnt vmcnt(" #n ")" ::: "memory")
; #define PG8_WAIT_L(n) asm volatile("s_waitcnt lgkmcnt(" #n ")" ::: "memory")
; #define PG8_BAR __builtin_amdgcn_s_barrier()
; #define PG8_SCHED __builtin_amdgcn_sched_barrier(0)
; template <class Epi, bool ALIGN_EPI>
; __device__ __forceinline__ void gemm_phase(LAS unsigned char* lds, const Gemm g, const StaticOrder& S, const Epi& E) {
;     ...
;             PG8_WAIT_V(8); PG8_WAIT_L(0); PG8_BAR; PG8_MMA(0, 0, At, B0); PG8_MMA(0, 1, At, B1); PG8_BAR; PG8_SCHED;
;             PG8_LDA(At, 0, 1); PG8_STAGE(PG8_SB(0, 0), b2, voffB); PG8_STAGE(PG8_SB(0, 1), b2 + hstep, voffB); PG8_STAGE(PG8_SA(0, 0), a2, voffA);
;             PG8_WAIT_V(8); PG8_WAIT_L(0); PG8_BAR; PG8_MMA(1, 0, At, B0); PG8_MMA(1, 1, At, B1); PG8_BAR; PG8_SCHED;
	s_waitcnt lgkmcnt(0)
	v_mfma_f32_16x16x32_bf16 v[126:129], v[146:149], v[188:191], v[126:129]
	v_mfma_f32_16x16x32_bf16 v[118:121], v[154:157], v[188:191], v[118:121]
	v_mfma_f32_16x16x32_bf16 v[110:113], v[146:149], v[196:199], v[110:113]
	v_mfma_f32_16x16x32_bf16 v[102:105], v[154:157], v[196:199], v[102:105]
	v_mfma_f32_16x16x32_bf16 v[94:97], v[146:149], v[204:207], v[94:97]
	v_mfma_f32_16x16x32_bf16 v[86:89], v[154:157], v[204:207], v[86:89]
	v_mfma_f32_16x16x32_bf16 v[78:81], v[146:149], v[212:215], v[78:81]
	v_mfma_f32_16x16x32_bf16 v[70:73], v[154:157], v[212:215], v[70:73]
	v_mfma_f32_16x16x32_bf16 v[126:129], v[150:153], v[192:195], v[126:129]
	v_mfma_f32_16x16x32_bf16 v[118:121], v[158:161], v[192:195], v[118:121]
	v_mfma_f32_16x16x32_bf16 v[110:113], v[150:153], v[200:203], v[110:113]
	v_mfma_f32_16x16x32_bf16 v[102:105], v[158:161], v[200:203], v[102:105]
	v_mfma_f32_16x16x32_bf16 v[94:97], v[150:153], v[208:211], v[94:97]
	v_mfma_f32_16x16x32_bf16 v[86:89], v[158:161], v[208:211], v[86:89]
	v_mfma_f32_16x16x32_bf16 v[78:81], v[150:153], v[216:219], v[78:81]
	v_mfma_f32_16x16x32_bf16 v[70:73], v[158:161], v[216:219], v[70:73]
	v_mfma_f32_16x16x32_bf16 v[122:125], v[172:175], v[188:191], v[122:125]
	v_mfma_f32_16x16x32_bf16 v[114:117], v[180:183], v[188:191], v[114:117]
	v_mfma_f32_16x16x32_bf16 v[106:109], v[172:175], v[196:199], v[106:109]
	v_mfma_f32_16x16x32_bf16 v[98:101], v[180:183], v[196:199], v[98:101]
	v_mfma_f32_16x16x32_bf16 v[90:93], v[172:175], v[204:207], v[90:93]
	v_mfma_f32_16x16x32_bf16 v[82:85], v[180:183], v[204:207], v[82:85]
	v_mfma_f32_16x16x32_bf16 v[74:77], v[172:175], v[212:215], v[74:77]
	v_mfma_f32_16x16x32_bf16 v[66:69], v[180:183], v[212:215], v[66:69]
	v_mfma_f32_16x16x32_bf16 v[122:125], v[176:179], v[192:195], v[122:125]
	v_mfma_f32_16x16x32_bf16 v[114:117], v[184:187], v[192:195], v[114:117]
	v_mfma_f32_16x16x32_bf16 v[106:109], v[176:179], v[200:203], v[106:109]
	v_mfma_f32_16x16x32_bf16 v[98:101], v[184:187], v[200:203], v[98:101]
	v_mfma_f32_16x16x32_bf16 v[90:93], v[176:179], v[208:211], v[90:93]
	v_mfma_f32_16x16x32_bf16 v[82:85], v[184:187], v[208:211], v[82:85]
	v_mfma_f32_16x16x32_bf16 v[74:77], v[176:179], v[216:219], v[74:77]
	v_mfma_f32_16x16x32_bf16 v[66:69], v[184:187], v[216:219], v[66:69]
	s_barrier
	s_setprio 0
	s_add_i32 s43, s58, s33
	v_lshl_add_u64 v[220:221], s[8:9], 0, v[132:133]
	s_mov_b32 m0, s43
	ds_read_b128 v[188:191], v170 offset:16384
	ds_read_b128 v[192:195], v170 offset:17408
	ds_read_b128 v[196:199], v170 offset:18432
	ds_read_b128 v[200:203], v170 offset:19456
	ds_read_b128 v[204:207], v170 offset:20480
	ds_read_b128 v[208:211], v170 offset:21504
	ds_read_b128 v[212:215], v170 offset:22528
	ds_read_b128 v[216:219], v170 offset:23552
	global_load_lds_dwordx4 v[220:221], off
	s_add_i32 m0, s43, 0x2000
	s_add_u32 s62, s8, 0x40000
	v_lshl_add_u64 v[222:223], s[8:9], 0, v[136:137]
	s_addc_u32 s63, s9, 0
	s_add_i32 s43, s59, s33
	global_load_lds_dwordx4 v[222:223], off
	v_lshl_add_u64 v[224:225], s[62:63], 0, v[132:133]
	s_mov_b32 m0, s43
	v_lshl_add_u64 v[226:227], s[10:11], 0, v[134:135]
	global_load_lds_dwordx4 v[224:225], off
	v_lshl_add_u64 v[224:225], s[62:63], 0, v[136:137]
	s_add_i32 m0, s43, 0x2000
	s_nop 0
	global_load_lds_dwordx4 v[224:225], off
	v_lshl_add_u64 v[224:225], s[10:11], 0, v[130:131]
	s_mov_b32 m0, s50
	s_nop 0
	global_load_lds_dwordx4 v[224:225], off
	s_mov_b32 m0, s51
	s_nop 0
	global_load_lds_dwordx4 v[226:227], off
	s_waitcnt vmcnt(8)
	s_waitcnt lgkmcnt(0)
	s_setprio 3
	s_barrier
	s_waitcnt lgkmcnt(0)
	v_mfma_f32_16x16x32_bf16 v[62:65], v[146:149], v[188:191], v[62:65]
	v_mfma_f32_16x16x32_bf16 v[54:57], v[154:157], v[188:191], v[54:57]
	v_mfma_f32_16x16x32_bf16 v[46:49], v[146:149], v[196:199], v[46:49]
	v_mfma_f32_16x16x32_bf16 v[38:41], v[154:157], v[196:199], v[38:41]
	v_mfma_f32_16x16x32_bf16 v[30:33], v[146:149], v[204:207], v[30:33]
	v_mfma_f32_16x16x32_bf16 v[22:25], v[154:157], v[204:207], v[22:25]
	v_mfma_f32_16x16x32_bf16 v[14:17], v[146:149], v[212:215], v[14:17]
	v_mfma_f32_16x16x32_bf16 v[6:9], v[154:157], v[212:215], v[6:9]
	v_mfma_f32_16x16x32_bf16 v[62:65], v[150:153], v[192:195], v[62:65]
	v_mfma_f32_16x16x32_bf16 v[54:57], v[158:161], v[192:195], v[54:57]
	v_mfma_f32_16x16x32_bf16 v[46:49], v[150:153], v[200:203], v[46:49]
	v_mfma_f32_16x16x32_bf16 v[38:41], v[158:161], v[200:203], v[38:41]
	v_mfma_f32_16x16x32_bf16 v[30:33], v[150:153], v[208:211], v[30:33]
	v_mfma_f32_16x16x32_bf16 v[22:25], v[158:161], v[208:211], v[22:25]
	v_mfma_f32_16x16x32_bf16 v[14:17], v[150:153], v[216:219], v[14:17]
	v_mfma_f32_16x16x32_bf16 v[6:9], v[158:161], v[216:219], v[6:9]
	v_mfma_f32_16x16x32_bf16 v[58:61], v[172:175], v[188:191], v[58:61]
	v_mfma_f32_16x16x32_bf16 v[50:53], v[180:183], v[188:191], v[50:53]
	v_mfma_f32_16x16x32_bf16 v[42:45], v[172:175], v[196:199], v[42:45]
	v_mfma_f32_16x16x32_bf16 v[34:37], v[180:183], v[196:199], v[34:37]
	v_mfma_f32_16x16x32_bf16 v[26:29], v[172:175], v[204:207], v[26:29]
	v_mfma_f32_16x16x32_bf16 v[18:21], v[180:183], v[204:207], v[18:21]
	v_mfma_f32_16x16x32_bf16 v[10:13], v[172:175], v[212:215], v[10:13]
	v_mfma_f32_16x16x32_bf16 v[2:5], v[180:183], v[212:215], v[2:5]
	v_mfma_f32_16x16x32_bf16 v[58:61], v[176:179], v[192:195], v[58:61]
	v_mfma_f32_16x16x32_bf16 v[50:53], v[184:187], v[192:195], v[50:53]
	v_mfma_f32_16x16x32_bf16 v[42:45], v[176:179], v[200:203], v[42:45]
	v_mfma_f32_16x16x32_bf16 v[34:37], v[184:187], v[200:203], v[34:37]
	v_mfma_f32_16x16x32_bf16 v[26:29], v[176:179], v[208:211], v[26:29]
	v_mfma_f32_16x16x32_bf16 v[18:21], v[184:187], v[208:211], v[18:21]
	v_mfma_f32_16x16x32_bf16 v[10:13], v[176:179], v[216:219], v[10:13]
	v_mfma_f32_16x16x32_bf16 v[2:5], v[184:187], v[216:219], v[2:5]
	s_barrier
; #define PG8_STAGE(bufoff, gbase, voff) do { _Pragma("unroll") for (int _i = 0; _i < 2; ++_i) \
;         __builtin_amdgcn_global_load_lds((const unsigned*)((const char*)(gbase) + (voff)[_i]), (LAS unsigned*)(lds + (bufoff) + ldsw + _i * 8192), 16, 0, 0); } while (0)
; #define PG8_LDA(dst, b, h) do { _Pragma("unroll") for (int m = 0; m < 4; ++m) _Pragma("unroll") for (int k = 0; k < 2; ++k) dst[m][k] = *(const LAS bf16x8*)(lds + PG8_SA(b, h) + aoff + m * 2048 + k * 1024); } while (0)
; #define PG8_LDB(dst, b, h) do { _Pragma("unroll") for (int n = 0; n < 2; ++n) _Pragma("unroll") for (int k = 0; k < 2; ++k) dst[n][k] = *(const LAS bf16x8*)(lds + PG8_SB(b, h) + boff + n * 2048 + k * 1024); } while (0)
; #define PG8_MMA(ai, bj, At, Bt) do { __builtin_amdgcn_s_setprio(3); _Pragma("unroll") for (int m = 0; m < 4; ++m) _Pragma("unroll") for (int n = 0; n < 2; ++n) _Pragma("unroll") for (int k = 0; k < 2; ++k) \
;         acc[ai][bj][m][n] = __builtin_amdgcn_mfma_f32_16x16x32_bf16(Bt[n][k], At[m][k], acc[ai][bj][m][n], 0, 0, 0); __builtin_amdgcn_s_setprio(0); } while (0)
; #define PG8_WAIT_V(n) asm volatile("s_waitcnt vmcnt(" #n ")" ::: "memory")
; #define PG8_WAIT_L(n) asm volatile("s_waitcnt lgkmcnt(" #n ")" ::: "memory")
; #define PG8_BAR __builtin_amdgcn_s_barrier()
; #define PG8_SCHED __builtin_amdgcn_sched_barrier(0)
; template <class Epi, bool ALIGN_EPI>
; __device__ __forceinline__ void gemm_phase(LAS unsigned char* lds, const Gemm g, const StaticOrder& S, const Epi& E) {
;     ...
;             PG8_LDB(B0, 1, 0); PG8_LDB(B1, 1, 1); PG8_SCHED; PG8_LDA(At, 1, 0); PG8_STAGE(PG8_SA(0, 1), a2 + hstep, voffA);
;             PG8_WAIT_V(8); PG8_WAIT_L(0); PG8_BAR; PG8_MMA(0, 0, At, B0); PG8_MMA(0, 1, At, B1); PG8_BAR; PG8_SCHED;
	s_setprio 0
	s_add_i32 s43, 0, 0x18000
	s_add_i32 s62, 0, 0x1c000
	v_add_u32_e32 v158, s43, v166
	v_add_u32_e32 v184, s62, v166
	ds_read_b128 v[146:149], v158
	ds_read_b128 v[150:153], v158 offset:1024
	ds_read_b128 v[154:157], v158 offset:2048
	ds_read_b128 v[158:161], v158 offset:3072
	ds_read_b128 v[172:175], v184
	ds_read_b128 v[176:179], v184 offset:1024
	ds_read_b128 v[180:183], v184 offset:2048
	ds_read_b128 v[184:187], v184 offset:3072
	s_add_u32 s10, s10, 0x40000
	s_addc_u32 s11, s11, 0
	s_mov_b32 m0, s52
	v_lshl_add_u64 v[228:229], s[10:11], 0, v[130:131]
	ds_read_b128 v[188:191], v170 offset:32768
	ds_read_b128 v[192:195], v170 offset:33792
	ds_read_b128 v[196:199], v170 offset:34816
	ds_read_b128 v[200:203], v170 offset:35840
	ds_read_b128 v[204:207], v170 offset:36864
	ds_read_b128 v[208:211], v170 offset:37888
	ds_read_b128 v[212:215], v170 offset:38912
	ds_read_b128 v[216:219], v170 offset:39936
	global_load_lds_dwordx4 v[228:229], off
	v_lshl_add_u64 v[228:229], s[10:11], 0, v[134:135]
	s_mov_b32 m0, s53
	s_nop 0
	global_load_lds_dwordx4 v[228:229], off
	s_waitcnt vmcnt(8)
	s_waitcnt lgkmcnt(0)
	s_setprio 3
	s_barrier
	s_waitcnt lgkmcnt(0)
	v_mfma_f32_16x16x32_bf16 v[126:129], v[146:149], v[188:191], v[126:129]
	v_mfma_f32_16x16x32_bf16 v[118:121], v[154:157], v[188:191], v[118:121]
	v_mfma_f32_16x16x32_bf16 v[110:113], v[146:149], v[196:199], v[110:113]
	v_mfma_f32_16x16x32_bf16 v[102:105], v[154:157], v[196:199], v[102:105]
	v_mfma_f32_16x16x32_bf16 v[94:97], v[146:149], v[204:207], v[94:97]
	v_mfma_f32_16x16x32_bf16 v[86:89], v[154:157], v[204:207], v[86:89]
	v_mfma_f32_16x16x32_bf16 v[78:81], v[146:149], v[212:215], v[78:81]
	v_mfma_f32_16x16x32_bf16 v[70:73], v[154:157], v[212:215], v[70:73]
	v_mfma_f32_16x16x32_bf16 v[126:129], v[150:153], v[192:195], v[126:129]
	v_mfma_f32_16x16x32_bf16 v[118:121], v[158:161], v[192:195], v[118:121]
	v_mfma_f32_16x16x32_bf16 v[110:113], v[150:153], v[200:203], v[110:113]
	v_mfma_f32_16x16x32_bf16 v[102:105], v[158:161], v[200:203], v[102:105]
	v_mfma_f32_16x16x32_bf16 v[94:97], v[150:153], v[208:211], v[94:97]
	v_mfma_f32_16x16x32_bf16 v[86:89], v[158:161], v[208:211], v[86:89]
	v_mfma_f32_16x16x32_bf16 v[78:81], v[150:153], v[216:219], v[78:81]
	v_mfma_f32_16x16x32_bf16 v[70:73], v[158:161], v[216:219], v[70:73]
	v_mfma_f32_16x16x32_bf16 v[122:125], v[172:175], v[188:191], v[122:125]
	v_mfma_f32_16x16x32_bf16 v[114:117], v[180:183], v[188:191], v[114:117]
	v_mfma_f32_16x16x32_bf16 v[106:109], v[172:175], v[196:199], v[106:109]
	v_mfma_f32_16x16x32_bf16 v[98:101], v[180:183], v[196:199], v[98:101]
	v_mfma_f32_16x16x32_bf16 v[90:93], v[172:175], v[204:207], v[90:93]
	v_mfma_f32_16x16x32_bf16 v[82:85], v[180:183], v[204:207], v[82:85]
	v_mfma_f32_16x16x32_bf16 v[74:77], v[172:175], v[212:215], v[74:77]
	v_mfma_f32_16x16x32_bf16 v[66:69], v[180:183], v[212:215], v[66:69]
	v_mfma_f32_16x16x32_bf16 v[122:125], v[176:179], v[192:195], v[122:125]
	v_mfma_f32_16x16x32_bf16 v[114:117], v[184:187], v[192:195], v[114:117]
	v_mfma_f32_16x16x32_bf16 v[106:109], v[176:179], v[200:203], v[106:109]
	v_mfma_f32_16x16x32_bf16 v[98:101], v[184:187], v[200:203], v[98:101]
	v_mfma_f32_16x16x32_bf16 v[90:93], v[176:179], v[208:211], v[90:93]
	v_mfma_f32_16x16x32_bf16 v[82:85], v[184:187], v[208:211], v[82:85]
	v_mfma_f32_16x16x32_bf16 v[74:77], v[176:179], v[216:219], v[74:77]
	v_mfma_f32_16x16x32_bf16 v[66:69], v[184:187], v[216:219], v[66:69]
	s_barrier
; #define PG8_STAGE(bufoff, gbase, voff) do { _Pragma("unroll") for (int _i = 0; _i < 2; ++_i) \
;         __builtin_amdgcn_global_load_lds((const unsigned*)((const char*)(gbase) + (voff)[_i]), (LAS unsigned*)(lds + (bufoff) + ldsw + _i * 8192), 16, 0, 0); } while (0)
; #define PG8_LDA(dst, b, h) do { _Pragma("unroll") for (int m = 0; m < 4; ++m) _Pragma("unroll") for (int k = 0; k < 2; ++k) dst[m][k] = *(const LAS bf16x8*)(lds + PG8_SA(b, h) + aoff + m * 2048 + k * 1024); } while (0)
; #define PG8_MMA(ai, bj, At, Bt) do { __builtin_amdgcn_s_setprio(3); _Pragma("unroll") for (int m = 0; m < 4; ++m) _Pragma("unroll") for (int n = 0; n < 2; ++n) _Pragma("unroll") for (int k = 0; k < 2; ++k) \
;         acc[ai][bj][m][n] = __builtin_amdgcn_mfma_f32_16x16x32_bf16(Bt[n][k], At[m][k], acc[ai][bj][m][n], 0, 0, 0); __builtin_amdgcn_s_setprio(0); } while (0)
; #define PG8_WAIT_V(n) asm volatile("s_waitcnt vmcnt(" #n ")" ::: "memory")
; #define PG8_WAIT_L(n) asm volatile("s_waitcnt lgkmcnt(" #n ")" ::: "memory")
; #define PG8_BAR __builtin_amdgcn_s_barrier()
; #define PG8_SCHED __builtin_amdgcn_sched_barrier(0)
; template <class Epi, bool ALIGN_EPI>
; __device__ __forceinline__ void gemm_phase(LAS unsigned char* lds, const Gemm g, const StaticOrder& S, const Epi& E) {
;     ...
;             PG8_LDA(At, 1, 1); PG8_STAGE(PG8_SB(1, 0), b3, voffB); PG8_STAGE(PG8_SB(1, 1), b3 + hstep, voffB); PG8_STAGE(PG8_SA(1, 0), a3, voffA);
;             PG8_WAIT_V(8); PG8_WAIT_L(0); PG8_BAR; PG8_MMA(1, 0, At, B0); PG8_MMA(1, 1, At, B1); PG8_BAR; PG8_SCHED;
;         }
;         if constexpr (ALIGN_EPI) { if (wr == 0) PG8_BAR; }
	s_setprio 0
	s_add_i32 s10, s43, s33
	v_lshl_add_u64 v[220:221], v[220:221], 0, s[36:37]
	s_mov_b32 m0, s10
	ds_read_b128 v[188:191], v170 offset:49152
	ds_read_b128 v[192:195], v170 offset:50176
	ds_read_b128 v[196:199], v170 offset:51200
	ds_read_b128 v[200:203], v170 offset:52224
	ds_read_b128 v[204:207], v170 offset:53248
	ds_read_b128 v[208:211], v170 offset:54272
	ds_read_b128 v[212:215], v170 offset:55296
	ds_read_b128 v[216:219], v170 offset:56320
	global_load_lds_dwordx4 v[220:221], off
	s_add_i32 m0, s10, 0x2000
	s_add_u32 s8, s8, 0x40080
	v_lshl_add_u64 v[220:221], v[222:223], 0, s[36:37]
	s_addc_u32 s9, s9, 0
	s_add_i32 s10, s62, s33
	global_load_lds_dwordx4 v[220:221], off
	v_lshl_add_u64 v[220:221], s[8:9], 0, v[132:133]
	s_mov_b32 m0, s10
	s_nop 0
	global_load_lds_dwordx4 v[220:221], off
	v_lshl_add_u64 v[220:221], s[8:9], 0, v[136:137]
	s_add_i32 m0, s10, 0x2000
	s_nop 0
	global_load_lds_dwordx4 v[220:221], off
	v_lshl_add_u64 v[220:221], v[224:225], 0, s[36:37]
	s_mov_b32 m0, s56
	s_nop 0
	global_load_lds_dwordx4 v[220:221], off
	v_lshl_add_u64 v[220:221], v[226:227], 0, s[36:37]
	s_mov_b32 m0, s57
	s_nop 0
	global_load_lds_dwordx4 v[220:221], off
	s_waitcnt vmcnt(8)
	s_waitcnt lgkmcnt(0)
	s_setprio 3
	s_barrier
	s_waitcnt lgkmcnt(0)
	v_mfma_f32_16x16x32_bf16 v[62:65], v[146:149], v[188:191], v[62:65]
	v_mfma_f32_16x16x32_bf16 v[54:57], v[154:157], v[188:191], v[54:57]
	v_mfma_f32_16x16x32_bf16 v[46:49], v[146:149], v[196:199], v[46:49]
	v_mfma_f32_16x16x32_bf16 v[38:41], v[154:157], v[196:199], v[38:41]
	v_mfma_f32_16x16x32_bf16 v[30:33], v[146:149], v[204:207], v[30:33]
	v_mfma_f32_16x16x32_bf16 v[22:25], v[154:157], v[204:207], v[22:25]
	v_mfma_f32_16x16x32_bf16 v[14:17], v[146:149], v[212:215], v[14:17]
	v_mfma_f32_16x16x32_bf16 v[6:9], v[154:157], v[212:215], v[6:9]
	v_mfma_f32_16x16x32_bf16 v[62:65], v[150:153], v[192:195], v[62:65]
	v_mfma_f32_16x16x32_bf16 v[54:57], v[158:161], v[192:195], v[54:57]
	v_mfma_f32_16x16x32_bf16 v[46:49], v[150:153], v[200:203], v[46:49]
	v_mfma_f32_16x16x32_bf16 v[38:41], v[158:161], v[200:203], v[38:41]
	v_mfma_f32_16x16x32_bf16 v[30:33], v[150:153], v[208:211], v[30:33]
	v_mfma_f32_16x16x32_bf16 v[22:25], v[158:161], v[208:211], v[22:25]
	v_mfma_f32_16x16x32_bf16 v[14:17], v[150:153], v[216:219], v[14:17]
	v_mfma_f32_16x16x32_bf16 v[6:9], v[158:161], v[216:219], v[6:9]
	v_mfma_f32_16x16x32_bf16 v[58:61], v[172:175], v[188:191], v[58:61]
	v_mfma_f32_16x16x32_bf16 v[50:53], v[180:183], v[188:191], v[50:53]
	v_mfma_f32_16x16x32_bf16 v[42:45], v[172:175], v[196:199], v[42:45]
	v_mfma_f32_16x16x32_bf16 v[34:37], v[180:183], v[196:199], v[34:37]
	v_mfma_f32_16x16x32_bf16 v[26:29], v[172:175], v[204:207], v[26:29]
	v_mfma_f32_16x16x32_bf16 v[18:21], v[180:183], v[204:207], v[18:21]
	v_mfma_f32_16x16x32_bf16 v[10:13], v[172:175], v[212:215], v[10:13]
	v_mfma_f32_16x16x32_bf16 v[2:5], v[180:183], v[212:215], v[2:5]
	v_mfma_f32_16x16x32_bf16 v[58:61], v[176:179], v[192:195], v[58:61]
	v_mfma_f32_16x16x32_bf16 v[50:53], v[184:187], v[192:195], v[50:53]
	v_mfma_f32_16x16x32_bf16 v[42:45], v[176:179], v[200:203], v[42:45]
	v_mfma_f32_16x16x32_bf16 v[34:37], v[184:187], v[200:203], v[34:37]
	v_mfma_f32_16x16x32_bf16 v[26:29], v[176:179], v[208:211], v[26:29]
	v_mfma_f32_16x16x32_bf16 v[18:21], v[184:187], v[208:211], v[18:21]
	v_mfma_f32_16x16x32_bf16 v[10:13], v[176:179], v[216:219], v[10:13]
	v_mfma_f32_16x16x32_bf16 v[2:5], v[184:187], v[216:219], v[2:5]
	s_barrier
	s_setprio 0
	s_add_i32 s41, s41, 2
	s_add_u32 s6, s6, 0x100
	s_addc_u32 s7, s7, 0
	s_add_u32 s16, s16, 0x100
	s_addc_u32 s17, s17, 0
	s_cmp_gt_u32 s41, 13
	s_cbranch_scc0 .LBB0_1428
	s_and_b64 vcc, exec, s[38:39]
	s_cbranch_vccz .LBB0_1431
	s_barrier

; #define PG8_STAGE(bufoff, gbase, voff) do { _Pragma("unroll") for (int _i = 0; _i < 2; ++_i) \
;         __builtin_amdgcn_global_load_lds((const unsigned*)((const char*)(gbase) + (voff)[_i]), (LAS unsigned*)(lds + (bufoff) + ldsw + _i * 8192), 16, 0, 0); } while (0)
; #define PG8_LDA(dst, b, h) do { _Pragma("unroll") for (int m = 0; m < 4; ++m) _Pragma("unroll") for (int k = 0; k < 2; ++k) dst[m][k] = *(const LAS bf16x8*)(lds + PG8_SA(b, h) + aoff + m * 2048 + k * 1024); } while (0)
; #define PG8_LDB(dst, b, h) do { _Pragma("unroll") for (int n = 0; n < 2; ++n) _Pragma("unroll") for (int k = 0; k < 2; ++k) dst[n][k] = *(const LAS bf16x8*)(lds + PG8_SB(b, h) + boff + n * 2048 + k * 1024); } while (0)
; #define PG8_MMA(ai, bj, At, Bt) do { __builtin_amdgcn_s_setprio(3); _Pragma("unroll") for (int m = 0; m < 4; ++m) _Pragma("unroll") for (int n = 0; n < 2; ++n) _Pragma("unroll") for (int k = 0; k < 2; ++k) \
;         acc[ai][bj][m][n] = __builtin_amdgcn_mfma_f32_16x16x32_bf16(Bt[n][k], At[m][k], acc[ai][bj][m][n], 0, 0, 0); __builtin_amdgcn_s_setprio(0); } while (0)
; #define PG8_WAIT_V(n) asm volatile("s_waitcnt vmcnt(" #n ")" ::: "memory")
; #define PG8_WAIT_L(n) asm volatile("s_waitcnt lgkmcnt(" #n ")" ::: "memory")
; #define PG8_BAR __builtin_amdgcn_s_barrier()
; #define PG8_SCHED __builtin_amdgcn_sched_barrier(0)
; template <class Epi, bool ALIGN_EPI>
; __device__ __forceinline__ void gemm_phase(LAS unsigned char* lds, const Gemm g, const StaticOrder& S, const Epi& E) {
;     ...
;         for (int t = 0; t < nt; t += 2) {
;             const bool last = (t == nt - 2);
;             const char* a1 = cA + (size_t)(t + 1) * kstep;
;             const char* a2 = last ? nA : cA + (size_t)(t + 2) * kstep; const char* b2 = last ? nB : cB + (size_t)(t + 2) * kstep;
;             const char* a3 = a2 + kstep; const char* b3 = b2 + kstep;
;             PG8_LDB(B0, 0, 0); PG8_LDB(B1, 0, 1); PG8_SCHED; PG8_LDA(At, 0, 0); PG8_STAGE(PG8_SA(1, 1), a1 + hstep, voffA);
;             PG8_WAIT_V(8); PG8_WAIT_L(0); PG8_BAR; PG8_MMA(0, 0, At, B0); PG8_MMA(0, 1, At, B1); PG8_BAR; PG8_SCHED;
;             PG8_LDA(At, 0, 1); PG8_STAGE(PG8_SB(0, 0), b2, voffB); PG8_STAGE(PG8_SB(0, 1), b2 + hstep, voffB); PG8_STAGE(PG8_SA(0, 0), a2, voffA);
.LBB0_1512:
	s_add_u32 s14, s14, 0xb0080
	s_addc_u32 s15, s15, 0
	s_add_u32 s43, s16, 0x100
	s_addc_u32 s44, s17, 0
	s_mov_b32 s45, -2
	ds_read_b128 v[144:147], v158
	ds_read_b128 v[148:151], v158 offset:1024
	ds_read_b128 v[162:165], v158 offset:2048
	ds_read_b128 v[166:169], v158 offset:3072
	ds_read_b128 v[170:173], v159
	ds_read_b128 v[174:177], v159 offset:1024
	ds_read_b128 v[178:181], v159 offset:2048
	ds_read_b128 v[182:185], v159 offset:3072
	s_add_u32 s16, s14, 0xfff50080
	s_addc_u32 s17, s15, -1
	s_cmp_eq_u32 s45, 40
	s_cselect_b32 s19, s5, s17
	s_cselect_b32 s18, s4, s16
	s_cselect_b32 s17, s13, s44
	s_cselect_b32 s16, s12, s43
	v_lshl_add_u64 v[218:219], s[14:15], 0, v[136:137]
	s_add_i32 m0, s26, 0xc000
	ds_read_b128 v[186:189], v160
	ds_read_b128 v[190:193], v160 offset:1024
	ds_read_b128 v[194:197], v160 offset:2048
	ds_read_b128 v[198:201], v160 offset:3072
	ds_read_b128 v[202:205], v160 offset:4096
	ds_read_b128 v[206:209], v160 offset:5120
	ds_read_b128 v[210:213], v160 offset:6144
	ds_read_b128 v[214:217], v160 offset:7168
	global_load_lds_dwordx4 v[218:219], off
	v_lshl_add_u64 v[218:219], s[14:15], 0, v[138:139]
	s_add_i32 m0, s26, 0xe000
	s_nop 0
	global_load_lds_dwordx4 v[218:219], off
	s_waitcnt vmcnt(8)
	s_waitcnt lgkmcnt(0)
	s_setprio 3
	s_barrier
	s_waitcnt lgkmcnt(0)
	v_mfma_f32_16x16x32_bf16 v[124:127], v[144:147], v[186:189], 0
	v_mfma_f32_16x16x32_bf16 v[120:123], v[162:165], v[186:189], 0
	v_mfma_f32_16x16x32_bf16 v[108:111], v[144:147], v[194:197], 0
	v_mfma_f32_16x16x32_bf16 v[104:107], v[162:165], v[194:197], 0
	v_mfma_f32_16x16x32_bf16 v[96:99], v[144:147], v[202:205], 0
	v_mfma_f32_16x16x32_bf16 v[88:91], v[162:165], v[202:205], 0
	v_mfma_f32_16x16x32_bf16 v[80:83], v[144:147], v[210:213], 0
	v_mfma_f32_16x16x32_bf16 v[72:75], v[162:165], v[210:213], 0
	v_mfma_f32_16x16x32_bf16 v[124:127], v[148:151], v[190:193], v[124:127]
	v_mfma_f32_16x16x32_bf16 v[120:123], v[166:169], v[190:193], v[120:123]
	v_mfma_f32_16x16x32_bf16 v[108:111], v[148:151], v[198:201], v[108:111]
	v_mfma_f32_16x16x32_bf16 v[104:107], v[166:169], v[198:201], v[104:107]
	v_mfma_f32_16x16x32_bf16 v[96:99], v[148:151], v[206:209], v[96:99]
	v_mfma_f32_16x16x32_bf16 v[88:91], v[166:169], v[206:209], v[88:91]
	v_mfma_f32_16x16x32_bf16 v[80:83], v[148:151], v[214:217], v[80:83]
	v_mfma_f32_16x16x32_bf16 v[72:75], v[166:169], v[214:217], v[72:75]
	v_mfma_f32_16x16x32_bf16 v[116:119], v[170:173], v[186:189], 0
	v_mfma_f32_16x16x32_bf16 v[112:115], v[178:181], v[186:189], 0
	v_mfma_f32_16x16x32_bf16 v[100:103], v[170:173], v[194:197], 0
	v_mfma_f32_16x16x32_bf16 v[92:95], v[178:181], v[194:197], 0
	v_mfma_f32_16x16x32_bf16 v[84:87], v[170:173], v[202:205], 0
	v_mfma_f32_16x16x32_bf16 v[76:79], v[178:181], v[202:205], 0
	v_mfma_f32_16x16x32_bf16 v[68:71], v[170:173], v[210:213], 0
	v_mfma_f32_16x16x32_bf16 v[64:67], v[178:181], v[210:213], 0
	v_mfma_f32_16x16x32_bf16 v[116:119], v[174:177], v[190:193], v[116:119]
	v_mfma_f32_16x16x32_bf16 v[112:115], v[182:185], v[190:193], v[112:115]
	v_mfma_f32_16x16x32_bf16 v[100:103], v[174:177], v[198:201], v[100:103]
	v_mfma_f32_16x16x32_bf16 v[92:95], v[182:185], v[198:201], v[92:95]
	v_mfma_f32_16x16x32_bf16 v[84:87], v[174:177], v[206:209], v[84:87]
	v_mfma_f32_16x16x32_bf16 v[76:79], v[182:185], v[206:209], v[76:79]
	v_mfma_f32_16x16x32_bf16 v[68:71], v[174:177], v[214:217], v[68:71]
	v_mfma_f32_16x16x32_bf16 v[64:67], v[182:185], v[214:217], v[64:67]
	s_barrier
	s_setprio 0
	s_add_i32 s46, s37, s23
	v_lshl_add_u64 v[218:219], s[16:17], 0, v[130:131]
	s_mov_b32 m0, s46
	ds_read_b128 v[186:189], v160 offset:16384
	ds_read_b128 v[190:193], v160 offset:17408
	ds_read_b128 v[194:197], v160 offset:18432
	ds_read_b128 v[198:201], v160 offset:19456
	ds_read_b128 v[202:205], v160 offset:20480
	ds_read_b128 v[206:209], v160 offset:21504
	ds_read_b128 v[210:213], v160 offset:22528
	ds_read_b128 v[214:217], v160 offset:23552
	global_load_lds_dwordx4 v[218:219], off
	s_add_i32 m0, s46, 0x2000
	s_add_u32 s46, s16, 0xb0000
	v_lshl_add_u64 v[220:221], s[16:17], 0, v[134:135]
	s_addc_u32 s47, s17, 0
	s_add_i32 s48, s38, s23
	global_load_lds_dwordx4 v[220:221], off
	v_lshl_add_u64 v[222:223], s[46:47], 0, v[130:131]
	s_mov_b32 m0, s48
	v_lshl_add_u64 v[224:225], s[18:19], 0, v[132:133]
	global_load_lds_dwordx4 v[222:223], off
	v_lshl_add_u64 v[222:223], s[46:47], 0, v[134:135]
	s_add_i32 m0, s48, 0x2000
	s_nop 0
	global_load_lds_dwordx4 v[222:223], off
	v_lshl_add_u64 v[222:223], s[18:19], 0, v[128:129]
	s_mov_b32 m0, s26
	s_nop 0
	global_load_lds_dwordx4 v[222:223], off
	s_mov_b32 m0, s27
	s_nop 0
	global_load_lds_dwordx4 v[224:225], off
	s_waitcnt vmcnt(8)
	s_waitcnt lgkmcnt(0)
	s_setprio 3
	s_barrier
; #define PG8_STAGE(bufoff, gbase, voff) do { _Pragma("unroll") for (int _i = 0; _i < 2; ++_i) \
;         __builtin_amdgcn_global_load_lds((const unsigned*)((const char*)(gbase) + (voff)[_i]), (LAS unsigned*)(lds + (bufoff) + ldsw + _i * 8192), 16, 0, 0); } while (0)
; #define PG8_LDA(dst, b, h) do { _Pragma("unroll") for (int m = 0; m < 4; ++m) _Pragma("unroll") for (int k = 0; k < 2; ++k) dst[m][k] = *(const LAS bf16x8*)(lds + PG8_SA(b, h) + aoff + m * 2048 + k * 1024); } while (0)
; #define PG8_LDB(dst, b, h) do { _Pragma("unroll") for (int n = 0; n < 2; ++n) _Pragma("unroll") for (int k = 0; k < 2; ++k) dst[n][k] = *(const LAS bf16x8*)(lds + PG8_SB(b, h) + boff + n * 2048 + k * 1024); } while (0)
; #define PG8_MMA(ai, bj, At, Bt) do { __builtin_amdgcn_s_setprio(3); _Pragma("unroll") for (int m = 0; m < 4; ++m) _Pragma("unroll") for (int n = 0; n < 2; ++n) _Pragma("unroll") for (int k = 0; k < 2; ++k) \
;         acc[ai][bj][m][n] = __builtin_amdgcn_mfma_f32_16x16x32_bf16(Bt[n][k], At[m][k], acc[ai][bj][m][n], 0, 0, 0); __builtin_amdgcn_s_setprio(0); } while (0)
; #define PG8_WAIT_V(n) asm volatile("s_waitcnt vmcnt(" #n ")" ::: "memory")
; #define PG8_BAR __builtin_amdgcn_s_barrier()
; template <class Epi, bool ALIGN_EPI>
; __device__ __forceinline__ void gemm_phase(LAS unsigned char* lds, const Gemm g, const StaticOrder& S, const Epi& E) {
;     ...
;             PG8_LDB(B0, 0, 0); PG8_LDB(B1, 0, 1); PG8_SCHED; PG8_LDA(At, 0, 0); PG8_STAGE(PG8_SA(1, 1), a1 + hstep, voffA);
;             PG8_WAIT_V(8); PG8_WAIT_L(0); PG8_BAR; PG8_MMA(0, 0, At, B0); PG8_MMA(0, 1, At, B1); PG8_BAR; PG8_SCHED;
;             PG8_LDA(At, 0, 1); PG8_STAGE(PG8_SB(0, 0), b2, voffB); PG8_STAGE(PG8_SB(0, 1), b2 + hstep, voffB); PG8_STAGE(PG8_SA(0, 0), a2, voffA);
;             PG8_WAIT_V(8); PG8_WAIT_L(0); PG8_BAR; PG8_MMA(1, 0, At, B0); PG8_MMA(1, 1, At, B1); PG8_BAR; PG8_SCHED;
;             PG8_LDB(B0, 1, 0); PG8_LDB(B1, 1, 1); PG8_SCHED; PG8_LDA(At, 1, 0); PG8_STAGE(PG8_SA(0, 1), a2 + hstep, voffA);
;             PG8_WAIT_V(8); PG8_WAIT_L(0); PG8_BAR; PG8_MMA(0, 0, At, B0); PG8_MMA(0, 1, At, B1); PG8_BAR; PG8_SCHED;
;             PG8_LDA(At, 1, 1); PG8_STAGE(PG8_SB(1, 0), b3, voffB); PG8_STAGE(PG8_SB(1, 1), b3 + hstep, voffB); PG8_STAGE(PG8_SA(1, 0), a3, voffA);
;             PG8_WAIT_V(8); PG8_WAIT_L(0); PG8_BAR; PG8_MMA(1, 0, At, B0); PG8_MMA(1, 1, At, B1); PG8_BAR; PG8_SCHED;
	s_waitcnt lgkmcnt(0)
	v_mfma_f32_16x16x32_bf16 v[60:63], v[144:147], v[186:189], 0
	v_mfma_f32_16x16x32_bf16 v[56:59], v[162:165], v[186:189], 0
	v_mfma_f32_16x16x32_bf16 v[48:51], v[144:147], v[194:197], 0
	v_mfma_f32_16x16x32_bf16 v[40:43], v[162:165], v[194:197], 0
	v_mfma_f32_16x16x32_bf16 v[32:35], v[144:147], v[202:205], 0
	v_mfma_f32_16x16x32_bf16 v[24:27], v[162:165], v[202:205], 0
	v_mfma_f32_16x16x32_bf16 v[16:19], v[144:147], v[210:213], 0
	v_mfma_f32_16x16x32_bf16 v[8:11], v[162:165], v[210:213], 0
	v_mfma_f32_16x16x32_bf16 v[60:63], v[148:151], v[190:193], v[60:63]
	v_mfma_f32_16x16x32_bf16 v[56:59], v[166:169], v[190:193], v[56:59]
	v_mfma_f32_16x16x32_bf16 v[48:51], v[148:151], v[198:201], v[48:51]
	v_mfma_f32_16x16x32_bf16 v[40:43], v[166:169], v[198:201], v[40:43]
	v_mfma_f32_16x16x32_bf16 v[32:35], v[148:151], v[206:209], v[32:35]
	v_mfma_f32_16x16x32_bf16 v[24:27], v[166:169], v[206:209], v[24:27]
	v_mfma_f32_16x16x32_bf16 v[16:19], v[148:151], v[214:217], v[16:19]
	v_mfma_f32_16x16x32_bf16 v[8:11], v[166:169], v[214:217], v[8:11]
	v_mfma_f32_16x16x32_bf16 v[52:55], v[170:173], v[186:189], 0
	v_mfma_f32_16x16x32_bf16 v[44:47], v[178:181], v[186:189], 0
	v_mfma_f32_16x16x32_bf16 v[36:39], v[170:173], v[194:197], 0
	v_mfma_f32_16x16x32_bf16 v[28:31], v[178:181], v[194:197], 0
	v_mfma_f32_16x16x32_bf16 v[20:23], v[170:173], v[202:205], 0
	v_mfma_f32_16x16x32_bf16 v[12:15], v[178:181], v[202:205], 0
	v_mfma_f32_16x16x32_bf16 v[4:7], v[170:173], v[210:213], 0
	v_mfma_f32_16x16x32_bf16 v[0:3], v[178:181], v[210:213], 0
	v_mfma_f32_16x16x32_bf16 v[52:55], v[174:177], v[190:193], v[52:55]
	v_mfma_f32_16x16x32_bf16 v[44:47], v[182:185], v[190:193], v[44:47]
	v_mfma_f32_16x16x32_bf16 v[36:39], v[174:177], v[198:201], v[36:39]
	v_mfma_f32_16x16x32_bf16 v[28:31], v[182:185], v[198:201], v[28:31]
	v_mfma_f32_16x16x32_bf16 v[20:23], v[174:177], v[206:209], v[20:23]
	v_mfma_f32_16x16x32_bf16 v[12:15], v[182:185], v[206:209], v[12:15]
	v_mfma_f32_16x16x32_bf16 v[4:7], v[174:177], v[214:217], v[4:7]
	v_mfma_f32_16x16x32_bf16 v[0:3], v[182:185], v[214:217], v[0:3]
	s_barrier
	s_setprio 0
	s_add_i32 s46, 0, 0x18000
	v_add_u32_e32 v161, s46, v156
	s_add_i32 s47, 0, 0x1c000
	ds_read_b128 v[144:147], v161
	ds_read_b128 v[148:151], v161 offset:1024
	ds_read_b128 v[162:165], v161 offset:2048
	ds_read_b128 v[166:169], v161 offset:3072
	v_add_u32_e32 v161, s47, v156
	ds_read_b128 v[170:173], v161
	ds_read_b128 v[174:177], v161 offset:1024
	ds_read_b128 v[178:181], v161 offset:2048
	ds_read_b128 v[182:185], v161 offset:3072
	s_add_u32 s18, s18, 0xb0000
	s_addc_u32 s19, s19, 0
	s_mov_b32 m0, s28
	v_lshl_add_u64 v[226:227], s[18:19], 0, v[128:129]
	ds_read_b128 v[186:189], v160 offset:32768
	ds_read_b128 v[190:193], v160 offset:33792
	ds_read_b128 v[194:197], v160 offset:34816
	ds_read_b128 v[198:201], v160 offset:35840
	ds_read_b128 v[202:205], v160 offset:36864
	ds_read_b128 v[206:209], v160 offset:37888
	ds_read_b128 v[210:213], v160 offset:38912
	ds_read_b128 v[214:217], v160 offset:39936
	global_load_lds_dwordx4 v[226:227], off
	v_lshl_add_u64 v[226:227], s[18:19], 0, v[132:133]
	s_mov_b32 m0, s29
	s_nop 0
	global_load_lds_dwordx4 v[226:227], off
	s_waitcnt vmcnt(8)
	s_waitcnt lgkmcnt(0)
	s_setprio 3
	s_barrier
	s_waitcnt lgkmcnt(0)
	v_mfma_f32_16x16x32_bf16 v[124:127], v[144:147], v[186:189], v[124:127]
	v_mfma_f32_16x16x32_bf16 v[120:123], v[162:165], v[186:189], v[120:123]
	v_mfma_f32_16x16x32_bf16 v[108:111], v[144:147], v[194:197], v[108:111]
	v_mfma_f32_16x16x32_bf16 v[104:107], v[162:165], v[194:197], v[104:107]
	v_mfma_f32_16x16x32_bf16 v[96:99], v[144:147], v[202:205], v[96:99]
	v_mfma_f32_16x16x32_bf16 v[88:91], v[162:165], v[202:205], v[88:91]
	v_mfma_f32_16x16x32_bf16 v[80:83], v[144:147], v[210:213], v[80:83]
	v_mfma_f32_16x16x32_bf16 v[72:75], v[162:165], v[210:213], v[72:75]
	v_mfma_f32_16x16x32_bf16 v[124:127], v[148:151], v[190:193], v[124:127]
	v_mfma_f32_16x16x32_bf16 v[120:123], v[166:169], v[190:193], v[120:123]
	v_mfma_f32_16x16x32_bf16 v[108:111], v[148:151], v[198:201], v[108:111]
	v_mfma_f32_16x16x32_bf16 v[104:107], v[166:169], v[198:201], v[104:107]
	v_mfma_f32_16x16x32_bf16 v[96:99], v[148:151], v[206:209], v[96:99]
	v_mfma_f32_16x16x32_bf16 v[88:91], v[166:169], v[206:209], v[88:91]
	v_mfma_f32_16x16x32_bf16 v[80:83], v[148:151], v[214:217], v[80:83]
	v_mfma_f32_16x16x32_bf16 v[72:75], v[166:169], v[214:217], v[72:75]
	v_mfma_f32_16x16x32_bf16 v[116:119], v[170:173], v[186:189], v[116:119]
	v_mfma_f32_16x16x32_bf16 v[112:115], v[178:181], v[186:189], v[112:115]
	v_mfma_f32_16x16x32_bf16 v[100:103], v[170:173], v[194:197], v[100:103]
	v_mfma_f32_16x16x32_bf16 v[92:95], v[178:181], v[194:197], v[92:95]
	v_mfma_f32_16x16x32_bf16 v[84:87], v[170:173], v[202:205], v[84:87]
	v_mfma_f32_16x16x32_bf16 v[76:79], v[178:181], v[202:205], v[76:79]
	v_mfma_f32_16x16x32_bf16 v[68:71], v[170:173], v[210:213], v[68:71]
	v_mfma_f32_16x16x32_bf16 v[64:67], v[178:181], v[210:213], v[64:67]
	v_mfma_f32_16x16x32_bf16 v[116:119], v[174:177], v[190:193], v[116:119]
	v_mfma_f32_16x16x32_bf16 v[112:115], v[182:185], v[190:193], v[112:115]
	v_mfma_f32_16x16x32_bf16 v[100:103], v[174:177], v[198:201], v[100:103]
	v_mfma_f32_16x16x32_bf16 v[92:95], v[182:185], v[198:201], v[92:95]
	v_mfma_f32_16x16x32_bf16 v[84:87], v[174:177], v[206:209], v[84:87]
	v_mfma_f32_16x16x32_bf16 v[76:79], v[182:185], v[206:209], v[76:79]
	v_mfma_f32_16x16x32_bf16 v[68:71], v[174:177], v[214:217], v[68:71]
	v_mfma_f32_16x16x32_bf16 v[64:67], v[182:185], v[214:217], v[64:67]
	s_barrier
; #define PG8_STAGE(bufoff, gbase, voff) do { _Pragma("unroll") for (int _i = 0; _i < 2; ++_i) \
;         __builtin_amdgcn_global_load_lds((const unsigned*)((const char*)(gbase) + (voff)[_i]), (LAS unsigned*)(lds + (bufoff) + ldsw + _i * 8192), 16, 0, 0); } while (0)
; #define PG8_LDA(dst, b, h) do { _Pragma("unroll") for (int m = 0; m < 4; ++m) _Pragma("unroll") for (int k = 0; k < 2; ++k) dst[m][k] = *(const LAS bf16x8*)(lds + PG8_SA(b, h) + aoff + m * 2048 + k * 1024); } while (0)
; #define PG8_LDB(dst, b, h) do { _Pragma("unroll") for (int n = 0; n < 2; ++n) _Pragma("unroll") for (int k = 0; k < 2; ++k) dst[n][k] = *(const LAS bf16x8*)(lds + PG8_SB(b, h) + boff + n * 2048 + k * 1024); } while (0)
; #define PG8_MMA(ai, bj, At, Bt) do { __builtin_amdgcn_s_setprio(3); _Pragma("unroll") for (int m = 0; m < 4; ++m) _Pragma("unroll") for (int n = 0; n < 2; ++n) _Pragma("unroll") for (int k = 0; k < 2; ++k) \
;         acc[ai][bj][m][n] = __builtin_amdgcn_mfma_f32_16x16x32_bf16(Bt[n][k], At[m][k], acc[ai][bj][m][n], 0, 0, 0); __builtin_amdgcn_s_setprio(0); } while (0)
; #define PG8_WAIT_V(n) asm volatile("s_waitcnt vmcnt(" #n ")" ::: "memory")
; #define PG8_BAR __builtin_amdgcn_s_barrier()
; template <class Epi, bool ALIGN_EPI>
; __device__ __forceinline__ void gemm_phase(LAS unsigned char* lds, const Gemm g, const StaticOrder& S, const Epi& E) {
;     ...
;             PG8_LDB(B0, 0, 0); PG8_LDB(B1, 0, 1); PG8_SCHED; PG8_LDA(At, 0, 0); PG8_STAGE(PG8_SA(1, 1), a1 + hstep, voffA);
;             PG8_WAIT_V(8); PG8_WAIT_L(0); PG8_BAR; PG8_MMA(0, 0, At, B0); PG8_MMA(0, 1, At, B1); PG8_BAR; PG8_SCHED;
;             PG8_LDA(At, 0, 1); PG8_STAGE(PG8_SB(0, 0), b2, voffB); PG8_STAGE(PG8_SB(0, 1), b2 + hstep, voffB); PG8_STAGE(PG8_SA(0, 0), a2, voffA);
;             PG8_WAIT_V(8); PG8_WAIT_L(0); PG8_BAR; PG8_MMA(1, 0, At, B0); PG8_MMA(1, 1, At, B1); PG8_BAR; PG8_SCHED;
;             PG8_LDB(B0, 1, 0); PG8_LDB(B1, 1, 1); PG8_SCHED; PG8_LDA(At, 1, 0); PG8_STAGE(PG8_SA(0, 1), a2 + hstep, voffA);
;             PG8_WAIT_V(8); PG8_WAIT_L(0); PG8_BAR; PG8_MMA(0, 0, At, B0); PG8_MMA(0, 1, At, B1); PG8_BAR; PG8_SCHED;
;             PG8_LDA(At, 1, 1); PG8_STAGE(PG8_SB(1, 0), b3, voffB); PG8_STAGE(PG8_SB(1, 1), b3 + hstep, voffB); PG8_STAGE(PG8_SA(1, 0), a3, voffA);
;             PG8_WAIT_V(8); PG8_WAIT_L(0); PG8_BAR; PG8_MMA(1, 0, At, B0); PG8_MMA(1, 1, At, B1); PG8_BAR; PG8_SCHED;
	s_setprio 0
	s_add_i32 s18, s46, s23
	v_lshl_add_u64 v[218:219], v[218:219], 0, s[8:9]
	s_mov_b32 m0, s18
	ds_read_b128 v[186:189], v160 offset:49152
	ds_read_b128 v[190:193], v160 offset:50176
	ds_read_b128 v[194:197], v160 offset:51200
	ds_read_b128 v[198:201], v160 offset:52224
	ds_read_b128 v[202:205], v160 offset:53248
	ds_read_b128 v[206:209], v160 offset:54272
	ds_read_b128 v[210:213], v160 offset:55296
	ds_read_b128 v[214:217], v160 offset:56320
	global_load_lds_dwordx4 v[218:219], off
	s_add_i32 m0, s18, 0x2000
	s_add_u32 s16, s16, 0xb0080
	v_lshl_add_u64 v[218:219], v[220:221], 0, s[8:9]
	s_addc_u32 s17, s17, 0
	s_add_i32 s18, s47, s23
	global_load_lds_dwordx4 v[218:219], off
	v_lshl_add_u64 v[218:219], s[16:17], 0, v[130:131]
	s_mov_b32 m0, s18
	s_nop 0
	global_load_lds_dwordx4 v[218:219], off
	v_lshl_add_u64 v[218:219], s[16:17], 0, v[134:135]
	s_add_i32 m0, s18, 0x2000
	s_nop 0
	global_load_lds_dwordx4 v[218:219], off
	v_lshl_add_u64 v[218:219], v[222:223], 0, s[8:9]
	s_mov_b32 m0, s31
	s_nop 0
	global_load_lds_dwordx4 v[218:219], off
	v_lshl_add_u64 v[218:219], v[224:225], 0, s[8:9]
	s_mov_b32 m0, s33
	s_nop 0
	global_load_lds_dwordx4 v[218:219], off
	s_waitcnt vmcnt(8)
	s_waitcnt lgkmcnt(0)
	s_setprio 3
	s_barrier
	s_waitcnt lgkmcnt(0)
	v_mfma_f32_16x16x32_bf16 v[60:63], v[144:147], v[186:189], v[60:63]
	v_mfma_f32_16x16x32_bf16 v[56:59], v[162:165], v[186:189], v[56:59]
	v_mfma_f32_16x16x32_bf16 v[48:51], v[144:147], v[194:197], v[48:51]
	v_mfma_f32_16x16x32_bf16 v[40:43], v[162:165], v[194:197], v[40:43]
	v_mfma_f32_16x16x32_bf16 v[32:35], v[144:147], v[202:205], v[32:35]
	v_mfma_f32_16x16x32_bf16 v[24:27], v[162:165], v[202:205], v[24:27]
	v_mfma_f32_16x16x32_bf16 v[16:19], v[144:147], v[210:213], v[16:19]
	v_mfma_f32_16x16x32_bf16 v[8:11], v[162:165], v[210:213], v[8:11]
	v_mfma_f32_16x16x32_bf16 v[60:63], v[148:151], v[190:193], v[60:63]
	v_mfma_f32_16x16x32_bf16 v[56:59], v[166:169], v[190:193], v[56:59]
	v_mfma_f32_16x16x32_bf16 v[48:51], v[148:151], v[198:201], v[48:51]
	v_mfma_f32_16x16x32_bf16 v[40:43], v[166:169], v[198:201], v[40:43]
	v_mfma_f32_16x16x32_bf16 v[32:35], v[148:151], v[206:209], v[32:35]
	v_mfma_f32_16x16x32_bf16 v[24:27], v[166:169], v[206:209], v[24:27]
	v_mfma_f32_16x16x32_bf16 v[16:19], v[148:151], v[214:217], v[16:19]
	v_mfma_f32_16x16x32_bf16 v[8:11], v[166:169], v[214:217], v[8:11]
	v_mfma_f32_16x16x32_bf16 v[52:55], v[170:173], v[186:189], v[52:55]
	v_mfma_f32_16x16x32_bf16 v[44:47], v[178:181], v[186:189], v[44:47]
	v_mfma_f32_16x16x32_bf16 v[36:39], v[170:173], v[194:197], v[36:39]
	v_mfma_f32_16x16x32_bf16 v[28:31], v[178:181], v[194:197], v[28:31]
	v_mfma_f32_16x16x32_bf16 v[20:23], v[170:173], v[202:205], v[20:23]
	v_mfma_f32_16x16x32_bf16 v[12:15], v[178:181], v[202:205], v[12:15]
	v_mfma_f32_16x16x32_bf16 v[4:7], v[170:173], v[210:213], v[4:7]
	v_mfma_f32_16x16x32_bf16 v[0:3], v[178:181], v[210:213], v[0:3]
	v_mfma_f32_16x16x32_bf16 v[52:55], v[174:177], v[190:193], v[52:55]
	v_mfma_f32_16x16x32_bf16 v[44:47], v[182:185], v[190:193], v[44:47]
	v_mfma_f32_16x16x32_bf16 v[36:39], v[174:177], v[198:201], v[36:39]
	v_mfma_f32_16x16x32_bf16 v[28:31], v[182:185], v[198:201], v[28:31]
	v_mfma_f32_16x16x32_bf16 v[20:23], v[174:177], v[206:209], v[20:23]
	v_mfma_f32_16x16x32_bf16 v[12:15], v[182:185], v[206:209], v[12:15]
	v_mfma_f32_16x16x32_bf16 v[4:7], v[174:177], v[214:217], v[4:7]
	v_mfma_f32_16x16x32_bf16 v[0:3], v[182:185], v[214:217], v[0:3]
	s_barrier
	s_setprio 0
	s_add_i32 s45, s45, 2
	s_add_u32 s14, s14, 0x100
	s_addc_u32 s15, s15, 0
	s_add_u32 s43, s43, 0x100
	s_addc_u32 s44, s44, 0
.LBB0_1513:
	ds_read_b128 v[144:147], v158
	ds_read_b128 v[148:151], v158 offset:1024
	ds_read_b128 v[162:165], v158 offset:2048
	ds_read_b128 v[166:169], v158 offset:3072
	ds_read_b128 v[170:173], v159
	ds_read_b128 v[174:177], v159 offset:1024
	ds_read_b128 v[178:181], v159 offset:2048
	ds_read_b128 v[182:185], v159 offset:3072
	s_add_u32 s16, s14, 0xfff50080
	s_addc_u32 s17, s15, -1
	s_cmp_eq_u32 s45, 40
	s_cselect_b32 s19, s5, s17
	s_cselect_b32 s18, s4, s16
	s_cselect_b32 s17, s13, s44
	s_cselect_b32 s16, s12, s43
	v_lshl_add_u64 v[218:219], s[14:15], 0, v[136:137]
	s_add_i32 m0, s26, 0xc000
	ds_read_b128 v[186:189], v160
	ds_read_b128 v[190:193], v160 offset:1024
	ds_read_b128 v[194:197], v160 offset:2048
	ds_read_b128 v[198:201], v160 offset:3072
	ds_read_b128 v[202:205], v160 offset:4096
	ds_read_b128 v[206:209], v160 offset:5120
	ds_read_b128 v[210:213], v160 offset:6144
	ds_read_b128 v[214:217], v160 offset:7168
	global_load_lds_dwordx4 v[218:219], off
	v_lshl_add_u64 v[218:219], s[14:15], 0, v[138:139]
	s_add_i32 m0, s26, 0xe000
	s_nop 0
	global_load_lds_dwordx4 v[218:219], off
	s_waitcnt vmcnt(8)
	s_waitcnt lgkmcnt(0)
	s_setprio 3
	s_barrier
; #define PG8_STAGE(bufoff, gbase, voff) do { _Pragma("unroll") for (int _i = 0; _i < 2; ++_i) \
;         __builtin_amdgcn_global_load_lds((const unsigned*)((const char*)(gbase) + (voff)[_i]), (LAS unsigned*)(lds + (bufoff) + ldsw + _i * 8192), 16, 0, 0); } while (0)
; #define PG8_LDA(dst, b, h) do { _Pragma("unroll") for (int m = 0; m < 4; ++m) _Pragma("unroll") for (int k = 0; k < 2; ++k) dst[m][k] = *(const LAS bf16x8*)(lds + PG8_SA(b, h) + aoff + m * 2048 + k * 1024); } while (0)
; #define PG8_LDB(dst, b, h) do { _Pragma("unroll") for (int n = 0; n < 2; ++n) _Pragma("unroll") for (int k = 0; k < 2; ++k) dst[n][k] = *(const LAS bf16x8*)(lds + PG8_SB(b, h) + boff + n * 2048 + k * 1024); } while (0)
; #define PG8_MMA(ai, bj, At, Bt) do { __builtin_amdgcn_s_setprio(3); _Pragma("unroll") for (int m = 0; m < 4; ++m) _Pragma("unroll") for (int n = 0; n < 2; ++n) _Pragma("unroll") for (int k = 0; k < 2; ++k) \
;         acc[ai][bj][m][n] = __builtin_amdgcn_mfma_f32_16x16x32_bf16(Bt[n][k], At[m][k], acc[ai][bj][m][n], 0, 0, 0); __builtin_amdgcn_s_setprio(0); } while (0)
; #define PG8_WAIT_V(n) asm volatile("s_waitcnt vmcnt(" #n ")" ::: "memory")
; #define PG8_BAR __builtin_amdgcn_s_barrier()
; template <class Epi, bool ALIGN_EPI>
; __device__ __forceinline__ void gemm_phase(LAS unsigned char* lds, const Gemm g, const StaticOrder& S, const Epi& E) {
;     ...
;             PG8_LDB(B0, 0, 0); PG8_LDB(B1, 0, 1); PG8_SCHED; PG8_LDA(At, 0, 0); PG8_STAGE(PG8_SA(1, 1), a1 + hstep, voffA);
;             PG8_WAIT_V(8); PG8_WAIT_L(0); PG8_BAR; PG8_MMA(0, 0, At, B0); PG8_MMA(0, 1, At, B1); PG8_BAR; PG8_SCHED;
;             PG8_LDA(At, 0, 1); PG8_STAGE(PG8_SB(0, 0), b2, voffB); PG8_STAGE(PG8_SB(0, 1), b2 + hstep, voffB); PG8_STAGE(PG8_SA(0, 0), a2, voffA);
;             PG8_WAIT_V(8); PG8_WAIT_L(0); PG8_BAR; PG8_MMA(1, 0, At, B0); PG8_MMA(1, 1, At, B1); PG8_BAR; PG8_SCHED;
;             PG8_LDB(B0, 1, 0); PG8_LDB(B1, 1, 1); PG8_SCHED; PG8_LDA(At, 1, 0); PG8_STAGE(PG8_SA(0, 1), a2 + hstep, voffA);
;             PG8_WAIT_V(8); PG8_WAIT_L(0); PG8_BAR; PG8_MMA(0, 0, At, B0); PG8_MMA(0, 1, At, B1); PG8_BAR; PG8_SCHED;
;             PG8_LDA(At, 1, 1); PG8_STAGE(PG8_SB(1, 0), b3, voffB); PG8_STAGE(PG8_SB(1, 1), b3 + hstep, voffB); PG8_STAGE(PG8_SA(1, 0), a3, voffA);
;             PG8_WAIT_V(8); PG8_WAIT_L(0); PG8_BAR; PG8_MMA(1, 0, At, B0); PG8_MMA(1, 1, At, B1); PG8_BAR; PG8_SCHED;
	s_waitcnt lgkmcnt(0)
	v_mfma_f32_16x16x32_bf16 v[124:127], v[144:147], v[186:189], v[124:127]
	v_mfma_f32_16x16x32_bf16 v[120:123], v[162:165], v[186:189], v[120:123]
	v_mfma_f32_16x16x32_bf16 v[108:111], v[144:147], v[194:197], v[108:111]
	v_mfma_f32_16x16x32_bf16 v[104:107], v[162:165], v[194:197], v[104:107]
	v_mfma_f32_16x16x32_bf16 v[96:99], v[144:147], v[202:205], v[96:99]
	v_mfma_f32_16x16x32_bf16 v[88:91], v[162:165], v[202:205], v[88:91]
	v_mfma_f32_16x16x32_bf16 v[80:83], v[144:147], v[210:213], v[80:83]
	v_mfma_f32_16x16x32_bf16 v[72:75], v[162:165], v[210:213], v[72:75]
	v_mfma_f32_16x16x32_bf16 v[124:127], v[148:151], v[190:193], v[124:127]
	v_mfma_f32_16x16x32_bf16 v[120:123], v[166:169], v[190:193], v[120:123]
	v_mfma_f32_16x16x32_bf16 v[108:111], v[148:151], v[198:201], v[108:111]
	v_mfma_f32_16x16x32_bf16 v[104:107], v[166:169], v[198:201], v[104:107]
	v_mfma_f32_16x16x32_bf16 v[96:99], v[148:151], v[206:209], v[96:99]
	v_mfma_f32_16x16x32_bf16 v[88:91], v[166:169], v[206:209], v[88:91]
	v_mfma_f32_16x16x32_bf16 v[80:83], v[148:151], v[214:217], v[80:83]
	v_mfma_f32_16x16x32_bf16 v[72:75], v[166:169], v[214:217], v[72:75]
	v_mfma_f32_16x16x32_bf16 v[116:119], v[170:173], v[186:189], v[116:119]
	v_mfma_f32_16x16x32_bf16 v[112:115], v[178:181], v[186:189], v[112:115]
	v_mfma_f32_16x16x32_bf16 v[100:103], v[170:173], v[194:197], v[100:103]
	v_mfma_f32_16x16x32_bf16 v[92:95], v[178:181], v[194:197], v[92:95]
	v_mfma_f32_16x16x32_bf16 v[84:87], v[170:173], v[202:205], v[84:87]
	v_mfma_f32_16x16x32_bf16 v[76:79], v[178:181], v[202:205], v[76:79]
	v_mfma_f32_16x16x32_bf16 v[68:71], v[170:173], v[210:213], v[68:71]
	v_mfma_f32_16x16x32_bf16 v[64:67], v[178:181], v[210:213], v[64:67]
	v_mfma_f32_16x16x32_bf16 v[116:119], v[174:177], v[190:193], v[116:119]
	v_mfma_f32_16x16x32_bf16 v[112:115], v[182:185], v[190:193], v[112:115]
	v_mfma_f32_16x16x32_bf16 v[100:103], v[174:177], v[198:201], v[100:103]
	v_mfma_f32_16x16x32_bf16 v[92:95], v[182:185], v[198:201], v[92:95]
	v_mfma_f32_16x16x32_bf16 v[84:87], v[174:177], v[206:209], v[84:87]
	v_mfma_f32_16x16x32_bf16 v[76:79], v[182:185], v[206:209], v[76:79]
	v_mfma_f32_16x16x32_bf16 v[68:71], v[174:177], v[214:217], v[68:71]
	v_mfma_f32_16x16x32_bf16 v[64:67], v[182:185], v[214:217], v[64:67]
	s_barrier
	s_setprio 0
	s_add_i32 s46, s37, s23
	v_lshl_add_u64 v[218:219], s[16:17], 0, v[130:131]
	s_mov_b32 m0, s46
	ds_read_b128 v[186:189], v160 offset:16384
	ds_read_b128 v[190:193], v160 offset:17408
	ds_read_b128 v[194:197], v160 offset:18432
	ds_read_b128 v[198:201], v160 offset:19456
	ds_read_b128 v[202:205], v160 offset:20480
	ds_read_b128 v[206:209], v160 offset:21504
	ds_read_b128 v[210:213], v160 offset:22528
	ds_read_b128 v[214:217], v160 offset:23552
	global_load_lds_dwordx4 v[218:219], off
	s_add_i32 m0, s46, 0x2000
	s_add_u32 s46, s16, 0xb0000
	v_lshl_add_u64 v[220:221], s[16:17], 0, v[134:135]
	s_addc_u32 s47, s17, 0
	s_add_i32 s48, s38, s23
	global_load_lds_dwordx4 v[220:221], off
	v_lshl_add_u64 v[222:223], s[46:47], 0, v[130:131]
	s_mov_b32 m0, s48
	v_lshl_add_u64 v[224:225], s[18:19], 0, v[132:133]
	global_load_lds_dwordx4 v[222:223], off
	v_lshl_add_u64 v[222:223], s[46:47], 0, v[134:135]
	s_add_i32 m0, s48, 0x2000
	s_nop 0
	global_load_lds_dwordx4 v[222:223], off
	v_lshl_add_u64 v[222:223], s[18:19], 0, v[128:129]
	s_mov_b32 m0, s26
	s_nop 0
	global_load_lds_dwordx4 v[222:223], off
	s_mov_b32 m0, s27
	s_nop 0
	global_load_lds_dwordx4 v[224:225], off
	s_waitcnt vmcnt(8)
	s_waitcnt lgkmcnt(0)
	s_setprio 3
	s_barrier
	s_waitcnt lgkmcnt(0)
	v_mfma_f32_16x16x32_bf16 v[60:63], v[144:147], v[186:189], v[60:63]
	v_mfma_f32_16x16x32_bf16 v[56:59], v[162:165], v[186:189], v[56:59]
	v_mfma_f32_16x16x32_bf16 v[48:51], v[144:147], v[194:197], v[48:51]
	v_mfma_f32_16x16x32_bf16 v[40:43], v[162:165], v[194:197], v[40:43]
	v_mfma_f32_16x16x32_bf16 v[32:35], v[144:147], v[202:205], v[32:35]
	v_mfma_f32_16x16x32_bf16 v[24:27], v[162:165], v[202:205], v[24:27]
	v_mfma_f32_16x16x32_bf16 v[16:19], v[144:147], v[210:213], v[16:19]
	v_mfma_f32_16x16x32_bf16 v[8:11], v[162:165], v[210:213], v[8:11]
	v_mfma_f32_16x16x32_bf16 v[60:63], v[148:151], v[190:193], v[60:63]
	v_mfma_f32_16x16x32_bf16 v[56:59], v[166:169], v[190:193], v[56:59]
	v_mfma_f32_16x16x32_bf16 v[48:51], v[148:151], v[198:201], v[48:51]
	v_mfma_f32_16x16x32_bf16 v[40:43], v[166:169], v[198:201], v[40:43]
	v_mfma_f32_16x16x32_bf16 v[32:35], v[148:151], v[206:209], v[32:35]
	v_mfma_f32_16x16x32_bf16 v[24:27], v[166:169], v[206:209], v[24:27]
	v_mfma_f32_16x16x32_bf16 v[16:19], v[148:151], v[214:217], v[16:19]
	v_mfma_f32_16x16x32_bf16 v[8:11], v[166:169], v[214:217], v[8:11]
	v_mfma_f32_16x16x32_bf16 v[52:55], v[170:173], v[186:189], v[52:55]
	v_mfma_f32_16x16x32_bf16 v[44:47], v[178:181], v[186:189], v[44:47]
	v_mfma_f32_16x16x32_bf16 v[36:39], v[170:173], v[194:197], v[36:39]
	v_mfma_f32_16x16x32_bf16 v[28:31], v[178:181], v[194:197], v[28:31]
	v_mfma_f32_16x16x32_bf16 v[20:23], v[170:173], v[202:205], v[20:23]
	v_mfma_f32_16x16x32_bf16 v[12:15], v[178:181], v[202:205], v[12:15]
	v_mfma_f32_16x16x32_bf16 v[4:7], v[170:173], v[210:213], v[4:7]
	v_mfma_f32_16x16x32_bf16 v[0:3], v[178:181], v[210:213], v[0:3]
	v_mfma_f32_16x16x32_bf16 v[52:55], v[174:177], v[190:193], v[52:55]
	v_mfma_f32_16x16x32_bf16 v[44:47], v[182:185], v[190:193], v[44:47]
	v_mfma_f32_16x16x32_bf16 v[36:39], v[174:177], v[198:201], v[36:39]
	v_mfma_f32_16x16x32_bf16 v[28:31], v[182:185], v[198:201], v[28:31]
	v_mfma_f32_16x16x32_bf16 v[20:23], v[174:177], v[206:209], v[20:23]
	v_mfma_f32_16x16x32_bf16 v[12:15], v[182:185], v[206:209], v[12:15]
	v_mfma_f32_16x16x32_bf16 v[4:7], v[174:177], v[214:217], v[4:7]
	v_mfma_f32_16x16x32_bf16 v[0:3], v[182:185], v[214:217], v[0:3]
	s_barrier
; #define PG8_STAGE(bufoff, gbase, voff) do { _Pragma("unroll") for (int _i = 0; _i < 2; ++_i) \
;         __builtin_amdgcn_global_load_lds((const unsigned*)((const char*)(gbase) + (voff)[_i]), (LAS unsigned*)(lds + (bufoff) + ldsw + _i * 8192), 16, 0, 0); } while (0)
; #define PG8_LDA(dst, b, h) do { _Pragma("unroll") for (int m = 0; m < 4; ++m) _Pragma("unroll") for (int k = 0; k < 2; ++k) dst[m][k] = *(const LAS bf16x8*)(lds + PG8_SA(b, h) + aoff + m * 2048 + k * 1024); } while (0)
; #define PG8_LDB(dst, b, h) do { _Pragma("unroll") for (int n = 0; n < 2; ++n) _Pragma("unroll") for (int k = 0; k < 2; ++k) dst[n][k] = *(const LAS bf16x8*)(lds + PG8_SB(b, h) + boff + n * 2048 + k * 1024); } while (0)
; #define PG8_MMA(ai, bj, At, Bt) do { __builtin_amdgcn_s_setprio(3); _Pragma("unroll") for (int m = 0; m < 4; ++m) _Pragma("unroll") for (int n = 0; n < 2; ++n) _Pragma("unroll") for (int k = 0; k < 2; ++k) \
;         acc[ai][bj][m][n] = __builtin_amdgcn_mfma_f32_16x16x32_bf16(Bt[n][k], At[m][k], acc[ai][bj][m][n], 0, 0, 0); __builtin_amdgcn_s_setprio(0); } while (0)
; #define PG8_WAIT_V(n) asm volatile("s_waitcnt vmcnt(" #n ")" ::: "memory")
; #define PG8_BAR __builtin_amdgcn_s_barrier()
; template <class Epi, bool ALIGN_EPI>
; __device__ __forceinline__ void gemm_phase(LAS unsigned char* lds, const Gemm g, const StaticOrder& S, const Epi& E) {
;     ...
;             PG8_LDB(B0, 0, 0); PG8_LDB(B1, 0, 1); PG8_SCHED; PG8_LDA(At, 0, 0); PG8_STAGE(PG8_SA(1, 1), a1 + hstep, voffA);
;             PG8_WAIT_V(8); PG8_WAIT_L(0); PG8_BAR; PG8_MMA(0, 0, At, B0); PG8_MMA(0, 1, At, B1); PG8_BAR; PG8_SCHED;
;             PG8_LDA(At, 0, 1); PG8_STAGE(PG8_SB(0, 0), b2, voffB); PG8_STAGE(PG8_SB(0, 1), b2 + hstep, voffB); PG8_STAGE(PG8_SA(0, 0), a2, voffA);
;             PG8_WAIT_V(8); PG8_WAIT_L(0); PG8_BAR; PG8_MMA(1, 0, At, B0); PG8_MMA(1, 1, At, B1); PG8_BAR; PG8_SCHED;
;             PG8_LDB(B0, 1, 0); PG8_LDB(B1, 1, 1); PG8_SCHED; PG8_LDA(At, 1, 0); PG8_STAGE(PG8_SA(0, 1), a2 + hstep, voffA);
;             PG8_WAIT_V(8); PG8_WAIT_L(0); PG8_BAR; PG8_MMA(0, 0, At, B0); PG8_MMA(0, 1, At, B1); PG8_BAR; PG8_SCHED;
;             PG8_LDA(At, 1, 1); PG8_STAGE(PG8_SB(1, 0), b3, voffB); PG8_STAGE(PG8_SB(1, 1), b3 + hstep, voffB); PG8_STAGE(PG8_SA(1, 0), a3, voffA);
;             PG8_WAIT_V(8); PG8_WAIT_L(0); PG8_BAR; PG8_MMA(1, 0, At, B0); PG8_MMA(1, 1, At, B1); PG8_BAR; PG8_SCHED;
	s_setprio 0
	s_add_i32 s46, 0, 0x18000
	v_add_u32_e32 v161, s46, v156
	s_add_i32 s47, 0, 0x1c000
	ds_read_b128 v[144:147], v161
	ds_read_b128 v[148:151], v161 offset:1024
	ds_read_b128 v[162:165], v161 offset:2048
	ds_read_b128 v[166:169], v161 offset:3072
	v_add_u32_e32 v161, s47, v156
	ds_read_b128 v[170:173], v161
	ds_read_b128 v[174:177], v161 offset:1024
	ds_read_b128 v[178:181], v161 offset:2048
	ds_read_b128 v[182:185], v161 offset:3072
	s_add_u32 s18, s18, 0xb0000
	s_addc_u32 s19, s19, 0
	s_mov_b32 m0, s28
	v_lshl_add_u64 v[226:227], s[18:19], 0, v[128:129]
	ds_read_b128 v[186:189], v160 offset:32768
	ds_read_b128 v[190:193], v160 offset:33792
	ds_read_b128 v[194:197], v160 offset:34816
	ds_read_b128 v[198:201], v160 offset:35840
	ds_read_b128 v[202:205], v160 offset:36864
	ds_read_b128 v[206:209], v160 offset:37888
	ds_read_b128 v[210:213], v160 offset:38912
	ds_read_b128 v[214:217], v160 offset:39936
	global_load_lds_dwordx4 v[226:227], off
	v_lshl_add_u64 v[226:227], s[18:19], 0, v[132:133]
	s_mov_b32 m0, s29
	s_nop 0
	global_load_lds_dwordx4 v[226:227], off
	s_waitcnt vmcnt(8)
	s_waitcnt lgkmcnt(0)
	s_setprio 3
	s_barrier
	s_waitcnt lgkmcnt(0)
	v_mfma_f32_16x16x32_bf16 v[124:127], v[144:147], v[186:189], v[124:127]
	v_mfma_f32_16x16x32_bf16 v[120:123], v[162:165], v[186:189], v[120:123]
	v_mfma_f32_16x16x32_bf16 v[108:111], v[144:147], v[194:197], v[108:111]
	v_mfma_f32_16x16x32_bf16 v[104:107], v[162:165], v[194:197], v[104:107]
	v_mfma_f32_16x16x32_bf16 v[96:99], v[144:147], v[202:205], v[96:99]
	v_mfma_f32_16x16x32_bf16 v[88:91], v[162:165], v[202:205], v[88:91]
	v_mfma_f32_16x16x32_bf16 v[80:83], v[144:147], v[210:213], v[80:83]
	v_mfma_f32_16x16x32_bf16 v[72:75], v[162:165], v[210:213], v[72:75]
	v_mfma_f32_16x16x32_bf16 v[124:127], v[148:151], v[190:193], v[124:127]
	v_mfma_f32_16x16x32_bf16 v[120:123], v[166:169], v[190:193], v[120:123]
	v_mfma_f32_16x16x32_bf16 v[108:111], v[148:151], v[198:201], v[108:111]
	v_mfma_f32_16x16x32_bf16 v[104:107], v[166:169], v[198:201], v[104:107]
	v_mfma_f32_16x16x32_bf16 v[96:99], v[148:151], v[206:209], v[96:99]
	v_mfma_f32_16x16x32_bf16 v[88:91], v[166:169], v[206:209], v[88:91]
	v_mfma_f32_16x16x32_bf16 v[80:83], v[148:151], v[214:217], v[80:83]
	v_mfma_f32_16x16x32_bf16 v[72:75], v[166:169], v[214:217], v[72:75]
	v_mfma_f32_16x16x32_bf16 v[116:119], v[170:173], v[186:189], v[116:119]
	v_mfma_f32_16x16x32_bf16 v[112:115], v[178:181], v[186:189], v[112:115]
	v_mfma_f32_16x16x32_bf16 v[100:103], v[170:173], v[194:197], v[100:103]
	v_mfma_f32_16x16x32_bf16 v[92:95], v[178:181], v[194:197], v[92:95]
	v_mfma_f32_16x16x32_bf16 v[84:87], v[170:173], v[202:205], v[84:87]
	v_mfma_f32_16x16x32_bf16 v[76:79], v[178:181], v[202:205], v[76:79]
	v_mfma_f32_16x16x32_bf16 v[68:71], v[170:173], v[210:213], v[68:71]
	v_mfma_f32_16x16x32_bf16 v[64:67], v[178:181], v[210:213], v[64:67]
	v_mfma_f32_16x16x32_bf16 v[116:119], v[174:177], v[190:193], v[116:119]
	v_mfma_f32_16x16x32_bf16 v[112:115], v[182:185], v[190:193], v[112:115]
	v_mfma_f32_16x16x32_bf16 v[100:103], v[174:177], v[198:201], v[100:103]
	v_mfma_f32_16x16x32_bf16 v[92:95], v[182:185], v[198:201], v[92:95]
	v_mfma_f32_16x16x32_bf16 v[84:87], v[174:177], v[206:209], v[84:87]
	v_mfma_f32_16x16x32_bf16 v[76:79], v[182:185], v[206:209], v[76:79]
	v_mfma_f32_16x16x32_bf16 v[68:71], v[174:177], v[214:217], v[68:71]
	v_mfma_f32_16x16x32_bf16 v[64:67], v[182:185], v[214:217], v[64:67]
	s_barrier
; #define PG8_STAGE(bufoff, gbase, voff) do { _Pragma("unroll") for (int _i = 0; _i < 2; ++_i) \
;         __builtin_amdgcn_global_load_lds((const unsigned*)((const char*)(gbase) + (voff)[_i]), (LAS unsigned*)(lds + (bufoff) + ldsw + _i * 8192), 16, 0, 0); } while (0)
; #define PG8_LDA(dst, b, h) do { _Pragma("unroll") for (int m = 0; m < 4; ++m) _Pragma("unroll") for (int k = 0; k < 2; ++k) dst[m][k] = *(const LAS bf16x8*)(lds + PG8_SA(b, h) + aoff + m * 2048 + k * 1024); } while (0)
; #define PG8_LDB(dst, b, h) do { _Pragma("unroll") for (int n = 0; n < 2; ++n) _Pragma("unroll") for (int k = 0; k < 2; ++k) dst[n][k] = *(const LAS bf16x8*)(lds + PG8_SB(b, h) + boff + n * 2048 + k * 1024); } while (0)
; #define PG8_BAR __builtin_amdgcn_s_barrier()
; template <class Epi, bool ALIGN_EPI>
; __device__ __forceinline__ void gemm_phase(LAS unsigned char* lds, const Gemm g, const StaticOrder& S, const Epi& E) {
;     ...
;         for (int t = 0; t < nt; t += 2) {
;             const bool last = (t == nt - 2);
;             const char* a1 = cA + (size_t)(t + 1) * kstep;
;             const char* a2 = last ? nA : cA + (size_t)(t + 2) * kstep; const char* b2 = last ? nB : cB + (size_t)(t + 2) * kstep;
;             const char* a3 = a2 + kstep; const char* b3 = b2 + kstep;
;             PG8_LDB(B0, 0, 0); PG8_LDB(B1, 0, 1); PG8_SCHED; PG8_LDA(At, 0, 0); PG8_STAGE(PG8_SA(1, 1), a1 + hstep, voffA);
;             PG8_WAIT_V(8); PG8_WAIT_L(0); PG8_BAR; PG8_MMA(0, 0, At, B0); PG8_MMA(0, 1, At, B1); PG8_BAR; PG8_SCHED;
;             PG8_LDA(At, 0, 1); PG8_STAGE(PG8_SB(0, 0), b2, voffB); PG8_STAGE(PG8_SB(0, 1), b2 + hstep, voffB); PG8_STAGE(PG8_SA(0, 0), a2, voffA);
;             PG8_WAIT_V(8); PG8_WAIT_L(0); PG8_BAR; PG8_MMA(1, 0, At, B0); PG8_MMA(1, 1, At, B1); PG8_BAR; PG8_SCHED;
;             PG8_LDB(B0, 1, 0); PG8_LDB(B1, 1, 1); PG8_SCHED; PG8_LDA(At, 1, 0); PG8_STAGE(PG8_SA(0, 1), a2 + hstep, voffA);
;             PG8_WAIT_V(8); PG8_WAIT_L(0); PG8_BAR; PG8_MMA(0, 0, At, B0); PG8_MMA(0, 1, At, B1); PG8_BAR; PG8_SCHED;
;             PG8_LDA(At, 1, 1); PG8_STAGE(PG8_SB(1, 0), b3, voffB); PG8_STAGE(PG8_SB(1, 1), b3 + hstep, voffB); PG8_STAGE(PG8_SA(1, 0), a3, voffA);
;             PG8_WAIT_V(8); PG8_WAIT_L(0); PG8_BAR; PG8_MMA(1, 0, At, B0); PG8_MMA(1, 1, At, B1); PG8_BAR; PG8_SCHED;
;         }
;         if constexpr (ALIGN_EPI) { if (wr == 0) PG8_BAR; }
	s_setprio 0
	s_add_i32 s18, s46, s23
	v_lshl_add_u64 v[218:219], v[218:219], 0, s[8:9]
	s_mov_b32 m0, s18
	ds_read_b128 v[186:189], v160 offset:49152
	ds_read_b128 v[190:193], v160 offset:50176
	ds_read_b128 v[194:197], v160 offset:51200
	ds_read_b128 v[198:201], v160 offset:52224
	ds_read_b128 v[202:205], v160 offset:53248
	ds_read_b128 v[206:209], v160 offset:54272
	ds_read_b128 v[210:213], v160 offset:55296
	ds_read_b128 v[214:217], v160 offset:56320
	global_load_lds_dwordx4 v[218:219], off
	s_add_i32 m0, s18, 0x2000
	s_add_u32 s16, s16, 0xb0080
	v_lshl_add_u64 v[218:219], v[220:221], 0, s[8:9]
	s_addc_u32 s17, s17, 0
	s_add_i32 s18, s47, s23
	global_load_lds_dwordx4 v[218:219], off
	v_lshl_add_u64 v[218:219], s[16:17], 0, v[130:131]
	s_mov_b32 m0, s18
	s_nop 0
	global_load_lds_dwordx4 v[218:219], off
	v_lshl_add_u64 v[218:219], s[16:17], 0, v[134:135]
	s_add_i32 m0, s18, 0x2000
	s_nop 0
	global_load_lds_dwordx4 v[218:219], off
	v_lshl_add_u64 v[218:219], v[222:223], 0, s[8:9]
	s_mov_b32 m0, s31
	s_nop 0
	global_load_lds_dwordx4 v[218:219], off
	v_lshl_add_u64 v[218:219], v[224:225], 0, s[8:9]
	s_mov_b32 m0, s33
	s_nop 0
	global_load_lds_dwordx4 v[218:219], off
	s_waitcnt vmcnt(8)
	s_waitcnt lgkmcnt(0)
	s_setprio 3
	s_barrier
	s_waitcnt lgkmcnt(0)
	v_mfma_f32_16x16x32_bf16 v[60:63], v[144:147], v[186:189], v[60:63]
	v_mfma_f32_16x16x32_bf16 v[56:59], v[162:165], v[186:189], v[56:59]
	v_mfma_f32_16x16x32_bf16 v[48:51], v[144:147], v[194:197], v[48:51]
	v_mfma_f32_16x16x32_bf16 v[40:43], v[162:165], v[194:197], v[40:43]
	v_mfma_f32_16x16x32_bf16 v[32:35], v[144:147], v[202:205], v[32:35]
	v_mfma_f32_16x16x32_bf16 v[24:27], v[162:165], v[202:205], v[24:27]
	v_mfma_f32_16x16x32_bf16 v[16:19], v[144:147], v[210:213], v[16:19]
	v_mfma_f32_16x16x32_bf16 v[8:11], v[162:165], v[210:213], v[8:11]
	v_mfma_f32_16x16x32_bf16 v[60:63], v[148:151], v[190:193], v[60:63]
	v_mfma_f32_16x16x32_bf16 v[56:59], v[166:169], v[190:193], v[56:59]
	v_mfma_f32_16x16x32_bf16 v[48:51], v[148:151], v[198:201], v[48:51]
	v_mfma_f32_16x16x32_bf16 v[40:43], v[166:169], v[198:201], v[40:43]
	v_mfma_f32_16x16x32_bf16 v[32:35], v[148:151], v[206:209], v[32:35]
	v_mfma_f32_16x16x32_bf16 v[24:27], v[166:169], v[206:209], v[24:27]
	v_mfma_f32_16x16x32_bf16 v[16:19], v[148:151], v[214:217], v[16:19]
	v_mfma_f32_16x16x32_bf16 v[8:11], v[166:169], v[214:217], v[8:11]
	v_mfma_f32_16x16x32_bf16 v[52:55], v[170:173], v[186:189], v[52:55]
	v_mfma_f32_16x16x32_bf16 v[44:47], v[178:181], v[186:189], v[44:47]
	v_mfma_f32_16x16x32_bf16 v[36:39], v[170:173], v[194:197], v[36:39]
	v_mfma_f32_16x16x32_bf16 v[28:31], v[178:181], v[194:197], v[28:31]
	v_mfma_f32_16x16x32_bf16 v[20:23], v[170:173], v[202:205], v[20:23]
	v_mfma_f32_16x16x32_bf16 v[12:15], v[178:181], v[202:205], v[12:15]
	v_mfma_f32_16x16x32_bf16 v[4:7], v[170:173], v[210:213], v[4:7]
	v_mfma_f32_16x16x32_bf16 v[0:3], v[178:181], v[210:213], v[0:3]
	v_mfma_f32_16x16x32_bf16 v[52:55], v[174:177], v[190:193], v[52:55]
	v_mfma_f32_16x16x32_bf16 v[44:47], v[182:185], v[190:193], v[44:47]
	v_mfma_f32_16x16x32_bf16 v[36:39], v[174:177], v[198:201], v[36:39]
	v_mfma_f32_16x16x32_bf16 v[28:31], v[182:185], v[198:201], v[28:31]
	v_mfma_f32_16x16x32_bf16 v[20:23], v[174:177], v[206:209], v[20:23]
	v_mfma_f32_16x16x32_bf16 v[12:15], v[182:185], v[206:209], v[12:15]
	v_mfma_f32_16x16x32_bf16 v[4:7], v[174:177], v[214:217], v[4:7]
	v_mfma_f32_16x16x32_bf16 v[0:3], v[182:185], v[214:217], v[0:3]
	s_barrier
	s_setprio 0
	s_add_i32 s45, s45, 2
	s_add_u32 s14, s14, 0x100
	s_addc_u32 s15, s15, 0
	s_add_u32 s43, s43, 0x100
	s_addc_u32 s44, s44, 0
	s_cmp_gt_u32 s45, 41
	s_cbranch_scc0 .LBB0_1513
	s_and_b64 vcc, exec, s[10:11]
	s_cbranch_vccz .LBB0_1516
	s_barrier
